# plus GEMM unit loop: trailing half's offset-restoring barrier moved behind the next unit's index arithmetic and accumulator zeroing (register-only code), both halves set up concurrently
# baseline (speedup 1.0000x reference)
; #define LAS __attribute__((address_space(3)))
;     __device__ __forceinline__ const float* in(int i) const { return (const float*)(const __attribute__((address_space(1))) float*)get(i); }
;     __device__ __forceinline__ float* out() const { return (float*)(__attribute__((address_space(1))) float*)get(34); }
;     __device__ __forceinline__ unsigned char* ws() const { return (unsigned char*)(__attribute__((address_space(1))) unsigned char*)get(35); }
; __global__ void __launch_bounds__(512, 2) mega_fwd(Args args) {
;     extern __shared__ __attribute__((aligned(16))) unsigned char lds[];
;     LAS unsigned char* ldsL = (LAS unsigned char*)lds;
;     const int Ggemm = (int)gridDim.x, Gthin = Ggemm < THIN_GRID ? Ggemm : THIN_GRID;
;     const int bid0 = blockIdx.x, G0 = gridDim.x, wave_s = __builtin_amdgcn_readfirstlane((int)threadIdx.x >> 6);
;     volatile LAS unsigned* MISC = (volatile LAS unsigned*)(ldsL + MISC_OFF);
;     PA a; a.tab = MISC + 64;
;     ...
;     if (threadIdx.x < 64) MISC[threadIdx.x] = 0u;
;     ...
;     if (threadIdx.x == 64) {
; #pragma unroll
;         for (int i = 0; i < 34; ++i) { const unsigned long long v = (unsigned long long)args.in[i]; a.tab[2 * i] = (unsigned)v; a.tab[2 * i + 1] = (unsigned)(v >> 32); }
;         { const unsigned long long v = (unsigned long long)args.out; a.tab[68] = (unsigned)v; a.tab[69] = (unsigned)(v >> 32); }
;         { const unsigned long long v = (unsigned long long)args.ws; a.tab[70] = (unsigned)v; a.tab[71] = (unsigned)(v >> 32); }
;     }
_Z8mega_fwd4Args:
	s_mov_b32 s100, 0
	s_load_dword s87, s[0:1], 0x128
	s_add_u32 s82, s0, 0x128
	s_mov_b32 s81, s2
	s_addc_u32 s83, s1, 0
	v_readfirstlane_b32 s20, v0
	v_cmp_gt_u32_e32 vcc, 64, v0
	s_and_saveexec_b64 s[2:3], vcc
	v_lshl_add_u32 v1, v0, 2, 0
	v_add_u32_e32 v1, 0x20000, v1
	v_mov_b32_e32 v2, 0
	ds_write_b32 v1, v2
	s_or_b64 exec, exec, s[2:3]
	v_cmp_eq_u32_e32 vcc, 64, v0
	s_and_saveexec_b64 s[2:3], vcc
	s_cbranch_execz .LBB0_4
	s_load_dwordx8 s[12:19], s[0:1], 0x0
	s_load_dwordx8 s[4:11], s[0:1], 0x20
	s_add_i32 s21, 0, 0x20100
	s_add_i32 s22, 0, 0x20104
	v_mov_b32_e32 v1, s21
	s_waitcnt lgkmcnt(0)
	v_mov_b32_e32 v2, s12
	ds_write_b32 v1, v2
	v_mov_b32_e32 v1, s22
	v_mov_b32_e32 v2, s13
	s_add_i32 s12, 0, 0x20108
	ds_write_b32 v1, v2
	v_mov_b32_e32 v1, s12
	v_mov_b32_e32 v2, s14
	s_add_i32 s12, 0, 0x2010c
	ds_write_b32 v1, v2
	v_mov_b32_e32 v1, s12
	v_mov_b32_e32 v2, s15
	s_add_i32 s12, 0, 0x20110
	ds_write_b32 v1, v2
	v_mov_b32_e32 v1, s12
	v_mov_b32_e32 v2, s16
	s_add_i32 s12, 0, 0x20114
	ds_write_b32 v1, v2
	v_mov_b32_e32 v1, s12
	v_mov_b32_e32 v2, s17
	s_add_i32 s12, 0, 0x20118
	ds_write_b32 v1, v2
	v_mov_b32_e32 v1, s12
	v_mov_b32_e32 v2, s18
	s_add_i32 s12, 0, 0x2011c
	ds_write_b32 v1, v2
	v_mov_b32_e32 v1, s12
	v_mov_b32_e32 v2, s19
	s_add_i32 s12, 0, 0x20120
	ds_write_b32 v1, v2
	v_mov_b32_e32 v1, s12
	v_mov_b32_e32 v2, s4
	s_add_i32 s4, 0, 0x20124
	ds_write_b32 v1, v2
	v_mov_b32_e32 v1, s4
	v_mov_b32_e32 v2, s5
	s_add_i32 s4, 0, 0x20128
	ds_write_b32 v1, v2
	v_mov_b32_e32 v1, s4
	v_mov_b32_e32 v2, s6
	s_add_i32 s4, 0, 0x2012c
	ds_write_b32 v1, v2
	v_mov_b32_e32 v1, s4
	v_mov_b32_e32 v2, s7
	s_add_i32 s4, 0, 0x20130
	ds_write_b32 v1, v2
	v_mov_b32_e32 v1, s4
	v_mov_b32_e32 v2, s8
	s_add_i32 s4, 0, 0x20134
	ds_write_b32 v1, v2
	v_mov_b32_e32 v1, s4
	v_mov_b32_e32 v2, s9
	s_add_i32 s4, 0, 0x20138
	ds_write_b32 v1, v2
	v_mov_b32_e32 v1, s4
	v_mov_b32_e32 v2, s10
	s_add_i32 s4, 0, 0x2013c
	ds_write_b32 v1, v2
	v_mov_b32_e32 v1, s4
	s_load_dwordx2 s[4:5], s[0:1], 0x40
	v_mov_b32_e32 v2, s11
	ds_write_b32 v1, v2
	s_add_i32 s6, 0, 0x20140
	v_mov_b32_e32 v1, s6
	s_load_dwordx2 s[6:7], s[0:1], 0x48
	s_load_dwordx2 s[8:9], s[0:1], 0x50
	s_load_dwordx2 s[10:11], s[0:1], 0x58
	s_waitcnt lgkmcnt(0)
	v_mov_b32_e32 v2, s4
	s_add_i32 s4, 0, 0x20144
	ds_write_b32 v1, v2
	v_mov_b32_e32 v1, s4
	v_mov_b32_e32 v2, s5
	s_add_i32 s4, 0, 0x20148
	ds_write_b32 v1, v2
	v_mov_b32_e32 v1, s4
	v_mov_b32_e32 v2, s6
	s_add_i32 s4, 0, 0x2014c
	ds_write_b32 v1, v2
	v_mov_b32_e32 v1, s4
	v_mov_b32_e32 v2, s7
	s_add_i32 s4, 0, 0x20150
	ds_write_b32 v1, v2
	v_mov_b32_e32 v1, s4
	v_mov_b32_e32 v2, s8
	s_add_i32 s4, 0, 0x20154
	ds_write_b32 v1, v2
	v_mov_b32_e32 v1, s4
	v_mov_b32_e32 v2, s9
	s_add_i32 s4, 0, 0x20158
	ds_write_b32 v1, v2
	v_mov_b32_e32 v1, s4
	v_mov_b32_e32 v2, s10
	s_add_i32 s4, 0, 0x2015c
	ds_write_b32 v1, v2
	v_mov_b32_e32 v1, s4
	s_load_dwordx2 s[4:5], s[0:1], 0x60
	v_mov_b32_e32 v2, s11
	ds_write_b32 v1, v2
	s_add_i32 s6, 0, 0x20160
	v_mov_b32_e32 v1, s6
	s_load_dwordx2 s[6:7], s[0:1], 0x68
	s_load_dwordx2 s[8:9], s[0:1], 0x70
	s_load_dwordx2 s[10:11], s[0:1], 0x78
	s_waitcnt lgkmcnt(0)
	v_mov_b32_e32 v2, s4
	s_add_i32 s4, 0, 0x20164
	ds_write_b32 v1, v2
	v_mov_b32_e32 v1, s4
	v_mov_b32_e32 v2, s5
	s_add_i32 s4, 0, 0x20168
	ds_write_b32 v1, v2
	v_mov_b32_e32 v1, s4
	v_mov_b32_e32 v2, s6
	s_add_i32 s4, 0, 0x2016c
	ds_write_b32 v1, v2
	v_mov_b32_e32 v1, s4
	v_mov_b32_e32 v2, s7
	s_add_i32 s4, 0, 0x20170
	ds_write_b32 v1, v2
	v_mov_b32_e32 v1, s4
	v_mov_b32_e32 v2, s8
	s_add_i32 s4, 0, 0x20174
	ds_write_b32 v1, v2
	v_mov_b32_e32 v1, s4
	v_mov_b32_e32 v2, s9
	s_add_i32 s4, 0, 0x20178
	ds_write_b32 v1, v2
	v_mov_b32_e32 v1, s4
	v_mov_b32_e32 v2, s10
	s_add_i32 s4, 0, 0x2017c
	ds_write_b32 v1, v2
	v_mov_b32_e32 v1, s4
	s_load_dwordx2 s[4:5], s[0:1], 0x80
	v_mov_b32_e32 v2, s11
	ds_write_b32 v1, v2
	s_add_i32 s6, 0, 0x20180
	v_mov_b32_e32 v1, s6
	s_load_dwordx2 s[6:7], s[0:1], 0x88
	s_load_dwordx2 s[8:9], s[0:1], 0x90
	s_load_dwordx2 s[10:11], s[0:1], 0x98
	s_waitcnt lgkmcnt(0)
;     __device__ __forceinline__ const float* in(int i) const { return (const float*)(const __attribute__((address_space(1))) float*)get(i); }
;     __device__ __forceinline__ float* out() const { return (float*)(__attribute__((address_space(1))) float*)get(34); }
;     __device__ __forceinline__ unsigned char* ws() const { return (unsigned char*)(__attribute__((address_space(1))) unsigned char*)get(35); }
; __global__ void __launch_bounds__(512, 2) mega_fwd(Args args) {
;     ...
;     if (threadIdx.x == 64) {
; #pragma unroll
;         for (int i = 0; i < 34; ++i) { const unsigned long long v = (unsigned long long)args.in[i]; a.tab[2 * i] = (unsigned)v; a.tab[2 * i + 1] = (unsigned)(v >> 32); }
;         { const unsigned long long v = (unsigned long long)args.out; a.tab[68] = (unsigned)v; a.tab[69] = (unsigned)(v >> 32); }
;         { const unsigned long long v = (unsigned long long)args.ws; a.tab[70] = (unsigned)v; a.tab[71] = (unsigned)(v >> 32); }
;     }
	v_mov_b32_e32 v2, s4
	s_add_i32 s4, 0, 0x20184
	ds_write_b32 v1, v2
	v_mov_b32_e32 v1, s4
	v_mov_b32_e32 v2, s5
	s_add_i32 s4, 0, 0x20188
	ds_write_b32 v1, v2
	v_mov_b32_e32 v1, s4
	v_mov_b32_e32 v2, s6
	s_add_i32 s4, 0, 0x2018c
	ds_write_b32 v1, v2
	v_mov_b32_e32 v1, s4
	v_mov_b32_e32 v2, s7
	s_add_i32 s4, 0, 0x20190
	ds_write_b32 v1, v2
	v_mov_b32_e32 v1, s4
	v_mov_b32_e32 v2, s8
	s_add_i32 s4, 0, 0x20194
	ds_write_b32 v1, v2
	v_mov_b32_e32 v1, s4
	v_mov_b32_e32 v2, s9
	s_add_i32 s4, 0, 0x20198
	ds_write_b32 v1, v2
	v_mov_b32_e32 v1, s4
	v_mov_b32_e32 v2, s10
	s_add_i32 s4, 0, 0x2019c
	ds_write_b32 v1, v2
	v_mov_b32_e32 v1, s4
	s_load_dwordx2 s[4:5], s[0:1], 0xa0
	v_mov_b32_e32 v2, s11
	ds_write_b32 v1, v2
	s_add_i32 s6, 0, 0x201a0
	v_mov_b32_e32 v1, s6
	s_load_dwordx2 s[6:7], s[0:1], 0xa8
	s_load_dwordx2 s[8:9], s[0:1], 0xb0
	s_load_dwordx2 s[10:11], s[0:1], 0xb8
	s_waitcnt lgkmcnt(0)
	v_mov_b32_e32 v2, s4
	s_add_i32 s4, 0, 0x201a4
	ds_write_b32 v1, v2
	v_mov_b32_e32 v1, s4
	v_mov_b32_e32 v2, s5
	s_add_i32 s4, 0, 0x201a8
	ds_write_b32 v1, v2
	v_mov_b32_e32 v1, s4
	v_mov_b32_e32 v2, s6
	s_add_i32 s4, 0, 0x201ac
	ds_write_b32 v1, v2
	v_mov_b32_e32 v1, s4
	v_mov_b32_e32 v2, s7
	s_add_i32 s4, 0, 0x201b0
	ds_write_b32 v1, v2
	v_mov_b32_e32 v1, s4
	v_mov_b32_e32 v2, s8
	s_add_i32 s4, 0, 0x201b4
	ds_write_b32 v1, v2
	v_mov_b32_e32 v1, s4
	v_mov_b32_e32 v2, s9
	s_add_i32 s4, 0, 0x201b8
	ds_write_b32 v1, v2
	v_mov_b32_e32 v1, s4
	v_mov_b32_e32 v2, s10
	s_add_i32 s4, 0, 0x201bc
	ds_write_b32 v1, v2
	v_mov_b32_e32 v1, s4
	s_load_dwordx2 s[4:5], s[0:1], 0xc0
	v_mov_b32_e32 v2, s11
	ds_write_b32 v1, v2
	s_add_i32 s6, 0, 0x201c0
	v_mov_b32_e32 v1, s6
	s_load_dwordx2 s[6:7], s[0:1], 0xc8
	s_load_dwordx2 s[8:9], s[0:1], 0xd0
	s_load_dwordx2 s[10:11], s[0:1], 0xd8
	s_waitcnt lgkmcnt(0)
	v_mov_b32_e32 v2, s4
	s_add_i32 s4, 0, 0x201c4
	ds_write_b32 v1, v2
	v_mov_b32_e32 v1, s4
	v_mov_b32_e32 v2, s5
	s_add_i32 s4, 0, 0x201c8
	ds_write_b32 v1, v2
	v_mov_b32_e32 v1, s4
	v_mov_b32_e32 v2, s6
	s_add_i32 s4, 0, 0x201cc
	ds_write_b32 v1, v2
	v_mov_b32_e32 v1, s4
	v_mov_b32_e32 v2, s7
	s_add_i32 s4, 0, 0x201d0
	ds_write_b32 v1, v2
	v_mov_b32_e32 v1, s4
	v_mov_b32_e32 v2, s8
	s_add_i32 s4, 0, 0x201d4
	ds_write_b32 v1, v2
	v_mov_b32_e32 v1, s4
	v_mov_b32_e32 v2, s9
	s_add_i32 s4, 0, 0x201d8
	ds_write_b32 v1, v2
	v_mov_b32_e32 v1, s4
	v_mov_b32_e32 v2, s10
	s_add_i32 s4, 0, 0x201dc
	ds_write_b32 v1, v2
	v_mov_b32_e32 v1, s4
	s_load_dwordx2 s[4:5], s[0:1], 0xe0
	v_mov_b32_e32 v2, s11
	ds_write_b32 v1, v2
	s_add_i32 s6, 0, 0x201e0
	v_mov_b32_e32 v1, s6
	s_load_dwordx2 s[6:7], s[0:1], 0xe8
	s_load_dwordx2 s[8:9], s[0:1], 0xf0
	s_load_dwordx2 s[10:11], s[0:1], 0xf8
	s_waitcnt lgkmcnt(0)
	v_mov_b32_e32 v2, s4
	s_add_i32 s4, 0, 0x201e4
	ds_write_b32 v1, v2
	v_mov_b32_e32 v1, s4
	v_mov_b32_e32 v2, s5
	s_add_i32 s4, 0, 0x201e8
	ds_write_b32 v1, v2
	v_mov_b32_e32 v1, s4
	v_mov_b32_e32 v2, s6
	s_add_i32 s4, 0, 0x201ec
	ds_write_b32 v1, v2
	v_mov_b32_e32 v1, s4
	v_mov_b32_e32 v2, s7
	s_add_i32 s4, 0, 0x201f0
	ds_write_b32 v1, v2
	v_mov_b32_e32 v1, s4
	v_mov_b32_e32 v2, s8
	s_add_i32 s4, 0, 0x201f4
	ds_write_b32 v1, v2
	v_mov_b32_e32 v1, s4
	v_mov_b32_e32 v2, s9
	s_add_i32 s4, 0, 0x201f8
	ds_write_b32 v1, v2
	v_mov_b32_e32 v1, s4
	v_mov_b32_e32 v2, s10
	s_add_i32 s4, 0, 0x201fc
	ds_write_b32 v1, v2
	v_mov_b32_e32 v1, s4
	s_load_dwordx2 s[4:5], s[0:1], 0x100
	v_mov_b32_e32 v2, s11
	ds_write_b32 v1, v2
	s_add_i32 s6, 0, 0x20200
	v_mov_b32_e32 v1, s6
	s_load_dwordx2 s[6:7], s[0:1], 0x108
	s_load_dwordx2 s[8:9], s[0:1], 0x110
	s_load_dwordx2 s[10:11], s[0:1], 0x118
	s_waitcnt lgkmcnt(0)
	v_mov_b32_e32 v2, s4
	s_add_i32 s0, 0, 0x20204
	ds_write_b32 v1, v2
	v_mov_b32_e32 v1, s0
	v_mov_b32_e32 v2, s5
	s_add_i32 s0, 0, 0x20208
	ds_write_b32 v1, v2
	v_mov_b32_e32 v1, s0
	v_mov_b32_e32 v2, s6
	s_add_i32 s0, 0, 0x2020c
	ds_write_b32 v1, v2
	v_mov_b32_e32 v1, s0
	v_mov_b32_e32 v2, s7
	s_add_i32 s0, 0, 0x20210
	ds_write_b32 v1, v2
	v_mov_b32_e32 v1, s0
	v_mov_b32_e32 v2, s8
	s_add_i32 s0, 0, 0x20214
	ds_write_b32 v1, v2
	v_mov_b32_e32 v1, s0
	v_mov_b32_e32 v2, s9
	s_add_i32 s0, 0, 0x20218
	ds_write_b32 v1, v2
	v_mov_b32_e32 v1, s0
	v_mov_b32_e32 v2, s10
	s_add_i32 s0, 0, 0x2021c
	ds_write_b32 v1, v2
	v_mov_b32_e32 v1, s0
	v_mov_b32_e32 v2, s11
	ds_write_b32 v1, v2

;     __host__ __device__ bool next(int i, Unit& u) const { const int L = base + i * Gp + cp; if (L >= end) return false; return T.next(L, u); }
;     __host__ __device__ bool next(int i, Unit& u) const { const int L = i * Gp + cp; if (cp < 0 || L >= n) return false; u.kb = L & 3; u.pn = (L >> 2) % nN; u.pm = pm0 + (L >> 2) / nN; return true; }
;     __host__ __device__ bool next(int i, Unit& u) const { const bool ok = T.next(i >> 2, u); u.kb = i & 3; return ok; }
; #define PG8_STAGE(bufoff, gbase, voff) do { _Pragma("unroll") for (int _i = 0; _i < 2; ++_i) \
;         __builtin_amdgcn_global_load_lds((const unsigned*)((const char*)(gbase) + (voff)[_i]), (PG8_LAS unsigned*)(lds + (bufoff) + ldsw + _i * 8192), 16, 0, 0); } while (0)
; #define PG8_WAIT_V(n) asm volatile("s_waitcnt vmcnt(" #n ")" ::: "memory")
; template <class Epi, class Sched, bool ALIGN_EPI = false, bool SP2 = false>
; __device__ __forceinline__ void gemm_phase(PG8_LAS unsigned char* lds, const Gemm g, const Sched& S, const Epi& E, const int tid) {
;     ...
;         const bool has_next = S.next(ui + 1, nxt);
;         const char* nA = has_next ? (const char*)g.A + (size_t)nxt.pm * tstep + (size_t)nxt.kb * g.sA : cA; const char* nB = has_next ? (const char*)g.Bt + (size_t)nxt.pn * tstep + (size_t)nxt.kb * g.sB : cB;
;         for (int t = 0; t < nt; t += 2) {
;             const bool last = (t == nt - 2);
;             const char* a1 = cA + (size_t)(t + 1) * kstep;
;             const char* a2 = last ? nA : cA + (size_t)(t + 2) * kstep; const char* b2 = last ? nB : cB + (size_t)(t + 2) * kstep;
;             const char* a3 = a2 + kstep; const char* b3 = b2 + kstep;
;             if (last && has_next) S.a_ready(nxt);
;             if constexpr (SP2) {
;             PG8_LDB(B0, 0, 0); PG8_LDB(B1, 0, 1); PG8_SCHED; PG8_LDA(At, 0, 0); PG8_STAGE(PG8_SA(1, 1), a1 + hstep, voffA);
;             PG8_WAIT_V(8); PG8_WAIT_L(0); PG8_BAR; PG8_MMA(0, 0, At, B0); PG8_MMA(0, 1, At, B1); PG8_BAR; PG8_SCHED;
;     ...
; #pragma unroll
;         for (int a = 0; a < 2; ++a)
; #pragma unroll
;             for (int b = 0; b < 2; ++b)
; #pragma unroll
;                 for (int m = 0; m < 4; ++m)
; #pragma unroll
;                     for (int n = 0; n < 2; ++n) acc[a][b][m][n] = (f32x4){0.f, 0.f, 0.f, 0.f};
;         cur = nxt; cA = nA; cB = nB; ++ui;
;         if constexpr (ALIGN_EPI) { if (wr == 1) PG8_BAR; }
.LBB0_340:
	s_ashr_i32 s37, s36, 31
	s_lshl_b64 s[38:39], s[36:37], 20
	s_add_u32 s38, s58, s38
	s_addc_u32 s39, s59, s39
	s_and_b64 s[40:41], s[6:7], exec
	s_cselect_b32 s1, s39, s11
	s_cselect_b32 s9, s38, s10
	s_ashr_i32 s35, s34, 31
	s_lshl_b64 s[40:41], s[34:35], 20
	s_add_u32 s40, s60, s40
	s_addc_u32 s41, s61, s41
	s_and_b64 s[42:43], s[6:7], exec
	s_cselect_b32 s35, s41, s13
	s_cselect_b32 s37, s40, s12
	s_add_u32 s10, s10, 0x80080
	s_addc_u32 s11, s11, 0
	s_add_u32 s44, s12, 0x100
	v_mov_b32_e32 v0, 0
	s_addc_u32 s45, s13, 0
	s_mov_b32 s46, -2
	v_mov_b32_e32 v1, v0
	v_mov_b32_e32 v2, v0
	v_mov_b32_e32 v3, v0
	v_mov_b32_e32 v4, v0
	v_mov_b32_e32 v5, v0
	v_mov_b32_e32 v6, v0
	v_mov_b32_e32 v7, v0
	v_mov_b32_e32 v32, v0
	v_mov_b32_e32 v33, v0
	v_mov_b32_e32 v34, v0
	v_mov_b32_e32 v35, v0
	v_mov_b32_e32 v36, v0
	v_mov_b32_e32 v37, v0
	v_mov_b32_e32 v38, v0
	v_mov_b32_e32 v39, v0
	v_mov_b32_e32 v64, v0
	v_mov_b32_e32 v65, v0
	v_mov_b32_e32 v66, v0
	v_mov_b32_e32 v67, v0
	v_mov_b32_e32 v68, v0
	v_mov_b32_e32 v69, v0
	v_mov_b32_e32 v70, v0
	v_mov_b32_e32 v71, v0
	v_mov_b32_e32 v88, v0
	v_mov_b32_e32 v89, v0
	v_mov_b32_e32 v90, v0
	v_mov_b32_e32 v91, v0
	v_mov_b32_e32 v92, v0
	v_mov_b32_e32 v93, v0
	v_mov_b32_e32 v94, v0
	v_mov_b32_e32 v95, v0
	v_mov_b32_e32 v8, v0
	v_mov_b32_e32 v9, v0
	v_mov_b32_e32 v10, v0
	v_mov_b32_e32 v11, v0
	v_mov_b32_e32 v12, v0
	v_mov_b32_e32 v13, v0
	v_mov_b32_e32 v14, v0
	v_mov_b32_e32 v15, v0
	v_mov_b32_e32 v48, v0
	v_mov_b32_e32 v49, v0
	v_mov_b32_e32 v50, v0
	v_mov_b32_e32 v51, v0
	v_mov_b32_e32 v52, v0
	v_mov_b32_e32 v53, v0
	v_mov_b32_e32 v54, v0
	v_mov_b32_e32 v55, v0
	v_mov_b32_e32 v72, v0
	v_mov_b32_e32 v73, v0
	v_mov_b32_e32 v74, v0
	v_mov_b32_e32 v75, v0
	v_mov_b32_e32 v76, v0
	v_mov_b32_e32 v77, v0
	v_mov_b32_e32 v78, v0
	v_mov_b32_e32 v79, v0
	v_mov_b32_e32 v96, v0
	v_mov_b32_e32 v97, v0
	v_mov_b32_e32 v98, v0
	v_mov_b32_e32 v99, v0
	v_mov_b32_e32 v100, v0
	v_mov_b32_e32 v101, v0
	v_mov_b32_e32 v102, v0
	v_mov_b32_e32 v103, v0
	v_mov_b32_e32 v112, v0
	v_mov_b32_e32 v113, v0
	v_mov_b32_e32 v114, v0
	v_mov_b32_e32 v115, v0
	v_mov_b32_e32 v116, v0
	v_mov_b32_e32 v117, v0
	v_mov_b32_e32 v118, v0
	v_mov_b32_e32 v119, v0
	v_mov_b32_e32 v128, v0
	v_mov_b32_e32 v129, v0
	v_mov_b32_e32 v130, v0
	v_mov_b32_e32 v131, v0
	v_mov_b32_e32 v132, v0
	v_mov_b32_e32 v133, v0
	v_mov_b32_e32 v134, v0
	v_mov_b32_e32 v135, v0
	v_mov_b32_e32 v144, v0
	v_mov_b32_e32 v145, v0
	v_mov_b32_e32 v146, v0
	v_mov_b32_e32 v147, v0
	v_mov_b32_e32 v148, v0
	v_mov_b32_e32 v149, v0
	v_mov_b32_e32 v150, v0
	v_mov_b32_e32 v151, v0
	v_mov_b32_e32 v160, v0
	v_mov_b32_e32 v161, v0
	v_mov_b32_e32 v162, v0
	v_mov_b32_e32 v163, v0
	v_mov_b32_e32 v164, v0
	v_mov_b32_e32 v165, v0
	v_mov_b32_e32 v166, v0
	v_mov_b32_e32 v167, v0
	v_mov_b32_e32 v120, v0
	v_mov_b32_e32 v121, v0
	v_mov_b32_e32 v122, v0
	v_mov_b32_e32 v123, v0
	v_mov_b32_e32 v124, v0
	v_mov_b32_e32 v125, v0
	v_mov_b32_e32 v126, v0
	v_mov_b32_e32 v127, v0
	v_mov_b32_e32 v136, v0
	v_mov_b32_e32 v137, v0
	v_mov_b32_e32 v138, v0
	v_mov_b32_e32 v139, v0
	v_mov_b32_e32 v140, v0
	v_mov_b32_e32 v141, v0
	v_mov_b32_e32 v142, v0
	v_mov_b32_e32 v143, v0
	v_mov_b32_e32 v152, v0
	v_mov_b32_e32 v153, v0
	v_mov_b32_e32 v154, v0
	v_mov_b32_e32 v155, v0
	v_mov_b32_e32 v156, v0
	v_mov_b32_e32 v157, v0
	v_mov_b32_e32 v158, v0
	v_mov_b32_e32 v159, v0
	v_mov_b32_e32 v168, v0
	v_mov_b32_e32 v169, v0
	v_mov_b32_e32 v170, v0
	v_mov_b32_e32 v171, v0
	v_mov_b32_e32 v172, v0
	v_mov_b32_e32 v173, v0
	v_mov_b32_e32 v174, v0
	v_mov_b32_e32 v175, v0
	s_cmp_eq_u32 s100, 0
	s_cbranch_scc1 .Lmy_nobar_341
	s_barrier
	s_mov_b32 s100, 0
.Lmy_nobar_341:
.LBB0_341:
	s_add_u32 s12, s10, 0xfff80080
	s_addc_u32 s13, s11, -1
	s_add_i32 s47, 0, 0x10000
	v_add_u32_e32 v28, s47, v197
	s_waitcnt vmcnt(0)
	v_add_u32_e32 v60, s33, v197
	ds_read_b128 v[16:19], v28
	ds_read_b128 v[20:23], v28 offset:1024
	ds_read_b128 v[24:27], v28 offset:2048
	ds_read_b128 v[28:31], v28 offset:3072
	ds_read_b128 v[40:43], v60
	ds_read_b128 v[44:47], v60 offset:1024
	ds_read_b128 v[56:59], v60 offset:2048
	ds_read_b128 v[60:63], v60 offset:3072
	s_cmp_eq_u32 s46, 28
	s_cselect_b32 s43, s1, s13
	s_cselect_b32 s42, s9, s12
	s_cselect_b32 s13, s35, s45
	s_cselect_b32 s12, s37, s44
	v_lshl_add_u64 v[194:195], s[10:11], 0, v[190:191]
	s_add_i32 m0, s63, 0xc000
	ds_read_b128 v[80:83], v240
	ds_read_b128 v[84:87], v240 offset:1024
	ds_read_b128 v[104:107], v240 offset:2048
	ds_read_b128 v[108:111], v240 offset:3072
	ds_read_b128 v[198:201], v240 offset:4096
	ds_read_b128 v[202:205], v240 offset:5120
	ds_read_b128 v[214:217], v240 offset:6144
	ds_read_b128 v[218:221], v240 offset:7168
	global_load_lds_dwordx4 v[194:195], off
	v_lshl_add_u64 v[194:195], s[10:11], 0, v[192:193]
	s_add_i32 m0, s63, 0xe000
	s_nop 0
	global_load_lds_dwordx4 v[194:195], off
	s_waitcnt vmcnt(8)
	s_waitcnt lgkmcnt(0)
	s_barrier
; #define PG8_STAGE(bufoff, gbase, voff) do { _Pragma("unroll") for (int _i = 0; _i < 2; ++_i) \
;         __builtin_amdgcn_global_load_lds((const unsigned*)((const char*)(gbase) + (voff)[_i]), (PG8_LAS unsigned*)(lds + (bufoff) + ldsw + _i * 8192), 16, 0, 0); } while (0)
; #define PG8_LDA(dst, b, h) do { _Pragma("unroll") for (int m = 0; m < 4; ++m) _Pragma("unroll") for (int k = 0; k < 2; ++k) dst[m][k] = *(const PG8_LAS bf16x8*)(lds + PG8_SA(b, h) + aoff + m * 2048 + k * 1024); } while (0)
; #define PG8_MMA(ai, bj, At, Bt) do { __builtin_amdgcn_s_setprio(1); _Pragma("unroll") for (int m = 0; m < 4; ++m) _Pragma("unroll") for (int n = 0; n < 2; ++n) _Pragma("unroll") for (int k = 0; k < 2; ++k) \
;         acc[ai][bj][m][n] = __builtin_amdgcn_mfma_f32_16x16x32_bf16(Bt[n][k], At[m][k], acc[ai][bj][m][n], 0, 0, 0); __builtin_amdgcn_s_setprio(0); } while (0)
; #define PG8_WAIT_V(n) asm volatile("s_waitcnt vmcnt(" #n ")" ::: "memory")
; #define PG8_WAIT_L(n) asm volatile("s_waitcnt lgkmcnt(" #n ")" ::: "memory")
; #define PG8_BAR __builtin_amdgcn_s_barrier()
; #define PG8_SCHED __builtin_amdgcn_sched_barrier(0)
; template <class Epi, class Sched, bool ALIGN_EPI = false, bool SP2 = false>
; __device__ __forceinline__ void gemm_phase(PG8_LAS unsigned char* lds, const Gemm g, const Sched& S, const Epi& E, const int tid) {
;     ...
;             PG8_WAIT_V(8); PG8_WAIT_L(0); PG8_BAR; PG8_MMA(0, 0, At, B0); PG8_MMA(0, 1, At, B1); PG8_BAR; PG8_SCHED;
;             PG8_LDA(At, 0, 1); PG8_STAGE(PG8_SB(0, 0), b2, voffB); PG8_STAGE(PG8_SB(0, 1), b2 + hstep, voffB); PG8_STAGE(PG8_SA(0, 0), a2, voffA);
;             PG8_WAIT_V(8); PG8_WAIT_L(0); PG8_BAR; PG8_MMA(1, 0, At, B0); PG8_MMA(1, 1, At, B1); PG8_BAR; PG8_SCHED;
	s_setprio 1
	s_waitcnt lgkmcnt(0)
	v_mfma_f32_16x16x32_bf16 v[172:175], v[16:19], v[80:83], v[172:175]
	v_mfma_f32_16x16x32_bf16 v[168:171], v[24:27], v[80:83], v[168:171]
	v_mfma_f32_16x16x32_bf16 v[156:159], v[16:19], v[104:107], v[156:159]
	v_mfma_f32_16x16x32_bf16 v[152:155], v[24:27], v[104:107], v[152:155]
	v_mfma_f32_16x16x32_bf16 v[140:143], v[16:19], v[198:201], v[140:143]
	v_mfma_f32_16x16x32_bf16 v[136:139], v[24:27], v[198:201], v[136:139]
	v_mfma_f32_16x16x32_bf16 v[124:127], v[16:19], v[214:217], v[124:127]
	v_mfma_f32_16x16x32_bf16 v[120:123], v[24:27], v[214:217], v[120:123]
	v_mfma_f32_16x16x32_bf16 v[172:175], v[20:23], v[84:87], v[172:175]
	v_mfma_f32_16x16x32_bf16 v[168:171], v[28:31], v[84:87], v[168:171]
	v_mfma_f32_16x16x32_bf16 v[156:159], v[20:23], v[108:111], v[156:159]
	v_mfma_f32_16x16x32_bf16 v[152:155], v[28:31], v[108:111], v[152:155]
	v_mfma_f32_16x16x32_bf16 v[140:143], v[20:23], v[202:205], v[140:143]
	v_mfma_f32_16x16x32_bf16 v[136:139], v[28:31], v[202:205], v[136:139]
	v_mfma_f32_16x16x32_bf16 v[124:127], v[20:23], v[218:221], v[124:127]
	v_mfma_f32_16x16x32_bf16 v[120:123], v[28:31], v[218:221], v[120:123]
	s_setprio 0
	s_setprio 1
	v_mfma_f32_16x16x32_bf16 v[164:167], v[40:43], v[80:83], v[164:167]
	v_mfma_f32_16x16x32_bf16 v[80:83], v[56:59], v[80:83], v[160:163]
	v_mfma_f32_16x16x32_bf16 v[164:167], v[44:47], v[84:87], v[164:167]
	v_mfma_f32_16x16x32_bf16 v[80:83], v[60:63], v[84:87], v[80:83]
	v_mfma_f32_16x16x32_bf16 v[84:87], v[40:43], v[104:107], v[148:151]
	v_mfma_f32_16x16x32_bf16 v[104:107], v[56:59], v[104:107], v[144:147]
	v_mfma_f32_16x16x32_bf16 v[128:131], v[56:59], v[198:201], v[128:131]
	v_mfma_f32_16x16x32_bf16 v[116:119], v[40:43], v[214:217], v[116:119]
	v_mfma_f32_16x16x32_bf16 v[112:115], v[56:59], v[214:217], v[112:115]
	v_mfma_f32_16x16x32_bf16 v[84:87], v[44:47], v[108:111], v[84:87]
	v_mfma_f32_16x16x32_bf16 v[104:107], v[60:63], v[108:111], v[104:107]
	v_mfma_f32_16x16x32_bf16 v[108:111], v[40:43], v[198:201], v[132:135]
	v_mfma_f32_16x16x32_bf16 v[128:131], v[60:63], v[202:205], v[128:131]
	v_mfma_f32_16x16x32_bf16 v[116:119], v[44:47], v[218:221], v[116:119]
	v_mfma_f32_16x16x32_bf16 v[112:115], v[60:63], v[218:221], v[112:115]
	v_mfma_f32_16x16x32_bf16 v[108:111], v[44:47], v[202:205], v[108:111]
	s_setprio 0
	s_barrier
	s_add_i32 s47, s47, s62
	v_lshl_add_u64 v[194:195], s[12:13], 0, v[178:179]
	s_mov_b32 m0, s47
	ds_read_b128 v[132:135], v240 offset:16384
	ds_read_b128 v[144:147], v240 offset:17408
	ds_read_b128 v[148:151], v240 offset:18432
	ds_read_b128 v[160:163], v240 offset:19456
	ds_read_b128 v[198:201], v240 offset:20480
	ds_read_b128 v[202:205], v240 offset:21504
	ds_read_b128 v[214:217], v240 offset:22528
	ds_read_b128 v[218:221], v240 offset:23552
	global_load_lds_dwordx4 v[194:195], off
	s_add_i32 m0, s47, 0x2000
	s_add_u32 s48, s12, 0x80000
	v_lshl_add_u64 v[206:207], s[12:13], 0, v[182:183]
	s_addc_u32 s49, s13, 0
	s_add_i32 s47, s33, s62
	global_load_lds_dwordx4 v[206:207], off
	v_lshl_add_u64 v[210:211], s[48:49], 0, v[178:179]
	s_mov_b32 m0, s47
	v_lshl_add_u64 v[234:235], s[42:43], 0, v[180:181]
	global_load_lds_dwordx4 v[210:211], off
	v_lshl_add_u64 v[210:211], s[48:49], 0, v[182:183]
	s_add_i32 m0, s47, 0x2000
	s_nop 0
	global_load_lds_dwordx4 v[210:211], off
	v_lshl_add_u64 v[210:211], s[42:43], 0, v[176:177]
	s_mov_b32 m0, s63
	s_nop 0
	global_load_lds_dwordx4 v[210:211], off
	s_mov_b32 m0, s64
	s_nop 0
	global_load_lds_dwordx4 v[234:235], off
	s_waitcnt vmcnt(8)
	s_waitcnt lgkmcnt(0)
	s_barrier
	s_setprio 1
	s_waitcnt lgkmcnt(0)
	v_mfma_f32_16x16x32_bf16 v[100:103], v[16:19], v[132:135], v[100:103]
	v_mfma_f32_16x16x32_bf16 v[96:99], v[24:27], v[132:135], v[96:99]
	v_mfma_f32_16x16x32_bf16 v[76:79], v[16:19], v[148:151], v[76:79]
	v_mfma_f32_16x16x32_bf16 v[72:75], v[24:27], v[148:151], v[72:75]
	v_mfma_f32_16x16x32_bf16 v[52:55], v[16:19], v[198:201], v[52:55]
	v_mfma_f32_16x16x32_bf16 v[48:51], v[24:27], v[198:201], v[48:51]
	v_mfma_f32_16x16x32_bf16 v[12:15], v[16:19], v[214:217], v[12:15]
	v_mfma_f32_16x16x32_bf16 v[8:11], v[24:27], v[214:217], v[8:11]
	v_mfma_f32_16x16x32_bf16 v[100:103], v[20:23], v[144:147], v[100:103]
	v_mfma_f32_16x16x32_bf16 v[96:99], v[28:31], v[144:147], v[96:99]
	v_mfma_f32_16x16x32_bf16 v[76:79], v[20:23], v[160:163], v[76:79]
	v_mfma_f32_16x16x32_bf16 v[72:75], v[28:31], v[160:163], v[72:75]
	v_mfma_f32_16x16x32_bf16 v[52:55], v[20:23], v[202:205], v[52:55]
	v_mfma_f32_16x16x32_bf16 v[48:51], v[28:31], v[202:205], v[48:51]
	v_mfma_f32_16x16x32_bf16 v[12:15], v[20:23], v[218:221], v[12:15]
	v_mfma_f32_16x16x32_bf16 v[8:11], v[28:31], v[218:221], v[8:11]
	s_setprio 0
	s_setprio 1
	v_mfma_f32_16x16x32_bf16 v[36:39], v[40:43], v[198:201], v[36:39]
	v_mfma_f32_16x16x32_bf16 v[32:35], v[56:59], v[198:201], v[32:35]
	v_mfma_f32_16x16x32_bf16 v[4:7], v[40:43], v[214:217], v[4:7]
	v_mfma_f32_16x16x32_bf16 v[0:3], v[56:59], v[214:217], v[0:3]
	v_mfma_f32_16x16x32_bf16 v[16:19], v[40:43], v[132:135], v[92:95]
	v_mfma_f32_16x16x32_bf16 v[20:23], v[56:59], v[132:135], v[88:91]
	v_mfma_f32_16x16x32_bf16 v[24:27], v[40:43], v[148:151], v[68:71]
	v_mfma_f32_16x16x32_bf16 v[28:31], v[56:59], v[148:151], v[64:67]
	v_mfma_f32_16x16x32_bf16 v[36:39], v[44:47], v[202:205], v[36:39]
	v_mfma_f32_16x16x32_bf16 v[32:35], v[60:63], v[202:205], v[32:35]
	v_mfma_f32_16x16x32_bf16 v[4:7], v[44:47], v[218:221], v[4:7]
	v_mfma_f32_16x16x32_bf16 v[0:3], v[60:63], v[218:221], v[0:3]
	v_mfma_f32_16x16x32_bf16 v[16:19], v[44:47], v[144:147], v[16:19]
	v_mfma_f32_16x16x32_bf16 v[20:23], v[60:63], v[144:147], v[20:23]
	v_mfma_f32_16x16x32_bf16 v[24:27], v[44:47], v[160:163], v[24:27]
	v_mfma_f32_16x16x32_bf16 v[28:31], v[60:63], v[160:163], v[28:31]
	s_setprio 0
	s_barrier
; #define PG8_STAGE(bufoff, gbase, voff) do { _Pragma("unroll") for (int _i = 0; _i < 2; ++_i) \
;         __builtin_amdgcn_global_load_lds((const unsigned*)((const char*)(gbase) + (voff)[_i]), (PG8_LAS unsigned*)(lds + (bufoff) + ldsw + _i * 8192), 16, 0, 0); } while (0)
; #define PG8_LDA(dst, b, h) do { _Pragma("unroll") for (int m = 0; m < 4; ++m) _Pragma("unroll") for (int k = 0; k < 2; ++k) dst[m][k] = *(const PG8_LAS bf16x8*)(lds + PG8_SA(b, h) + aoff + m * 2048 + k * 1024); } while (0)
; #define PG8_LDB(dst, b, h) do { _Pragma("unroll") for (int n = 0; n < 2; ++n) _Pragma("unroll") for (int k = 0; k < 2; ++k) dst[n][k] = *(const PG8_LAS bf16x8*)(lds + PG8_SB(b, h) + boff + n * 2048 + k * 1024); } while (0)
; #define PG8_MMA(ai, bj, At, Bt) do { __builtin_amdgcn_s_setprio(1); _Pragma("unroll") for (int m = 0; m < 4; ++m) _Pragma("unroll") for (int n = 0; n < 2; ++n) _Pragma("unroll") for (int k = 0; k < 2; ++k) \
;         acc[ai][bj][m][n] = __builtin_amdgcn_mfma_f32_16x16x32_bf16(Bt[n][k], At[m][k], acc[ai][bj][m][n], 0, 0, 0); __builtin_amdgcn_s_setprio(0); } while (0)
; #define PG8_WAIT_V(n) asm volatile("s_waitcnt vmcnt(" #n ")" ::: "memory")
; #define PG8_WAIT_L(n) asm volatile("s_waitcnt lgkmcnt(" #n ")" ::: "memory")
; #define PG8_BAR __builtin_amdgcn_s_barrier()
; #define PG8_SCHED __builtin_amdgcn_sched_barrier(0)
; template <class Epi, class Sched, bool ALIGN_EPI = false, bool SP2 = false>
; __device__ __forceinline__ void gemm_phase(PG8_LAS unsigned char* lds, const Gemm g, const Sched& S, const Epi& E, const int tid) {
;     ...
;             PG8_LDB(B0, 1, 0); PG8_LDB(B1, 1, 1); PG8_SCHED; PG8_LDA(At, 1, 0); PG8_STAGE(PG8_SA(0, 1), a2 + hstep, voffA);
;             PG8_WAIT_V(8); PG8_WAIT_L(0); PG8_BAR; PG8_MMA(0, 0, At, B0); PG8_MMA(0, 1, At, B1); PG8_BAR; PG8_SCHED;
	s_add_i32 s47, 0, 0x18000
	s_add_i32 s48, 0, 0x1c000
	v_add_u32_e32 v60, s47, v197
	v_add_u32_e32 v64, s48, v197
	ds_read_b128 v[40:43], v60
	ds_read_b128 v[44:47], v60 offset:1024
	ds_read_b128 v[56:59], v60 offset:2048
	ds_read_b128 v[60:63], v60 offset:3072
	ds_read_b128 v[198:201], v64
	ds_read_b128 v[202:205], v64 offset:1024
	ds_read_b128 v[214:217], v64 offset:2048
	ds_read_b128 v[218:221], v64 offset:3072
	s_add_u32 s42, s42, 0x80000
	s_addc_u32 s43, s43, 0
	s_mov_b32 m0, s65
	v_lshl_add_u64 v[132:133], s[42:43], 0, v[176:177]
	ds_read_b128 v[64:67], v240 offset:32768
	ds_read_b128 v[68:71], v240 offset:33792
	ds_read_b128 v[88:91], v240 offset:34816
	ds_read_b128 v[92:95], v240 offset:35840
	ds_read_b128 v[222:225], v240 offset:36864
	ds_read_b128 v[226:229], v240 offset:37888
	ds_read_b128 v[230:233], v240 offset:38912
	ds_read_b128 v[242:245], v240 offset:39936
	global_load_lds_dwordx4 v[132:133], off
	v_lshl_add_u64 v[132:133], s[42:43], 0, v[180:181]
	s_mov_b32 m0, s66
	s_nop 0
	global_load_lds_dwordx4 v[132:133], off
	s_waitcnt vmcnt(8)
	s_waitcnt lgkmcnt(0)
	s_barrier
	s_setprio 1
	s_waitcnt lgkmcnt(0)
	v_mfma_f32_16x16x32_bf16 v[132:135], v[40:43], v[64:67], v[172:175]
	v_mfma_f32_16x16x32_bf16 v[172:175], v[44:47], v[68:71], v[132:135]
	v_mfma_f32_16x16x32_bf16 v[132:135], v[56:59], v[64:67], v[168:171]
	v_mfma_f32_16x16x32_bf16 v[168:171], v[60:63], v[68:71], v[132:135]
	v_mfma_f32_16x16x32_bf16 v[132:135], v[40:43], v[88:91], v[156:159]
	v_mfma_f32_16x16x32_bf16 v[156:159], v[44:47], v[92:95], v[132:135]
	v_mfma_f32_16x16x32_bf16 v[132:135], v[56:59], v[88:91], v[152:155]
	v_mfma_f32_16x16x32_bf16 v[152:155], v[60:63], v[92:95], v[132:135]
	v_mfma_f32_16x16x32_bf16 v[132:135], v[40:43], v[222:225], v[140:143]
	v_mfma_f32_16x16x32_bf16 v[140:143], v[44:47], v[226:229], v[132:135]
	v_mfma_f32_16x16x32_bf16 v[132:135], v[56:59], v[222:225], v[136:139]
	v_mfma_f32_16x16x32_bf16 v[124:127], v[40:43], v[230:233], v[124:127]
	v_mfma_f32_16x16x32_bf16 v[120:123], v[56:59], v[230:233], v[120:123]
	v_mfma_f32_16x16x32_bf16 v[136:139], v[60:63], v[226:229], v[132:135]
	v_mfma_f32_16x16x32_bf16 v[124:127], v[44:47], v[242:245], v[124:127]
	v_mfma_f32_16x16x32_bf16 v[120:123], v[60:63], v[242:245], v[120:123]
	s_setprio 0
	s_setprio 1
	v_mfma_f32_16x16x32_bf16 v[132:135], v[198:201], v[64:67], v[164:167]
	v_mfma_f32_16x16x32_bf16 v[64:67], v[214:217], v[64:67], v[80:83]
	v_mfma_f32_16x16x32_bf16 v[160:163], v[218:221], v[68:71], v[64:67]
	v_mfma_f32_16x16x32_bf16 v[64:67], v[198:201], v[88:91], v[84:87]
	v_mfma_f32_16x16x32_bf16 v[148:151], v[202:205], v[92:95], v[64:67]
	v_mfma_f32_16x16x32_bf16 v[64:67], v[214:217], v[88:91], v[104:107]
	v_mfma_f32_16x16x32_bf16 v[144:147], v[218:221], v[92:95], v[64:67]
	v_mfma_f32_16x16x32_bf16 v[64:67], v[198:201], v[222:225], v[108:111]
	v_mfma_f32_16x16x32_bf16 v[164:167], v[202:205], v[68:71], v[132:135]
	v_mfma_f32_16x16x32_bf16 v[132:135], v[202:205], v[226:229], v[64:67]
	v_mfma_f32_16x16x32_bf16 v[64:67], v[214:217], v[222:225], v[128:131]
	v_mfma_f32_16x16x32_bf16 v[128:131], v[218:221], v[226:229], v[64:67]
	v_mfma_f32_16x16x32_bf16 v[64:67], v[198:201], v[230:233], v[116:119]
	v_mfma_f32_16x16x32_bf16 v[116:119], v[202:205], v[242:245], v[64:67]
	v_mfma_f32_16x16x32_bf16 v[64:67], v[214:217], v[230:233], v[112:115]
	v_mfma_f32_16x16x32_bf16 v[112:115], v[218:221], v[242:245], v[64:67]
	s_setprio 0
	s_barrier
; #define PG8_STAGE(bufoff, gbase, voff) do { _Pragma("unroll") for (int _i = 0; _i < 2; ++_i) \
;         __builtin_amdgcn_global_load_lds((const unsigned*)((const char*)(gbase) + (voff)[_i]), (PG8_LAS unsigned*)(lds + (bufoff) + ldsw + _i * 8192), 16, 0, 0); } while (0)
; #define PG8_LDA(dst, b, h) do { _Pragma("unroll") for (int m = 0; m < 4; ++m) _Pragma("unroll") for (int k = 0; k < 2; ++k) dst[m][k] = *(const PG8_LAS bf16x8*)(lds + PG8_SA(b, h) + aoff + m * 2048 + k * 1024); } while (0)
; #define PG8_MMA(ai, bj, At, Bt) do { __builtin_amdgcn_s_setprio(1); _Pragma("unroll") for (int m = 0; m < 4; ++m) _Pragma("unroll") for (int n = 0; n < 2; ++n) _Pragma("unroll") for (int k = 0; k < 2; ++k) \
;         acc[ai][bj][m][n] = __builtin_amdgcn_mfma_f32_16x16x32_bf16(Bt[n][k], At[m][k], acc[ai][bj][m][n], 0, 0, 0); __builtin_amdgcn_s_setprio(0); } while (0)
; #define PG8_WAIT_V(n) asm volatile("s_waitcnt vmcnt(" #n ")" ::: "memory")
; #define PG8_WAIT_L(n) asm volatile("s_waitcnt lgkmcnt(" #n ")" ::: "memory")
; #define PG8_BAR __builtin_amdgcn_s_barrier()
; #define PG8_SCHED __builtin_amdgcn_sched_barrier(0)
; template <class Epi, class Sched, bool ALIGN_EPI = false, bool SP2 = false>
; __device__ __forceinline__ void gemm_phase(PG8_LAS unsigned char* lds, const Gemm g, const Sched& S, const Epi& E, const int tid) {
;     ...
;             PG8_LDA(At, 1, 1); PG8_STAGE(PG8_SB(1, 0), b3, voffB); PG8_STAGE(PG8_SB(1, 1), b3 + hstep, voffB); PG8_STAGE(PG8_SA(1, 0), a3, voffA);
;             PG8_WAIT_V(8); PG8_WAIT_L(0); PG8_BAR; PG8_MMA(1, 0, At, B0); PG8_MMA(1, 1, At, B1); PG8_BAR; PG8_SCHED;
;     ...
;         if constexpr (ALIGN_EPI) { if (wr == 0) PG8_BAR; }
	s_add_i32 s42, s47, s62
	v_lshl_add_u64 v[88:89], v[194:195], 0, s[2:3]
	s_mov_b32 m0, s42
	s_nop 1
	ds_read_b128 v[64:67], v240 offset:49152
	ds_read_b128 v[68:71], v240 offset:50176
	ds_read_b128 v[80:83], v240 offset:51200
	ds_read_b128 v[84:87], v240 offset:52224
	ds_read_b128 v[104:107], v240 offset:53248
	ds_read_b128 v[108:111], v240 offset:54272
	ds_read_b128 v[222:225], v240 offset:55296
	ds_read_b128 v[226:229], v240 offset:56320
	global_load_lds_dwordx4 v[88:89], off
	s_add_i32 m0, s42, 0x2000
	s_add_u32 s12, s12, 0x80080
	v_lshl_add_u64 v[88:89], v[206:207], 0, s[2:3]
	s_addc_u32 s13, s13, 0
	s_add_i32 s42, s48, s62
	global_load_lds_dwordx4 v[88:89], off
	v_lshl_add_u64 v[88:89], s[12:13], 0, v[178:179]
	s_mov_b32 m0, s42
	s_nop 0
	global_load_lds_dwordx4 v[88:89], off
	v_lshl_add_u64 v[88:89], s[12:13], 0, v[182:183]
	s_add_i32 m0, s42, 0x2000
	s_nop 0
	global_load_lds_dwordx4 v[88:89], off
	v_lshl_add_u64 v[88:89], v[210:211], 0, s[2:3]
	s_mov_b32 m0, s70
	s_nop 0
	global_load_lds_dwordx4 v[88:89], off
	v_lshl_add_u64 v[88:89], v[234:235], 0, s[2:3]
	s_mov_b32 m0, s71
	s_nop 0
	global_load_lds_dwordx4 v[88:89], off
	s_waitcnt vmcnt(8)
	s_waitcnt lgkmcnt(0)
	s_barrier
	s_setprio 1
	s_waitcnt lgkmcnt(0)
	v_mfma_f32_16x16x32_bf16 v[88:91], v[40:43], v[64:67], v[100:103]
	v_mfma_f32_16x16x32_bf16 v[100:103], v[44:47], v[68:71], v[88:91]
	v_mfma_f32_16x16x32_bf16 v[88:91], v[56:59], v[64:67], v[96:99]
	v_mfma_f32_16x16x32_bf16 v[76:79], v[40:43], v[80:83], v[76:79]
	v_mfma_f32_16x16x32_bf16 v[72:75], v[56:59], v[80:83], v[72:75]
	v_mfma_f32_16x16x32_bf16 v[52:55], v[40:43], v[104:107], v[52:55]
	v_mfma_f32_16x16x32_bf16 v[48:51], v[56:59], v[104:107], v[48:51]
	v_mfma_f32_16x16x32_bf16 v[12:15], v[40:43], v[222:225], v[12:15]
	v_mfma_f32_16x16x32_bf16 v[8:11], v[56:59], v[222:225], v[8:11]
	v_mfma_f32_16x16x32_bf16 v[96:99], v[60:63], v[68:71], v[88:91]
	v_mfma_f32_16x16x32_bf16 v[76:79], v[44:47], v[84:87], v[76:79]
	v_mfma_f32_16x16x32_bf16 v[72:75], v[60:63], v[84:87], v[72:75]
	v_mfma_f32_16x16x32_bf16 v[52:55], v[44:47], v[108:111], v[52:55]
	v_mfma_f32_16x16x32_bf16 v[48:51], v[60:63], v[108:111], v[48:51]
	v_mfma_f32_16x16x32_bf16 v[12:15], v[44:47], v[226:229], v[12:15]
	v_mfma_f32_16x16x32_bf16 v[8:11], v[60:63], v[226:229], v[8:11]
	s_setprio 0
	s_setprio 1
	v_mfma_f32_16x16x32_bf16 v[16:19], v[198:201], v[64:67], v[16:19]
	v_mfma_f32_16x16x32_bf16 v[92:95], v[202:205], v[68:71], v[16:19]
	v_mfma_f32_16x16x32_bf16 v[16:19], v[214:217], v[64:67], v[20:23]
	v_mfma_f32_16x16x32_bf16 v[88:91], v[218:221], v[68:71], v[16:19]
	v_mfma_f32_16x16x32_bf16 v[16:19], v[198:201], v[80:83], v[24:27]
	v_mfma_f32_16x16x32_bf16 v[68:71], v[202:205], v[84:87], v[16:19]
	v_mfma_f32_16x16x32_bf16 v[16:19], v[214:217], v[80:83], v[28:31]
	v_mfma_f32_16x16x32_bf16 v[64:67], v[218:221], v[84:87], v[16:19]
	v_mfma_f32_16x16x32_bf16 v[16:19], v[198:201], v[104:107], v[36:39]
	v_mfma_f32_16x16x32_bf16 v[36:39], v[202:205], v[108:111], v[16:19]
	v_mfma_f32_16x16x32_bf16 v[16:19], v[214:217], v[104:107], v[32:35]
	v_mfma_f32_16x16x32_bf16 v[4:7], v[198:201], v[222:225], v[4:7]
	v_mfma_f32_16x16x32_bf16 v[0:3], v[214:217], v[222:225], v[0:3]
	v_mfma_f32_16x16x32_bf16 v[32:35], v[218:221], v[108:111], v[16:19]
	v_mfma_f32_16x16x32_bf16 v[4:7], v[202:205], v[226:229], v[4:7]
	v_mfma_f32_16x16x32_bf16 v[0:3], v[218:221], v[226:229], v[0:3]
	s_setprio 0
	s_barrier
	s_add_i32 s46, s46, 2
	s_add_u32 s10, s10, 0x100
	s_addc_u32 s11, s11, 0
	s_add_u32 s44, s44, 0x100
	s_addc_u32 s45, s45, 0
	s_cmp_gt_u32 s46, 29
	s_cbranch_scc0 .LBB0_341
	s_and_b64 vcc, exec, s[30:31]
	s_cbranch_vccz .LBB0_344
	s_barrier

; #define PG8_BAR __builtin_amdgcn_s_barrier()
; template <class Epi, class Sched, bool ALIGN_EPI = false, bool SP2 = false>
; __device__ __forceinline__ void gemm_phase(PG8_LAS unsigned char* lds, const Gemm g, const Sched& S, const Epi& E, const int tid) {
;     ...
;         if (!has_next) break;
;     ...
;         if constexpr (ALIGN_EPI) { if (wr == 1) PG8_BAR; }
.LBB0_703:
	s_andn2_b64 vcc, exec, s[14:15]
	s_cbranch_vccnz .LBB0_332
	s_mov_b32 s100, 1
	s_branch .LBB0_332

;     __host__ __device__ bool next(int i, Unit& u) const { const int L = base + i * Gp + cp; if (L >= end) return false; return T.next(L, u); }
;     __host__ __device__ bool next(int i, Unit& u) const { const int L = i * Gp + cp; if (cp < 0 || L >= n) return false; u.kb = L & 3; u.pn = (L >> 2) % nN; u.pm = pm0 + (L >> 2) / nN; return true; }
;     __host__ __device__ bool next(int i, Unit& u) const { const bool ok = T.next(i >> 2, u); u.kb = i & 3; return ok; }
; #define PG8_STAGE(bufoff, gbase, voff) do { _Pragma("unroll") for (int _i = 0; _i < 2; ++_i) \
;         __builtin_amdgcn_global_load_lds((const unsigned*)((const char*)(gbase) + (voff)[_i]), (PG8_LAS unsigned*)(lds + (bufoff) + ldsw + _i * 8192), 16, 0, 0); } while (0)
; #define PG8_WAIT_V(n) asm volatile("s_waitcnt vmcnt(" #n ")" ::: "memory")
; template <class Epi, class Sched, bool ALIGN_EPI = false, bool SP2 = false>
; __device__ __forceinline__ void gemm_phase(PG8_LAS unsigned char* lds, const Gemm g, const Sched& S, const Epi& E, const int tid) {
;     ...
;         const bool has_next = S.next(ui + 1, nxt);
;         const char* nA = has_next ? (const char*)g.A + (size_t)nxt.pm * tstep + (size_t)nxt.kb * g.sA : cA; const char* nB = has_next ? (const char*)g.Bt + (size_t)nxt.pn * tstep + (size_t)nxt.kb * g.sB : cB;
;         for (int t = 0; t < nt; t += 2) {
;             const bool last = (t == nt - 2);
;             const char* a1 = cA + (size_t)(t + 1) * kstep;
;             const char* a2 = last ? nA : cA + (size_t)(t + 2) * kstep; const char* b2 = last ? nB : cB + (size_t)(t + 2) * kstep;
;             const char* a3 = a2 + kstep; const char* b3 = b2 + kstep;
;             if (last && has_next) S.a_ready(nxt);
;             if constexpr (SP2) {
;             PG8_LDB(B0, 0, 0); PG8_LDB(B1, 0, 1); PG8_SCHED; PG8_LDA(At, 0, 0); PG8_STAGE(PG8_SA(1, 1), a1 + hstep, voffA);
;             PG8_WAIT_V(8); PG8_WAIT_L(0); PG8_BAR; PG8_MMA(0, 0, At, B0); PG8_MMA(0, 1, At, B1); PG8_BAR; PG8_SCHED;
;     ...
; #pragma unroll
;         for (int a = 0; a < 2; ++a)
; #pragma unroll
;             for (int b = 0; b < 2; ++b)
; #pragma unroll
;                 for (int m = 0; m < 4; ++m)
; #pragma unroll
;                     for (int n = 0; n < 2; ++n) acc[a][b][m][n] = (f32x4){0.f, 0.f, 0.f, 0.f};
;         cur = nxt; cA = nA; cB = nB; ++ui;
;         if constexpr (ALIGN_EPI) { if (wr == 1) PG8_BAR; }
.LBB0_767:
	s_ashr_i32 s15, s14, 31
	s_lshl_b64 s[16:17], s[14:15], 20
	s_add_u32 s16, s34, s16
	s_addc_u32 s17, s35, s17
	s_and_b64 s[18:19], s[12:13], exec
	s_cselect_b32 s15, s17, s25
	s_cselect_b32 s21, s16, s24
	s_ashr_i32 s11, s10, 31
	s_lshl_b64 s[18:19], s[10:11], 20
	s_add_u32 s18, s36, s18
	s_addc_u32 s19, s37, s19
	s_and_b64 s[28:29], s[12:13], exec
	s_cselect_b32 s11, s19, s27
	s_cselect_b32 s48, s18, s26
	s_add_u32 s24, s24, 0x80080
	s_addc_u32 s25, s25, 0
	s_add_u32 s49, s26, 0x100
	v_mov_b32_e32 v0, 0
	s_addc_u32 s50, s27, 0
	s_mov_b32 s51, -2
	v_mov_b32_e32 v1, v0
	v_mov_b32_e32 v2, v0
	v_mov_b32_e32 v3, v0
	v_mov_b32_e32 v4, v0
	v_mov_b32_e32 v5, v0
	v_mov_b32_e32 v6, v0
	v_mov_b32_e32 v7, v0
	v_mov_b32_e32 v16, v0
	v_mov_b32_e32 v17, v0
	v_mov_b32_e32 v18, v0
	v_mov_b32_e32 v19, v0
	v_mov_b32_e32 v20, v0
	v_mov_b32_e32 v21, v0
	v_mov_b32_e32 v22, v0
	v_mov_b32_e32 v23, v0
	v_mov_b32_e32 v32, v0
	v_mov_b32_e32 v33, v0
	v_mov_b32_e32 v34, v0
	v_mov_b32_e32 v35, v0
	v_mov_b32_e32 v36, v0
	v_mov_b32_e32 v37, v0
	v_mov_b32_e32 v38, v0
	v_mov_b32_e32 v39, v0
	v_mov_b32_e32 v56, v0
	v_mov_b32_e32 v57, v0
	v_mov_b32_e32 v58, v0
	v_mov_b32_e32 v59, v0
	v_mov_b32_e32 v60, v0
	v_mov_b32_e32 v61, v0
	v_mov_b32_e32 v62, v0
	v_mov_b32_e32 v63, v0
	v_mov_b32_e32 v8, v0
	v_mov_b32_e32 v9, v0
	v_mov_b32_e32 v10, v0
	v_mov_b32_e32 v11, v0
	v_mov_b32_e32 v12, v0
	v_mov_b32_e32 v13, v0
	v_mov_b32_e32 v14, v0
	v_mov_b32_e32 v15, v0
	v_mov_b32_e32 v24, v0
	v_mov_b32_e32 v25, v0
	v_mov_b32_e32 v26, v0
	v_mov_b32_e32 v27, v0
	v_mov_b32_e32 v28, v0
	v_mov_b32_e32 v29, v0
	v_mov_b32_e32 v30, v0
	v_mov_b32_e32 v31, v0
	v_mov_b32_e32 v40, v0
	v_mov_b32_e32 v41, v0
	v_mov_b32_e32 v42, v0
	v_mov_b32_e32 v43, v0
	v_mov_b32_e32 v44, v0
	v_mov_b32_e32 v45, v0
	v_mov_b32_e32 v46, v0
	v_mov_b32_e32 v47, v0
	v_mov_b32_e32 v72, v0
	v_mov_b32_e32 v73, v0
	v_mov_b32_e32 v74, v0
	v_mov_b32_e32 v75, v0
	v_mov_b32_e32 v76, v0
	v_mov_b32_e32 v77, v0
	v_mov_b32_e32 v78, v0
	v_mov_b32_e32 v79, v0
	v_mov_b32_e32 v80, v0
	v_mov_b32_e32 v81, v0
	v_mov_b32_e32 v82, v0
	v_mov_b32_e32 v83, v0
	v_mov_b32_e32 v84, v0
	v_mov_b32_e32 v85, v0
	v_mov_b32_e32 v86, v0
	v_mov_b32_e32 v87, v0
	v_mov_b32_e32 v96, v0
	v_mov_b32_e32 v97, v0
	v_mov_b32_e32 v98, v0
	v_mov_b32_e32 v99, v0
	v_mov_b32_e32 v100, v0
	v_mov_b32_e32 v101, v0
	v_mov_b32_e32 v102, v0
	v_mov_b32_e32 v103, v0
	v_mov_b32_e32 v112, v0
	v_mov_b32_e32 v113, v0
	v_mov_b32_e32 v114, v0
	v_mov_b32_e32 v115, v0
	v_mov_b32_e32 v116, v0
	v_mov_b32_e32 v117, v0
	v_mov_b32_e32 v118, v0
	v_mov_b32_e32 v119, v0
	v_mov_b32_e32 v128, v0
	v_mov_b32_e32 v129, v0
	v_mov_b32_e32 v130, v0
	v_mov_b32_e32 v131, v0
	v_mov_b32_e32 v132, v0
	v_mov_b32_e32 v133, v0
	v_mov_b32_e32 v134, v0
	v_mov_b32_e32 v135, v0
	v_mov_b32_e32 v88, v0
	v_mov_b32_e32 v89, v0
	v_mov_b32_e32 v90, v0
	v_mov_b32_e32 v91, v0
	v_mov_b32_e32 v92, v0
	v_mov_b32_e32 v93, v0
	v_mov_b32_e32 v94, v0
	v_mov_b32_e32 v95, v0
	v_mov_b32_e32 v104, v0
	v_mov_b32_e32 v105, v0
	v_mov_b32_e32 v106, v0
	v_mov_b32_e32 v107, v0
	v_mov_b32_e32 v108, v0
	v_mov_b32_e32 v109, v0
	v_mov_b32_e32 v110, v0
	v_mov_b32_e32 v111, v0
	v_mov_b32_e32 v120, v0
	v_mov_b32_e32 v121, v0
	v_mov_b32_e32 v122, v0
	v_mov_b32_e32 v123, v0
	v_mov_b32_e32 v124, v0
	v_mov_b32_e32 v125, v0
	v_mov_b32_e32 v126, v0
	v_mov_b32_e32 v127, v0
	v_mov_b32_e32 v136, v0
	v_mov_b32_e32 v137, v0
	v_mov_b32_e32 v138, v0
	v_mov_b32_e32 v139, v0
	v_mov_b32_e32 v140, v0
	v_mov_b32_e32 v141, v0
	v_mov_b32_e32 v142, v0
	v_mov_b32_e32 v143, v0
	s_cmp_eq_u32 s100, 0
	s_cbranch_scc1 .Lmy_nobar_768
	s_barrier
	s_mov_b32 s100, 0
.Lmy_nobar_768:
.LBB0_768:
	s_add_u32 s26, s24, 0xfff80080
	s_addc_u32 s27, s25, -1
	s_add_i32 s52, 0, 0x10000
	v_add_u32_e32 v68, s52, v157
	v_add_u32_e32 v154, s33, v157
	ds_read_b128 v[48:51], v68
	ds_read_b128 v[52:55], v68 offset:1024
	ds_read_b128 v[64:67], v68 offset:2048
	ds_read_b128 v[68:71], v68 offset:3072
	ds_read_b128 v[162:165], v154
	ds_read_b128 v[166:169], v154 offset:1024
	ds_read_b128 v[170:173], v154 offset:2048
	ds_read_b128 v[174:177], v154 offset:3072
	s_cmp_eq_u32 s51, 28
	s_cselect_b32 s29, s15, s27
	s_cselect_b32 s28, s21, s26
	s_cselect_b32 s27, s11, s50
	s_cselect_b32 s26, s48, s49
	v_lshl_add_u64 v[206:207], s[24:25], 0, v[150:151]
	s_add_i32 m0, s23, 0xc000
	ds_read_b128 v[178:181], v161
	ds_read_b128 v[182:185], v161 offset:1024
	ds_read_b128 v[186:189], v161 offset:2048
	ds_read_b128 v[190:193], v161 offset:3072
	ds_read_b128 v[194:197], v161 offset:4096
	ds_read_b128 v[198:201], v161 offset:5120
	ds_read_b128 v[202:205], v161 offset:6144
	ds_read_b128 v[214:217], v161 offset:7168
	global_load_lds_dwordx4 v[206:207], off
	v_lshl_add_u64 v[206:207], s[24:25], 0, v[152:153]
	s_add_i32 m0, s23, 0xe000
	s_nop 0
	global_load_lds_dwordx4 v[206:207], off
	s_waitcnt vmcnt(8)
	s_waitcnt lgkmcnt(0)
	s_barrier
; #define PG8_STAGE(bufoff, gbase, voff) do { _Pragma("unroll") for (int _i = 0; _i < 2; ++_i) \
;         __builtin_amdgcn_global_load_lds((const unsigned*)((const char*)(gbase) + (voff)[_i]), (PG8_LAS unsigned*)(lds + (bufoff) + ldsw + _i * 8192), 16, 0, 0); } while (0)
; #define PG8_LDA(dst, b, h) do { _Pragma("unroll") for (int m = 0; m < 4; ++m) _Pragma("unroll") for (int k = 0; k < 2; ++k) dst[m][k] = *(const PG8_LAS bf16x8*)(lds + PG8_SA(b, h) + aoff + m * 2048 + k * 1024); } while (0)
; #define PG8_MMA(ai, bj, At, Bt) do { __builtin_amdgcn_s_setprio(1); _Pragma("unroll") for (int m = 0; m < 4; ++m) _Pragma("unroll") for (int n = 0; n < 2; ++n) _Pragma("unroll") for (int k = 0; k < 2; ++k) \
;         acc[ai][bj][m][n] = __builtin_amdgcn_mfma_f32_16x16x32_bf16(Bt[n][k], At[m][k], acc[ai][bj][m][n], 0, 0, 0); __builtin_amdgcn_s_setprio(0); } while (0)
; #define PG8_WAIT_V(n) asm volatile("s_waitcnt vmcnt(" #n ")" ::: "memory")
; #define PG8_WAIT_L(n) asm volatile("s_waitcnt lgkmcnt(" #n ")" ::: "memory")
; #define PG8_BAR __builtin_amdgcn_s_barrier()
; #define PG8_SCHED __builtin_amdgcn_sched_barrier(0)
; template <class Epi, class Sched, bool ALIGN_EPI = false, bool SP2 = false>
; __device__ __forceinline__ void gemm_phase(PG8_LAS unsigned char* lds, const Gemm g, const Sched& S, const Epi& E, const int tid) {
;     ...
;             PG8_WAIT_V(8); PG8_WAIT_L(0); PG8_BAR; PG8_MMA(0, 0, At, B0); PG8_MMA(0, 1, At, B1); PG8_BAR; PG8_SCHED;
;             PG8_LDA(At, 0, 1); PG8_STAGE(PG8_SB(0, 0), b2, voffB); PG8_STAGE(PG8_SB(0, 1), b2 + hstep, voffB); PG8_STAGE(PG8_SA(0, 0), a2, voffA);
;             PG8_WAIT_V(8); PG8_WAIT_L(0); PG8_BAR; PG8_MMA(1, 0, At, B0); PG8_MMA(1, 1, At, B1); PG8_BAR; PG8_SCHED;
	s_setprio 1
	s_waitcnt lgkmcnt(0)
	v_mfma_f32_16x16x32_bf16 v[140:143], v[48:51], v[178:181], v[140:143]
	v_mfma_f32_16x16x32_bf16 v[136:139], v[64:67], v[178:181], v[136:139]
	v_mfma_f32_16x16x32_bf16 v[124:127], v[48:51], v[186:189], v[124:127]
	v_mfma_f32_16x16x32_bf16 v[120:123], v[64:67], v[186:189], v[120:123]
	v_mfma_f32_16x16x32_bf16 v[108:111], v[48:51], v[194:197], v[108:111]
	v_mfma_f32_16x16x32_bf16 v[104:107], v[64:67], v[194:197], v[104:107]
	v_mfma_f32_16x16x32_bf16 v[92:95], v[48:51], v[202:205], v[92:95]
	v_mfma_f32_16x16x32_bf16 v[88:91], v[64:67], v[202:205], v[88:91]
	v_mfma_f32_16x16x32_bf16 v[140:143], v[52:55], v[182:185], v[140:143]
	v_mfma_f32_16x16x32_bf16 v[136:139], v[68:71], v[182:185], v[136:139]
	v_mfma_f32_16x16x32_bf16 v[124:127], v[52:55], v[190:193], v[124:127]
	v_mfma_f32_16x16x32_bf16 v[120:123], v[68:71], v[190:193], v[120:123]
	v_mfma_f32_16x16x32_bf16 v[108:111], v[52:55], v[198:201], v[108:111]
	v_mfma_f32_16x16x32_bf16 v[104:107], v[68:71], v[198:201], v[104:107]
	v_mfma_f32_16x16x32_bf16 v[92:95], v[52:55], v[214:217], v[92:95]
	v_mfma_f32_16x16x32_bf16 v[88:91], v[68:71], v[214:217], v[88:91]
	s_setprio 0
	s_setprio 1
	v_mfma_f32_16x16x32_bf16 v[132:135], v[162:165], v[178:181], v[132:135]
	v_mfma_f32_16x16x32_bf16 v[128:131], v[170:173], v[178:181], v[128:131]
	v_mfma_f32_16x16x32_bf16 v[116:119], v[162:165], v[186:189], v[116:119]
	v_mfma_f32_16x16x32_bf16 v[112:115], v[170:173], v[186:189], v[112:115]
	v_mfma_f32_16x16x32_bf16 v[100:103], v[162:165], v[194:197], v[100:103]
	v_mfma_f32_16x16x32_bf16 v[96:99], v[170:173], v[194:197], v[96:99]
	v_mfma_f32_16x16x32_bf16 v[84:87], v[162:165], v[202:205], v[84:87]
	v_mfma_f32_16x16x32_bf16 v[80:83], v[170:173], v[202:205], v[80:83]
	v_mfma_f32_16x16x32_bf16 v[132:135], v[166:169], v[182:185], v[132:135]
	v_mfma_f32_16x16x32_bf16 v[128:131], v[174:177], v[182:185], v[128:131]
	v_mfma_f32_16x16x32_bf16 v[116:119], v[166:169], v[190:193], v[116:119]
	v_mfma_f32_16x16x32_bf16 v[112:115], v[174:177], v[190:193], v[112:115]
	v_mfma_f32_16x16x32_bf16 v[100:103], v[166:169], v[198:201], v[100:103]
	v_mfma_f32_16x16x32_bf16 v[96:99], v[174:177], v[198:201], v[96:99]
	v_mfma_f32_16x16x32_bf16 v[84:87], v[166:169], v[214:217], v[84:87]
	v_mfma_f32_16x16x32_bf16 v[80:83], v[174:177], v[214:217], v[80:83]
	s_setprio 0
	s_barrier
	s_add_i32 s52, s52, s38
	v_lshl_add_u64 v[206:207], s[26:27], 0, v[208:209]
	s_mov_b32 m0, s52
	ds_read_b128 v[178:181], v161 offset:16384
	ds_read_b128 v[182:185], v161 offset:17408
	ds_read_b128 v[186:189], v161 offset:18432
	ds_read_b128 v[190:193], v161 offset:19456
	ds_read_b128 v[194:197], v161 offset:20480
	ds_read_b128 v[198:201], v161 offset:21504
	ds_read_b128 v[202:205], v161 offset:22528
	ds_read_b128 v[214:217], v161 offset:23552
	global_load_lds_dwordx4 v[206:207], off
	s_add_i32 m0, s52, 0x2000
	s_add_u32 s52, s26, 0x80000
	v_lshl_add_u64 v[210:211], s[26:27], 0, v[144:145]
	s_addc_u32 s53, s27, 0
	s_add_i32 s54, s33, s38
	global_load_lds_dwordx4 v[210:211], off
	v_lshl_add_u64 v[218:219], s[52:53], 0, v[208:209]
	s_mov_b32 m0, s54
	v_lshl_add_u64 v[220:221], s[28:29], 0, v[146:147]
	global_load_lds_dwordx4 v[218:219], off
	v_lshl_add_u64 v[218:219], s[52:53], 0, v[144:145]
	s_add_i32 m0, s54, 0x2000
	s_nop 0
	global_load_lds_dwordx4 v[218:219], off
	v_lshl_add_u64 v[218:219], s[28:29], 0, v[148:149]
	s_mov_b32 m0, s23
	s_nop 0
	global_load_lds_dwordx4 v[218:219], off
	s_mov_b32 m0, s39
	s_nop 0
	global_load_lds_dwordx4 v[220:221], off
	s_waitcnt vmcnt(8)
	s_waitcnt lgkmcnt(0)
	s_barrier
	s_setprio 1
	s_waitcnt lgkmcnt(0)
	v_mfma_f32_16x16x32_bf16 v[76:79], v[48:51], v[178:181], v[76:79]
	v_mfma_f32_16x16x32_bf16 v[72:75], v[64:67], v[178:181], v[72:75]
	v_mfma_f32_16x16x32_bf16 v[44:47], v[48:51], v[186:189], v[44:47]
	v_mfma_f32_16x16x32_bf16 v[40:43], v[64:67], v[186:189], v[40:43]
	v_mfma_f32_16x16x32_bf16 v[28:31], v[48:51], v[194:197], v[28:31]
	v_mfma_f32_16x16x32_bf16 v[24:27], v[64:67], v[194:197], v[24:27]
	v_mfma_f32_16x16x32_bf16 v[12:15], v[48:51], v[202:205], v[12:15]
	v_mfma_f32_16x16x32_bf16 v[8:11], v[64:67], v[202:205], v[8:11]
	v_mfma_f32_16x16x32_bf16 v[76:79], v[52:55], v[182:185], v[76:79]
	v_mfma_f32_16x16x32_bf16 v[72:75], v[68:71], v[182:185], v[72:75]
	v_mfma_f32_16x16x32_bf16 v[44:47], v[52:55], v[190:193], v[44:47]
	v_mfma_f32_16x16x32_bf16 v[40:43], v[68:71], v[190:193], v[40:43]
	v_mfma_f32_16x16x32_bf16 v[28:31], v[52:55], v[198:201], v[28:31]
	v_mfma_f32_16x16x32_bf16 v[24:27], v[68:71], v[198:201], v[24:27]
	v_mfma_f32_16x16x32_bf16 v[12:15], v[52:55], v[214:217], v[12:15]
	v_mfma_f32_16x16x32_bf16 v[8:11], v[68:71], v[214:217], v[8:11]
	s_setprio 0
	s_setprio 1
	v_mfma_f32_16x16x32_bf16 v[36:39], v[162:165], v[186:189], v[36:39]
	v_mfma_f32_16x16x32_bf16 v[32:35], v[170:173], v[186:189], v[32:35]
	v_mfma_f32_16x16x32_bf16 v[20:23], v[162:165], v[194:197], v[20:23]
	v_mfma_f32_16x16x32_bf16 v[16:19], v[170:173], v[194:197], v[16:19]
	v_mfma_f32_16x16x32_bf16 v[4:7], v[162:165], v[202:205], v[4:7]
	v_mfma_f32_16x16x32_bf16 v[0:3], v[170:173], v[202:205], v[0:3]
	v_mfma_f32_16x16x32_bf16 v[48:51], v[162:165], v[178:181], v[60:63]
	v_mfma_f32_16x16x32_bf16 v[52:55], v[170:173], v[178:181], v[56:59]
	v_mfma_f32_16x16x32_bf16 v[36:39], v[166:169], v[190:193], v[36:39]
	v_mfma_f32_16x16x32_bf16 v[32:35], v[174:177], v[190:193], v[32:35]
	v_mfma_f32_16x16x32_bf16 v[20:23], v[166:169], v[198:201], v[20:23]
	v_mfma_f32_16x16x32_bf16 v[16:19], v[174:177], v[198:201], v[16:19]
	v_mfma_f32_16x16x32_bf16 v[4:7], v[166:169], v[214:217], v[4:7]
	v_mfma_f32_16x16x32_bf16 v[0:3], v[174:177], v[214:217], v[0:3]
	v_mfma_f32_16x16x32_bf16 v[48:51], v[166:169], v[182:185], v[48:51]
	v_mfma_f32_16x16x32_bf16 v[52:55], v[174:177], v[182:185], v[52:55]
	s_setprio 0
	s_barrier
; #define PG8_STAGE(bufoff, gbase, voff) do { _Pragma("unroll") for (int _i = 0; _i < 2; ++_i) \
;         __builtin_amdgcn_global_load_lds((const unsigned*)((const char*)(gbase) + (voff)[_i]), (PG8_LAS unsigned*)(lds + (bufoff) + ldsw + _i * 8192), 16, 0, 0); } while (0)
; #define PG8_LDA(dst, b, h) do { _Pragma("unroll") for (int m = 0; m < 4; ++m) _Pragma("unroll") for (int k = 0; k < 2; ++k) dst[m][k] = *(const PG8_LAS bf16x8*)(lds + PG8_SA(b, h) + aoff + m * 2048 + k * 1024); } while (0)
; #define PG8_LDB(dst, b, h) do { _Pragma("unroll") for (int n = 0; n < 2; ++n) _Pragma("unroll") for (int k = 0; k < 2; ++k) dst[n][k] = *(const PG8_LAS bf16x8*)(lds + PG8_SB(b, h) + boff + n * 2048 + k * 1024); } while (0)
; #define PG8_MMA(ai, bj, At, Bt) do { __builtin_amdgcn_s_setprio(1); _Pragma("unroll") for (int m = 0; m < 4; ++m) _Pragma("unroll") for (int n = 0; n < 2; ++n) _Pragma("unroll") for (int k = 0; k < 2; ++k) \
;         acc[ai][bj][m][n] = __builtin_amdgcn_mfma_f32_16x16x32_bf16(Bt[n][k], At[m][k], acc[ai][bj][m][n], 0, 0, 0); __builtin_amdgcn_s_setprio(0); } while (0)
; #define PG8_WAIT_V(n) asm volatile("s_waitcnt vmcnt(" #n ")" ::: "memory")
; #define PG8_WAIT_L(n) asm volatile("s_waitcnt lgkmcnt(" #n ")" ::: "memory")
; #define PG8_BAR __builtin_amdgcn_s_barrier()
; #define PG8_SCHED __builtin_amdgcn_sched_barrier(0)
; template <class Epi, class Sched, bool ALIGN_EPI = false, bool SP2 = false>
; __device__ __forceinline__ void gemm_phase(PG8_LAS unsigned char* lds, const Gemm g, const Sched& S, const Epi& E, const int tid) {
;     ...
;             PG8_LDB(B0, 1, 0); PG8_LDB(B1, 1, 1); PG8_SCHED; PG8_LDA(At, 1, 0); PG8_STAGE(PG8_SA(0, 1), a2 + hstep, voffA);
;             PG8_WAIT_V(8); PG8_WAIT_L(0); PG8_BAR; PG8_MMA(0, 0, At, B0); PG8_MMA(0, 1, At, B1); PG8_BAR; PG8_SCHED;
;             PG8_LDA(At, 1, 1); PG8_STAGE(PG8_SB(1, 0), b3, voffB); PG8_STAGE(PG8_SB(1, 1), b3 + hstep, voffB); PG8_STAGE(PG8_SA(1, 0), a3, voffA);
;             PG8_WAIT_V(8); PG8_WAIT_L(0); PG8_BAR; PG8_MMA(1, 0, At, B0); PG8_MMA(1, 1, At, B1); PG8_BAR; PG8_SCHED;
	s_add_i32 s52, 0, 0x18000
	s_add_i32 s53, 0, 0x1c000
	v_add_u32_e32 v68, s52, v157
	v_add_u32_e32 v154, s53, v157
	ds_read_b128 v[56:59], v68
	ds_read_b128 v[60:63], v68 offset:1024
	ds_read_b128 v[64:67], v68 offset:2048
	ds_read_b128 v[68:71], v68 offset:3072
	ds_read_b128 v[162:165], v154
	ds_read_b128 v[166:169], v154 offset:1024
	ds_read_b128 v[170:173], v154 offset:2048
	ds_read_b128 v[174:177], v154 offset:3072
	s_add_u32 s28, s28, 0x80000
	s_addc_u32 s29, s29, 0
	s_mov_b32 m0, s40
	v_lshl_add_u64 v[222:223], s[28:29], 0, v[148:149]
	ds_read_b128 v[178:181], v161 offset:32768
	ds_read_b128 v[182:185], v161 offset:33792
	ds_read_b128 v[186:189], v161 offset:34816
	ds_read_b128 v[190:193], v161 offset:35840
	ds_read_b128 v[194:197], v161 offset:36864
	ds_read_b128 v[198:201], v161 offset:37888
	ds_read_b128 v[202:205], v161 offset:38912
	ds_read_b128 v[214:217], v161 offset:39936
	global_load_lds_dwordx4 v[222:223], off
	v_lshl_add_u64 v[222:223], s[28:29], 0, v[146:147]
	s_mov_b32 m0, s41
	s_nop 0
	global_load_lds_dwordx4 v[222:223], off
	s_waitcnt vmcnt(8)
	s_waitcnt lgkmcnt(0)
	s_barrier
	s_setprio 1
	s_waitcnt lgkmcnt(0)
	v_mfma_f32_16x16x32_bf16 v[140:143], v[56:59], v[178:181], v[140:143]
	v_mfma_f32_16x16x32_bf16 v[136:139], v[64:67], v[178:181], v[136:139]
	v_mfma_f32_16x16x32_bf16 v[124:127], v[56:59], v[186:189], v[124:127]
	v_mfma_f32_16x16x32_bf16 v[120:123], v[64:67], v[186:189], v[120:123]
	v_mfma_f32_16x16x32_bf16 v[108:111], v[56:59], v[194:197], v[108:111]
	v_mfma_f32_16x16x32_bf16 v[104:107], v[64:67], v[194:197], v[104:107]
	v_mfma_f32_16x16x32_bf16 v[92:95], v[56:59], v[202:205], v[92:95]
	v_mfma_f32_16x16x32_bf16 v[88:91], v[64:67], v[202:205], v[88:91]
	v_mfma_f32_16x16x32_bf16 v[140:143], v[60:63], v[182:185], v[140:143]
	v_mfma_f32_16x16x32_bf16 v[136:139], v[68:71], v[182:185], v[136:139]
	v_mfma_f32_16x16x32_bf16 v[124:127], v[60:63], v[190:193], v[124:127]
	v_mfma_f32_16x16x32_bf16 v[120:123], v[68:71], v[190:193], v[120:123]
	v_mfma_f32_16x16x32_bf16 v[108:111], v[60:63], v[198:201], v[108:111]
	v_mfma_f32_16x16x32_bf16 v[104:107], v[68:71], v[198:201], v[104:107]
	v_mfma_f32_16x16x32_bf16 v[92:95], v[60:63], v[214:217], v[92:95]
	v_mfma_f32_16x16x32_bf16 v[88:91], v[68:71], v[214:217], v[88:91]
	s_setprio 0
	s_setprio 1
	v_mfma_f32_16x16x32_bf16 v[132:135], v[162:165], v[178:181], v[132:135]
	v_mfma_f32_16x16x32_bf16 v[128:131], v[170:173], v[178:181], v[128:131]
	v_mfma_f32_16x16x32_bf16 v[116:119], v[162:165], v[186:189], v[116:119]
	v_mfma_f32_16x16x32_bf16 v[112:115], v[170:173], v[186:189], v[112:115]
	v_mfma_f32_16x16x32_bf16 v[100:103], v[162:165], v[194:197], v[100:103]
	v_mfma_f32_16x16x32_bf16 v[96:99], v[170:173], v[194:197], v[96:99]
	v_mfma_f32_16x16x32_bf16 v[84:87], v[162:165], v[202:205], v[84:87]
	v_mfma_f32_16x16x32_bf16 v[80:83], v[170:173], v[202:205], v[80:83]
	v_mfma_f32_16x16x32_bf16 v[132:135], v[166:169], v[182:185], v[132:135]
	v_mfma_f32_16x16x32_bf16 v[128:131], v[174:177], v[182:185], v[128:131]
	v_mfma_f32_16x16x32_bf16 v[116:119], v[166:169], v[190:193], v[116:119]
	v_mfma_f32_16x16x32_bf16 v[112:115], v[174:177], v[190:193], v[112:115]
	v_mfma_f32_16x16x32_bf16 v[100:103], v[166:169], v[198:201], v[100:103]
	v_mfma_f32_16x16x32_bf16 v[96:99], v[174:177], v[198:201], v[96:99]
	v_mfma_f32_16x16x32_bf16 v[84:87], v[166:169], v[214:217], v[84:87]
	v_mfma_f32_16x16x32_bf16 v[80:83], v[174:177], v[214:217], v[80:83]
	s_setprio 0
	s_barrier
	s_add_i32 s28, s52, s38
	v_lshl_add_u64 v[206:207], v[206:207], 0, s[2:3]
	s_mov_b32 m0, s28
	ds_read_b128 v[178:181], v161 offset:49152
	ds_read_b128 v[182:185], v161 offset:50176
	ds_read_b128 v[186:189], v161 offset:51200
	ds_read_b128 v[190:193], v161 offset:52224
	ds_read_b128 v[194:197], v161 offset:53248
	ds_read_b128 v[198:201], v161 offset:54272
	ds_read_b128 v[202:205], v161 offset:55296
	ds_read_b128 v[214:217], v161 offset:56320
	global_load_lds_dwordx4 v[206:207], off
	s_add_i32 m0, s28, 0x2000
	s_add_u32 s26, s26, 0x80080
	v_lshl_add_u64 v[206:207], v[210:211], 0, s[2:3]
	s_addc_u32 s27, s27, 0
	s_add_i32 s28, s53, s38
	global_load_lds_dwordx4 v[206:207], off
	v_lshl_add_u64 v[206:207], s[26:27], 0, v[208:209]
	s_mov_b32 m0, s28
	s_nop 0
	global_load_lds_dwordx4 v[206:207], off
	v_lshl_add_u64 v[206:207], s[26:27], 0, v[144:145]
	s_add_i32 m0, s28, 0x2000
	s_nop 0
	global_load_lds_dwordx4 v[206:207], off
	v_lshl_add_u64 v[206:207], v[218:219], 0, s[2:3]
	s_mov_b32 m0, s45
	s_nop 0
	global_load_lds_dwordx4 v[206:207], off
	v_lshl_add_u64 v[206:207], v[220:221], 0, s[2:3]
	s_mov_b32 m0, s46
	s_nop 0
	global_load_lds_dwordx4 v[206:207], off
	s_waitcnt vmcnt(8)
	s_waitcnt lgkmcnt(0)
	s_barrier
; #define PG8_MMA(ai, bj, At, Bt) do { __builtin_amdgcn_s_setprio(1); _Pragma("unroll") for (int m = 0; m < 4; ++m) _Pragma("unroll") for (int n = 0; n < 2; ++n) _Pragma("unroll") for (int k = 0; k < 2; ++k) \
;         acc[ai][bj][m][n] = __builtin_amdgcn_mfma_f32_16x16x32_bf16(Bt[n][k], At[m][k], acc[ai][bj][m][n], 0, 0, 0); __builtin_amdgcn_s_setprio(0); } while (0)
; #define PG8_WAIT_V(n) asm volatile("s_waitcnt vmcnt(" #n ")" ::: "memory")
; #define PG8_WAIT_L(n) asm volatile("s_waitcnt lgkmcnt(" #n ")" ::: "memory")
; #define PG8_BAR __builtin_amdgcn_s_barrier()
; #define PG8_SCHED __builtin_amdgcn_sched_barrier(0)
; __device__ __forceinline__ unsigned pk2(float lo, float hi) { const f32x2 v = {lo, hi}; return __builtin_bit_cast(unsigned, __builtin_convertvector(v, bf16x2_t)); }
; template <class Epi, class Sched, bool ALIGN_EPI = false, bool SP2 = false>
; __device__ __forceinline__ void gemm_phase(PG8_LAS unsigned char* lds, const Gemm g, const Sched& S, const Epi& E, const int tid) {
;     ...
;             PG8_WAIT_V(8); PG8_WAIT_L(0); PG8_BAR; PG8_MMA(1, 0, At, B0); PG8_MMA(1, 1, At, B1); PG8_BAR; PG8_SCHED;
;     __device__ __forceinline__ void operator()(const f32x4 (&acc)[2][2][4][2], const Unit& un, int wr, int wc, int fr, int fq) const {
;         const int rbase = un.pm * 256 + wr * 64 + fr, cw = un.pn * 256 + wc * 32 + 8 * fq;
;         const int slot = un.pm < (NLAT / 256) ? (un.pm >> 5) : 4; const float* sw = shw + (size_t)slot * DFF;
;         f32x4 s0[2], s1[2]; float rr[2][4];
; #pragma unroll
;         for (int bj = 0; bj < 2; ++bj) { s0[bj] = *(const f32x4*)(sw + cw + bj * 128); s1[bj] = *(const f32x4*)(sw + cw + bj * 128 + 4); }
; #pragma unroll
;         for (int ai = 0; ai < 2; ++ai)
; #pragma unroll
;             for (int m = 0; m < 4; ++m) rr[ai][m] = rs[rbase + ai * 128 + m * 16];
;         EPI_LOOP { const int row = rbase + ai * 128 + m * 16, col = cw + bj * 128; const float r = rr[ai][m];
;             f32x4 v0 = acc[ai][bj][m][0] * r + s0[bj], v1 = acc[ai][bj][m][1] * r + s1[bj];
;             v0 = (f32x4){sigmoidf_(v0.x), sigmoidf_(v0.y), sigmoidf_(v0.z), sigmoidf_(v0.w)}; v1 = (f32x4){sigmoidf_(v1.x), sigmoidf_(v1.y), sigmoidf_(v1.z), sigmoidf_(v1.w)};
;             u32x4 w; w.x = pk2(v0.x, v0.y); w.y = pk2(v0.z, v0.w); w.z = pk2(v1.x, v1.y); w.w = pk2(v1.z, v1.w);
;             *(u32x4*)(o + (size_t)row * DFF + col) = w; }
	s_setprio 1
	s_waitcnt lgkmcnt(0)
	v_mfma_f32_16x16x32_bf16 v[76:79], v[56:59], v[178:181], v[76:79]
	v_mfma_f32_16x16x32_bf16 v[72:75], v[64:67], v[178:181], v[72:75]
	v_mfma_f32_16x16x32_bf16 v[44:47], v[56:59], v[186:189], v[44:47]
	v_mfma_f32_16x16x32_bf16 v[40:43], v[64:67], v[186:189], v[40:43]
	v_mfma_f32_16x16x32_bf16 v[28:31], v[56:59], v[194:197], v[28:31]
	v_mfma_f32_16x16x32_bf16 v[24:27], v[64:67], v[194:197], v[24:27]
	v_mfma_f32_16x16x32_bf16 v[12:15], v[56:59], v[202:205], v[12:15]
	v_mfma_f32_16x16x32_bf16 v[8:11], v[64:67], v[202:205], v[8:11]
	v_mfma_f32_16x16x32_bf16 v[76:79], v[60:63], v[182:185], v[76:79]
	v_mfma_f32_16x16x32_bf16 v[72:75], v[68:71], v[182:185], v[72:75]
	v_mfma_f32_16x16x32_bf16 v[44:47], v[60:63], v[190:193], v[44:47]
	v_mfma_f32_16x16x32_bf16 v[40:43], v[68:71], v[190:193], v[40:43]
	v_mfma_f32_16x16x32_bf16 v[28:31], v[60:63], v[198:201], v[28:31]
	v_mfma_f32_16x16x32_bf16 v[24:27], v[68:71], v[198:201], v[24:27]
	v_mfma_f32_16x16x32_bf16 v[12:15], v[60:63], v[214:217], v[12:15]
	v_mfma_f32_16x16x32_bf16 v[8:11], v[68:71], v[214:217], v[8:11]
	s_setprio 0
	s_setprio 1
	v_mfma_f32_16x16x32_bf16 v[48:51], v[162:165], v[178:181], v[48:51]
	v_mfma_f32_16x16x32_bf16 v[60:63], v[166:169], v[182:185], v[48:51]
	v_mfma_f32_16x16x32_bf16 v[48:51], v[170:173], v[178:181], v[52:55]
	v_mfma_f32_16x16x32_bf16 v[36:39], v[162:165], v[186:189], v[36:39]
	v_mfma_f32_16x16x32_bf16 v[32:35], v[170:173], v[186:189], v[32:35]
	v_mfma_f32_16x16x32_bf16 v[20:23], v[162:165], v[194:197], v[20:23]
	v_mfma_f32_16x16x32_bf16 v[16:19], v[170:173], v[194:197], v[16:19]
	v_mfma_f32_16x16x32_bf16 v[4:7], v[162:165], v[202:205], v[4:7]
	v_mfma_f32_16x16x32_bf16 v[0:3], v[170:173], v[202:205], v[0:3]
	v_mfma_f32_16x16x32_bf16 v[56:59], v[174:177], v[182:185], v[48:51]
	v_mfma_f32_16x16x32_bf16 v[36:39], v[166:169], v[190:193], v[36:39]
	v_mfma_f32_16x16x32_bf16 v[32:35], v[174:177], v[190:193], v[32:35]
	v_mfma_f32_16x16x32_bf16 v[20:23], v[166:169], v[198:201], v[20:23]
	v_mfma_f32_16x16x32_bf16 v[16:19], v[174:177], v[198:201], v[16:19]
	v_mfma_f32_16x16x32_bf16 v[4:7], v[166:169], v[214:217], v[4:7]
	v_mfma_f32_16x16x32_bf16 v[0:3], v[174:177], v[214:217], v[0:3]
	s_setprio 0
	s_barrier
	s_add_i32 s51, s51, 2
	s_add_u32 s24, s24, 0x100
	s_addc_u32 s25, s25, 0
	s_add_u32 s49, s49, 0x100
	s_addc_u32 s50, s50, 0
	s_cmp_gt_u32 s51, 29
	s_cbranch_scc0 .LBB0_768
	s_ashr_i32 s24, s20, 5
	s_ashr_i32 s25, s24, 31
	s_lshl_b64 s[24:25], s[24:25], 13
	s_cmpk_lt_i32 s20, 0x80
	s_cselect_b32 s25, s25, 0
	s_cselect_b32 s24, s24, 0x8000
	s_lshl_b64 s[24:25], s[24:25], 2
	v_lshl_or_b32 v176, s22, 8, v159
	s_add_u32 s24, s42, s24
	v_lshl_add_u32 v178, s20, 8, v155
	s_addc_u32 s25, s43, s25
	v_ashrrev_i32_e32 v177, 31, v176
	v_ashrrev_i32_e32 v179, 31, v178
	v_lshl_add_u64 v[52:53], v[176:177], 2, s[24:25]
	v_lshl_add_u64 v[180:181], v[178:179], 2, s[6:7]
	global_load_dwordx4 v[64:67], v[52:53], off offset:16
	global_load_dwordx4 v[68:71], v[52:53], off
	global_load_dwordx4 v[48:51], v[52:53], off offset:528
	s_nop 0
	global_load_dwordx4 v[52:55], v[52:53], off offset:512
	v_or_b32_e32 v172, 16, v178
	global_load_dword v174, v[180:181], off
	v_ashrrev_i32_e32 v173, 31, v172
	v_lshl_add_u64 v[162:163], v[172:173], 2, s[6:7]
	global_load_dword v170, v[162:163], off
	v_or_b32_e32 v168, 32, v178
	v_ashrrev_i32_e32 v169, 31, v168
	v_lshl_add_u64 v[162:163], v[168:169], 2, s[6:7]
	global_load_dword v166, v[162:163], off
	v_or_b32_e32 v164, 48, v178
	v_lshlrev_b64 v[178:179], 14, v[178:179]
	v_ashrrev_i32_e32 v165, 31, v164
	v_lshl_add_u64 v[162:163], v[164:165], 2, s[6:7]
	global_load_dword v162, v[162:163], off
	s_nop 0
	global_load_dword v160, v[180:181], off offset:512
	global_load_dword v158, v[180:181], off offset:576
	global_load_dword v156, v[180:181], off offset:640
	global_load_dword v154, v[180:181], off offset:704
	s_and_b64 vcc, exec, s[8:9]
	s_cbranch_vccz .LBB0_771
	s_barrier
.LBB0_771:
	s_mov_b64 s[20:21], 0x240000
	s_waitcnt vmcnt(0)
	v_pk_fma_f32 v[142:143], v[142:143], v[174:175], v[70:71] op_sel_hi:[1,0,1]
	v_pk_fma_f32 v[140:141], v[140:141], v[174:175], v[68:69] op_sel_hi:[1,0,1]
	v_pk_fma_f32 v[138:139], v[138:139], v[174:175], v[66:67] op_sel_hi:[1,0,1]
	v_pk_fma_f32 v[136:137], v[136:137], v[174:175], v[64:65] op_sel_hi:[1,0,1]
	v_mul_f32_e32 v140, 0xbfb8aa3b, v140
	v_mul_f32_e32 v141, 0xbfb8aa3b, v141
	v_mul_f32_e32 v142, 0xbfb8aa3b, v142
	v_mul_f32_e32 v143, 0xbfb8aa3b, v143
	v_mul_f32_e32 v136, 0xbfb8aa3b, v136
	v_mul_f32_e32 v137, 0xbfb8aa3b, v137
	v_mul_f32_e32 v138, 0xbfb8aa3b, v138
	v_mul_f32_e32 v139, 0xbfb8aa3b, v139
	v_exp_f32_e32 v140, v140
	v_exp_f32_e32 v141, v141
	v_exp_f32_e32 v142, v142
	v_exp_f32_e32 v143, v143
	v_exp_f32_e32 v136, v136
	v_exp_f32_e32 v137, v137
	v_exp_f32_e32 v138, v138
	v_exp_f32_e32 v139, v139
	v_add_f32_e32 v140, 1.0, v140
	v_add_f32_e32 v141, 1.0, v141
	v_add_f32_e32 v142, 1.0, v142
	v_add_f32_e32 v143, 1.0, v143
	v_add_f32_e32 v136, 1.0, v136
	v_add_f32_e32 v137, 1.0, v137
	v_add_f32_e32 v138, 1.0, v138
	v_add_f32_e32 v139, 1.0, v139
	v_pk_fma_f32 v[128:129], v[128:129], v[174:175], v[48:49] op_sel_hi:[1,0,1]
	v_rcp_f32_e32 v140, v140
	v_rcp_f32_e32 v141, v141
	v_rcp_f32_e32 v142, v142
	v_rcp_f32_e32 v143, v143
	v_rcp_f32_e32 v136, v136
	v_rcp_f32_e32 v137, v137
	v_rcp_f32_e32 v138, v138
	v_rcp_f32_e32 v139, v139
	v_mul_f32_e32 v128, 0xbfb8aa3b, v128
	v_exp_f32_e32 v128, v128
	v_cvt_pk_bf16_f32 v140, v140, v141
	v_cvt_pk_bf16_f32 v141, v142, v143
	v_cvt_pk_bf16_f32 v142, v136, v137
	v_cvt_pk_bf16_f32 v143, v138, v139
	v_lshl_add_u64 v[136:137], s[4:5], 0, v[178:179]
; __device__ __forceinline__ unsigned pk2(float lo, float hi) { const f32x2 v = {lo, hi}; return __builtin_bit_cast(unsigned, __builtin_convertvector(v, bf16x2_t)); }
; __device__ __forceinline__ float sigmoidf_(float x) { return __builtin_amdgcn_rcpf(1.f + __builtin_amdgcn_exp2f(-x * LOG2E)); }
; #define EPI_LOOP _Pragma("unroll") for (int ai = 0; ai < 2; ++ai) _Pragma("unroll") for (int m = 0; m < 4; ++m) _Pragma("unroll") for (int bj = 0; bj < 2; ++bj)
;     __device__ __forceinline__ void operator()(const f32x4 (&acc)[2][2][4][2], const Unit& un, int wr, int wc, int fr, int fq) const {
;     ...
;         EPI_LOOP { const int row = rbase + ai * 128 + m * 16, col = cw + bj * 128; const float r = rr[ai][m];
;             f32x4 v0 = acc[ai][bj][m][0] * r + s0[bj], v1 = acc[ai][bj][m][1] * r + s1[bj];
;             v0 = (f32x4){sigmoidf_(v0.x), sigmoidf_(v0.y), sigmoidf_(v0.z), sigmoidf_(v0.w)}; v1 = (f32x4){sigmoidf_(v1.x), sigmoidf_(v1.y), sigmoidf_(v1.z), sigmoidf_(v1.w)};
;             u32x4 w; w.x = pk2(v0.x, v0.y); w.y = pk2(v0.z, v0.w); w.z = pk2(v1.x, v1.y); w.w = pk2(v1.z, v1.w);
;             *(u32x4*)(o + (size_t)row * DFF + col) = w; }
	v_lshlrev_b64 v[138:139], 1, v[176:177]
	v_lshl_add_u64 v[136:137], v[136:137], 0, v[138:139]
	v_add_f32_e32 v128, 1.0, v128
	global_store_dwordx4 v[136:137], v[140:143], off
	v_pk_fma_f32 v[130:131], v[130:131], v[174:175], v[50:51] op_sel_hi:[1,0,1]
	v_pk_fma_f32 v[134:135], v[134:135], v[174:175], v[54:55] op_sel_hi:[1,0,1]
	v_rcp_f32_e32 v140, v128
	v_mul_f32_e32 v128, 0xbfb8aa3b, v129
	v_exp_f32_e32 v128, v128
	v_pk_fma_f32 v[132:133], v[132:133], v[174:175], v[52:53] op_sel_hi:[1,0,1]
	v_mul_f32_e32 v134, 0xbfb8aa3b, v134
	v_mul_f32_e32 v132, 0xbfb8aa3b, v132
	v_add_f32_e32 v128, 1.0, v128
	v_rcp_f32_e32 v141, v128
	v_mul_f32_e32 v128, 0xbfb8aa3b, v130
	v_exp_f32_e32 v128, v128
	v_mul_f32_e32 v133, 0xbfb8aa3b, v133
	v_mul_f32_e32 v135, 0xbfb8aa3b, v135
	v_exp_f32_e32 v132, v132
	v_add_f32_e32 v128, 1.0, v128
	v_rcp_f32_e32 v142, v128
	v_mul_f32_e32 v128, 0xbfb8aa3b, v131
	v_exp_f32_e32 v133, v133
	v_exp_f32_e32 v134, v134
	v_exp_f32_e32 v135, v135
	v_exp_f32_e32 v128, v128
	v_pk_fma_f32 v[120:121], v[120:121], v[170:171], v[64:65] op_sel_hi:[1,0,1]
	v_add_f32_e32 v132, 1.0, v132
	v_add_f32_e32 v133, 1.0, v133
	v_add_f32_e32 v134, 1.0, v134
	v_add_f32_e32 v135, 1.0, v135
	v_add_f32_e32 v128, 1.0, v128
	v_mul_f32_e32 v120, 0xbfb8aa3b, v120
	v_rcp_f32_e32 v132, v132
	v_rcp_f32_e32 v133, v133
	v_rcp_f32_e32 v134, v134
	v_rcp_f32_e32 v135, v135
	v_rcp_f32_e32 v131, v128
	v_exp_f32_e32 v120, v120
	v_cvt_pk_bf16_f32 v128, v132, v133
	v_cvt_pk_bf16_f32 v129, v134, v135
	v_cvt_pk_bf16_f32 v130, v140, v141
	v_cvt_pk_bf16_f32 v131, v142, v131
	v_add_f32_e32 v120, 1.0, v120
	global_store_dwordx4 v[136:137], v[128:131], off offset:256
	v_pk_fma_f32 v[122:123], v[122:123], v[170:171], v[66:67] op_sel_hi:[1,0,1]
	v_pk_fma_f32 v[124:125], v[124:125], v[170:171], v[68:69] op_sel_hi:[1,0,1]
	v_rcp_f32_e32 v130, v120
	v_mul_f32_e32 v120, 0xbfb8aa3b, v121
	v_exp_f32_e32 v120, v120
	v_pk_fma_f32 v[126:127], v[126:127], v[170:171], v[70:71] op_sel_hi:[1,0,1]
	v_mul_f32_e32 v124, 0xbfb8aa3b, v124
	v_mul_f32_e32 v125, 0xbfb8aa3b, v125
	v_add_f32_e32 v120, 1.0, v120
	v_rcp_f32_e32 v131, v120
	v_mul_f32_e32 v120, 0xbfb8aa3b, v122
	v_exp_f32_e32 v120, v120
	v_exp_f32_e32 v124, v124
	v_exp_f32_e32 v125, v125
	v_mul_f32_e32 v126, 0xbfb8aa3b, v126
	v_add_f32_e32 v120, 1.0, v120
	v_mul_f32_e32 v127, 0xbfb8aa3b, v127
	v_rcp_f32_e32 v132, v120
	v_mul_f32_e32 v120, 0xbfb8aa3b, v123
	v_exp_f32_e32 v126, v126
	v_exp_f32_e32 v127, v127
	v_exp_f32_e32 v120, v120
	v_add_f32_e32 v124, 1.0, v124
	v_add_f32_e32 v125, 1.0, v125
	v_pk_fma_f32 v[112:113], v[112:113], v[170:171], v[48:49] op_sel_hi:[1,0,1]
	v_rcp_f32_e32 v124, v124
	v_rcp_f32_e32 v125, v125
	v_add_f32_e32 v126, 1.0, v126
	v_add_f32_e32 v127, 1.0, v127
	v_add_f32_e32 v120, 1.0, v120
	v_mul_f32_e32 v112, 0xbfb8aa3b, v112
	v_rcp_f32_e32 v126, v126
	v_rcp_f32_e32 v127, v127
	v_rcp_f32_e32 v123, v120
	v_exp_f32_e32 v112, v112
	v_lshlrev_b64 v[128:129], 14, v[172:173]
	v_cvt_pk_bf16_f32 v120, v124, v125
	v_lshl_add_u64 v[124:125], s[4:5], 0, v[128:129]
	v_cvt_pk_bf16_f32 v121, v126, v127
	v_cvt_pk_bf16_f32 v122, v130, v131
	v_cvt_pk_bf16_f32 v123, v132, v123
	v_lshl_add_u64 v[124:125], v[124:125], 0, v[138:139]
	v_add_f32_e32 v112, 1.0, v112
	global_store_dwordx4 v[124:125], v[120:123], off
	v_pk_fma_f32 v[114:115], v[114:115], v[170:171], v[50:51] op_sel_hi:[1,0,1]
	v_pk_fma_f32 v[118:119], v[118:119], v[170:171], v[54:55] op_sel_hi:[1,0,1]
	v_rcp_f32_e32 v120, v112
	v_mul_f32_e32 v112, 0xbfb8aa3b, v113
	v_exp_f32_e32 v112, v112
	v_pk_fma_f32 v[116:117], v[116:117], v[170:171], v[52:53] op_sel_hi:[1,0,1]
	v_mul_f32_e32 v118, 0xbfb8aa3b, v118
	v_mul_f32_e32 v116, 0xbfb8aa3b, v116
	v_add_f32_e32 v112, 1.0, v112
	v_rcp_f32_e32 v121, v112
	v_mul_f32_e32 v112, 0xbfb8aa3b, v114
	v_exp_f32_e32 v112, v112
	v_mul_f32_e32 v117, 0xbfb8aa3b, v117
	v_mul_f32_e32 v119, 0xbfb8aa3b, v119
	v_exp_f32_e32 v116, v116
	v_add_f32_e32 v112, 1.0, v112
	v_rcp_f32_e32 v122, v112
	v_mul_f32_e32 v112, 0xbfb8aa3b, v115
	v_exp_f32_e32 v117, v117
	v_exp_f32_e32 v118, v118
	v_exp_f32_e32 v119, v119
	v_exp_f32_e32 v112, v112
	v_pk_fma_f32 v[104:105], v[104:105], v[166:167], v[64:65] op_sel_hi:[1,0,1]
	v_add_f32_e32 v116, 1.0, v116
	v_add_f32_e32 v117, 1.0, v117
	v_add_f32_e32 v118, 1.0, v118
	v_add_f32_e32 v119, 1.0, v119
	v_add_f32_e32 v112, 1.0, v112
	v_mul_f32_e32 v104, 0xbfb8aa3b, v104
	v_rcp_f32_e32 v116, v116
	v_rcp_f32_e32 v117, v117
	v_rcp_f32_e32 v118, v118
	v_rcp_f32_e32 v119, v119
	v_rcp_f32_e32 v115, v112
	v_exp_f32_e32 v104, v104
	v_cvt_pk_bf16_f32 v112, v116, v117
	v_cvt_pk_bf16_f32 v113, v118, v119
	v_cvt_pk_bf16_f32 v114, v120, v121
	v_cvt_pk_bf16_f32 v115, v122, v115
	v_add_f32_e32 v104, 1.0, v104
	global_store_dwordx4 v[124:125], v[112:115], off offset:256
	v_pk_fma_f32 v[106:107], v[106:107], v[166:167], v[66:67] op_sel_hi:[1,0,1]
	v_pk_fma_f32 v[108:109], v[108:109], v[166:167], v[68:69] op_sel_hi:[1,0,1]
	v_rcp_f32_e32 v114, v104
	v_mul_f32_e32 v104, 0xbfb8aa3b, v105
	v_exp_f32_e32 v104, v104
	v_pk_fma_f32 v[110:111], v[110:111], v[166:167], v[70:71] op_sel_hi:[1,0,1]
	v_mul_f32_e32 v108, 0xbfb8aa3b, v108
	v_mul_f32_e32 v109, 0xbfb8aa3b, v109
	v_add_f32_e32 v104, 1.0, v104
	v_rcp_f32_e32 v115, v104
	v_mul_f32_e32 v104, 0xbfb8aa3b, v106
	v_exp_f32_e32 v104, v104
	v_exp_f32_e32 v108, v108
	v_exp_f32_e32 v109, v109
	v_mul_f32_e32 v110, 0xbfb8aa3b, v110
	v_add_f32_e32 v104, 1.0, v104
	v_mul_f32_e32 v111, 0xbfb8aa3b, v111
	v_rcp_f32_e32 v116, v104
	v_mul_f32_e32 v104, 0xbfb8aa3b, v107
	v_exp_f32_e32 v110, v110
	v_exp_f32_e32 v111, v111
	v_exp_f32_e32 v104, v104
	v_add_f32_e32 v108, 1.0, v108
	v_add_f32_e32 v109, 1.0, v109
; __device__ __forceinline__ unsigned pk2(float lo, float hi) { const f32x2 v = {lo, hi}; return __builtin_bit_cast(unsigned, __builtin_convertvector(v, bf16x2_t)); }
; __device__ __forceinline__ float sigmoidf_(float x) { return __builtin_amdgcn_rcpf(1.f + __builtin_amdgcn_exp2f(-x * LOG2E)); }
; #define EPI_LOOP _Pragma("unroll") for (int ai = 0; ai < 2; ++ai) _Pragma("unroll") for (int m = 0; m < 4; ++m) _Pragma("unroll") for (int bj = 0; bj < 2; ++bj)
;     __device__ __forceinline__ void operator()(const f32x4 (&acc)[2][2][4][2], const Unit& un, int wr, int wc, int fr, int fq) const {
;     ...
;         EPI_LOOP { const int row = rbase + ai * 128 + m * 16, col = cw + bj * 128; const float r = rr[ai][m];
;             f32x4 v0 = acc[ai][bj][m][0] * r + s0[bj], v1 = acc[ai][bj][m][1] * r + s1[bj];
;             v0 = (f32x4){sigmoidf_(v0.x), sigmoidf_(v0.y), sigmoidf_(v0.z), sigmoidf_(v0.w)}; v1 = (f32x4){sigmoidf_(v1.x), sigmoidf_(v1.y), sigmoidf_(v1.z), sigmoidf_(v1.w)};
;             u32x4 w; w.x = pk2(v0.x, v0.y); w.y = pk2(v0.z, v0.w); w.z = pk2(v1.x, v1.y); w.w = pk2(v1.z, v1.w);
;             *(u32x4*)(o + (size_t)row * DFF + col) = w; }
	v_pk_fma_f32 v[96:97], v[96:97], v[166:167], v[48:49] op_sel_hi:[1,0,1]
	v_rcp_f32_e32 v108, v108
	v_rcp_f32_e32 v109, v109
	v_add_f32_e32 v110, 1.0, v110
	v_add_f32_e32 v111, 1.0, v111
	v_add_f32_e32 v104, 1.0, v104
	v_mul_f32_e32 v96, 0xbfb8aa3b, v96
	v_rcp_f32_e32 v110, v110
	v_rcp_f32_e32 v111, v111
	v_rcp_f32_e32 v107, v104
	v_exp_f32_e32 v96, v96
	v_lshlrev_b64 v[112:113], 14, v[168:169]
	v_cvt_pk_bf16_f32 v104, v108, v109
	v_lshl_add_u64 v[108:109], s[4:5], 0, v[112:113]
	v_cvt_pk_bf16_f32 v105, v110, v111
	v_cvt_pk_bf16_f32 v106, v114, v115
	v_cvt_pk_bf16_f32 v107, v116, v107
	v_lshl_add_u64 v[108:109], v[108:109], 0, v[138:139]
	v_add_f32_e32 v96, 1.0, v96
	global_store_dwordx4 v[108:109], v[104:107], off
	v_pk_fma_f32 v[98:99], v[98:99], v[166:167], v[50:51] op_sel_hi:[1,0,1]
	v_pk_fma_f32 v[102:103], v[102:103], v[166:167], v[54:55] op_sel_hi:[1,0,1]
	v_rcp_f32_e32 v104, v96
	v_mul_f32_e32 v96, 0xbfb8aa3b, v97
	v_exp_f32_e32 v96, v96
	v_pk_fma_f32 v[100:101], v[100:101], v[166:167], v[52:53] op_sel_hi:[1,0,1]
	v_mul_f32_e32 v102, 0xbfb8aa3b, v102
	v_mul_f32_e32 v100, 0xbfb8aa3b, v100
	v_add_f32_e32 v96, 1.0, v96
	v_rcp_f32_e32 v105, v96
	v_mul_f32_e32 v96, 0xbfb8aa3b, v98
	v_exp_f32_e32 v96, v96
	v_mul_f32_e32 v101, 0xbfb8aa3b, v101
	v_mul_f32_e32 v103, 0xbfb8aa3b, v103
	v_exp_f32_e32 v100, v100
	v_add_f32_e32 v96, 1.0, v96
	v_rcp_f32_e32 v106, v96
	v_mul_f32_e32 v96, 0xbfb8aa3b, v99
	v_exp_f32_e32 v101, v101
	v_exp_f32_e32 v102, v102
	v_exp_f32_e32 v103, v103
	v_exp_f32_e32 v96, v96
	v_pk_fma_f32 v[88:89], v[88:89], v[162:163], v[64:65] op_sel_hi:[1,0,1]
	v_add_f32_e32 v100, 1.0, v100
	v_add_f32_e32 v101, 1.0, v101
	v_add_f32_e32 v102, 1.0, v102
	v_add_f32_e32 v103, 1.0, v103
	v_add_f32_e32 v96, 1.0, v96
	v_mul_f32_e32 v88, 0xbfb8aa3b, v88
	v_rcp_f32_e32 v100, v100
	v_rcp_f32_e32 v101, v101
	v_rcp_f32_e32 v102, v102
	v_rcp_f32_e32 v103, v103
	v_rcp_f32_e32 v99, v96
	v_exp_f32_e32 v88, v88
	v_cvt_pk_bf16_f32 v96, v100, v101
	v_cvt_pk_bf16_f32 v97, v102, v103
	v_cvt_pk_bf16_f32 v98, v104, v105
	v_cvt_pk_bf16_f32 v99, v106, v99
	v_add_f32_e32 v88, 1.0, v88
	global_store_dwordx4 v[108:109], v[96:99], off offset:256
	v_pk_fma_f32 v[90:91], v[90:91], v[162:163], v[66:67] op_sel_hi:[1,0,1]
	v_pk_fma_f32 v[92:93], v[92:93], v[162:163], v[68:69] op_sel_hi:[1,0,1]
	v_rcp_f32_e32 v98, v88
	v_mul_f32_e32 v88, 0xbfb8aa3b, v89
	v_exp_f32_e32 v88, v88
	v_pk_fma_f32 v[94:95], v[94:95], v[162:163], v[70:71] op_sel_hi:[1,0,1]
	v_mul_f32_e32 v92, 0xbfb8aa3b, v92
	v_mul_f32_e32 v93, 0xbfb8aa3b, v93
	v_add_f32_e32 v88, 1.0, v88
	v_rcp_f32_e32 v99, v88
	v_mul_f32_e32 v88, 0xbfb8aa3b, v90
	v_exp_f32_e32 v88, v88
	v_exp_f32_e32 v92, v92
	v_exp_f32_e32 v93, v93
	v_mul_f32_e32 v94, 0xbfb8aa3b, v94
	v_add_f32_e32 v88, 1.0, v88
	v_mul_f32_e32 v95, 0xbfb8aa3b, v95
	v_rcp_f32_e32 v100, v88
	v_mul_f32_e32 v88, 0xbfb8aa3b, v91
	v_exp_f32_e32 v94, v94
	v_exp_f32_e32 v95, v95
	v_exp_f32_e32 v88, v88
	v_add_f32_e32 v92, 1.0, v92
	v_add_f32_e32 v93, 1.0, v93
	v_pk_fma_f32 v[80:81], v[80:81], v[162:163], v[48:49] op_sel_hi:[1,0,1]
	v_rcp_f32_e32 v92, v92
	v_rcp_f32_e32 v93, v93
	v_add_f32_e32 v94, 1.0, v94
	v_add_f32_e32 v95, 1.0, v95
	v_add_f32_e32 v88, 1.0, v88
	v_mul_f32_e32 v80, 0xbfb8aa3b, v80
	v_rcp_f32_e32 v94, v94
	v_rcp_f32_e32 v95, v95
	v_rcp_f32_e32 v91, v88
	v_exp_f32_e32 v80, v80
	v_lshlrev_b64 v[96:97], 14, v[164:165]
	v_cvt_pk_bf16_f32 v88, v92, v93
	v_lshl_add_u64 v[92:93], s[4:5], 0, v[96:97]
	v_cvt_pk_bf16_f32 v89, v94, v95
	v_cvt_pk_bf16_f32 v90, v98, v99
	v_cvt_pk_bf16_f32 v91, v100, v91
	v_lshl_add_u64 v[92:93], v[92:93], 0, v[138:139]
	v_add_f32_e32 v80, 1.0, v80
	global_store_dwordx4 v[92:93], v[88:91], off
	v_pk_fma_f32 v[82:83], v[82:83], v[162:163], v[50:51] op_sel_hi:[1,0,1]
	v_pk_fma_f32 v[86:87], v[86:87], v[162:163], v[54:55] op_sel_hi:[1,0,1]
	v_rcp_f32_e32 v88, v80
	v_mul_f32_e32 v80, 0xbfb8aa3b, v81
	v_exp_f32_e32 v80, v80
	v_pk_fma_f32 v[84:85], v[84:85], v[162:163], v[52:53] op_sel_hi:[1,0,1]
	v_mul_f32_e32 v86, 0xbfb8aa3b, v86
	v_mul_f32_e32 v84, 0xbfb8aa3b, v84
	v_add_f32_e32 v80, 1.0, v80
	v_rcp_f32_e32 v89, v80
	v_mul_f32_e32 v80, 0xbfb8aa3b, v82
	v_exp_f32_e32 v80, v80
	v_mul_f32_e32 v85, 0xbfb8aa3b, v85
	v_mul_f32_e32 v87, 0xbfb8aa3b, v87
	v_exp_f32_e32 v84, v84
	v_add_f32_e32 v80, 1.0, v80
	v_rcp_f32_e32 v90, v80
	v_mul_f32_e32 v80, 0xbfb8aa3b, v83
	v_exp_f32_e32 v85, v85
	v_exp_f32_e32 v86, v86
	v_exp_f32_e32 v87, v87
	v_exp_f32_e32 v80, v80
	v_pk_fma_f32 v[72:73], v[72:73], v[160:161], v[64:65] op_sel_hi:[1,0,1]
	v_add_f32_e32 v84, 1.0, v84
	v_add_f32_e32 v85, 1.0, v85
	v_add_f32_e32 v86, 1.0, v86
	v_add_f32_e32 v87, 1.0, v87
	v_add_f32_e32 v80, 1.0, v80
	v_mul_f32_e32 v72, 0xbfb8aa3b, v72
	v_rcp_f32_e32 v84, v84
	v_rcp_f32_e32 v85, v85
	v_rcp_f32_e32 v86, v86
	v_rcp_f32_e32 v87, v87
	v_rcp_f32_e32 v83, v80
	v_exp_f32_e32 v72, v72
	v_cvt_pk_bf16_f32 v80, v84, v85
	v_cvt_pk_bf16_f32 v81, v86, v87
	v_cvt_pk_bf16_f32 v82, v88, v89
	v_cvt_pk_bf16_f32 v83, v90, v83
	v_add_f32_e32 v72, 1.0, v72
	global_store_dwordx4 v[92:93], v[80:83], off offset:256
	v_pk_fma_f32 v[74:75], v[74:75], v[160:161], v[66:67] op_sel_hi:[1,0,1]
	v_pk_fma_f32 v[78:79], v[78:79], v[160:161], v[70:71] op_sel_hi:[1,0,1]
	v_rcp_f32_e32 v80, v72
	v_mul_f32_e32 v72, 0xbfb8aa3b, v73
	v_exp_f32_e32 v72, v72
	v_pk_fma_f32 v[76:77], v[76:77], v[160:161], v[68:69] op_sel_hi:[1,0,1]
	v_mul_f32_e32 v78, 0xbfb8aa3b, v78
	v_mul_f32_e32 v79, 0xbfb8aa3b, v79
	v_add_f32_e32 v72, 1.0, v72
	v_rcp_f32_e32 v81, v72
	v_mul_f32_e32 v72, 0xbfb8aa3b, v74
	v_exp_f32_e32 v72, v72
	v_mul_f32_e32 v76, 0xbfb8aa3b, v76
	v_mul_f32_e32 v77, 0xbfb8aa3b, v77
	v_exp_f32_e32 v78, v78
; __device__ __forceinline__ unsigned pk2(float lo, float hi) { const f32x2 v = {lo, hi}; return __builtin_bit_cast(unsigned, __builtin_convertvector(v, bf16x2_t)); }
; __device__ __forceinline__ float sigmoidf_(float x) { return __builtin_amdgcn_rcpf(1.f + __builtin_amdgcn_exp2f(-x * LOG2E)); }
; #define EPI_LOOP _Pragma("unroll") for (int ai = 0; ai < 2; ++ai) _Pragma("unroll") for (int m = 0; m < 4; ++m) _Pragma("unroll") for (int bj = 0; bj < 2; ++bj)
;     __device__ __forceinline__ void operator()(const f32x4 (&acc)[2][2][4][2], const Unit& un, int wr, int wc, int fr, int fq) const {
;     ...
;         EPI_LOOP { const int row = rbase + ai * 128 + m * 16, col = cw + bj * 128; const float r = rr[ai][m];
;             f32x4 v0 = acc[ai][bj][m][0] * r + s0[bj], v1 = acc[ai][bj][m][1] * r + s1[bj];
;             v0 = (f32x4){sigmoidf_(v0.x), sigmoidf_(v0.y), sigmoidf_(v0.z), sigmoidf_(v0.w)}; v1 = (f32x4){sigmoidf_(v1.x), sigmoidf_(v1.y), sigmoidf_(v1.z), sigmoidf_(v1.w)};
;             u32x4 w; w.x = pk2(v0.x, v0.y); w.y = pk2(v0.z, v0.w); w.z = pk2(v1.x, v1.y); w.w = pk2(v1.z, v1.w);
;             *(u32x4*)(o + (size_t)row * DFF + col) = w; }
	v_add_f32_e32 v72, 1.0, v72
	v_exp_f32_e32 v79, v79
	v_rcp_f32_e32 v82, v72
	v_mul_f32_e32 v72, 0xbfb8aa3b, v75
	v_exp_f32_e32 v76, v76
	v_exp_f32_e32 v77, v77
	v_exp_f32_e32 v72, v72
	v_add_f32_e32 v78, 1.0, v78
	v_add_f32_e32 v79, 1.0, v79
	v_pk_fma_f32 v[56:57], v[56:57], v[160:161], v[48:49] op_sel_hi:[1,0,1]
	v_add_f32_e32 v76, 1.0, v76
	v_add_f32_e32 v77, 1.0, v77
	v_rcp_f32_e32 v78, v78
	v_rcp_f32_e32 v79, v79
	v_add_f32_e32 v72, 1.0, v72
	v_mul_f32_e32 v56, 0xbfb8aa3b, v56
	v_rcp_f32_e32 v76, v76
	v_rcp_f32_e32 v77, v77
	v_rcp_f32_e32 v75, v72
	v_exp_f32_e32 v56, v56
	v_cvt_pk_bf16_f32 v73, v78, v79
	v_add_co_u32_e32 v78, vcc, s78, v136
	v_cvt_pk_bf16_f32 v72, v76, v77
	v_cvt_pk_bf16_f32 v74, v80, v81
	v_cvt_pk_bf16_f32 v75, v82, v75
	v_addc_co_u32_e32 v79, vcc, 0, v137, vcc
	v_add_f32_e32 v56, 1.0, v56
	global_store_dwordx4 v[78:79], v[72:75], off
	v_pk_fma_f32 v[58:59], v[58:59], v[160:161], v[50:51] op_sel_hi:[1,0,1]
	v_pk_fma_f32 v[62:63], v[62:63], v[160:161], v[54:55] op_sel_hi:[1,0,1]
	v_rcp_f32_e32 v72, v56
	v_mul_f32_e32 v56, 0xbfb8aa3b, v57
	v_exp_f32_e32 v56, v56
	v_pk_fma_f32 v[60:61], v[60:61], v[160:161], v[52:53] op_sel_hi:[1,0,1]
	v_mul_f32_e32 v62, 0xbfb8aa3b, v62
	v_mul_f32_e32 v60, 0xbfb8aa3b, v60
	v_add_f32_e32 v56, 1.0, v56
	v_rcp_f32_e32 v73, v56
	v_mul_f32_e32 v56, 0xbfb8aa3b, v58
	v_exp_f32_e32 v56, v56
	v_mul_f32_e32 v61, 0xbfb8aa3b, v61
	v_mul_f32_e32 v63, 0xbfb8aa3b, v63
	v_exp_f32_e32 v60, v60
	v_add_f32_e32 v56, 1.0, v56
	v_rcp_f32_e32 v74, v56
	v_mul_f32_e32 v56, 0xbfb8aa3b, v59
	v_exp_f32_e32 v61, v61
	v_exp_f32_e32 v62, v62
	v_exp_f32_e32 v63, v63
	v_exp_f32_e32 v56, v56
	v_pk_fma_f32 v[40:41], v[40:41], v[158:159], v[64:65] op_sel_hi:[1,0,1]
	v_add_f32_e32 v60, 1.0, v60
	v_add_f32_e32 v61, 1.0, v61
	v_add_f32_e32 v62, 1.0, v62
	v_add_f32_e32 v63, 1.0, v63
	v_add_f32_e32 v56, 1.0, v56
	v_mul_f32_e32 v40, 0xbfb8aa3b, v40
	v_rcp_f32_e32 v60, v60
	v_rcp_f32_e32 v61, v61
	v_rcp_f32_e32 v62, v62
	v_rcp_f32_e32 v63, v63
	v_rcp_f32_e32 v59, v56
	v_exp_f32_e32 v40, v40
	v_lshl_add_u64 v[76:77], v[136:137], 0, s[56:57]
	v_cvt_pk_bf16_f32 v56, v60, v61
	v_cvt_pk_bf16_f32 v57, v62, v63
	v_cvt_pk_bf16_f32 v58, v72, v73
	v_cvt_pk_bf16_f32 v59, v74, v59
	v_add_f32_e32 v40, 1.0, v40
	global_store_dwordx4 v[76:77], v[56:59], off offset:256
	v_pk_fma_f32 v[42:43], v[42:43], v[158:159], v[66:67] op_sel_hi:[1,0,1]
	v_pk_fma_f32 v[46:47], v[46:47], v[158:159], v[70:71] op_sel_hi:[1,0,1]
	v_rcp_f32_e32 v56, v40
	v_mul_f32_e32 v40, 0xbfb8aa3b, v41
	v_exp_f32_e32 v40, v40
	v_pk_fma_f32 v[44:45], v[44:45], v[158:159], v[68:69] op_sel_hi:[1,0,1]
	v_mul_f32_e32 v46, 0xbfb8aa3b, v46
	v_mul_f32_e32 v47, 0xbfb8aa3b, v47
	v_add_f32_e32 v40, 1.0, v40
	v_rcp_f32_e32 v57, v40
	v_mul_f32_e32 v40, 0xbfb8aa3b, v42
	v_exp_f32_e32 v40, v40
	v_mul_f32_e32 v44, 0xbfb8aa3b, v44
	v_mul_f32_e32 v45, 0xbfb8aa3b, v45
	v_exp_f32_e32 v46, v46
	v_add_f32_e32 v40, 1.0, v40
	v_exp_f32_e32 v47, v47
	v_rcp_f32_e32 v58, v40
	v_mul_f32_e32 v40, 0xbfb8aa3b, v43
	v_exp_f32_e32 v44, v44
	v_exp_f32_e32 v45, v45
	v_exp_f32_e32 v40, v40
	v_add_f32_e32 v46, 1.0, v46
	v_add_f32_e32 v47, 1.0, v47
	v_pk_fma_f32 v[32:33], v[32:33], v[158:159], v[48:49] op_sel_hi:[1,0,1]
	v_add_f32_e32 v44, 1.0, v44
	v_add_f32_e32 v45, 1.0, v45
	v_rcp_f32_e32 v46, v46
	v_rcp_f32_e32 v47, v47
	v_add_f32_e32 v40, 1.0, v40
	v_mul_f32_e32 v32, 0xbfb8aa3b, v32
	v_rcp_f32_e32 v44, v44
	v_rcp_f32_e32 v45, v45
	v_rcp_f32_e32 v43, v40
	v_exp_f32_e32 v32, v32
	v_cvt_pk_bf16_f32 v41, v46, v47
	v_add_co_u32_e32 v46, vcc, s74, v136
	v_cvt_pk_bf16_f32 v40, v44, v45
	v_cvt_pk_bf16_f32 v42, v56, v57
	v_cvt_pk_bf16_f32 v43, v58, v43
	v_addc_co_u32_e32 v47, vcc, 0, v137, vcc
	v_add_f32_e32 v32, 1.0, v32
	global_store_dwordx4 v[46:47], v[40:43], off
	v_pk_fma_f32 v[34:35], v[34:35], v[158:159], v[50:51] op_sel_hi:[1,0,1]
	v_pk_fma_f32 v[38:39], v[38:39], v[158:159], v[54:55] op_sel_hi:[1,0,1]
	v_rcp_f32_e32 v40, v32
	v_mul_f32_e32 v32, 0xbfb8aa3b, v33
	v_exp_f32_e32 v32, v32
	v_pk_fma_f32 v[36:37], v[36:37], v[158:159], v[52:53] op_sel_hi:[1,0,1]
	v_mul_f32_e32 v38, 0xbfb8aa3b, v38
	v_mul_f32_e32 v36, 0xbfb8aa3b, v36
	v_add_f32_e32 v32, 1.0, v32
	v_rcp_f32_e32 v41, v32
	v_mul_f32_e32 v32, 0xbfb8aa3b, v34
	v_exp_f32_e32 v32, v32
	v_mul_f32_e32 v37, 0xbfb8aa3b, v37
	v_mul_f32_e32 v39, 0xbfb8aa3b, v39
	v_exp_f32_e32 v36, v36
	v_add_f32_e32 v32, 1.0, v32
	v_rcp_f32_e32 v42, v32
	v_mul_f32_e32 v32, 0xbfb8aa3b, v35
	v_exp_f32_e32 v37, v37
	v_exp_f32_e32 v38, v38
	v_exp_f32_e32 v39, v39
	v_exp_f32_e32 v32, v32
	v_pk_fma_f32 v[24:25], v[24:25], v[156:157], v[64:65] op_sel_hi:[1,0,1]
	v_add_f32_e32 v36, 1.0, v36
	v_add_f32_e32 v37, 1.0, v37
	v_add_f32_e32 v38, 1.0, v38
	v_add_f32_e32 v39, 1.0, v39
	v_add_f32_e32 v32, 1.0, v32
	v_mul_f32_e32 v24, 0xbfb8aa3b, v24
	v_rcp_f32_e32 v36, v36
	v_rcp_f32_e32 v37, v37
	v_rcp_f32_e32 v38, v38
	v_rcp_f32_e32 v39, v39
	v_rcp_f32_e32 v35, v32
	v_exp_f32_e32 v24, v24
	v_lshl_add_u64 v[44:45], v[136:137], 0, s[20:21]
	v_cvt_pk_bf16_f32 v32, v36, v37
	v_cvt_pk_bf16_f32 v33, v38, v39
	v_cvt_pk_bf16_f32 v34, v40, v41
	v_cvt_pk_bf16_f32 v35, v42, v35
	v_add_f32_e32 v24, 1.0, v24
	global_store_dwordx4 v[44:45], v[32:35], off offset:256
	v_pk_fma_f32 v[26:27], v[26:27], v[156:157], v[66:67] op_sel_hi:[1,0,1]
	v_pk_fma_f32 v[30:31], v[30:31], v[156:157], v[70:71] op_sel_hi:[1,0,1]
	v_rcp_f32_e32 v32, v24
	v_mul_f32_e32 v24, 0xbfb8aa3b, v25
	v_exp_f32_e32 v24, v24
	v_pk_fma_f32 v[28:29], v[28:29], v[156:157], v[68:69] op_sel_hi:[1,0,1]
; #define PG8_BAR __builtin_amdgcn_s_barrier()
; __device__ __forceinline__ unsigned pk2(float lo, float hi) { const f32x2 v = {lo, hi}; return __builtin_bit_cast(unsigned, __builtin_convertvector(v, bf16x2_t)); }
; __device__ __forceinline__ float sigmoidf_(float x) { return __builtin_amdgcn_rcpf(1.f + __builtin_amdgcn_exp2f(-x * LOG2E)); }
; #define EPI_LOOP _Pragma("unroll") for (int ai = 0; ai < 2; ++ai) _Pragma("unroll") for (int m = 0; m < 4; ++m) _Pragma("unroll") for (int bj = 0; bj < 2; ++bj)
; template <class Epi, class Sched, bool ALIGN_EPI = false, bool SP2 = false>
; __device__ __forceinline__ void gemm_phase(PG8_LAS unsigned char* lds, const Gemm g, const Sched& S, const Epi& E, const int tid) {
;     ...
;         if (!has_next) break;
;     ...
;         if constexpr (ALIGN_EPI) { if (wr == 1) PG8_BAR; }
;     __device__ __forceinline__ void operator()(const f32x4 (&acc)[2][2][4][2], const Unit& un, int wr, int wc, int fr, int fq) const {
;     ...
;         EPI_LOOP { const int row = rbase + ai * 128 + m * 16, col = cw + bj * 128; const float r = rr[ai][m];
;             f32x4 v0 = acc[ai][bj][m][0] * r + s0[bj], v1 = acc[ai][bj][m][1] * r + s1[bj];
;             v0 = (f32x4){sigmoidf_(v0.x), sigmoidf_(v0.y), sigmoidf_(v0.z), sigmoidf_(v0.w)}; v1 = (f32x4){sigmoidf_(v1.x), sigmoidf_(v1.y), sigmoidf_(v1.z), sigmoidf_(v1.w)};
;             u32x4 w; w.x = pk2(v0.x, v0.y); w.y = pk2(v0.z, v0.w); w.z = pk2(v1.x, v1.y); w.w = pk2(v1.z, v1.w);
;             *(u32x4*)(o + (size_t)row * DFF + col) = w; }
	v_mul_f32_e32 v30, 0xbfb8aa3b, v30
	v_mul_f32_e32 v31, 0xbfb8aa3b, v31
	v_add_f32_e32 v24, 1.0, v24
	v_rcp_f32_e32 v33, v24
	v_mul_f32_e32 v24, 0xbfb8aa3b, v26
	v_exp_f32_e32 v24, v24
	v_mul_f32_e32 v28, 0xbfb8aa3b, v28
	v_mul_f32_e32 v29, 0xbfb8aa3b, v29
	v_exp_f32_e32 v30, v30
	v_add_f32_e32 v24, 1.0, v24
	v_exp_f32_e32 v31, v31
	v_rcp_f32_e32 v34, v24
	v_mul_f32_e32 v24, 0xbfb8aa3b, v27
	v_exp_f32_e32 v28, v28
	v_exp_f32_e32 v29, v29
	v_exp_f32_e32 v24, v24
	v_add_f32_e32 v30, 1.0, v30
	v_add_f32_e32 v31, 1.0, v31
	v_pk_fma_f32 v[16:17], v[16:17], v[156:157], v[48:49] op_sel_hi:[1,0,1]
	v_add_f32_e32 v28, 1.0, v28
	v_add_f32_e32 v29, 1.0, v29
	v_rcp_f32_e32 v30, v30
	v_rcp_f32_e32 v31, v31
	v_add_f32_e32 v24, 1.0, v24
	v_mul_f32_e32 v16, 0xbfb8aa3b, v16
	v_rcp_f32_e32 v28, v28
	v_rcp_f32_e32 v29, v29
	v_rcp_f32_e32 v27, v24
	v_exp_f32_e32 v16, v16
	v_cvt_pk_bf16_f32 v25, v30, v31
	v_add_co_u32_e32 v30, vcc, s71, v136
	v_cvt_pk_bf16_f32 v24, v28, v29
	v_cvt_pk_bf16_f32 v26, v32, v33
	v_cvt_pk_bf16_f32 v27, v34, v27
	v_addc_co_u32_e32 v31, vcc, 0, v137, vcc
	v_add_f32_e32 v16, 1.0, v16
	global_store_dwordx4 v[30:31], v[24:27], off
	v_pk_fma_f32 v[18:19], v[18:19], v[156:157], v[50:51] op_sel_hi:[1,0,1]
	v_pk_fma_f32 v[22:23], v[22:23], v[156:157], v[54:55] op_sel_hi:[1,0,1]
	v_rcp_f32_e32 v24, v16
	v_mul_f32_e32 v16, 0xbfb8aa3b, v17
	v_exp_f32_e32 v16, v16
	v_pk_fma_f32 v[20:21], v[20:21], v[156:157], v[52:53] op_sel_hi:[1,0,1]
	v_mul_f32_e32 v22, 0xbfb8aa3b, v22
	v_mul_f32_e32 v20, 0xbfb8aa3b, v20
	v_add_f32_e32 v16, 1.0, v16
	v_rcp_f32_e32 v25, v16
	v_mul_f32_e32 v16, 0xbfb8aa3b, v18
	v_exp_f32_e32 v16, v16
	v_mul_f32_e32 v21, 0xbfb8aa3b, v21
	v_mul_f32_e32 v23, 0xbfb8aa3b, v23
	v_exp_f32_e32 v20, v20
	v_add_f32_e32 v16, 1.0, v16
	v_rcp_f32_e32 v26, v16
	v_mul_f32_e32 v16, 0xbfb8aa3b, v19
	v_exp_f32_e32 v21, v21
	v_exp_f32_e32 v22, v22
	v_exp_f32_e32 v23, v23
	v_exp_f32_e32 v16, v16
	v_pk_fma_f32 v[8:9], v[8:9], v[154:155], v[64:65] op_sel_hi:[1,0,1]
	v_add_f32_e32 v20, 1.0, v20
	v_add_f32_e32 v21, 1.0, v21
	v_add_f32_e32 v22, 1.0, v22
	v_add_f32_e32 v23, 1.0, v23
	v_add_f32_e32 v16, 1.0, v16
	v_mul_f32_e32 v8, 0xbfb8aa3b, v8
	v_rcp_f32_e32 v20, v20
	v_rcp_f32_e32 v21, v21
	v_rcp_f32_e32 v22, v22
	v_rcp_f32_e32 v23, v23
	v_rcp_f32_e32 v19, v16
	v_exp_f32_e32 v8, v8
	s_mov_b64 s[20:21], 0x280000
	v_lshl_add_u64 v[28:29], v[136:137], 0, s[20:21]
	v_cvt_pk_bf16_f32 v16, v20, v21
	v_cvt_pk_bf16_f32 v17, v22, v23
	v_cvt_pk_bf16_f32 v18, v24, v25
	v_cvt_pk_bf16_f32 v19, v26, v19
	v_add_f32_e32 v8, 1.0, v8
	global_store_dwordx4 v[28:29], v[16:19], off offset:256
	v_pk_fma_f32 v[10:11], v[10:11], v[154:155], v[66:67] op_sel_hi:[1,0,1]
	v_pk_fma_f32 v[14:15], v[14:15], v[154:155], v[70:71] op_sel_hi:[1,0,1]
	v_rcp_f32_e32 v16, v8
	v_mul_f32_e32 v8, 0xbfb8aa3b, v9
	v_exp_f32_e32 v8, v8
	v_pk_fma_f32 v[12:13], v[12:13], v[154:155], v[68:69] op_sel_hi:[1,0,1]
	v_mul_f32_e32 v14, 0xbfb8aa3b, v14
	v_mul_f32_e32 v15, 0xbfb8aa3b, v15
	v_add_f32_e32 v8, 1.0, v8
	v_rcp_f32_e32 v17, v8
	v_mul_f32_e32 v8, 0xbfb8aa3b, v10
	v_exp_f32_e32 v8, v8
	v_mul_f32_e32 v12, 0xbfb8aa3b, v12
	v_mul_f32_e32 v13, 0xbfb8aa3b, v13
	v_exp_f32_e32 v14, v14
	v_add_f32_e32 v8, 1.0, v8
	v_exp_f32_e32 v15, v15
	v_rcp_f32_e32 v18, v8
	v_mul_f32_e32 v8, 0xbfb8aa3b, v11
	v_exp_f32_e32 v12, v12
	v_exp_f32_e32 v13, v13
	v_exp_f32_e32 v8, v8
	v_add_f32_e32 v14, 1.0, v14
	v_add_f32_e32 v15, 1.0, v15
	v_pk_fma_f32 v[0:1], v[0:1], v[154:155], v[48:49] op_sel_hi:[1,0,1]
	v_add_f32_e32 v12, 1.0, v12
	v_add_f32_e32 v13, 1.0, v13
	v_rcp_f32_e32 v14, v14
	v_rcp_f32_e32 v15, v15
	v_add_f32_e32 v8, 1.0, v8
	v_mul_f32_e32 v0, 0xbfb8aa3b, v0
	v_rcp_f32_e32 v12, v12
	v_rcp_f32_e32 v13, v13
	v_rcp_f32_e32 v11, v8
	v_exp_f32_e32 v0, v0
	v_cvt_pk_bf16_f32 v9, v14, v15
	v_add_co_u32_e32 v14, vcc, s72, v136
	v_cvt_pk_bf16_f32 v8, v12, v13
	v_cvt_pk_bf16_f32 v10, v16, v17
	v_cvt_pk_bf16_f32 v11, v18, v11
	v_addc_co_u32_e32 v15, vcc, 0, v137, vcc
	v_add_f32_e32 v0, 1.0, v0
	global_store_dwordx4 v[14:15], v[8:11], off
	v_pk_fma_f32 v[2:3], v[2:3], v[154:155], v[50:51] op_sel_hi:[1,0,1]
	v_pk_fma_f32 v[6:7], v[6:7], v[154:155], v[54:55] op_sel_hi:[1,0,1]
	v_rcp_f32_e32 v8, v0
	v_mul_f32_e32 v0, 0xbfb8aa3b, v1
	v_exp_f32_e32 v0, v0
	v_pk_fma_f32 v[4:5], v[4:5], v[154:155], v[52:53] op_sel_hi:[1,0,1]
	v_mul_f32_e32 v6, 0xbfb8aa3b, v6
	v_mul_f32_e32 v4, 0xbfb8aa3b, v4
	v_add_f32_e32 v0, 1.0, v0
	v_rcp_f32_e32 v9, v0
	v_mul_f32_e32 v0, 0xbfb8aa3b, v2
	v_exp_f32_e32 v0, v0
	v_mul_f32_e32 v5, 0xbfb8aa3b, v5
	v_mul_f32_e32 v7, 0xbfb8aa3b, v7
	v_exp_f32_e32 v4, v4
	v_add_f32_e32 v0, 1.0, v0
	v_rcp_f32_e32 v10, v0
	v_mul_f32_e32 v0, 0xbfb8aa3b, v3
	v_exp_f32_e32 v5, v5
	v_exp_f32_e32 v6, v6
	v_exp_f32_e32 v7, v7
	v_exp_f32_e32 v0, v0
	v_add_f32_e32 v4, 1.0, v4
	v_add_f32_e32 v5, 1.0, v5
	v_add_f32_e32 v6, 1.0, v6
	v_add_f32_e32 v7, 1.0, v7
	v_add_f32_e32 v0, 1.0, v0
	v_rcp_f32_e32 v4, v4
	v_rcp_f32_e32 v5, v5
	v_rcp_f32_e32 v6, v6
	v_rcp_f32_e32 v7, v7
	v_rcp_f32_e32 v3, v0
	s_mov_b64 s[20:21], 0x2c0000
	v_lshl_add_u64 v[12:13], v[136:137], 0, s[20:21]
	v_cvt_pk_bf16_f32 v0, v4, v5
	v_cvt_pk_bf16_f32 v1, v6, v7
	v_cvt_pk_bf16_f32 v2, v8, v9
	v_cvt_pk_bf16_f32 v3, v10, v3
	s_mov_b64 s[20:21], -1
	s_andn2_b64 vcc, exec, s[12:13]
	global_store_dwordx4 v[12:13], v[0:3], off offset:256
	s_cbranch_vccnz .LBB0_764
	s_andn2_b64 vcc, exec, s[0:1]
	s_cbranch_vccnz .LBB0_763
	s_mov_b32 s100, 1
	s_branch .LBB0_763

;     __host__ __device__ bool next(int i, Unit& u) const { const int L = base + i * Gp + cp; if (L >= end) return false; return T.next(L, u); }
;     __host__ __device__ bool next(int i, Unit& u) const { const int L = i * Gp + cp; if (cp < 0 || L >= n) return false; u.kb = L & 3; u.pn = (L >> 2) % nN; u.pm = pm0 + (L >> 2) / nN; return true; }
;     __host__ __device__ bool next(int i, Unit& u) const { const bool ok = T.next(i >> 2, u); u.kb = i & 3; return ok; }
; #define PG8_STAGE(bufoff, gbase, voff) do { _Pragma("unroll") for (int _i = 0; _i < 2; ++_i) \
;         __builtin_amdgcn_global_load_lds((const unsigned*)((const char*)(gbase) + (voff)[_i]), (PG8_LAS unsigned*)(lds + (bufoff) + ldsw + _i * 8192), 16, 0, 0); } while (0)
; #define PG8_WAIT_V(n) asm volatile("s_waitcnt vmcnt(" #n ")" ::: "memory")
; template <class Epi, class Sched, bool ALIGN_EPI = false, bool SP2 = false>
; __device__ __forceinline__ void gemm_phase(PG8_LAS unsigned char* lds, const Gemm g, const Sched& S, const Epi& E, const int tid) {
;     ...
;         const bool has_next = S.next(ui + 1, nxt);
;         const char* nA = has_next ? (const char*)g.A + (size_t)nxt.pm * tstep + (size_t)nxt.kb * g.sA : cA; const char* nB = has_next ? (const char*)g.Bt + (size_t)nxt.pn * tstep + (size_t)nxt.kb * g.sB : cB;
;         for (int t = 0; t < nt; t += 2) {
;             const bool last = (t == nt - 2);
;             const char* a1 = cA + (size_t)(t + 1) * kstep;
;             const char* a2 = last ? nA : cA + (size_t)(t + 2) * kstep; const char* b2 = last ? nB : cB + (size_t)(t + 2) * kstep;
;             const char* a3 = a2 + kstep; const char* b3 = b2 + kstep;
;             if (last && has_next) S.a_ready(nxt);
;             if constexpr (SP2) {
;             PG8_LDB(B0, 0, 0); PG8_LDB(B1, 0, 1); PG8_SCHED; PG8_LDA(At, 0, 0); PG8_STAGE(PG8_SA(1, 1), a1 + hstep, voffA);
;             PG8_WAIT_V(8); PG8_WAIT_L(0); PG8_BAR; PG8_MMA(0, 0, At, B0); PG8_MMA(0, 1, At, B1); PG8_BAR; PG8_SCHED;
;     ...
; #pragma unroll
;         for (int a = 0; a < 2; ++a)
; #pragma unroll
;             for (int b = 0; b < 2; ++b)
; #pragma unroll
;                 for (int m = 0; m < 4; ++m)
; #pragma unroll
;                     for (int n = 0; n < 2; ++n) acc[a][b][m][n] = (f32x4){0.f, 0.f, 0.f, 0.f};
;         cur = nxt; cA = nA; cB = nB; ++ui;
;         if constexpr (ALIGN_EPI) { if (wr == 1) PG8_BAR; }
.LBB0_1030:
	s_ashr_i32 s13, s12, 31
	s_lshl_b64 s[14:15], s[12:13], 18
	s_add_u32 s14, s30, s14
	s_addc_u32 s15, s31, s15
	s_and_b64 s[16:17], s[0:1], exec
	s_cselect_b32 s13, s15, s23
	s_cselect_b32 s19, s14, s22
	s_ashr_i32 s11, s10, 31
	s_lshl_b64 s[16:17], s[10:11], 18
	s_add_u32 s16, s34, s16
	s_addc_u32 s17, s35, s17
	s_and_b64 s[26:27], s[0:1], exec
	s_cselect_b32 s11, s17, s25
	s_cselect_b32 s47, s16, s24
	s_add_u32 s22, s22, 0x20080
	s_addc_u32 s23, s23, 0
	s_add_u32 s48, s24, 0x100
	v_mov_b32_e32 v0, 0
	s_addc_u32 s49, s25, 0
	s_mov_b32 s50, -2
	v_mov_b32_e32 v1, v0
	v_mov_b32_e32 v2, v0
	v_mov_b32_e32 v3, v0
	v_mov_b32_e32 v4, v0
	v_mov_b32_e32 v5, v0
	v_mov_b32_e32 v6, v0
	v_mov_b32_e32 v7, v0
	v_mov_b32_e32 v16, v0
	v_mov_b32_e32 v17, v0
	v_mov_b32_e32 v18, v0
	v_mov_b32_e32 v19, v0
	v_mov_b32_e32 v20, v0
	v_mov_b32_e32 v21, v0
	v_mov_b32_e32 v22, v0
	v_mov_b32_e32 v23, v0
	v_mov_b32_e32 v32, v0
	v_mov_b32_e32 v33, v0
	v_mov_b32_e32 v34, v0
	v_mov_b32_e32 v35, v0
	v_mov_b32_e32 v36, v0
	v_mov_b32_e32 v37, v0
	v_mov_b32_e32 v38, v0
	v_mov_b32_e32 v39, v0
	v_mov_b32_e32 v48, v0
	v_mov_b32_e32 v49, v0
	v_mov_b32_e32 v50, v0
	v_mov_b32_e32 v51, v0
	v_mov_b32_e32 v52, v0
	v_mov_b32_e32 v53, v0
	v_mov_b32_e32 v54, v0
	v_mov_b32_e32 v55, v0
	v_mov_b32_e32 v8, v0
	v_mov_b32_e32 v9, v0
	v_mov_b32_e32 v10, v0
	v_mov_b32_e32 v11, v0
	v_mov_b32_e32 v12, v0
	v_mov_b32_e32 v13, v0
	v_mov_b32_e32 v14, v0
	v_mov_b32_e32 v15, v0
	v_mov_b32_e32 v24, v0
	v_mov_b32_e32 v25, v0
	v_mov_b32_e32 v26, v0
	v_mov_b32_e32 v27, v0
	v_mov_b32_e32 v28, v0
	v_mov_b32_e32 v29, v0
	v_mov_b32_e32 v30, v0
	v_mov_b32_e32 v31, v0
	v_mov_b32_e32 v40, v0
	v_mov_b32_e32 v41, v0
	v_mov_b32_e32 v42, v0
	v_mov_b32_e32 v43, v0
	v_mov_b32_e32 v44, v0
	v_mov_b32_e32 v45, v0
	v_mov_b32_e32 v46, v0
	v_mov_b32_e32 v47, v0
	v_mov_b32_e32 v56, v0
	v_mov_b32_e32 v57, v0
	v_mov_b32_e32 v58, v0
	v_mov_b32_e32 v59, v0
	v_mov_b32_e32 v60, v0
	v_mov_b32_e32 v61, v0
	v_mov_b32_e32 v62, v0
	v_mov_b32_e32 v63, v0
	v_mov_b32_e32 v64, v0
	v_mov_b32_e32 v65, v0
	v_mov_b32_e32 v66, v0
	v_mov_b32_e32 v67, v0
	v_mov_b32_e32 v68, v0
	v_mov_b32_e32 v69, v0
	v_mov_b32_e32 v70, v0
	v_mov_b32_e32 v71, v0
	v_mov_b32_e32 v80, v0
	v_mov_b32_e32 v81, v0
	v_mov_b32_e32 v82, v0
	v_mov_b32_e32 v83, v0
	v_mov_b32_e32 v84, v0
	v_mov_b32_e32 v85, v0
	v_mov_b32_e32 v86, v0
	v_mov_b32_e32 v87, v0
	v_mov_b32_e32 v96, v0
	v_mov_b32_e32 v97, v0
	v_mov_b32_e32 v98, v0
	v_mov_b32_e32 v99, v0
	v_mov_b32_e32 v100, v0
	v_mov_b32_e32 v101, v0
	v_mov_b32_e32 v102, v0
	v_mov_b32_e32 v103, v0
	v_mov_b32_e32 v112, v0
	v_mov_b32_e32 v113, v0
	v_mov_b32_e32 v114, v0
	v_mov_b32_e32 v115, v0
	v_mov_b32_e32 v116, v0
	v_mov_b32_e32 v117, v0
	v_mov_b32_e32 v118, v0
	v_mov_b32_e32 v119, v0
	v_mov_b32_e32 v72, v0
	v_mov_b32_e32 v73, v0
	v_mov_b32_e32 v74, v0
	v_mov_b32_e32 v75, v0
	v_mov_b32_e32 v76, v0
	v_mov_b32_e32 v77, v0
	v_mov_b32_e32 v78, v0
	v_mov_b32_e32 v79, v0
	v_mov_b32_e32 v88, v0
	v_mov_b32_e32 v89, v0
	v_mov_b32_e32 v90, v0
	v_mov_b32_e32 v91, v0
	v_mov_b32_e32 v92, v0
	v_mov_b32_e32 v93, v0
	v_mov_b32_e32 v94, v0
	v_mov_b32_e32 v95, v0
	v_mov_b32_e32 v104, v0
	v_mov_b32_e32 v105, v0
	v_mov_b32_e32 v106, v0
	v_mov_b32_e32 v107, v0
	v_mov_b32_e32 v108, v0
	v_mov_b32_e32 v109, v0
	v_mov_b32_e32 v110, v0
	v_mov_b32_e32 v111, v0
	v_mov_b32_e32 v120, v0
	v_mov_b32_e32 v121, v0
	v_mov_b32_e32 v122, v0
	v_mov_b32_e32 v123, v0
	v_mov_b32_e32 v124, v0
	v_mov_b32_e32 v125, v0
	v_mov_b32_e32 v126, v0
	v_mov_b32_e32 v127, v0
	s_cmp_eq_u32 s100, 0
	s_cbranch_scc1 .Lmy_nobar_1031
	s_barrier
	s_mov_b32 s100, 0
.Lmy_nobar_1031:
.LBB0_1031:
	s_add_u32 s24, s22, 0xfffe0080
	s_addc_u32 s25, s23, -1
	s_add_i32 s51, 0, 0x10000
	v_add_u32_e32 v138, s51, v141
	ds_read_b128 v[144:147], v138
	ds_read_b128 v[148:151], v138 offset:1024
	ds_read_b128 v[152:155], v138 offset:2048
	ds_read_b128 v[156:159], v138 offset:3072
	v_add_u32_e32 v138, s33, v141
	ds_read_b128 v[160:163], v138
	ds_read_b128 v[164:167], v138 offset:1024
	ds_read_b128 v[168:171], v138 offset:2048
	ds_read_b128 v[172:175], v138 offset:3072
	s_cmp_eq_u32 s50, 4
	s_cselect_b32 s27, s13, s25
	s_cselect_b32 s26, s19, s24
	s_cselect_b32 s25, s11, s49
	s_cselect_b32 s24, s47, s48
	v_lshl_add_u64 v[138:139], s[22:23], 0, v[134:135]
	s_add_i32 m0, s21, 0xc000
	ds_read_b128 v[176:179], v143
	ds_read_b128 v[180:183], v143 offset:1024
	ds_read_b128 v[184:187], v143 offset:2048
	ds_read_b128 v[188:191], v143 offset:3072
	ds_read_b128 v[192:195], v143 offset:4096
	ds_read_b128 v[196:199], v143 offset:5120
	ds_read_b128 v[200:203], v143 offset:6144
	ds_read_b128 v[204:207], v143 offset:7168
	global_load_lds_dwordx4 v[138:139], off
	v_lshl_add_u64 v[138:139], s[22:23], 0, v[136:137]
	s_add_i32 m0, s21, 0xe000
	s_nop 0
	global_load_lds_dwordx4 v[138:139], off
	s_waitcnt vmcnt(8)
	s_waitcnt lgkmcnt(0)
	s_barrier
; #define PG8_STAGE(bufoff, gbase, voff) do { _Pragma("unroll") for (int _i = 0; _i < 2; ++_i) \
;         __builtin_amdgcn_global_load_lds((const unsigned*)((const char*)(gbase) + (voff)[_i]), (PG8_LAS unsigned*)(lds + (bufoff) + ldsw + _i * 8192), 16, 0, 0); } while (0)
; #define PG8_LDA(dst, b, h) do { _Pragma("unroll") for (int m = 0; m < 4; ++m) _Pragma("unroll") for (int k = 0; k < 2; ++k) dst[m][k] = *(const PG8_LAS bf16x8*)(lds + PG8_SA(b, h) + aoff + m * 2048 + k * 1024); } while (0)
; #define PG8_MMA(ai, bj, At, Bt) do { __builtin_amdgcn_s_setprio(1); _Pragma("unroll") for (int m = 0; m < 4; ++m) _Pragma("unroll") for (int n = 0; n < 2; ++n) _Pragma("unroll") for (int k = 0; k < 2; ++k) \
;         acc[ai][bj][m][n] = __builtin_amdgcn_mfma_f32_16x16x32_bf16(Bt[n][k], At[m][k], acc[ai][bj][m][n], 0, 0, 0); __builtin_amdgcn_s_setprio(0); } while (0)
; #define PG8_WAIT_V(n) asm volatile("s_waitcnt vmcnt(" #n ")" ::: "memory")
; #define PG8_WAIT_L(n) asm volatile("s_waitcnt lgkmcnt(" #n ")" ::: "memory")
; #define PG8_BAR __builtin_amdgcn_s_barrier()
; #define PG8_SCHED __builtin_amdgcn_sched_barrier(0)
; template <class Epi, class Sched, bool ALIGN_EPI = false, bool SP2 = false>
; __device__ __forceinline__ void gemm_phase(PG8_LAS unsigned char* lds, const Gemm g, const Sched& S, const Epi& E, const int tid) {
;     ...
;             PG8_WAIT_V(8); PG8_WAIT_L(0); PG8_BAR; PG8_MMA(0, 0, At, B0); PG8_MMA(0, 1, At, B1); PG8_BAR; PG8_SCHED;
;             PG8_LDA(At, 0, 1); PG8_STAGE(PG8_SB(0, 0), b2, voffB); PG8_STAGE(PG8_SB(0, 1), b2 + hstep, voffB); PG8_STAGE(PG8_SA(0, 0), a2, voffA);
;             PG8_WAIT_V(8); PG8_WAIT_L(0); PG8_BAR; PG8_MMA(1, 0, At, B0); PG8_MMA(1, 1, At, B1); PG8_BAR; PG8_SCHED;
	s_setprio 1
	s_waitcnt lgkmcnt(0)
	v_mfma_f32_16x16x32_bf16 v[124:127], v[144:147], v[176:179], v[124:127]
	v_mfma_f32_16x16x32_bf16 v[120:123], v[152:155], v[176:179], v[120:123]
	v_mfma_f32_16x16x32_bf16 v[108:111], v[144:147], v[184:187], v[108:111]
	v_mfma_f32_16x16x32_bf16 v[104:107], v[152:155], v[184:187], v[104:107]
	v_mfma_f32_16x16x32_bf16 v[92:95], v[144:147], v[192:195], v[92:95]
	v_mfma_f32_16x16x32_bf16 v[88:91], v[152:155], v[192:195], v[88:91]
	v_mfma_f32_16x16x32_bf16 v[76:79], v[144:147], v[200:203], v[76:79]
	v_mfma_f32_16x16x32_bf16 v[72:75], v[152:155], v[200:203], v[72:75]
	v_mfma_f32_16x16x32_bf16 v[124:127], v[148:151], v[180:183], v[124:127]
	v_mfma_f32_16x16x32_bf16 v[120:123], v[156:159], v[180:183], v[120:123]
	v_mfma_f32_16x16x32_bf16 v[108:111], v[148:151], v[188:191], v[108:111]
	v_mfma_f32_16x16x32_bf16 v[104:107], v[156:159], v[188:191], v[104:107]
	v_mfma_f32_16x16x32_bf16 v[92:95], v[148:151], v[196:199], v[92:95]
	v_mfma_f32_16x16x32_bf16 v[88:91], v[156:159], v[196:199], v[88:91]
	v_mfma_f32_16x16x32_bf16 v[76:79], v[148:151], v[204:207], v[76:79]
	v_mfma_f32_16x16x32_bf16 v[72:75], v[156:159], v[204:207], v[72:75]
	s_setprio 0
	s_setprio 1
	v_mfma_f32_16x16x32_bf16 v[116:119], v[160:163], v[176:179], v[116:119]
	v_mfma_f32_16x16x32_bf16 v[112:115], v[168:171], v[176:179], v[112:115]
	v_mfma_f32_16x16x32_bf16 v[100:103], v[160:163], v[184:187], v[100:103]
	v_mfma_f32_16x16x32_bf16 v[96:99], v[168:171], v[184:187], v[96:99]
	v_mfma_f32_16x16x32_bf16 v[84:87], v[160:163], v[192:195], v[84:87]
	v_mfma_f32_16x16x32_bf16 v[80:83], v[168:171], v[192:195], v[80:83]
	v_mfma_f32_16x16x32_bf16 v[68:71], v[160:163], v[200:203], v[68:71]
	v_mfma_f32_16x16x32_bf16 v[64:67], v[168:171], v[200:203], v[64:67]
	v_mfma_f32_16x16x32_bf16 v[116:119], v[164:167], v[180:183], v[116:119]
	v_mfma_f32_16x16x32_bf16 v[112:115], v[172:175], v[180:183], v[112:115]
	v_mfma_f32_16x16x32_bf16 v[100:103], v[164:167], v[188:191], v[100:103]
	v_mfma_f32_16x16x32_bf16 v[96:99], v[172:175], v[188:191], v[96:99]
	v_mfma_f32_16x16x32_bf16 v[84:87], v[164:167], v[196:199], v[84:87]
	v_mfma_f32_16x16x32_bf16 v[80:83], v[172:175], v[196:199], v[80:83]
	v_mfma_f32_16x16x32_bf16 v[68:71], v[164:167], v[204:207], v[68:71]
	v_mfma_f32_16x16x32_bf16 v[64:67], v[172:175], v[204:207], v[64:67]
	s_setprio 0
	s_barrier
	s_add_i32 s51, s51, s36
	v_lshl_add_u64 v[138:139], s[24:25], 0, v[208:209]
	s_mov_b32 m0, s51
	ds_read_b128 v[176:179], v143 offset:16384
	ds_read_b128 v[180:183], v143 offset:17408
	ds_read_b128 v[184:187], v143 offset:18432
	ds_read_b128 v[188:191], v143 offset:19456
	ds_read_b128 v[192:195], v143 offset:20480
	ds_read_b128 v[196:199], v143 offset:21504
	ds_read_b128 v[200:203], v143 offset:22528
	ds_read_b128 v[204:207], v143 offset:23552
	global_load_lds_dwordx4 v[138:139], off
	s_add_i32 m0, s51, 0x2000
	s_add_u32 s52, s24, 0x20000
	v_lshl_add_u64 v[210:211], s[24:25], 0, v[128:129]
	s_addc_u32 s53, s25, 0
	s_add_i32 s51, s33, s36
	global_load_lds_dwordx4 v[210:211], off
	v_lshl_add_u64 v[214:215], s[52:53], 0, v[208:209]
	s_mov_b32 m0, s51
	v_lshl_add_u64 v[216:217], s[26:27], 0, v[130:131]
	global_load_lds_dwordx4 v[214:215], off
	v_lshl_add_u64 v[214:215], s[52:53], 0, v[128:129]
	s_add_i32 m0, s51, 0x2000
	s_nop 0
	global_load_lds_dwordx4 v[214:215], off
	v_lshl_add_u64 v[214:215], s[26:27], 0, v[132:133]
	s_mov_b32 m0, s21
	s_nop 0
	global_load_lds_dwordx4 v[214:215], off
	s_mov_b32 m0, s40
	s_nop 0
	global_load_lds_dwordx4 v[216:217], off
	s_waitcnt vmcnt(8)
	s_waitcnt lgkmcnt(0)
	s_barrier
	s_setprio 1
	s_waitcnt lgkmcnt(0)
	v_mfma_f32_16x16x32_bf16 v[60:63], v[144:147], v[176:179], v[60:63]
	v_mfma_f32_16x16x32_bf16 v[56:59], v[152:155], v[176:179], v[56:59]
	v_mfma_f32_16x16x32_bf16 v[44:47], v[144:147], v[184:187], v[44:47]
	v_mfma_f32_16x16x32_bf16 v[40:43], v[152:155], v[184:187], v[40:43]
	v_mfma_f32_16x16x32_bf16 v[28:31], v[144:147], v[192:195], v[28:31]
	v_mfma_f32_16x16x32_bf16 v[24:27], v[152:155], v[192:195], v[24:27]
	v_mfma_f32_16x16x32_bf16 v[12:15], v[144:147], v[200:203], v[12:15]
	v_mfma_f32_16x16x32_bf16 v[8:11], v[152:155], v[200:203], v[8:11]
	v_mfma_f32_16x16x32_bf16 v[60:63], v[148:151], v[180:183], v[60:63]
	v_mfma_f32_16x16x32_bf16 v[56:59], v[156:159], v[180:183], v[56:59]
	v_mfma_f32_16x16x32_bf16 v[44:47], v[148:151], v[188:191], v[44:47]
	v_mfma_f32_16x16x32_bf16 v[40:43], v[156:159], v[188:191], v[40:43]
	v_mfma_f32_16x16x32_bf16 v[28:31], v[148:151], v[196:199], v[28:31]
	v_mfma_f32_16x16x32_bf16 v[24:27], v[156:159], v[196:199], v[24:27]
	v_mfma_f32_16x16x32_bf16 v[12:15], v[148:151], v[204:207], v[12:15]
	v_mfma_f32_16x16x32_bf16 v[8:11], v[156:159], v[204:207], v[8:11]
	s_setprio 0
	s_setprio 1
	v_mfma_f32_16x16x32_bf16 v[52:55], v[160:163], v[176:179], v[52:55]
	v_mfma_f32_16x16x32_bf16 v[48:51], v[168:171], v[176:179], v[48:51]
	v_mfma_f32_16x16x32_bf16 v[36:39], v[160:163], v[184:187], v[36:39]
	v_mfma_f32_16x16x32_bf16 v[32:35], v[168:171], v[184:187], v[32:35]
	v_mfma_f32_16x16x32_bf16 v[20:23], v[160:163], v[192:195], v[20:23]
	v_mfma_f32_16x16x32_bf16 v[16:19], v[168:171], v[192:195], v[16:19]
	v_mfma_f32_16x16x32_bf16 v[4:7], v[160:163], v[200:203], v[4:7]
	v_mfma_f32_16x16x32_bf16 v[0:3], v[168:171], v[200:203], v[0:3]
	v_mfma_f32_16x16x32_bf16 v[52:55], v[164:167], v[180:183], v[52:55]
	v_mfma_f32_16x16x32_bf16 v[48:51], v[172:175], v[180:183], v[48:51]
	v_mfma_f32_16x16x32_bf16 v[36:39], v[164:167], v[188:191], v[36:39]
	v_mfma_f32_16x16x32_bf16 v[32:35], v[172:175], v[188:191], v[32:35]
	v_mfma_f32_16x16x32_bf16 v[20:23], v[164:167], v[196:199], v[20:23]
	v_mfma_f32_16x16x32_bf16 v[16:19], v[172:175], v[196:199], v[16:19]
	v_mfma_f32_16x16x32_bf16 v[4:7], v[164:167], v[204:207], v[4:7]
	v_mfma_f32_16x16x32_bf16 v[0:3], v[172:175], v[204:207], v[0:3]
	s_setprio 0
	s_barrier
; #define PG8_STAGE(bufoff, gbase, voff) do { _Pragma("unroll") for (int _i = 0; _i < 2; ++_i) \
;         __builtin_amdgcn_global_load_lds((const unsigned*)((const char*)(gbase) + (voff)[_i]), (PG8_LAS unsigned*)(lds + (bufoff) + ldsw + _i * 8192), 16, 0, 0); } while (0)
; #define PG8_LDA(dst, b, h) do { _Pragma("unroll") for (int m = 0; m < 4; ++m) _Pragma("unroll") for (int k = 0; k < 2; ++k) dst[m][k] = *(const PG8_LAS bf16x8*)(lds + PG8_SA(b, h) + aoff + m * 2048 + k * 1024); } while (0)
; #define PG8_LDB(dst, b, h) do { _Pragma("unroll") for (int n = 0; n < 2; ++n) _Pragma("unroll") for (int k = 0; k < 2; ++k) dst[n][k] = *(const PG8_LAS bf16x8*)(lds + PG8_SB(b, h) + boff + n * 2048 + k * 1024); } while (0)
; #define PG8_MMA(ai, bj, At, Bt) do { __builtin_amdgcn_s_setprio(1); _Pragma("unroll") for (int m = 0; m < 4; ++m) _Pragma("unroll") for (int n = 0; n < 2; ++n) _Pragma("unroll") for (int k = 0; k < 2; ++k) \
;         acc[ai][bj][m][n] = __builtin_amdgcn_mfma_f32_16x16x32_bf16(Bt[n][k], At[m][k], acc[ai][bj][m][n], 0, 0, 0); __builtin_amdgcn_s_setprio(0); } while (0)
; #define PG8_WAIT_V(n) asm volatile("s_waitcnt vmcnt(" #n ")" ::: "memory")
; #define PG8_WAIT_L(n) asm volatile("s_waitcnt lgkmcnt(" #n ")" ::: "memory")
; #define PG8_BAR __builtin_amdgcn_s_barrier()
; #define PG8_SCHED __builtin_amdgcn_sched_barrier(0)
; template <class Epi, class Sched, bool ALIGN_EPI = false, bool SP2 = false>
; __device__ __forceinline__ void gemm_phase(PG8_LAS unsigned char* lds, const Gemm g, const Sched& S, const Epi& E, const int tid) {
;     ...
;             PG8_LDB(B0, 1, 0); PG8_LDB(B1, 1, 1); PG8_SCHED; PG8_LDA(At, 1, 0); PG8_STAGE(PG8_SA(0, 1), a2 + hstep, voffA);
;             PG8_WAIT_V(8); PG8_WAIT_L(0); PG8_BAR; PG8_MMA(0, 0, At, B0); PG8_MMA(0, 1, At, B1); PG8_BAR; PG8_SCHED;
;             PG8_LDA(At, 1, 1); PG8_STAGE(PG8_SB(1, 0), b3, voffB); PG8_STAGE(PG8_SB(1, 1), b3 + hstep, voffB); PG8_STAGE(PG8_SA(1, 0), a3, voffA);
;             PG8_WAIT_V(8); PG8_WAIT_L(0); PG8_BAR; PG8_MMA(1, 0, At, B0); PG8_MMA(1, 1, At, B1); PG8_BAR; PG8_SCHED;
	s_add_i32 s51, 0, 0x18000
	s_add_i32 s52, 0, 0x1c000
	v_add_u32_e32 v156, s51, v141
	v_add_u32_e32 v172, s52, v141
	ds_read_b128 v[144:147], v156
	ds_read_b128 v[148:151], v156 offset:1024
	ds_read_b128 v[152:155], v156 offset:2048
	ds_read_b128 v[156:159], v156 offset:3072
	ds_read_b128 v[160:163], v172
	ds_read_b128 v[164:167], v172 offset:1024
	ds_read_b128 v[168:171], v172 offset:2048
	ds_read_b128 v[172:175], v172 offset:3072
	s_add_u32 s26, s26, 0x20000
	s_addc_u32 s27, s27, 0
	s_mov_b32 m0, s41
	v_lshl_add_u64 v[218:219], s[26:27], 0, v[132:133]
	ds_read_b128 v[176:179], v143 offset:32768
	ds_read_b128 v[180:183], v143 offset:33792
	ds_read_b128 v[184:187], v143 offset:34816
	ds_read_b128 v[188:191], v143 offset:35840
	ds_read_b128 v[192:195], v143 offset:36864
	ds_read_b128 v[196:199], v143 offset:37888
	ds_read_b128 v[200:203], v143 offset:38912
	ds_read_b128 v[204:207], v143 offset:39936
	global_load_lds_dwordx4 v[218:219], off
	v_lshl_add_u64 v[218:219], s[26:27], 0, v[130:131]
	s_mov_b32 m0, s42
	s_nop 0
	global_load_lds_dwordx4 v[218:219], off
	s_waitcnt vmcnt(8)
	s_waitcnt lgkmcnt(0)
	s_barrier
	s_setprio 1
	s_waitcnt lgkmcnt(0)
	v_mfma_f32_16x16x32_bf16 v[124:127], v[144:147], v[176:179], v[124:127]
	v_mfma_f32_16x16x32_bf16 v[120:123], v[152:155], v[176:179], v[120:123]
	v_mfma_f32_16x16x32_bf16 v[108:111], v[144:147], v[184:187], v[108:111]
	v_mfma_f32_16x16x32_bf16 v[104:107], v[152:155], v[184:187], v[104:107]
	v_mfma_f32_16x16x32_bf16 v[92:95], v[144:147], v[192:195], v[92:95]
	v_mfma_f32_16x16x32_bf16 v[88:91], v[152:155], v[192:195], v[88:91]
	v_mfma_f32_16x16x32_bf16 v[76:79], v[144:147], v[200:203], v[76:79]
	v_mfma_f32_16x16x32_bf16 v[72:75], v[152:155], v[200:203], v[72:75]
	v_mfma_f32_16x16x32_bf16 v[124:127], v[148:151], v[180:183], v[124:127]
	v_mfma_f32_16x16x32_bf16 v[120:123], v[156:159], v[180:183], v[120:123]
	v_mfma_f32_16x16x32_bf16 v[108:111], v[148:151], v[188:191], v[108:111]
	v_mfma_f32_16x16x32_bf16 v[104:107], v[156:159], v[188:191], v[104:107]
	v_mfma_f32_16x16x32_bf16 v[92:95], v[148:151], v[196:199], v[92:95]
	v_mfma_f32_16x16x32_bf16 v[88:91], v[156:159], v[196:199], v[88:91]
	v_mfma_f32_16x16x32_bf16 v[76:79], v[148:151], v[204:207], v[76:79]
	v_mfma_f32_16x16x32_bf16 v[72:75], v[156:159], v[204:207], v[72:75]
	s_setprio 0
	s_setprio 1
	v_mfma_f32_16x16x32_bf16 v[116:119], v[160:163], v[176:179], v[116:119]
	v_mfma_f32_16x16x32_bf16 v[112:115], v[168:171], v[176:179], v[112:115]
	v_mfma_f32_16x16x32_bf16 v[100:103], v[160:163], v[184:187], v[100:103]
	v_mfma_f32_16x16x32_bf16 v[96:99], v[168:171], v[184:187], v[96:99]
	v_mfma_f32_16x16x32_bf16 v[84:87], v[160:163], v[192:195], v[84:87]
	v_mfma_f32_16x16x32_bf16 v[80:83], v[168:171], v[192:195], v[80:83]
	v_mfma_f32_16x16x32_bf16 v[68:71], v[160:163], v[200:203], v[68:71]
	v_mfma_f32_16x16x32_bf16 v[64:67], v[168:171], v[200:203], v[64:67]
	v_mfma_f32_16x16x32_bf16 v[116:119], v[164:167], v[180:183], v[116:119]
	v_mfma_f32_16x16x32_bf16 v[112:115], v[172:175], v[180:183], v[112:115]
	v_mfma_f32_16x16x32_bf16 v[100:103], v[164:167], v[188:191], v[100:103]
	v_mfma_f32_16x16x32_bf16 v[96:99], v[172:175], v[188:191], v[96:99]
	v_mfma_f32_16x16x32_bf16 v[84:87], v[164:167], v[196:199], v[84:87]
	v_mfma_f32_16x16x32_bf16 v[80:83], v[172:175], v[196:199], v[80:83]
	v_mfma_f32_16x16x32_bf16 v[68:71], v[164:167], v[204:207], v[68:71]
	v_mfma_f32_16x16x32_bf16 v[64:67], v[172:175], v[204:207], v[64:67]
	s_setprio 0
	s_barrier
	s_add_i32 s26, s51, s36
	v_lshl_add_u64 v[138:139], v[138:139], 0, s[2:3]
	s_mov_b32 m0, s26
	ds_read_b128 v[176:179], v143 offset:49152
	ds_read_b128 v[180:183], v143 offset:50176
	ds_read_b128 v[184:187], v143 offset:51200
	ds_read_b128 v[188:191], v143 offset:52224
	ds_read_b128 v[192:195], v143 offset:53248
	ds_read_b128 v[196:199], v143 offset:54272
	ds_read_b128 v[200:203], v143 offset:55296
	ds_read_b128 v[204:207], v143 offset:56320
	global_load_lds_dwordx4 v[138:139], off
	s_add_i32 m0, s26, 0x2000
	s_add_u32 s24, s24, 0x20080
	v_lshl_add_u64 v[138:139], v[210:211], 0, s[2:3]
	s_addc_u32 s25, s25, 0
	s_add_i32 s26, s52, s36
	global_load_lds_dwordx4 v[138:139], off
	v_lshl_add_u64 v[138:139], s[24:25], 0, v[208:209]
	s_mov_b32 m0, s26
	s_nop 0
	global_load_lds_dwordx4 v[138:139], off
	v_lshl_add_u64 v[138:139], s[24:25], 0, v[128:129]
	s_add_i32 m0, s26, 0x2000
	s_nop 0
	global_load_lds_dwordx4 v[138:139], off
	v_lshl_add_u64 v[138:139], v[214:215], 0, s[2:3]
	s_mov_b32 m0, s43
	s_nop 0
	global_load_lds_dwordx4 v[138:139], off
	v_lshl_add_u64 v[138:139], v[216:217], 0, s[2:3]
	s_mov_b32 m0, s44
	s_nop 0
	global_load_lds_dwordx4 v[138:139], off
	s_waitcnt vmcnt(8)
	s_waitcnt lgkmcnt(0)
	s_barrier
; #define PG8_MMA(ai, bj, At, Bt) do { __builtin_amdgcn_s_setprio(1); _Pragma("unroll") for (int m = 0; m < 4; ++m) _Pragma("unroll") for (int n = 0; n < 2; ++n) _Pragma("unroll") for (int k = 0; k < 2; ++k) \
;         acc[ai][bj][m][n] = __builtin_amdgcn_mfma_f32_16x16x32_bf16(Bt[n][k], At[m][k], acc[ai][bj][m][n], 0, 0, 0); __builtin_amdgcn_s_setprio(0); } while (0)
; #define PG8_WAIT_V(n) asm volatile("s_waitcnt vmcnt(" #n ")" ::: "memory")
; #define PG8_WAIT_L(n) asm volatile("s_waitcnt lgkmcnt(" #n ")" ::: "memory")
; #define PG8_BAR __builtin_amdgcn_s_barrier()
; #define PG8_SCHED __builtin_amdgcn_sched_barrier(0)
; __device__ __forceinline__ unsigned pk2(float lo, float hi) { const f32x2 v = {lo, hi}; return __builtin_bit_cast(unsigned, __builtin_convertvector(v, bf16x2_t)); }
; __device__ __forceinline__ float sigmoidf_(float x) { return __builtin_amdgcn_rcpf(1.f + __builtin_amdgcn_exp2f(-x * LOG2E)); }
; #define EPI_LOOP _Pragma("unroll") for (int ai = 0; ai < 2; ++ai) _Pragma("unroll") for (int m = 0; m < 4; ++m) _Pragma("unroll") for (int bj = 0; bj < 2; ++bj)
; template <class Epi, class Sched, bool ALIGN_EPI = false, bool SP2 = false>
; __device__ __forceinline__ void gemm_phase(PG8_LAS unsigned char* lds, const Gemm g, const Sched& S, const Epi& E, const int tid) {
;     ...
;             PG8_WAIT_V(8); PG8_WAIT_L(0); PG8_BAR; PG8_MMA(1, 0, At, B0); PG8_MMA(1, 1, At, B1); PG8_BAR; PG8_SCHED;
;     ...
;         if constexpr (ALIGN_EPI) { if (wr == 0) PG8_BAR; }
;     __device__ __forceinline__ void operator()(const f32x4 (&acc)[2][2][4][2], const Unit& un, int wr, int wc, int fr, int fq) const {
;         const int rbase = un.pm * 256 + wr * 64 + fr, cw = un.pn * 256 + wc * 32 + 8 * fq;
;         EPI_LOOP { const int row = rbase + ai * 128 + m * 16; const f32x4 v0 = acc[ai][bj][m][0], v1 = acc[ai][bj][m][1];
;             u32x2 w; w.x = pk2(v0.x * sigmoidf_(v0.y), v0.z * sigmoidf_(v0.w)); w.y = pk2(v1.x * sigmoidf_(v1.y), v1.z * sigmoidf_(v1.w));
;             *(u32x2*)(o + (size_t)row * 512 + ((cw + bj * 128) >> 1)) = w; }
	s_setprio 1
	s_waitcnt lgkmcnt(0)
	v_mfma_f32_16x16x32_bf16 v[60:63], v[144:147], v[176:179], v[60:63]
	v_mfma_f32_16x16x32_bf16 v[56:59], v[152:155], v[176:179], v[56:59]
	v_mfma_f32_16x16x32_bf16 v[44:47], v[144:147], v[184:187], v[44:47]
	v_mfma_f32_16x16x32_bf16 v[40:43], v[152:155], v[184:187], v[40:43]
	v_mfma_f32_16x16x32_bf16 v[28:31], v[144:147], v[192:195], v[28:31]
	v_mfma_f32_16x16x32_bf16 v[24:27], v[152:155], v[192:195], v[24:27]
	v_mfma_f32_16x16x32_bf16 v[12:15], v[144:147], v[200:203], v[12:15]
	v_mfma_f32_16x16x32_bf16 v[8:11], v[152:155], v[200:203], v[8:11]
	v_mfma_f32_16x16x32_bf16 v[60:63], v[148:151], v[180:183], v[60:63]
	v_mfma_f32_16x16x32_bf16 v[56:59], v[156:159], v[180:183], v[56:59]
	v_mfma_f32_16x16x32_bf16 v[44:47], v[148:151], v[188:191], v[44:47]
	v_mfma_f32_16x16x32_bf16 v[40:43], v[156:159], v[188:191], v[40:43]
	v_mfma_f32_16x16x32_bf16 v[28:31], v[148:151], v[196:199], v[28:31]
	v_mfma_f32_16x16x32_bf16 v[24:27], v[156:159], v[196:199], v[24:27]
	v_mfma_f32_16x16x32_bf16 v[12:15], v[148:151], v[204:207], v[12:15]
	v_mfma_f32_16x16x32_bf16 v[8:11], v[156:159], v[204:207], v[8:11]
	s_setprio 0
	s_setprio 1
	v_mfma_f32_16x16x32_bf16 v[52:55], v[160:163], v[176:179], v[52:55]
	v_mfma_f32_16x16x32_bf16 v[48:51], v[168:171], v[176:179], v[48:51]
	v_mfma_f32_16x16x32_bf16 v[36:39], v[160:163], v[184:187], v[36:39]
	v_mfma_f32_16x16x32_bf16 v[32:35], v[168:171], v[184:187], v[32:35]
	v_mfma_f32_16x16x32_bf16 v[20:23], v[160:163], v[192:195], v[20:23]
	v_mfma_f32_16x16x32_bf16 v[16:19], v[168:171], v[192:195], v[16:19]
	v_mfma_f32_16x16x32_bf16 v[4:7], v[160:163], v[200:203], v[4:7]
	v_mfma_f32_16x16x32_bf16 v[0:3], v[168:171], v[200:203], v[0:3]
	v_mfma_f32_16x16x32_bf16 v[52:55], v[164:167], v[180:183], v[52:55]
	v_mfma_f32_16x16x32_bf16 v[48:51], v[172:175], v[180:183], v[48:51]
	v_mfma_f32_16x16x32_bf16 v[36:39], v[164:167], v[188:191], v[36:39]
	v_mfma_f32_16x16x32_bf16 v[32:35], v[172:175], v[188:191], v[32:35]
	v_mfma_f32_16x16x32_bf16 v[20:23], v[164:167], v[196:199], v[20:23]
	v_mfma_f32_16x16x32_bf16 v[16:19], v[172:175], v[196:199], v[16:19]
	v_mfma_f32_16x16x32_bf16 v[4:7], v[164:167], v[204:207], v[4:7]
	v_mfma_f32_16x16x32_bf16 v[0:3], v[172:175], v[204:207], v[0:3]
	s_setprio 0
	s_barrier
	s_add_i32 s50, s50, 2
	s_add_u32 s22, s22, 0x100
	s_addc_u32 s23, s23, 0
	s_add_u32 s48, s48, 0x100
	s_addc_u32 s49, s49, 0
	s_cmp_gt_u32 s50, 5
	s_cbranch_scc0 .LBB0_1031
	s_and_b64 vcc, exec, s[8:9]
	s_cbranch_vccz .LBB0_1034
	s_barrier
.LBB0_1034:
	v_mul_f32_e32 v125, 0xbfb8aa3b, v125
	v_exp_f32_e32 v125, v125
	v_mul_f32_e32 v121, 0xbfb8aa3b, v121
	v_exp_f32_e32 v121, v121
	v_mul_f32_e32 v117, 0xbfb8aa3b, v117
	v_add_f32_e32 v125, 1.0, v125
	v_rcp_f32_e32 v146, v125
	v_mul_f32_e32 v125, 0xbfb8aa3b, v127
	v_exp_f32_e32 v125, v125
	v_add_f32_e32 v121, 1.0, v121
	v_lshl_add_u32 v138, s20, 8, v140
	v_lshl_or_b32 v148, s18, 8, v142
	v_add_f32_e32 v125, 1.0, v125
	v_rcp_f32_e32 v147, v125
	v_mov_b32_e32 v125, v126
	v_rcp_f32_e32 v126, v121
	v_mul_f32_e32 v121, 0xbfb8aa3b, v123
	v_exp_f32_e32 v121, v121
	v_exp_f32_e32 v117, v117
	v_ashrrev_i32_e32 v139, 31, v138
	v_lshlrev_b64 v[144:145], 10, v[138:139]
	v_add_f32_e32 v121, 1.0, v121
	v_rcp_f32_e32 v127, v121
	v_mov_b32_e32 v121, v122
	v_ashrrev_i32_e32 v122, 1, v148
	v_pk_mul_f32 v[124:125], v[124:125], v[146:147]
	v_pk_mul_f32 v[120:121], v[120:121], v[126:127]
	v_ashrrev_i32_e32 v123, 31, v122
	v_cvt_pk_bf16_f32 v124, v124, v125
	v_cvt_pk_bf16_f32 v125, v120, v121
	v_lshl_add_u64 v[120:121], s[6:7], 0, v[144:145]
	v_lshlrev_b64 v[122:123], 1, v[122:123]
	v_lshl_add_u64 v[120:121], v[120:121], 0, v[122:123]
	v_add_f32_e32 v117, 1.0, v117
	global_store_dwordx2 v[120:121], v[124:125], off
	v_rcp_f32_e32 v124, v117
	v_mul_f32_e32 v117, 0xbfb8aa3b, v119
	v_mul_f32_e32 v113, 0xbfb8aa3b, v113
	v_exp_f32_e32 v117, v117
	v_exp_f32_e32 v113, v113
	v_mul_f32_e32 v109, 0xbfb8aa3b, v109
	v_exp_f32_e32 v109, v109
	v_add_f32_e32 v117, 1.0, v117
	v_add_f32_e32 v113, 1.0, v113
	v_rcp_f32_e32 v125, v117
	v_mov_b32_e32 v117, v118
	v_rcp_f32_e32 v118, v113
	v_mul_f32_e32 v113, 0xbfb8aa3b, v115
	v_exp_f32_e32 v113, v113
	v_add_f32_e32 v109, 1.0, v109
	v_mul_f32_e32 v105, 0xbfb8aa3b, v105
	v_exp_f32_e32 v105, v105
	v_add_f32_e32 v113, 1.0, v113
	v_rcp_f32_e32 v119, v113
	v_mov_b32_e32 v113, v114
	v_rcp_f32_e32 v114, v109
	v_mul_f32_e32 v109, 0xbfb8aa3b, v111
	v_exp_f32_e32 v109, v109
	v_add_f32_e32 v105, 1.0, v105
	v_mul_f32_e32 v101, 0xbfb8aa3b, v101
	v_exp_f32_e32 v101, v101
	v_add_f32_e32 v109, 1.0, v109
	v_rcp_f32_e32 v115, v109
	v_mov_b32_e32 v109, v110
	v_rcp_f32_e32 v110, v105
	v_mul_f32_e32 v105, 0xbfb8aa3b, v107
	v_exp_f32_e32 v105, v105
	v_add_f32_e32 v101, 1.0, v101
	v_mul_f32_e32 v97, 0xbfb8aa3b, v97
	v_exp_f32_e32 v97, v97
	v_add_f32_e32 v105, 1.0, v105
	v_rcp_f32_e32 v111, v105
	v_mov_b32_e32 v105, v106
	v_rcp_f32_e32 v106, v101
	v_mul_f32_e32 v101, 0xbfb8aa3b, v103
	v_exp_f32_e32 v101, v101
	v_add_f32_e32 v97, 1.0, v97
	v_mul_f32_e32 v93, 0xbfb8aa3b, v93
	v_exp_f32_e32 v93, v93
	v_add_f32_e32 v101, 1.0, v101
	v_rcp_f32_e32 v107, v101
	v_mov_b32_e32 v101, v102
	v_rcp_f32_e32 v102, v97
	v_mul_f32_e32 v97, 0xbfb8aa3b, v99
	v_exp_f32_e32 v97, v97
	v_add_f32_e32 v93, 1.0, v93
	v_mul_f32_e32 v89, 0xbfb8aa3b, v89
	v_exp_f32_e32 v89, v89
	v_add_f32_e32 v97, 1.0, v97
	v_rcp_f32_e32 v103, v97
	v_mov_b32_e32 v97, v98
	v_rcp_f32_e32 v98, v93
	v_mul_f32_e32 v93, 0xbfb8aa3b, v95
	v_exp_f32_e32 v93, v93
	v_add_f32_e32 v89, 1.0, v89
	v_mul_f32_e32 v85, 0xbfb8aa3b, v85
	v_exp_f32_e32 v85, v85
	v_add_f32_e32 v93, 1.0, v93
	v_rcp_f32_e32 v99, v93
	v_mov_b32_e32 v93, v94
; __device__ __forceinline__ unsigned pk2(float lo, float hi) { const f32x2 v = {lo, hi}; return __builtin_bit_cast(unsigned, __builtin_convertvector(v, bf16x2_t)); }
; __device__ __forceinline__ float sigmoidf_(float x) { return __builtin_amdgcn_rcpf(1.f + __builtin_amdgcn_exp2f(-x * LOG2E)); }
; #define EPI_LOOP _Pragma("unroll") for (int ai = 0; ai < 2; ++ai) _Pragma("unroll") for (int m = 0; m < 4; ++m) _Pragma("unroll") for (int bj = 0; bj < 2; ++bj)
;     __device__ __forceinline__ void operator()(const f32x4 (&acc)[2][2][4][2], const Unit& un, int wr, int wc, int fr, int fq) const {
;         const int rbase = un.pm * 256 + wr * 64 + fr, cw = un.pn * 256 + wc * 32 + 8 * fq;
;         EPI_LOOP { const int row = rbase + ai * 128 + m * 16; const f32x4 v0 = acc[ai][bj][m][0], v1 = acc[ai][bj][m][1];
;             u32x2 w; w.x = pk2(v0.x * sigmoidf_(v0.y), v0.z * sigmoidf_(v0.w)); w.y = pk2(v1.x * sigmoidf_(v1.y), v1.z * sigmoidf_(v1.w));
;             *(u32x2*)(o + (size_t)row * 512 + ((cw + bj * 128) >> 1)) = w; }
	v_rcp_f32_e32 v94, v89
	v_mul_f32_e32 v89, 0xbfb8aa3b, v91
	v_exp_f32_e32 v89, v89
	v_add_f32_e32 v85, 1.0, v85
	v_mul_f32_e32 v81, 0xbfb8aa3b, v81
	v_exp_f32_e32 v81, v81
	v_add_f32_e32 v89, 1.0, v89
	v_rcp_f32_e32 v95, v89
	v_mov_b32_e32 v89, v90
	v_rcp_f32_e32 v90, v85
	v_mul_f32_e32 v85, 0xbfb8aa3b, v87
	v_exp_f32_e32 v85, v85
	v_add_f32_e32 v81, 1.0, v81
	v_mul_f32_e32 v77, 0xbfb8aa3b, v77
	v_exp_f32_e32 v77, v77
	v_add_f32_e32 v85, 1.0, v85
	v_rcp_f32_e32 v91, v85
	v_mov_b32_e32 v85, v86
	v_rcp_f32_e32 v86, v81
	v_mul_f32_e32 v81, 0xbfb8aa3b, v83
	v_exp_f32_e32 v81, v81
	v_add_f32_e32 v77, 1.0, v77
	v_mul_f32_e32 v73, 0xbfb8aa3b, v73
	v_exp_f32_e32 v73, v73
	v_add_f32_e32 v81, 1.0, v81
	v_rcp_f32_e32 v87, v81
	v_mov_b32_e32 v81, v82
	v_rcp_f32_e32 v82, v77
	v_mul_f32_e32 v77, 0xbfb8aa3b, v79
	v_exp_f32_e32 v77, v77
	v_add_f32_e32 v73, 1.0, v73
	v_mul_f32_e32 v69, 0xbfb8aa3b, v69
	v_exp_f32_e32 v69, v69
	v_add_f32_e32 v77, 1.0, v77
	v_rcp_f32_e32 v83, v77
	v_mov_b32_e32 v77, v78
	v_rcp_f32_e32 v78, v73
	v_mul_f32_e32 v73, 0xbfb8aa3b, v75
	v_exp_f32_e32 v73, v73
	v_add_f32_e32 v69, 1.0, v69
	v_mul_f32_e32 v65, 0xbfb8aa3b, v65
	v_exp_f32_e32 v65, v65
	v_add_f32_e32 v73, 1.0, v73
	v_rcp_f32_e32 v79, v73
	v_mov_b32_e32 v73, v74
	v_rcp_f32_e32 v74, v69
	v_mul_f32_e32 v69, 0xbfb8aa3b, v71
	v_exp_f32_e32 v69, v69
	v_add_f32_e32 v65, 1.0, v65
	v_mul_f32_e32 v61, 0xbfb8aa3b, v61
	v_exp_f32_e32 v61, v61
	v_add_f32_e32 v69, 1.0, v69
	v_rcp_f32_e32 v75, v69
	v_mov_b32_e32 v69, v70
	v_rcp_f32_e32 v70, v65
	v_mul_f32_e32 v65, 0xbfb8aa3b, v67
	v_exp_f32_e32 v65, v65
	v_pk_mul_f32 v[68:69], v[68:69], v[74:75]
	v_add_f32_e32 v61, 1.0, v61
	v_cvt_pk_bf16_f32 v68, v68, v69
	v_add_f32_e32 v65, 1.0, v65
	v_rcp_f32_e32 v71, v65
	v_mov_b32_e32 v65, v66
	v_mul_f32_e32 v57, 0xbfb8aa3b, v57
	v_exp_f32_e32 v57, v57
	v_pk_mul_f32 v[64:65], v[64:65], v[70:71]
	v_mul_f32_e32 v53, 0xbfb8aa3b, v53
	v_cvt_pk_bf16_f32 v69, v64, v65
	v_rcp_f32_e32 v64, v61
	v_mul_f32_e32 v61, 0xbfb8aa3b, v63
	v_exp_f32_e32 v61, v61
	v_add_f32_e32 v57, 1.0, v57
	v_exp_f32_e32 v53, v53
	s_mov_b32 s11, 0x20000
	v_add_f32_e32 v61, 1.0, v61
	v_rcp_f32_e32 v65, v61
	v_mov_b32_e32 v61, v62
	v_rcp_f32_e32 v62, v57
	v_mul_f32_e32 v57, 0xbfb8aa3b, v59
	v_exp_f32_e32 v57, v57
	v_pk_mul_f32 v[60:61], v[60:61], v[64:65]
	v_add_f32_e32 v53, 1.0, v53
	v_cvt_pk_bf16_f32 v60, v60, v61
	v_add_f32_e32 v57, 1.0, v57
	v_rcp_f32_e32 v63, v57
	v_mov_b32_e32 v57, v58
	v_add_co_u32_e32 v58, vcc, s11, v120
	v_pk_mul_f32 v[56:57], v[56:57], v[62:63]
	s_nop 0
	v_addc_co_u32_e32 v59, vcc, 0, v121, vcc
	v_cvt_pk_bf16_f32 v61, v56, v57
	global_store_dwordx2 v[58:59], v[60:61], off
	v_rcp_f32_e32 v58, v53
	v_mul_f32_e32 v53, 0xbfb8aa3b, v55
	v_mul_f32_e32 v49, 0xbfb8aa3b, v49
	v_exp_f32_e32 v53, v53
	v_exp_f32_e32 v49, v49
	v_mul_f32_e32 v45, 0xbfb8aa3b, v45
	v_exp_f32_e32 v45, v45
	v_add_f32_e32 v53, 1.0, v53
	v_add_f32_e32 v49, 1.0, v49
	v_rcp_f32_e32 v59, v53
	v_mov_b32_e32 v53, v54
	v_rcp_f32_e32 v54, v49
	v_mul_f32_e32 v49, 0xbfb8aa3b, v51
	v_exp_f32_e32 v49, v49
	v_pk_mul_f32 v[52:53], v[52:53], v[58:59]
	v_add_f32_e32 v45, 1.0, v45
	v_cvt_pk_bf16_f32 v52, v52, v53
	v_add_f32_e32 v49, 1.0, v49
	v_rcp_f32_e32 v55, v49
	v_mov_b32_e32 v49, v50
	v_mul_f32_e32 v41, 0xbfb8aa3b, v41
	v_exp_f32_e32 v41, v41
	v_pk_mul_f32 v[48:49], v[48:49], v[54:55]
	v_mul_f32_e32 v37, 0xbfb8aa3b, v37
	v_cvt_pk_bf16_f32 v53, v48, v49
	v_rcp_f32_e32 v48, v45
	v_mul_f32_e32 v45, 0xbfb8aa3b, v47
	v_exp_f32_e32 v45, v45
	v_add_f32_e32 v41, 1.0, v41
	v_exp_f32_e32 v37, v37
	s_mov_b32 s11, 0x24000
	v_add_f32_e32 v45, 1.0, v45
	v_rcp_f32_e32 v49, v45
	v_mov_b32_e32 v45, v46
	v_rcp_f32_e32 v46, v41
	v_mul_f32_e32 v41, 0xbfb8aa3b, v43
	v_exp_f32_e32 v41, v41
	v_pk_mul_f32 v[44:45], v[44:45], v[48:49]
	v_add_f32_e32 v37, 1.0, v37
	v_cvt_pk_bf16_f32 v44, v44, v45
	v_add_f32_e32 v41, 1.0, v41
	v_rcp_f32_e32 v47, v41
	v_mov_b32_e32 v41, v42
	v_add_co_u32_e32 v42, vcc, s11, v120
	v_pk_mul_f32 v[40:41], v[40:41], v[46:47]
	s_nop 0
	v_addc_co_u32_e32 v43, vcc, 0, v121, vcc
	v_cvt_pk_bf16_f32 v45, v40, v41
	global_store_dwordx2 v[42:43], v[44:45], off
	v_rcp_f32_e32 v42, v37
	v_mul_f32_e32 v37, 0xbfb8aa3b, v39
	v_mul_f32_e32 v33, 0xbfb8aa3b, v33
	v_exp_f32_e32 v37, v37
	v_exp_f32_e32 v33, v33
	v_mul_f32_e32 v29, 0xbfb8aa3b, v29
	v_exp_f32_e32 v29, v29
	v_add_f32_e32 v37, 1.0, v37
	v_add_f32_e32 v33, 1.0, v33
	v_rcp_f32_e32 v43, v37
	v_mov_b32_e32 v37, v38
	v_rcp_f32_e32 v38, v33
	v_mul_f32_e32 v33, 0xbfb8aa3b, v35
	v_exp_f32_e32 v33, v33
	v_pk_mul_f32 v[36:37], v[36:37], v[42:43]
	v_add_f32_e32 v29, 1.0, v29
	v_cvt_pk_bf16_f32 v36, v36, v37
	v_add_f32_e32 v33, 1.0, v33
	v_rcp_f32_e32 v39, v33
	v_mov_b32_e32 v33, v34
	v_mul_f32_e32 v25, 0xbfb8aa3b, v25
	v_exp_f32_e32 v25, v25
	v_pk_mul_f32 v[32:33], v[32:33], v[38:39]
	v_mul_f32_e32 v21, 0xbfb8aa3b, v21
	v_cvt_pk_bf16_f32 v37, v32, v33
	v_rcp_f32_e32 v32, v29
	v_mul_f32_e32 v29, 0xbfb8aa3b, v31
	v_exp_f32_e32 v29, v29
	v_add_f32_e32 v25, 1.0, v25
	v_exp_f32_e32 v21, v21
	s_mov_b32 s11, 0x28000
	v_add_f32_e32 v29, 1.0, v29
	v_rcp_f32_e32 v33, v29
	v_mov_b32_e32 v29, v30
; #define PG8_BAR __builtin_amdgcn_s_barrier()
; __device__ __forceinline__ unsigned pk2(float lo, float hi) { const f32x2 v = {lo, hi}; return __builtin_bit_cast(unsigned, __builtin_convertvector(v, bf16x2_t)); }
; __device__ __forceinline__ float sigmoidf_(float x) { return __builtin_amdgcn_rcpf(1.f + __builtin_amdgcn_exp2f(-x * LOG2E)); }
; #define EPI_LOOP _Pragma("unroll") for (int ai = 0; ai < 2; ++ai) _Pragma("unroll") for (int m = 0; m < 4; ++m) _Pragma("unroll") for (int bj = 0; bj < 2; ++bj)
; template <class Epi, class Sched, bool ALIGN_EPI = false, bool SP2 = false>
; __device__ __forceinline__ void gemm_phase(PG8_LAS unsigned char* lds, const Gemm g, const Sched& S, const Epi& E, const int tid) {
;     ...
;         if (!has_next) break;
;     ...
;         if constexpr (ALIGN_EPI) { if (wr == 1) PG8_BAR; }
;     __device__ __forceinline__ void operator()(const f32x4 (&acc)[2][2][4][2], const Unit& un, int wr, int wc, int fr, int fq) const {
;         const int rbase = un.pm * 256 + wr * 64 + fr, cw = un.pn * 256 + wc * 32 + 8 * fq;
;         EPI_LOOP { const int row = rbase + ai * 128 + m * 16; const f32x4 v0 = acc[ai][bj][m][0], v1 = acc[ai][bj][m][1];
;             u32x2 w; w.x = pk2(v0.x * sigmoidf_(v0.y), v0.z * sigmoidf_(v0.w)); w.y = pk2(v1.x * sigmoidf_(v1.y), v1.z * sigmoidf_(v1.w));
;             *(u32x2*)(o + (size_t)row * 512 + ((cw + bj * 128) >> 1)) = w; }
	v_rcp_f32_e32 v30, v25
	v_mul_f32_e32 v25, 0xbfb8aa3b, v27
	v_exp_f32_e32 v25, v25
	v_pk_mul_f32 v[28:29], v[28:29], v[32:33]
	v_add_f32_e32 v21, 1.0, v21
	v_cvt_pk_bf16_f32 v28, v28, v29
	v_add_f32_e32 v25, 1.0, v25
	v_rcp_f32_e32 v31, v25
	v_mov_b32_e32 v25, v26
	v_add_co_u32_e32 v26, vcc, s11, v120
	v_pk_mul_f32 v[24:25], v[24:25], v[30:31]
	s_nop 0
	v_addc_co_u32_e32 v27, vcc, 0, v121, vcc
	v_cvt_pk_bf16_f32 v29, v24, v25
	global_store_dwordx2 v[26:27], v[28:29], off
	v_rcp_f32_e32 v26, v21
	v_mul_f32_e32 v21, 0xbfb8aa3b, v23
	v_mul_f32_e32 v17, 0xbfb8aa3b, v17
	v_exp_f32_e32 v21, v21
	v_exp_f32_e32 v17, v17
	v_mul_f32_e32 v13, 0xbfb8aa3b, v13
	v_exp_f32_e32 v13, v13
	v_add_f32_e32 v21, 1.0, v21
	v_add_f32_e32 v17, 1.0, v17
	v_rcp_f32_e32 v27, v21
	v_mov_b32_e32 v21, v22
	v_rcp_f32_e32 v22, v17
	v_mul_f32_e32 v17, 0xbfb8aa3b, v19
	v_exp_f32_e32 v17, v17
	v_pk_mul_f32 v[20:21], v[20:21], v[26:27]
	v_add_f32_e32 v13, 1.0, v13
	v_cvt_pk_bf16_f32 v20, v20, v21
	v_add_f32_e32 v17, 1.0, v17
	v_rcp_f32_e32 v23, v17
	v_mov_b32_e32 v17, v18
	v_mul_f32_e32 v9, 0xbfb8aa3b, v9
	v_exp_f32_e32 v9, v9
	v_pk_mul_f32 v[16:17], v[16:17], v[22:23]
	v_mul_f32_e32 v5, 0xbfb8aa3b, v5
	v_cvt_pk_bf16_f32 v21, v16, v17
	v_rcp_f32_e32 v16, v13
	v_mul_f32_e32 v13, 0xbfb8aa3b, v15
	v_exp_f32_e32 v13, v13
	v_add_f32_e32 v9, 1.0, v9
	v_exp_f32_e32 v5, v5
	s_mov_b32 s11, 0x2c000
	v_add_f32_e32 v13, 1.0, v13
	v_rcp_f32_e32 v17, v13
	v_mov_b32_e32 v13, v14
	v_rcp_f32_e32 v14, v9
	v_mul_f32_e32 v9, 0xbfb8aa3b, v11
	v_exp_f32_e32 v9, v9
	v_pk_mul_f32 v[12:13], v[12:13], v[16:17]
	v_add_f32_e32 v5, 1.0, v5
	v_cvt_pk_bf16_f32 v12, v12, v13
	v_add_f32_e32 v9, 1.0, v9
	v_rcp_f32_e32 v15, v9
	v_mov_b32_e32 v9, v10
	v_add_co_u32_e32 v10, vcc, s11, v120
	v_pk_mul_f32 v[8:9], v[8:9], v[14:15]
	s_nop 0
	v_addc_co_u32_e32 v11, vcc, 0, v121, vcc
	v_cvt_pk_bf16_f32 v13, v8, v9
	global_store_dwordx2 v[10:11], v[12:13], off
	v_rcp_f32_e32 v10, v5
	v_mul_f32_e32 v5, 0xbfb8aa3b, v7
	v_mul_f32_e32 v1, 0xbfb8aa3b, v1
	v_exp_f32_e32 v5, v5
	v_exp_f32_e32 v1, v1
	v_pk_mul_f32 v[116:117], v[116:117], v[124:125]
	v_pk_mul_f32 v[112:113], v[112:113], v[118:119]
	v_add_f32_e32 v5, 1.0, v5
	v_add_f32_e32 v1, 1.0, v1
	v_rcp_f32_e32 v11, v5
	v_mov_b32_e32 v5, v6
	v_rcp_f32_e32 v6, v1
	v_mul_f32_e32 v1, 0xbfb8aa3b, v3
	v_exp_f32_e32 v1, v1
	v_pk_mul_f32 v[100:101], v[100:101], v[106:107]
	v_pk_mul_f32 v[96:97], v[96:97], v[102:103]
	v_pk_mul_f32 v[84:85], v[84:85], v[90:91]
	v_add_f32_e32 v1, 1.0, v1
	v_pk_mul_f32 v[80:81], v[80:81], v[86:87]
	v_rcp_f32_e32 v7, v1
	v_cvt_pk_bf16_f32 v116, v116, v117
	v_cvt_pk_bf16_f32 v117, v112, v113
	v_or_b32_e32 v112, 16, v138
	v_cvt_pk_bf16_f32 v100, v100, v101
	v_cvt_pk_bf16_f32 v101, v96, v97
	v_or_b32_e32 v96, 32, v138
	v_cvt_pk_bf16_f32 v84, v84, v85
	v_cvt_pk_bf16_f32 v85, v80, v81
	v_or_b32_e32 v80, 48, v138
	s_mov_b64 s[18:19], 0x20000
	v_ashrrev_i32_e32 v113, 31, v112
	v_ashrrev_i32_e32 v97, 31, v96
	v_ashrrev_i32_e32 v81, 31, v80
	v_lshl_add_u64 v[56:57], v[120:121], 0, s[18:19]
	s_mov_b64 s[18:19], 0x24000
	v_lshlrev_b64 v[112:113], 10, v[112:113]
	v_pk_mul_f32 v[108:109], v[108:109], v[114:115]
	v_pk_mul_f32 v[104:105], v[104:105], v[110:111]
	v_lshlrev_b64 v[96:97], 10, v[96:97]
	v_pk_mul_f32 v[92:93], v[92:93], v[98:99]
	v_pk_mul_f32 v[88:89], v[88:89], v[94:95]
	v_lshlrev_b64 v[80:81], 10, v[80:81]
	v_pk_mul_f32 v[76:77], v[76:77], v[82:83]
	v_pk_mul_f32 v[72:73], v[72:73], v[78:79]
	v_lshl_add_u64 v[40:41], v[120:121], 0, s[18:19]
	s_mov_b64 s[18:19], 0x28000
	v_mov_b32_e32 v1, v2
	v_cvt_pk_bf16_f32 v108, v108, v109
	v_cvt_pk_bf16_f32 v109, v104, v105
	v_lshl_add_u64 v[104:105], s[6:7], 0, v[112:113]
	v_cvt_pk_bf16_f32 v92, v92, v93
	v_cvt_pk_bf16_f32 v93, v88, v89
	v_lshl_add_u64 v[88:89], s[6:7], 0, v[96:97]
	v_cvt_pk_bf16_f32 v76, v76, v77
	v_cvt_pk_bf16_f32 v77, v72, v73
	v_lshl_add_u64 v[72:73], s[6:7], 0, v[80:81]
	v_lshl_add_u64 v[24:25], v[120:121], 0, s[18:19]
	s_mov_b64 s[18:19], 0x2c000
	v_pk_mul_f32 v[4:5], v[4:5], v[10:11]
	v_pk_mul_f32 v[0:1], v[0:1], v[6:7]
	v_lshl_add_u64 v[104:105], v[104:105], 0, v[122:123]
	v_lshl_add_u64 v[88:89], v[88:89], 0, v[122:123]
	v_lshl_add_u64 v[72:73], v[72:73], 0, v[122:123]
	v_lshl_add_u64 v[8:9], v[120:121], 0, s[18:19]
	v_cvt_pk_bf16_f32 v4, v4, v5
	v_cvt_pk_bf16_f32 v5, v0, v1
	s_mov_b64 s[18:19], -1
	s_andn2_b64 vcc, exec, s[0:1]
	global_store_dwordx2 v[120:121], v[116:117], off offset:128
	global_store_dwordx2 v[104:105], v[108:109], off
	global_store_dwordx2 v[104:105], v[100:101], off offset:128
	global_store_dwordx2 v[88:89], v[92:93], off
	global_store_dwordx2 v[88:89], v[84:85], off offset:128
	global_store_dwordx2 v[72:73], v[76:77], off
	global_store_dwordx2 v[72:73], v[68:69], off offset:128
	global_store_dwordx2 v[56:57], v[52:53], off offset:128
	global_store_dwordx2 v[40:41], v[36:37], off offset:128
	global_store_dwordx2 v[24:25], v[20:21], off offset:128
	global_store_dwordx2 v[8:9], v[4:5], off offset:128
	s_cbranch_vccnz .LBB0_1027
	s_andn2_b64 vcc, exec, s[4:5]
	s_cbranch_vccnz .LBB0_1026
	s_mov_b32 s100, 1
	s_branch .LBB0_1026

;     __host__ __device__ bool next(int i, Unit& u) const { const int L = base + i * Gp + cp; if (L >= end) return false; return T.next(L, u); }
;     __host__ __device__ bool next(int i, Unit& u) const { const int L = i * Gp + cp; if (cp < 0 || L >= n) return false; u.kb = L & 3; u.pn = (L >> 2) % nN; u.pm = pm0 + (L >> 2) / nN; return true; }
;     __host__ __device__ bool next(int i, Unit& u) const { const bool ok = T.next(i >> 2, u); u.kb = i & 3; return ok; }
; #define PG8_STAGE(bufoff, gbase, voff) do { _Pragma("unroll") for (int _i = 0; _i < 2; ++_i) \
;         __builtin_amdgcn_global_load_lds((const unsigned*)((const char*)(gbase) + (voff)[_i]), (PG8_LAS unsigned*)(lds + (bufoff) + ldsw + _i * 8192), 16, 0, 0); } while (0)
; #define PG8_WAIT_V(n) asm volatile("s_waitcnt vmcnt(" #n ")" ::: "memory")
; template <class Epi, class Sched, bool ALIGN_EPI = false, bool SP2 = false>
; __device__ __forceinline__ void gemm_phase(PG8_LAS unsigned char* lds, const Gemm g, const Sched& S, const Epi& E, const int tid) {
;     ...
;         const bool has_next = S.next(ui + 1, nxt);
;         const char* nA = has_next ? (const char*)g.A + (size_t)nxt.pm * tstep + (size_t)nxt.kb * g.sA : cA; const char* nB = has_next ? (const char*)g.Bt + (size_t)nxt.pn * tstep + (size_t)nxt.kb * g.sB : cB;
;         for (int t = 0; t < nt; t += 2) {
;             const bool last = (t == nt - 2);
;             const char* a1 = cA + (size_t)(t + 1) * kstep;
;             const char* a2 = last ? nA : cA + (size_t)(t + 2) * kstep; const char* b2 = last ? nB : cB + (size_t)(t + 2) * kstep;
;             const char* a3 = a2 + kstep; const char* b3 = b2 + kstep;
;             if (last && has_next) S.a_ready(nxt);
;             if constexpr (SP2) {
;             PG8_LDB(B0, 0, 0); PG8_LDB(B1, 0, 1); PG8_SCHED; PG8_LDA(At, 0, 0); PG8_STAGE(PG8_SA(1, 1), a1 + hstep, voffA);
;             PG8_WAIT_V(8); PG8_WAIT_L(0); PG8_BAR; PG8_MMA(0, 0, At, B0); PG8_MMA(0, 1, At, B1); PG8_BAR; PG8_SCHED;
;     ...
; #pragma unroll
;         for (int a = 0; a < 2; ++a)
; #pragma unroll
;             for (int b = 0; b < 2; ++b)
; #pragma unroll
;                 for (int m = 0; m < 4; ++m)
; #pragma unroll
;                     for (int n = 0; n < 2; ++n) acc[a][b][m][n] = (f32x4){0.f, 0.f, 0.f, 0.f};
;         cur = nxt; cA = nA; cB = nB; ++ui;
;         if constexpr (ALIGN_EPI) { if (wr == 1) PG8_BAR; }
.LBB0_1046:
	s_ashr_i32 s15, s14, 31
	s_lshl_b64 s[16:17], s[14:15], 20
	s_add_u32 s16, s34, s16
	s_addc_u32 s17, s35, s17
	s_and_b64 s[18:19], s[12:13], exec
	s_cselect_b32 s15, s17, s25
	s_cselect_b32 s21, s16, s24
	s_ashr_i32 s11, s10, 31
	s_lshl_b64 s[18:19], s[10:11], 20
	s_add_u32 s18, s36, s18
	s_addc_u32 s19, s37, s19
	s_and_b64 s[28:29], s[12:13], exec
	s_cselect_b32 s11, s19, s27
	s_cselect_b32 s47, s18, s26
	s_add_u32 s24, s24, 0x80080
	s_addc_u32 s25, s25, 0
	s_add_u32 s48, s26, 0x100
	v_mov_b32_e32 v0, 0
	s_addc_u32 s49, s27, 0
	s_mov_b32 s50, -2
	v_mov_b32_e32 v1, v0
	v_mov_b32_e32 v2, v0
	v_mov_b32_e32 v3, v0
	v_mov_b32_e32 v4, v0
	v_mov_b32_e32 v5, v0
	v_mov_b32_e32 v6, v0
	v_mov_b32_e32 v7, v0
	v_mov_b32_e32 v16, v0
	v_mov_b32_e32 v17, v0
	v_mov_b32_e32 v18, v0
	v_mov_b32_e32 v19, v0
	v_mov_b32_e32 v20, v0
	v_mov_b32_e32 v21, v0
	v_mov_b32_e32 v22, v0
	v_mov_b32_e32 v23, v0
	v_mov_b32_e32 v32, v0
	v_mov_b32_e32 v33, v0
	v_mov_b32_e32 v34, v0
	v_mov_b32_e32 v35, v0
	v_mov_b32_e32 v36, v0
	v_mov_b32_e32 v37, v0
	v_mov_b32_e32 v38, v0
	v_mov_b32_e32 v39, v0
	v_mov_b32_e32 v56, v0
	v_mov_b32_e32 v57, v0
	v_mov_b32_e32 v58, v0
	v_mov_b32_e32 v59, v0
	v_mov_b32_e32 v60, v0
	v_mov_b32_e32 v61, v0
	v_mov_b32_e32 v62, v0
	v_mov_b32_e32 v63, v0
	v_mov_b32_e32 v8, v0
	v_mov_b32_e32 v9, v0
	v_mov_b32_e32 v10, v0
	v_mov_b32_e32 v11, v0
	v_mov_b32_e32 v12, v0
	v_mov_b32_e32 v13, v0
	v_mov_b32_e32 v14, v0
	v_mov_b32_e32 v15, v0
	v_mov_b32_e32 v24, v0
	v_mov_b32_e32 v25, v0
	v_mov_b32_e32 v26, v0
	v_mov_b32_e32 v27, v0
	v_mov_b32_e32 v28, v0
	v_mov_b32_e32 v29, v0
	v_mov_b32_e32 v30, v0
	v_mov_b32_e32 v31, v0
	v_mov_b32_e32 v40, v0
	v_mov_b32_e32 v41, v0
	v_mov_b32_e32 v42, v0
	v_mov_b32_e32 v43, v0
	v_mov_b32_e32 v44, v0
	v_mov_b32_e32 v45, v0
	v_mov_b32_e32 v46, v0
	v_mov_b32_e32 v47, v0
	v_mov_b32_e32 v72, v0
	v_mov_b32_e32 v73, v0
	v_mov_b32_e32 v74, v0
	v_mov_b32_e32 v75, v0
	v_mov_b32_e32 v76, v0
	v_mov_b32_e32 v77, v0
	v_mov_b32_e32 v78, v0
	v_mov_b32_e32 v79, v0
	v_mov_b32_e32 v80, v0
	v_mov_b32_e32 v81, v0
	v_mov_b32_e32 v82, v0
	v_mov_b32_e32 v83, v0
	v_mov_b32_e32 v84, v0
	v_mov_b32_e32 v85, v0
	v_mov_b32_e32 v86, v0
	v_mov_b32_e32 v87, v0
	v_mov_b32_e32 v96, v0
	v_mov_b32_e32 v97, v0
	v_mov_b32_e32 v98, v0
	v_mov_b32_e32 v99, v0
	v_mov_b32_e32 v100, v0
	v_mov_b32_e32 v101, v0
	v_mov_b32_e32 v102, v0
	v_mov_b32_e32 v103, v0
	v_mov_b32_e32 v112, v0
	v_mov_b32_e32 v113, v0
	v_mov_b32_e32 v114, v0
	v_mov_b32_e32 v115, v0
	v_mov_b32_e32 v116, v0
	v_mov_b32_e32 v117, v0
	v_mov_b32_e32 v118, v0
	v_mov_b32_e32 v119, v0
	v_mov_b32_e32 v128, v0
	v_mov_b32_e32 v129, v0
	v_mov_b32_e32 v130, v0
	v_mov_b32_e32 v131, v0
	v_mov_b32_e32 v132, v0
	v_mov_b32_e32 v133, v0
	v_mov_b32_e32 v134, v0
	v_mov_b32_e32 v135, v0
	v_mov_b32_e32 v88, v0
	v_mov_b32_e32 v89, v0
	v_mov_b32_e32 v90, v0
	v_mov_b32_e32 v91, v0
	v_mov_b32_e32 v92, v0
	v_mov_b32_e32 v93, v0
	v_mov_b32_e32 v94, v0
	v_mov_b32_e32 v95, v0
	v_mov_b32_e32 v104, v0
	v_mov_b32_e32 v105, v0
	v_mov_b32_e32 v106, v0
	v_mov_b32_e32 v107, v0
	v_mov_b32_e32 v108, v0
	v_mov_b32_e32 v109, v0
	v_mov_b32_e32 v110, v0
	v_mov_b32_e32 v111, v0
	v_mov_b32_e32 v120, v0
	v_mov_b32_e32 v121, v0
	v_mov_b32_e32 v122, v0
	v_mov_b32_e32 v123, v0
	v_mov_b32_e32 v124, v0
	v_mov_b32_e32 v125, v0
	v_mov_b32_e32 v126, v0
	v_mov_b32_e32 v127, v0
	v_mov_b32_e32 v136, v0
	v_mov_b32_e32 v137, v0
	v_mov_b32_e32 v138, v0
	v_mov_b32_e32 v139, v0
	v_mov_b32_e32 v140, v0
	v_mov_b32_e32 v141, v0
	v_mov_b32_e32 v142, v0
	v_mov_b32_e32 v143, v0
	s_cmp_eq_u32 s100, 0
	s_cbranch_scc1 .Lmy_nobar_1047
	s_barrier
	s_mov_b32 s100, 0
.Lmy_nobar_1047:
.LBB0_1047:
	s_add_u32 s26, s24, 0xfff80080
	s_addc_u32 s27, s25, -1
	s_add_i32 s51, 0, 0x10000
	v_add_u32_e32 v68, s51, v157
	v_add_u32_e32 v154, s33, v157
	ds_read_b128 v[48:51], v68
	ds_read_b128 v[52:55], v68 offset:1024
	ds_read_b128 v[64:67], v68 offset:2048
	ds_read_b128 v[68:71], v68 offset:3072
	ds_read_b128 v[162:165], v154
	ds_read_b128 v[166:169], v154 offset:1024
	ds_read_b128 v[170:173], v154 offset:2048
	ds_read_b128 v[174:177], v154 offset:3072
	s_cmp_eq_u32 s50, 28
	s_cselect_b32 s29, s15, s27
	s_cselect_b32 s28, s21, s26
	s_cselect_b32 s27, s11, s49
	s_cselect_b32 s26, s47, s48
	v_lshl_add_u64 v[206:207], s[24:25], 0, v[150:151]
	s_add_i32 m0, s23, 0xc000
	ds_read_b128 v[178:181], v161
	ds_read_b128 v[182:185], v161 offset:1024
	ds_read_b128 v[186:189], v161 offset:2048
	ds_read_b128 v[190:193], v161 offset:3072
	ds_read_b128 v[194:197], v161 offset:4096
	ds_read_b128 v[198:201], v161 offset:5120
	ds_read_b128 v[202:205], v161 offset:6144
	ds_read_b128 v[214:217], v161 offset:7168
	global_load_lds_dwordx4 v[206:207], off
	v_lshl_add_u64 v[206:207], s[24:25], 0, v[152:153]
	s_add_i32 m0, s23, 0xe000
	s_nop 0
	global_load_lds_dwordx4 v[206:207], off
	s_waitcnt vmcnt(8)
	s_waitcnt lgkmcnt(0)
	s_barrier
; #define PG8_STAGE(bufoff, gbase, voff) do { _Pragma("unroll") for (int _i = 0; _i < 2; ++_i) \
;         __builtin_amdgcn_global_load_lds((const unsigned*)((const char*)(gbase) + (voff)[_i]), (PG8_LAS unsigned*)(lds + (bufoff) + ldsw + _i * 8192), 16, 0, 0); } while (0)
; #define PG8_LDA(dst, b, h) do { _Pragma("unroll") for (int m = 0; m < 4; ++m) _Pragma("unroll") for (int k = 0; k < 2; ++k) dst[m][k] = *(const PG8_LAS bf16x8*)(lds + PG8_SA(b, h) + aoff + m * 2048 + k * 1024); } while (0)
; #define PG8_MMA(ai, bj, At, Bt) do { __builtin_amdgcn_s_setprio(1); _Pragma("unroll") for (int m = 0; m < 4; ++m) _Pragma("unroll") for (int n = 0; n < 2; ++n) _Pragma("unroll") for (int k = 0; k < 2; ++k) \
;         acc[ai][bj][m][n] = __builtin_amdgcn_mfma_f32_16x16x32_bf16(Bt[n][k], At[m][k], acc[ai][bj][m][n], 0, 0, 0); __builtin_amdgcn_s_setprio(0); } while (0)
; #define PG8_WAIT_V(n) asm volatile("s_waitcnt vmcnt(" #n ")" ::: "memory")
; #define PG8_WAIT_L(n) asm volatile("s_waitcnt lgkmcnt(" #n ")" ::: "memory")
; #define PG8_BAR __builtin_amdgcn_s_barrier()
; #define PG8_SCHED __builtin_amdgcn_sched_barrier(0)
; template <class Epi, class Sched, bool ALIGN_EPI = false, bool SP2 = false>
; __device__ __forceinline__ void gemm_phase(PG8_LAS unsigned char* lds, const Gemm g, const Sched& S, const Epi& E, const int tid) {
;     ...
;             PG8_WAIT_V(8); PG8_WAIT_L(0); PG8_BAR; PG8_MMA(0, 0, At, B0); PG8_MMA(0, 1, At, B1); PG8_BAR; PG8_SCHED;
;             PG8_LDA(At, 0, 1); PG8_STAGE(PG8_SB(0, 0), b2, voffB); PG8_STAGE(PG8_SB(0, 1), b2 + hstep, voffB); PG8_STAGE(PG8_SA(0, 0), a2, voffA);
;             PG8_WAIT_V(8); PG8_WAIT_L(0); PG8_BAR; PG8_MMA(1, 0, At, B0); PG8_MMA(1, 1, At, B1); PG8_BAR; PG8_SCHED;
	s_setprio 1
	s_waitcnt lgkmcnt(0)
	v_mfma_f32_16x16x32_bf16 v[140:143], v[48:51], v[178:181], v[140:143]
	v_mfma_f32_16x16x32_bf16 v[136:139], v[64:67], v[178:181], v[136:139]
	v_mfma_f32_16x16x32_bf16 v[124:127], v[48:51], v[186:189], v[124:127]
	v_mfma_f32_16x16x32_bf16 v[120:123], v[64:67], v[186:189], v[120:123]
	v_mfma_f32_16x16x32_bf16 v[108:111], v[48:51], v[194:197], v[108:111]
	v_mfma_f32_16x16x32_bf16 v[104:107], v[64:67], v[194:197], v[104:107]
	v_mfma_f32_16x16x32_bf16 v[92:95], v[48:51], v[202:205], v[92:95]
	v_mfma_f32_16x16x32_bf16 v[88:91], v[64:67], v[202:205], v[88:91]
	v_mfma_f32_16x16x32_bf16 v[140:143], v[52:55], v[182:185], v[140:143]
	v_mfma_f32_16x16x32_bf16 v[136:139], v[68:71], v[182:185], v[136:139]
	v_mfma_f32_16x16x32_bf16 v[124:127], v[52:55], v[190:193], v[124:127]
	v_mfma_f32_16x16x32_bf16 v[120:123], v[68:71], v[190:193], v[120:123]
	v_mfma_f32_16x16x32_bf16 v[108:111], v[52:55], v[198:201], v[108:111]
	v_mfma_f32_16x16x32_bf16 v[104:107], v[68:71], v[198:201], v[104:107]
	v_mfma_f32_16x16x32_bf16 v[92:95], v[52:55], v[214:217], v[92:95]
	v_mfma_f32_16x16x32_bf16 v[88:91], v[68:71], v[214:217], v[88:91]
	s_setprio 0
	s_setprio 1
	v_mfma_f32_16x16x32_bf16 v[132:135], v[162:165], v[178:181], v[132:135]
	v_mfma_f32_16x16x32_bf16 v[128:131], v[170:173], v[178:181], v[128:131]
	v_mfma_f32_16x16x32_bf16 v[116:119], v[162:165], v[186:189], v[116:119]
	v_mfma_f32_16x16x32_bf16 v[112:115], v[170:173], v[186:189], v[112:115]
	v_mfma_f32_16x16x32_bf16 v[100:103], v[162:165], v[194:197], v[100:103]
	v_mfma_f32_16x16x32_bf16 v[96:99], v[170:173], v[194:197], v[96:99]
	v_mfma_f32_16x16x32_bf16 v[84:87], v[162:165], v[202:205], v[84:87]
	v_mfma_f32_16x16x32_bf16 v[80:83], v[170:173], v[202:205], v[80:83]
	v_mfma_f32_16x16x32_bf16 v[132:135], v[166:169], v[182:185], v[132:135]
	v_mfma_f32_16x16x32_bf16 v[128:131], v[174:177], v[182:185], v[128:131]
	v_mfma_f32_16x16x32_bf16 v[116:119], v[166:169], v[190:193], v[116:119]
	v_mfma_f32_16x16x32_bf16 v[112:115], v[174:177], v[190:193], v[112:115]
	v_mfma_f32_16x16x32_bf16 v[100:103], v[166:169], v[198:201], v[100:103]
	v_mfma_f32_16x16x32_bf16 v[96:99], v[174:177], v[198:201], v[96:99]
	v_mfma_f32_16x16x32_bf16 v[84:87], v[166:169], v[214:217], v[84:87]
	v_mfma_f32_16x16x32_bf16 v[80:83], v[174:177], v[214:217], v[80:83]
	s_setprio 0
	s_barrier
	s_add_i32 s51, s51, s38
	v_lshl_add_u64 v[206:207], s[26:27], 0, v[208:209]
	s_mov_b32 m0, s51
	ds_read_b128 v[178:181], v161 offset:16384
	ds_read_b128 v[182:185], v161 offset:17408
	ds_read_b128 v[186:189], v161 offset:18432
	ds_read_b128 v[190:193], v161 offset:19456
	ds_read_b128 v[194:197], v161 offset:20480
	ds_read_b128 v[198:201], v161 offset:21504
	ds_read_b128 v[202:205], v161 offset:22528
	ds_read_b128 v[214:217], v161 offset:23552
	global_load_lds_dwordx4 v[206:207], off
	s_add_i32 m0, s51, 0x2000
	s_add_u32 s52, s26, 0x80000
	v_lshl_add_u64 v[210:211], s[26:27], 0, v[144:145]
	s_addc_u32 s53, s27, 0
	s_add_i32 s51, s33, s38
	global_load_lds_dwordx4 v[210:211], off
	v_lshl_add_u64 v[218:219], s[52:53], 0, v[208:209]
	s_mov_b32 m0, s51
	v_lshl_add_u64 v[220:221], s[28:29], 0, v[146:147]
	global_load_lds_dwordx4 v[218:219], off
	v_lshl_add_u64 v[218:219], s[52:53], 0, v[144:145]
	s_add_i32 m0, s51, 0x2000
	s_nop 0
	global_load_lds_dwordx4 v[218:219], off
	v_lshl_add_u64 v[218:219], s[28:29], 0, v[148:149]
	s_mov_b32 m0, s23
	s_nop 0
	global_load_lds_dwordx4 v[218:219], off
	s_mov_b32 m0, s39
	s_nop 0
	global_load_lds_dwordx4 v[220:221], off
	s_waitcnt vmcnt(8)
	s_waitcnt lgkmcnt(0)
	s_barrier
	s_setprio 1
	s_waitcnt lgkmcnt(0)
	v_mfma_f32_16x16x32_bf16 v[76:79], v[48:51], v[178:181], v[76:79]
	v_mfma_f32_16x16x32_bf16 v[72:75], v[64:67], v[178:181], v[72:75]
	v_mfma_f32_16x16x32_bf16 v[44:47], v[48:51], v[186:189], v[44:47]
	v_mfma_f32_16x16x32_bf16 v[40:43], v[64:67], v[186:189], v[40:43]
	v_mfma_f32_16x16x32_bf16 v[28:31], v[48:51], v[194:197], v[28:31]
	v_mfma_f32_16x16x32_bf16 v[24:27], v[64:67], v[194:197], v[24:27]
	v_mfma_f32_16x16x32_bf16 v[12:15], v[48:51], v[202:205], v[12:15]
	v_mfma_f32_16x16x32_bf16 v[8:11], v[64:67], v[202:205], v[8:11]
	v_mfma_f32_16x16x32_bf16 v[76:79], v[52:55], v[182:185], v[76:79]
	v_mfma_f32_16x16x32_bf16 v[72:75], v[68:71], v[182:185], v[72:75]
	v_mfma_f32_16x16x32_bf16 v[44:47], v[52:55], v[190:193], v[44:47]
	v_mfma_f32_16x16x32_bf16 v[40:43], v[68:71], v[190:193], v[40:43]
	v_mfma_f32_16x16x32_bf16 v[28:31], v[52:55], v[198:201], v[28:31]
	v_mfma_f32_16x16x32_bf16 v[24:27], v[68:71], v[198:201], v[24:27]
	v_mfma_f32_16x16x32_bf16 v[12:15], v[52:55], v[214:217], v[12:15]
	v_mfma_f32_16x16x32_bf16 v[8:11], v[68:71], v[214:217], v[8:11]
	s_setprio 0
	s_setprio 1
	v_mfma_f32_16x16x32_bf16 v[36:39], v[162:165], v[186:189], v[36:39]
	v_mfma_f32_16x16x32_bf16 v[32:35], v[170:173], v[186:189], v[32:35]
	v_mfma_f32_16x16x32_bf16 v[20:23], v[162:165], v[194:197], v[20:23]
	v_mfma_f32_16x16x32_bf16 v[16:19], v[170:173], v[194:197], v[16:19]
	v_mfma_f32_16x16x32_bf16 v[4:7], v[162:165], v[202:205], v[4:7]
	v_mfma_f32_16x16x32_bf16 v[0:3], v[170:173], v[202:205], v[0:3]
	v_mfma_f32_16x16x32_bf16 v[48:51], v[162:165], v[178:181], v[60:63]
	v_mfma_f32_16x16x32_bf16 v[52:55], v[170:173], v[178:181], v[56:59]
	v_mfma_f32_16x16x32_bf16 v[36:39], v[166:169], v[190:193], v[36:39]
	v_mfma_f32_16x16x32_bf16 v[32:35], v[174:177], v[190:193], v[32:35]
	v_mfma_f32_16x16x32_bf16 v[20:23], v[166:169], v[198:201], v[20:23]
	v_mfma_f32_16x16x32_bf16 v[16:19], v[174:177], v[198:201], v[16:19]
	v_mfma_f32_16x16x32_bf16 v[4:7], v[166:169], v[214:217], v[4:7]
	v_mfma_f32_16x16x32_bf16 v[0:3], v[174:177], v[214:217], v[0:3]
	v_mfma_f32_16x16x32_bf16 v[48:51], v[166:169], v[182:185], v[48:51]
	v_mfma_f32_16x16x32_bf16 v[52:55], v[174:177], v[182:185], v[52:55]
	s_setprio 0
	s_barrier
; #define PG8_STAGE(bufoff, gbase, voff) do { _Pragma("unroll") for (int _i = 0; _i < 2; ++_i) \
;         __builtin_amdgcn_global_load_lds((const unsigned*)((const char*)(gbase) + (voff)[_i]), (PG8_LAS unsigned*)(lds + (bufoff) + ldsw + _i * 8192), 16, 0, 0); } while (0)
; #define PG8_LDA(dst, b, h) do { _Pragma("unroll") for (int m = 0; m < 4; ++m) _Pragma("unroll") for (int k = 0; k < 2; ++k) dst[m][k] = *(const PG8_LAS bf16x8*)(lds + PG8_SA(b, h) + aoff + m * 2048 + k * 1024); } while (0)
; #define PG8_LDB(dst, b, h) do { _Pragma("unroll") for (int n = 0; n < 2; ++n) _Pragma("unroll") for (int k = 0; k < 2; ++k) dst[n][k] = *(const PG8_LAS bf16x8*)(lds + PG8_SB(b, h) + boff + n * 2048 + k * 1024); } while (0)
; #define PG8_MMA(ai, bj, At, Bt) do { __builtin_amdgcn_s_setprio(1); _Pragma("unroll") for (int m = 0; m < 4; ++m) _Pragma("unroll") for (int n = 0; n < 2; ++n) _Pragma("unroll") for (int k = 0; k < 2; ++k) \
;         acc[ai][bj][m][n] = __builtin_amdgcn_mfma_f32_16x16x32_bf16(Bt[n][k], At[m][k], acc[ai][bj][m][n], 0, 0, 0); __builtin_amdgcn_s_setprio(0); } while (0)
; #define PG8_WAIT_V(n) asm volatile("s_waitcnt vmcnt(" #n ")" ::: "memory")
; #define PG8_WAIT_L(n) asm volatile("s_waitcnt lgkmcnt(" #n ")" ::: "memory")
; #define PG8_BAR __builtin_amdgcn_s_barrier()
; #define PG8_SCHED __builtin_amdgcn_sched_barrier(0)
; template <class Epi, class Sched, bool ALIGN_EPI = false, bool SP2 = false>
; __device__ __forceinline__ void gemm_phase(PG8_LAS unsigned char* lds, const Gemm g, const Sched& S, const Epi& E, const int tid) {
;     ...
;             PG8_LDB(B0, 1, 0); PG8_LDB(B1, 1, 1); PG8_SCHED; PG8_LDA(At, 1, 0); PG8_STAGE(PG8_SA(0, 1), a2 + hstep, voffA);
;             PG8_WAIT_V(8); PG8_WAIT_L(0); PG8_BAR; PG8_MMA(0, 0, At, B0); PG8_MMA(0, 1, At, B1); PG8_BAR; PG8_SCHED;
;             PG8_LDA(At, 1, 1); PG8_STAGE(PG8_SB(1, 0), b3, voffB); PG8_STAGE(PG8_SB(1, 1), b3 + hstep, voffB); PG8_STAGE(PG8_SA(1, 0), a3, voffA);
;             PG8_WAIT_V(8); PG8_WAIT_L(0); PG8_BAR; PG8_MMA(1, 0, At, B0); PG8_MMA(1, 1, At, B1); PG8_BAR; PG8_SCHED;
	s_add_i32 s51, 0, 0x18000
	s_add_i32 s52, 0, 0x1c000
	v_add_u32_e32 v68, s51, v157
	v_add_u32_e32 v154, s52, v157
	ds_read_b128 v[56:59], v68
	ds_read_b128 v[60:63], v68 offset:1024
	ds_read_b128 v[64:67], v68 offset:2048
	ds_read_b128 v[68:71], v68 offset:3072
	ds_read_b128 v[162:165], v154
	ds_read_b128 v[166:169], v154 offset:1024
	ds_read_b128 v[170:173], v154 offset:2048
	ds_read_b128 v[174:177], v154 offset:3072
	s_add_u32 s28, s28, 0x80000
	s_addc_u32 s29, s29, 0
	s_mov_b32 m0, s40
	v_lshl_add_u64 v[222:223], s[28:29], 0, v[148:149]
	ds_read_b128 v[178:181], v161 offset:32768
	ds_read_b128 v[182:185], v161 offset:33792
	ds_read_b128 v[186:189], v161 offset:34816
	ds_read_b128 v[190:193], v161 offset:35840
	ds_read_b128 v[194:197], v161 offset:36864
	ds_read_b128 v[198:201], v161 offset:37888
	ds_read_b128 v[202:205], v161 offset:38912
	ds_read_b128 v[214:217], v161 offset:39936
	global_load_lds_dwordx4 v[222:223], off
	v_lshl_add_u64 v[222:223], s[28:29], 0, v[146:147]
	s_mov_b32 m0, s41
	s_nop 0
	global_load_lds_dwordx4 v[222:223], off
	s_waitcnt vmcnt(8)
	s_waitcnt lgkmcnt(0)
	s_barrier
	s_setprio 1
	s_waitcnt lgkmcnt(0)
	v_mfma_f32_16x16x32_bf16 v[140:143], v[56:59], v[178:181], v[140:143]
	v_mfma_f32_16x16x32_bf16 v[136:139], v[64:67], v[178:181], v[136:139]
	v_mfma_f32_16x16x32_bf16 v[124:127], v[56:59], v[186:189], v[124:127]
	v_mfma_f32_16x16x32_bf16 v[120:123], v[64:67], v[186:189], v[120:123]
	v_mfma_f32_16x16x32_bf16 v[108:111], v[56:59], v[194:197], v[108:111]
	v_mfma_f32_16x16x32_bf16 v[104:107], v[64:67], v[194:197], v[104:107]
	v_mfma_f32_16x16x32_bf16 v[92:95], v[56:59], v[202:205], v[92:95]
	v_mfma_f32_16x16x32_bf16 v[88:91], v[64:67], v[202:205], v[88:91]
	v_mfma_f32_16x16x32_bf16 v[140:143], v[60:63], v[182:185], v[140:143]
	v_mfma_f32_16x16x32_bf16 v[136:139], v[68:71], v[182:185], v[136:139]
	v_mfma_f32_16x16x32_bf16 v[124:127], v[60:63], v[190:193], v[124:127]
	v_mfma_f32_16x16x32_bf16 v[120:123], v[68:71], v[190:193], v[120:123]
	v_mfma_f32_16x16x32_bf16 v[108:111], v[60:63], v[198:201], v[108:111]
	v_mfma_f32_16x16x32_bf16 v[104:107], v[68:71], v[198:201], v[104:107]
	v_mfma_f32_16x16x32_bf16 v[92:95], v[60:63], v[214:217], v[92:95]
	v_mfma_f32_16x16x32_bf16 v[88:91], v[68:71], v[214:217], v[88:91]
	s_setprio 0
	s_setprio 1
	v_mfma_f32_16x16x32_bf16 v[132:135], v[162:165], v[178:181], v[132:135]
	v_mfma_f32_16x16x32_bf16 v[128:131], v[170:173], v[178:181], v[128:131]
	v_mfma_f32_16x16x32_bf16 v[116:119], v[162:165], v[186:189], v[116:119]
	v_mfma_f32_16x16x32_bf16 v[112:115], v[170:173], v[186:189], v[112:115]
	v_mfma_f32_16x16x32_bf16 v[100:103], v[162:165], v[194:197], v[100:103]
	v_mfma_f32_16x16x32_bf16 v[96:99], v[170:173], v[194:197], v[96:99]
	v_mfma_f32_16x16x32_bf16 v[84:87], v[162:165], v[202:205], v[84:87]
	v_mfma_f32_16x16x32_bf16 v[80:83], v[170:173], v[202:205], v[80:83]
	v_mfma_f32_16x16x32_bf16 v[132:135], v[166:169], v[182:185], v[132:135]
	v_mfma_f32_16x16x32_bf16 v[128:131], v[174:177], v[182:185], v[128:131]
	v_mfma_f32_16x16x32_bf16 v[116:119], v[166:169], v[190:193], v[116:119]
	v_mfma_f32_16x16x32_bf16 v[112:115], v[174:177], v[190:193], v[112:115]
	v_mfma_f32_16x16x32_bf16 v[100:103], v[166:169], v[198:201], v[100:103]
	v_mfma_f32_16x16x32_bf16 v[96:99], v[174:177], v[198:201], v[96:99]
	v_mfma_f32_16x16x32_bf16 v[84:87], v[166:169], v[214:217], v[84:87]
	v_mfma_f32_16x16x32_bf16 v[80:83], v[174:177], v[214:217], v[80:83]
	s_setprio 0
	s_barrier
	s_add_i32 s28, s51, s38
	v_lshl_add_u64 v[206:207], v[206:207], 0, s[2:3]
	s_mov_b32 m0, s28
	ds_read_b128 v[178:181], v161 offset:49152
	ds_read_b128 v[182:185], v161 offset:50176
	ds_read_b128 v[186:189], v161 offset:51200
	ds_read_b128 v[190:193], v161 offset:52224
	ds_read_b128 v[194:197], v161 offset:53248
	ds_read_b128 v[198:201], v161 offset:54272
	ds_read_b128 v[202:205], v161 offset:55296
	ds_read_b128 v[214:217], v161 offset:56320
	global_load_lds_dwordx4 v[206:207], off
	s_add_i32 m0, s28, 0x2000
	s_add_u32 s26, s26, 0x80080
	v_lshl_add_u64 v[206:207], v[210:211], 0, s[2:3]
	s_addc_u32 s27, s27, 0
	s_add_i32 s28, s52, s38
	global_load_lds_dwordx4 v[206:207], off
	v_lshl_add_u64 v[206:207], s[26:27], 0, v[208:209]
	s_mov_b32 m0, s28
	s_nop 0
	global_load_lds_dwordx4 v[206:207], off
	v_lshl_add_u64 v[206:207], s[26:27], 0, v[144:145]
	s_add_i32 m0, s28, 0x2000
	s_nop 0
	global_load_lds_dwordx4 v[206:207], off
	v_lshl_add_u64 v[206:207], v[218:219], 0, s[2:3]
	s_mov_b32 m0, s44
	s_nop 0
	global_load_lds_dwordx4 v[206:207], off
	v_lshl_add_u64 v[206:207], v[220:221], 0, s[2:3]
	s_mov_b32 m0, s45
	s_nop 0
	global_load_lds_dwordx4 v[206:207], off
	s_waitcnt vmcnt(8)
	s_waitcnt lgkmcnt(0)
	s_barrier
; #define PG8_MMA(ai, bj, At, Bt) do { __builtin_amdgcn_s_setprio(1); _Pragma("unroll") for (int m = 0; m < 4; ++m) _Pragma("unroll") for (int n = 0; n < 2; ++n) _Pragma("unroll") for (int k = 0; k < 2; ++k) \
;         acc[ai][bj][m][n] = __builtin_amdgcn_mfma_f32_16x16x32_bf16(Bt[n][k], At[m][k], acc[ai][bj][m][n], 0, 0, 0); __builtin_amdgcn_s_setprio(0); } while (0)
; #define PG8_WAIT_V(n) asm volatile("s_waitcnt vmcnt(" #n ")" ::: "memory")
; #define PG8_WAIT_L(n) asm volatile("s_waitcnt lgkmcnt(" #n ")" ::: "memory")
; #define PG8_BAR __builtin_amdgcn_s_barrier()
; #define PG8_SCHED __builtin_amdgcn_sched_barrier(0)
; template <class Epi, class Sched, bool ALIGN_EPI = false, bool SP2 = false>
; __device__ __forceinline__ void gemm_phase(PG8_LAS unsigned char* lds, const Gemm g, const Sched& S, const Epi& E, const int tid) {
;     ...
;             PG8_WAIT_V(8); PG8_WAIT_L(0); PG8_BAR; PG8_MMA(1, 0, At, B0); PG8_MMA(1, 1, At, B1); PG8_BAR; PG8_SCHED;
;     ...
;         if constexpr (ALIGN_EPI) { if (wr == 0) PG8_BAR; }
;     __device__ __forceinline__ void operator()(const f32x4 (&acc)[2][2][4][2], const Unit& un, int wr, int wc, int fr, int fq) const {
;         const int rbase = un.pm * 256 + wr * 64 + fr, cw = un.pn * 256 + wc * 32 + 8 * fq;
;         const int slot = un.pm < (NLAT / 256) ? (un.pm >> 5) : 4; const float* sw = shw + (size_t)slot * DFF;
;         f32x4 s0[2], s1[2]; float rr[2][4];
; #pragma unroll
;         for (int bj = 0; bj < 2; ++bj) { s0[bj] = *(const f32x4*)(sw + cw + bj * 128); s1[bj] = *(const f32x4*)(sw + cw + bj * 128 + 4); }
; #pragma unroll
;         for (int ai = 0; ai < 2; ++ai)
; #pragma unroll
;             for (int m = 0; m < 4; ++m) rr[ai][m] = rs[rbase + ai * 128 + m * 16];
	s_setprio 1
	s_waitcnt lgkmcnt(0)
	v_mfma_f32_16x16x32_bf16 v[76:79], v[56:59], v[178:181], v[76:79]
	v_mfma_f32_16x16x32_bf16 v[72:75], v[64:67], v[178:181], v[72:75]
	v_mfma_f32_16x16x32_bf16 v[44:47], v[56:59], v[186:189], v[44:47]
	v_mfma_f32_16x16x32_bf16 v[40:43], v[64:67], v[186:189], v[40:43]
	v_mfma_f32_16x16x32_bf16 v[28:31], v[56:59], v[194:197], v[28:31]
	v_mfma_f32_16x16x32_bf16 v[24:27], v[64:67], v[194:197], v[24:27]
	v_mfma_f32_16x16x32_bf16 v[12:15], v[56:59], v[202:205], v[12:15]
	v_mfma_f32_16x16x32_bf16 v[8:11], v[64:67], v[202:205], v[8:11]
	v_mfma_f32_16x16x32_bf16 v[76:79], v[60:63], v[182:185], v[76:79]
	v_mfma_f32_16x16x32_bf16 v[72:75], v[68:71], v[182:185], v[72:75]
	v_mfma_f32_16x16x32_bf16 v[44:47], v[60:63], v[190:193], v[44:47]
	v_mfma_f32_16x16x32_bf16 v[40:43], v[68:71], v[190:193], v[40:43]
	v_mfma_f32_16x16x32_bf16 v[28:31], v[60:63], v[198:201], v[28:31]
	v_mfma_f32_16x16x32_bf16 v[24:27], v[68:71], v[198:201], v[24:27]
	v_mfma_f32_16x16x32_bf16 v[12:15], v[60:63], v[214:217], v[12:15]
	v_mfma_f32_16x16x32_bf16 v[8:11], v[68:71], v[214:217], v[8:11]
	s_setprio 0
	s_setprio 1
	v_mfma_f32_16x16x32_bf16 v[48:51], v[162:165], v[178:181], v[48:51]
	v_mfma_f32_16x16x32_bf16 v[60:63], v[166:169], v[182:185], v[48:51]
	v_mfma_f32_16x16x32_bf16 v[48:51], v[170:173], v[178:181], v[52:55]
	v_mfma_f32_16x16x32_bf16 v[36:39], v[162:165], v[186:189], v[36:39]
	v_mfma_f32_16x16x32_bf16 v[32:35], v[170:173], v[186:189], v[32:35]
	v_mfma_f32_16x16x32_bf16 v[20:23], v[162:165], v[194:197], v[20:23]
	v_mfma_f32_16x16x32_bf16 v[16:19], v[170:173], v[194:197], v[16:19]
	v_mfma_f32_16x16x32_bf16 v[4:7], v[162:165], v[202:205], v[4:7]
	v_mfma_f32_16x16x32_bf16 v[0:3], v[170:173], v[202:205], v[0:3]
	v_mfma_f32_16x16x32_bf16 v[56:59], v[174:177], v[182:185], v[48:51]
	v_mfma_f32_16x16x32_bf16 v[36:39], v[166:169], v[190:193], v[36:39]
	v_mfma_f32_16x16x32_bf16 v[32:35], v[174:177], v[190:193], v[32:35]
	v_mfma_f32_16x16x32_bf16 v[20:23], v[166:169], v[198:201], v[20:23]
	v_mfma_f32_16x16x32_bf16 v[16:19], v[174:177], v[198:201], v[16:19]
	v_mfma_f32_16x16x32_bf16 v[4:7], v[166:169], v[214:217], v[4:7]
	v_mfma_f32_16x16x32_bf16 v[0:3], v[174:177], v[214:217], v[0:3]
	s_setprio 0
	s_barrier
	s_add_i32 s50, s50, 2
	s_add_u32 s24, s24, 0x100
	s_addc_u32 s25, s25, 0
	s_add_u32 s48, s48, 0x100
	s_addc_u32 s49, s49, 0
	s_cmp_gt_u32 s50, 29
	s_cbranch_scc0 .LBB0_1047
	s_ashr_i32 s24, s20, 5
	s_ashr_i32 s25, s24, 31
	s_lshl_b64 s[24:25], s[24:25], 13
	s_cmpk_lt_i32 s20, 0x80
	s_cselect_b32 s25, s25, 0
	s_cselect_b32 s24, s24, 0x8000
	s_lshl_b64 s[24:25], s[24:25], 2
	v_lshl_or_b32 v176, s22, 8, v159
	s_add_u32 s24, s42, s24
	v_lshl_add_u32 v178, s20, 8, v155
	s_addc_u32 s25, s43, s25
	v_ashrrev_i32_e32 v177, 31, v176
	v_ashrrev_i32_e32 v179, 31, v178
	v_lshl_add_u64 v[52:53], v[176:177], 2, s[24:25]
	v_lshl_add_u64 v[180:181], v[178:179], 2, s[6:7]
	global_load_dwordx4 v[64:67], v[52:53], off offset:16
	global_load_dwordx4 v[68:71], v[52:53], off
	global_load_dwordx4 v[48:51], v[52:53], off offset:528
	s_nop 0
	global_load_dwordx4 v[52:55], v[52:53], off offset:512
	v_or_b32_e32 v172, 16, v178
	global_load_dword v174, v[180:181], off
	v_ashrrev_i32_e32 v173, 31, v172
	v_lshl_add_u64 v[162:163], v[172:173], 2, s[6:7]
	global_load_dword v170, v[162:163], off
	v_or_b32_e32 v168, 32, v178
	v_ashrrev_i32_e32 v169, 31, v168
	v_lshl_add_u64 v[162:163], v[168:169], 2, s[6:7]
	global_load_dword v166, v[162:163], off
	v_or_b32_e32 v164, 48, v178
	v_lshlrev_b64 v[178:179], 14, v[178:179]
	v_ashrrev_i32_e32 v165, 31, v164
	v_lshl_add_u64 v[162:163], v[164:165], 2, s[6:7]
	global_load_dword v162, v[162:163], off
	s_nop 0
	global_load_dword v160, v[180:181], off offset:512
	global_load_dword v158, v[180:181], off offset:576
	global_load_dword v156, v[180:181], off offset:640
	global_load_dword v154, v[180:181], off offset:704
	s_and_b64 vcc, exec, s[8:9]
	s_cbranch_vccz .LBB0_1050
	s_barrier

.LBB0_1127:
	s_ashr_i32 s13, s12, 31
	s_lshl_b64 s[18:19], s[12:13], 18
	s_add_u32 s13, s34, s18
	s_addc_u32 s15, s35, s19
	s_lshl_b32 s18, s47, 21
	s_add_u32 s18, s13, s18
	s_addc_u32 s19, s15, 0
	s_and_b64 s[4:5], s[4:5], exec
	s_cselect_b32 s13, s19, s25
	s_cselect_b32 s15, s18, s24
	s_add_u32 s4, s26, 0x20080
	s_addc_u32 s5, s27, 0
	s_add_u32 s21, s24, 0x100
	v_mov_b32_e32 v0, 0
	s_addc_u32 s23, s25, 0
	s_mov_b32 s49, -2
	v_mov_b32_e32 v1, v0
	v_mov_b32_e32 v2, v0
	v_mov_b32_e32 v3, v0
	v_mov_b32_e32 v4, v0
	v_mov_b32_e32 v5, v0
	v_mov_b32_e32 v6, v0
	v_mov_b32_e32 v7, v0
	v_mov_b32_e32 v16, v0
	v_mov_b32_e32 v17, v0
	v_mov_b32_e32 v18, v0
	v_mov_b32_e32 v19, v0
	v_mov_b32_e32 v20, v0
	v_mov_b32_e32 v21, v0
	v_mov_b32_e32 v22, v0
	v_mov_b32_e32 v23, v0
	v_mov_b32_e32 v32, v0
	v_mov_b32_e32 v33, v0
	v_mov_b32_e32 v34, v0
	v_mov_b32_e32 v35, v0
	v_mov_b32_e32 v36, v0
	v_mov_b32_e32 v37, v0
	v_mov_b32_e32 v38, v0
	v_mov_b32_e32 v39, v0
	v_mov_b32_e32 v48, v0
	v_mov_b32_e32 v49, v0
	v_mov_b32_e32 v50, v0
	v_mov_b32_e32 v51, v0
	v_mov_b32_e32 v52, v0
	v_mov_b32_e32 v53, v0
	v_mov_b32_e32 v54, v0
	v_mov_b32_e32 v55, v0
	v_mov_b32_e32 v8, v0
	v_mov_b32_e32 v9, v0
	v_mov_b32_e32 v10, v0
	v_mov_b32_e32 v11, v0
	v_mov_b32_e32 v12, v0
	v_mov_b32_e32 v13, v0
	v_mov_b32_e32 v14, v0
	v_mov_b32_e32 v15, v0
	v_mov_b32_e32 v24, v0
	v_mov_b32_e32 v25, v0
	v_mov_b32_e32 v26, v0
	v_mov_b32_e32 v27, v0
	v_mov_b32_e32 v28, v0
	v_mov_b32_e32 v29, v0
	v_mov_b32_e32 v30, v0
	v_mov_b32_e32 v31, v0
	v_mov_b32_e32 v40, v0
	v_mov_b32_e32 v41, v0
	v_mov_b32_e32 v42, v0
	v_mov_b32_e32 v43, v0
	v_mov_b32_e32 v44, v0
	v_mov_b32_e32 v45, v0
	v_mov_b32_e32 v46, v0
	v_mov_b32_e32 v47, v0
	v_mov_b32_e32 v56, v0
	v_mov_b32_e32 v57, v0
	v_mov_b32_e32 v58, v0
	v_mov_b32_e32 v59, v0
	v_mov_b32_e32 v60, v0
	v_mov_b32_e32 v61, v0
	v_mov_b32_e32 v62, v0
	v_mov_b32_e32 v63, v0
	v_mov_b32_e32 v64, v0
	v_mov_b32_e32 v65, v0
	v_mov_b32_e32 v66, v0
	v_mov_b32_e32 v67, v0
	v_mov_b32_e32 v68, v0
	v_mov_b32_e32 v69, v0
	v_mov_b32_e32 v70, v0
	v_mov_b32_e32 v71, v0
	v_mov_b32_e32 v72, v0
	v_mov_b32_e32 v73, v0
	v_mov_b32_e32 v74, v0
	v_mov_b32_e32 v75, v0
	v_mov_b32_e32 v76, v0
	v_mov_b32_e32 v77, v0
	v_mov_b32_e32 v78, v0
	v_mov_b32_e32 v79, v0
	v_mov_b32_e32 v80, v0
	v_mov_b32_e32 v81, v0
	v_mov_b32_e32 v82, v0
	v_mov_b32_e32 v83, v0
	v_mov_b32_e32 v84, v0
	v_mov_b32_e32 v85, v0
	v_mov_b32_e32 v86, v0
	v_mov_b32_e32 v87, v0
	v_mov_b32_e32 v112, v0
	v_mov_b32_e32 v113, v0
	v_mov_b32_e32 v114, v0
	v_mov_b32_e32 v115, v0
	v_mov_b32_e32 v116, v0
	v_mov_b32_e32 v117, v0
	v_mov_b32_e32 v118, v0
	v_mov_b32_e32 v119, v0
	v_mov_b32_e32 v88, v0
	v_mov_b32_e32 v89, v0
	v_mov_b32_e32 v90, v0
	v_mov_b32_e32 v91, v0
	v_mov_b32_e32 v92, v0
	v_mov_b32_e32 v93, v0
	v_mov_b32_e32 v94, v0
	v_mov_b32_e32 v95, v0
	v_mov_b32_e32 v96, v0
	v_mov_b32_e32 v97, v0
	v_mov_b32_e32 v98, v0
	v_mov_b32_e32 v99, v0
	v_mov_b32_e32 v100, v0
	v_mov_b32_e32 v101, v0
	v_mov_b32_e32 v102, v0
	v_mov_b32_e32 v103, v0
	v_mov_b32_e32 v104, v0
	v_mov_b32_e32 v105, v0
	v_mov_b32_e32 v106, v0
	v_mov_b32_e32 v107, v0
	v_mov_b32_e32 v108, v0
	v_mov_b32_e32 v109, v0
	v_mov_b32_e32 v110, v0
	v_mov_b32_e32 v111, v0
	v_mov_b32_e32 v120, v0
	v_mov_b32_e32 v121, v0
	v_mov_b32_e32 v122, v0
	v_mov_b32_e32 v123, v0
	v_mov_b32_e32 v124, v0
	v_mov_b32_e32 v125, v0
	v_mov_b32_e32 v126, v0
	v_mov_b32_e32 v127, v0
	s_cmp_eq_u32 s100, 0
	s_cbranch_scc1 .Lmy_nobar_1128
	s_barrier
	s_mov_b32 s100, 0
.Lmy_nobar_1128:
.LBB0_1128:
	s_add_u32 s24, s4, 0xfffe0080
	s_addc_u32 s25, s5, -1
	s_add_i32 s50, 0, 0x10000
	v_add_u32_e32 v140, s50, v211
	v_add_u32_e32 v156, s33, v211
	ds_read_b128 v[128:131], v140
	ds_read_b128 v[132:135], v140 offset:1024
	ds_read_b128 v[136:139], v140 offset:2048
	ds_read_b128 v[140:143], v140 offset:3072
	ds_read_b128 v[144:147], v156
	ds_read_b128 v[148:151], v156 offset:1024
	ds_read_b128 v[152:155], v156 offset:2048
	ds_read_b128 v[156:159], v156 offset:3072
	s_cmp_eq_u32 s49, 4
	s_cselect_b32 s27, s17, s25
	s_cselect_b32 s26, s16, s24
	s_cselect_b32 s25, s13, s23
	s_cselect_b32 s24, s15, s21
	v_lshl_add_u64 v[192:193], s[4:5], 0, v[200:201]
	s_add_i32 m0, s37, 0xc000
	ds_read_b128 v[160:163], v225
	ds_read_b128 v[164:167], v225 offset:1024
	ds_read_b128 v[168:171], v225 offset:2048
	ds_read_b128 v[172:175], v225 offset:3072
	ds_read_b128 v[176:179], v225 offset:4096
	ds_read_b128 v[180:183], v225 offset:5120
	ds_read_b128 v[184:187], v225 offset:6144
	ds_read_b128 v[188:191], v225 offset:7168
	global_load_lds_dwordx4 v[192:193], off
	v_lshl_add_u64 v[192:193], s[4:5], 0, v[202:203]
	s_add_i32 m0, s37, 0xe000
	s_nop 0
	global_load_lds_dwordx4 v[192:193], off
	s_waitcnt vmcnt(8)
	s_waitcnt lgkmcnt(0)
	s_barrier
	s_setprio 1
	s_waitcnt lgkmcnt(0)
	v_mfma_f32_16x16x32_bf16 v[124:127], v[128:131], v[160:163], v[124:127]
	v_mfma_f32_16x16x32_bf16 v[120:123], v[136:139], v[160:163], v[120:123]
	v_mfma_f32_16x16x32_bf16 v[108:111], v[128:131], v[168:171], v[108:111]
	v_mfma_f32_16x16x32_bf16 v[104:107], v[136:139], v[168:171], v[104:107]
	v_mfma_f32_16x16x32_bf16 v[100:103], v[128:131], v[176:179], v[100:103]
	v_mfma_f32_16x16x32_bf16 v[96:99], v[136:139], v[176:179], v[96:99]
	v_mfma_f32_16x16x32_bf16 v[92:95], v[128:131], v[184:187], v[92:95]
	v_mfma_f32_16x16x32_bf16 v[88:91], v[136:139], v[184:187], v[88:91]
	v_mfma_f32_16x16x32_bf16 v[124:127], v[132:135], v[164:167], v[124:127]
	v_mfma_f32_16x16x32_bf16 v[120:123], v[140:143], v[164:167], v[120:123]
	v_mfma_f32_16x16x32_bf16 v[108:111], v[132:135], v[172:175], v[108:111]
	v_mfma_f32_16x16x32_bf16 v[104:107], v[140:143], v[172:175], v[104:107]
	v_mfma_f32_16x16x32_bf16 v[100:103], v[132:135], v[180:183], v[100:103]
	v_mfma_f32_16x16x32_bf16 v[96:99], v[140:143], v[180:183], v[96:99]
	v_mfma_f32_16x16x32_bf16 v[92:95], v[132:135], v[188:191], v[92:95]
	v_mfma_f32_16x16x32_bf16 v[88:91], v[140:143], v[188:191], v[88:91]
	s_setprio 0
	s_setprio 1
	v_mfma_f32_16x16x32_bf16 v[116:119], v[144:147], v[160:163], v[116:119]
	v_mfma_f32_16x16x32_bf16 v[112:115], v[152:155], v[160:163], v[112:115]
	v_mfma_f32_16x16x32_bf16 v[84:87], v[144:147], v[168:171], v[84:87]
	v_mfma_f32_16x16x32_bf16 v[80:83], v[152:155], v[168:171], v[80:83]
	v_mfma_f32_16x16x32_bf16 v[76:79], v[144:147], v[176:179], v[76:79]
	v_mfma_f32_16x16x32_bf16 v[72:75], v[152:155], v[176:179], v[72:75]
	v_mfma_f32_16x16x32_bf16 v[68:71], v[144:147], v[184:187], v[68:71]
	v_mfma_f32_16x16x32_bf16 v[64:67], v[152:155], v[184:187], v[64:67]
	v_mfma_f32_16x16x32_bf16 v[116:119], v[148:151], v[164:167], v[116:119]
	v_mfma_f32_16x16x32_bf16 v[112:115], v[156:159], v[164:167], v[112:115]
	v_mfma_f32_16x16x32_bf16 v[84:87], v[148:151], v[172:175], v[84:87]
	v_mfma_f32_16x16x32_bf16 v[80:83], v[156:159], v[172:175], v[80:83]
	v_mfma_f32_16x16x32_bf16 v[76:79], v[148:151], v[180:183], v[76:79]
	v_mfma_f32_16x16x32_bf16 v[72:75], v[156:159], v[180:183], v[72:75]
	v_mfma_f32_16x16x32_bf16 v[68:71], v[148:151], v[188:191], v[68:71]
	v_mfma_f32_16x16x32_bf16 v[64:67], v[156:159], v[188:191], v[64:67]
	s_setprio 0
	s_barrier
	s_add_i32 s50, s50, s36
	v_lshl_add_u64 v[192:193], s[24:25], 0, v[208:209]
	s_mov_b32 m0, s50
	ds_read_b128 v[160:163], v225 offset:16384
	ds_read_b128 v[164:167], v225 offset:17408
	ds_read_b128 v[168:171], v225 offset:18432
	ds_read_b128 v[172:175], v225 offset:19456
	ds_read_b128 v[176:179], v225 offset:20480
	ds_read_b128 v[180:183], v225 offset:21504
	ds_read_b128 v[184:187], v225 offset:22528
	ds_read_b128 v[188:191], v225 offset:23552
	global_load_lds_dwordx4 v[192:193], off
	s_add_i32 m0, s50, 0x2000
	s_add_u32 s50, s24, 0x20000
	v_lshl_add_u64 v[204:205], s[24:25], 0, v[198:199]
	s_addc_u32 s51, s25, 0
	s_add_i32 s52, s33, s36
	global_load_lds_dwordx4 v[204:205], off
	v_lshl_add_u64 v[206:207], s[50:51], 0, v[208:209]
	s_mov_b32 m0, s52
	v_lshl_add_u64 v[214:215], s[26:27], 0, v[196:197]
	global_load_lds_dwordx4 v[206:207], off
	v_lshl_add_u64 v[206:207], s[50:51], 0, v[198:199]
	s_add_i32 m0, s52, 0x2000
	s_nop 0
	global_load_lds_dwordx4 v[206:207], off
	v_lshl_add_u64 v[206:207], s[26:27], 0, v[194:195]
	s_mov_b32 m0, s37
	s_nop 0
	global_load_lds_dwordx4 v[206:207], off
	s_mov_b32 m0, s38
	s_nop 0
	global_load_lds_dwordx4 v[214:215], off
	s_waitcnt vmcnt(8)
	s_waitcnt lgkmcnt(0)
	s_barrier
	s_setprio 1
	s_waitcnt lgkmcnt(0)
	v_mfma_f32_16x16x32_bf16 v[60:63], v[128:131], v[160:163], v[60:63]
	v_mfma_f32_16x16x32_bf16 v[56:59], v[136:139], v[160:163], v[56:59]
	v_mfma_f32_16x16x32_bf16 v[44:47], v[128:131], v[168:171], v[44:47]
	v_mfma_f32_16x16x32_bf16 v[40:43], v[136:139], v[168:171], v[40:43]
	v_mfma_f32_16x16x32_bf16 v[28:31], v[128:131], v[176:179], v[28:31]
	v_mfma_f32_16x16x32_bf16 v[24:27], v[136:139], v[176:179], v[24:27]
	v_mfma_f32_16x16x32_bf16 v[12:15], v[128:131], v[184:187], v[12:15]
	v_mfma_f32_16x16x32_bf16 v[8:11], v[136:139], v[184:187], v[8:11]
	v_mfma_f32_16x16x32_bf16 v[60:63], v[132:135], v[164:167], v[60:63]
	v_mfma_f32_16x16x32_bf16 v[56:59], v[140:143], v[164:167], v[56:59]
	v_mfma_f32_16x16x32_bf16 v[44:47], v[132:135], v[172:175], v[44:47]
	v_mfma_f32_16x16x32_bf16 v[40:43], v[140:143], v[172:175], v[40:43]
	v_mfma_f32_16x16x32_bf16 v[28:31], v[132:135], v[180:183], v[28:31]
	v_mfma_f32_16x16x32_bf16 v[24:27], v[140:143], v[180:183], v[24:27]
	v_mfma_f32_16x16x32_bf16 v[12:15], v[132:135], v[188:191], v[12:15]
	v_mfma_f32_16x16x32_bf16 v[8:11], v[140:143], v[188:191], v[8:11]
	s_setprio 0
	s_setprio 1
	v_mfma_f32_16x16x32_bf16 v[52:55], v[144:147], v[160:163], v[52:55]
	v_mfma_f32_16x16x32_bf16 v[48:51], v[152:155], v[160:163], v[48:51]
	v_mfma_f32_16x16x32_bf16 v[36:39], v[144:147], v[168:171], v[36:39]
	v_mfma_f32_16x16x32_bf16 v[32:35], v[152:155], v[168:171], v[32:35]
	v_mfma_f32_16x16x32_bf16 v[20:23], v[144:147], v[176:179], v[20:23]
	v_mfma_f32_16x16x32_bf16 v[16:19], v[152:155], v[176:179], v[16:19]
	v_mfma_f32_16x16x32_bf16 v[4:7], v[144:147], v[184:187], v[4:7]
	v_mfma_f32_16x16x32_bf16 v[0:3], v[152:155], v[184:187], v[0:3]
	v_mfma_f32_16x16x32_bf16 v[52:55], v[148:151], v[164:167], v[52:55]
	v_mfma_f32_16x16x32_bf16 v[48:51], v[156:159], v[164:167], v[48:51]
	v_mfma_f32_16x16x32_bf16 v[36:39], v[148:151], v[172:175], v[36:39]
	v_mfma_f32_16x16x32_bf16 v[32:35], v[156:159], v[172:175], v[32:35]
	v_mfma_f32_16x16x32_bf16 v[20:23], v[148:151], v[180:183], v[20:23]
	v_mfma_f32_16x16x32_bf16 v[16:19], v[156:159], v[180:183], v[16:19]
	v_mfma_f32_16x16x32_bf16 v[4:7], v[148:151], v[188:191], v[4:7]
	v_mfma_f32_16x16x32_bf16 v[0:3], v[156:159], v[188:191], v[0:3]
	s_setprio 0
	s_barrier
	s_add_i32 s50, 0, 0x18000
	s_add_i32 s51, 0, 0x1c000
	v_add_u32_e32 v140, s50, v211
	v_add_u32_e32 v156, s51, v211
	ds_read_b128 v[128:131], v140
	ds_read_b128 v[132:135], v140 offset:1024
	ds_read_b128 v[136:139], v140 offset:2048
	ds_read_b128 v[140:143], v140 offset:3072
	ds_read_b128 v[144:147], v156
	ds_read_b128 v[148:151], v156 offset:1024
	ds_read_b128 v[152:155], v156 offset:2048
	ds_read_b128 v[156:159], v156 offset:3072
	s_add_u32 s26, s26, 0x20000
	s_addc_u32 s27, s27, 0
	s_mov_b32 m0, s39
	v_lshl_add_u64 v[216:217], s[26:27], 0, v[194:195]
	ds_read_b128 v[160:163], v225 offset:32768
	ds_read_b128 v[164:167], v225 offset:33792
	ds_read_b128 v[168:171], v225 offset:34816
	ds_read_b128 v[172:175], v225 offset:35840
	ds_read_b128 v[176:179], v225 offset:36864
	ds_read_b128 v[180:183], v225 offset:37888
	ds_read_b128 v[184:187], v225 offset:38912
	ds_read_b128 v[188:191], v225 offset:39936
	global_load_lds_dwordx4 v[216:217], off
	v_lshl_add_u64 v[216:217], s[26:27], 0, v[196:197]
	s_mov_b32 m0, s40
	s_nop 0
	global_load_lds_dwordx4 v[216:217], off
	s_waitcnt vmcnt(8)
	s_waitcnt lgkmcnt(0)
	s_barrier
	s_setprio 1
	s_waitcnt lgkmcnt(0)
	v_mfma_f32_16x16x32_bf16 v[124:127], v[128:131], v[160:163], v[124:127]
	v_mfma_f32_16x16x32_bf16 v[120:123], v[136:139], v[160:163], v[120:123]
	v_mfma_f32_16x16x32_bf16 v[108:111], v[128:131], v[168:171], v[108:111]
	v_mfma_f32_16x16x32_bf16 v[104:107], v[136:139], v[168:171], v[104:107]
	v_mfma_f32_16x16x32_bf16 v[100:103], v[128:131], v[176:179], v[100:103]
	v_mfma_f32_16x16x32_bf16 v[96:99], v[136:139], v[176:179], v[96:99]
	v_mfma_f32_16x16x32_bf16 v[92:95], v[128:131], v[184:187], v[92:95]
	v_mfma_f32_16x16x32_bf16 v[88:91], v[136:139], v[184:187], v[88:91]
	v_mfma_f32_16x16x32_bf16 v[124:127], v[132:135], v[164:167], v[124:127]
	v_mfma_f32_16x16x32_bf16 v[120:123], v[140:143], v[164:167], v[120:123]
	v_mfma_f32_16x16x32_bf16 v[108:111], v[132:135], v[172:175], v[108:111]
	v_mfma_f32_16x16x32_bf16 v[104:107], v[140:143], v[172:175], v[104:107]
	v_mfma_f32_16x16x32_bf16 v[100:103], v[132:135], v[180:183], v[100:103]
	v_mfma_f32_16x16x32_bf16 v[96:99], v[140:143], v[180:183], v[96:99]
	v_mfma_f32_16x16x32_bf16 v[92:95], v[132:135], v[188:191], v[92:95]
	v_mfma_f32_16x16x32_bf16 v[88:91], v[140:143], v[188:191], v[88:91]
	s_setprio 0
	s_setprio 1
	v_mfma_f32_16x16x32_bf16 v[116:119], v[144:147], v[160:163], v[116:119]
	v_mfma_f32_16x16x32_bf16 v[112:115], v[152:155], v[160:163], v[112:115]
	v_mfma_f32_16x16x32_bf16 v[84:87], v[144:147], v[168:171], v[84:87]
	v_mfma_f32_16x16x32_bf16 v[80:83], v[152:155], v[168:171], v[80:83]
	v_mfma_f32_16x16x32_bf16 v[76:79], v[144:147], v[176:179], v[76:79]
	v_mfma_f32_16x16x32_bf16 v[72:75], v[152:155], v[176:179], v[72:75]
	v_mfma_f32_16x16x32_bf16 v[68:71], v[144:147], v[184:187], v[68:71]
	v_mfma_f32_16x16x32_bf16 v[64:67], v[152:155], v[184:187], v[64:67]
	v_mfma_f32_16x16x32_bf16 v[116:119], v[148:151], v[164:167], v[116:119]
	v_mfma_f32_16x16x32_bf16 v[112:115], v[156:159], v[164:167], v[112:115]
	v_mfma_f32_16x16x32_bf16 v[84:87], v[148:151], v[172:175], v[84:87]
	v_mfma_f32_16x16x32_bf16 v[80:83], v[156:159], v[172:175], v[80:83]
	v_mfma_f32_16x16x32_bf16 v[76:79], v[148:151], v[180:183], v[76:79]
	v_mfma_f32_16x16x32_bf16 v[72:75], v[156:159], v[180:183], v[72:75]
	v_mfma_f32_16x16x32_bf16 v[68:71], v[148:151], v[188:191], v[68:71]
	v_mfma_f32_16x16x32_bf16 v[64:67], v[156:159], v[188:191], v[64:67]
	s_setprio 0
	s_barrier
	s_add_i32 s26, s50, s36
	v_lshl_add_u64 v[192:193], v[192:193], 0, s[2:3]
	s_mov_b32 m0, s26
	ds_read_b128 v[160:163], v225 offset:49152
	ds_read_b128 v[164:167], v225 offset:50176
	ds_read_b128 v[168:171], v225 offset:51200
	ds_read_b128 v[172:175], v225 offset:52224
	ds_read_b128 v[176:179], v225 offset:53248
	ds_read_b128 v[180:183], v225 offset:54272
	ds_read_b128 v[184:187], v225 offset:55296
	ds_read_b128 v[188:191], v225 offset:56320
	global_load_lds_dwordx4 v[192:193], off
	s_add_i32 m0, s26, 0x2000
	s_add_u32 s24, s24, 0x20080
	v_lshl_add_u64 v[192:193], v[204:205], 0, s[2:3]
	s_addc_u32 s25, s25, 0
	s_add_i32 s26, s51, s36
	global_load_lds_dwordx4 v[192:193], off
	v_lshl_add_u64 v[192:193], s[24:25], 0, v[208:209]
	s_mov_b32 m0, s26
	s_nop 0
	global_load_lds_dwordx4 v[192:193], off
	v_lshl_add_u64 v[192:193], s[24:25], 0, v[198:199]
	s_add_i32 m0, s26, 0x2000
	s_nop 0
	global_load_lds_dwordx4 v[192:193], off
	v_lshl_add_u64 v[192:193], v[206:207], 0, s[2:3]
	s_mov_b32 m0, s43
	s_nop 0
	global_load_lds_dwordx4 v[192:193], off
	v_lshl_add_u64 v[192:193], v[214:215], 0, s[2:3]
	s_mov_b32 m0, s44
	s_nop 0
	global_load_lds_dwordx4 v[192:193], off
	s_waitcnt vmcnt(8)
	s_waitcnt lgkmcnt(0)
	s_barrier
	s_setprio 1
	s_waitcnt lgkmcnt(0)
	v_mfma_f32_16x16x32_bf16 v[60:63], v[128:131], v[160:163], v[60:63]
	v_mfma_f32_16x16x32_bf16 v[56:59], v[136:139], v[160:163], v[56:59]
	v_mfma_f32_16x16x32_bf16 v[44:47], v[128:131], v[168:171], v[44:47]
	v_mfma_f32_16x16x32_bf16 v[40:43], v[136:139], v[168:171], v[40:43]
	v_mfma_f32_16x16x32_bf16 v[28:31], v[128:131], v[176:179], v[28:31]
	v_mfma_f32_16x16x32_bf16 v[24:27], v[136:139], v[176:179], v[24:27]
	v_mfma_f32_16x16x32_bf16 v[12:15], v[128:131], v[184:187], v[12:15]
	v_mfma_f32_16x16x32_bf16 v[8:11], v[136:139], v[184:187], v[8:11]
	v_mfma_f32_16x16x32_bf16 v[60:63], v[132:135], v[164:167], v[60:63]
	v_mfma_f32_16x16x32_bf16 v[56:59], v[140:143], v[164:167], v[56:59]
	v_mfma_f32_16x16x32_bf16 v[44:47], v[132:135], v[172:175], v[44:47]
	v_mfma_f32_16x16x32_bf16 v[40:43], v[140:143], v[172:175], v[40:43]
	v_mfma_f32_16x16x32_bf16 v[28:31], v[132:135], v[180:183], v[28:31]
	v_mfma_f32_16x16x32_bf16 v[24:27], v[140:143], v[180:183], v[24:27]
	v_mfma_f32_16x16x32_bf16 v[12:15], v[132:135], v[188:191], v[12:15]
	v_mfma_f32_16x16x32_bf16 v[8:11], v[140:143], v[188:191], v[8:11]
	s_setprio 0
	s_setprio 1
	v_mfma_f32_16x16x32_bf16 v[52:55], v[144:147], v[160:163], v[52:55]
	v_mfma_f32_16x16x32_bf16 v[48:51], v[152:155], v[160:163], v[48:51]
	v_mfma_f32_16x16x32_bf16 v[36:39], v[144:147], v[168:171], v[36:39]
	v_mfma_f32_16x16x32_bf16 v[32:35], v[152:155], v[168:171], v[32:35]
	v_mfma_f32_16x16x32_bf16 v[20:23], v[144:147], v[176:179], v[20:23]
	v_mfma_f32_16x16x32_bf16 v[16:19], v[152:155], v[176:179], v[16:19]
	v_mfma_f32_16x16x32_bf16 v[4:7], v[144:147], v[184:187], v[4:7]
	v_mfma_f32_16x16x32_bf16 v[0:3], v[152:155], v[184:187], v[0:3]
	v_mfma_f32_16x16x32_bf16 v[52:55], v[148:151], v[164:167], v[52:55]
	v_mfma_f32_16x16x32_bf16 v[48:51], v[156:159], v[164:167], v[48:51]
	v_mfma_f32_16x16x32_bf16 v[36:39], v[148:151], v[172:175], v[36:39]
	v_mfma_f32_16x16x32_bf16 v[32:35], v[156:159], v[172:175], v[32:35]
	v_mfma_f32_16x16x32_bf16 v[20:23], v[148:151], v[180:183], v[20:23]
	v_mfma_f32_16x16x32_bf16 v[16:19], v[156:159], v[180:183], v[16:19]
	v_mfma_f32_16x16x32_bf16 v[4:7], v[148:151], v[188:191], v[4:7]
	v_mfma_f32_16x16x32_bf16 v[0:3], v[156:159], v[188:191], v[0:3]
	s_setprio 0
	s_barrier
	s_add_i32 s49, s49, 2
	s_add_u32 s4, s4, 0x100
	s_addc_u32 s5, s5, 0
	s_add_u32 s21, s21, 0x100
	s_addc_u32 s23, s23, 0
	s_cmp_gt_u32 s49, 5
	s_cbranch_scc0 .LBB0_1128
	s_and_b64 vcc, exec, s[10:11]
	s_cbranch_vccz .LBB0_1131
	s_barrier

.LBB0_1165:
	s_waitcnt vmcnt(10)
	v_lshlrev_b32_e32 v138, 16, v100
	v_and_b32_e32 v139, 0xffff0000, v100
	v_lshlrev_b32_e32 v100, 16, v101
	v_and_b32_e32 v101, 0xffff0000, v101
	s_waitcnt vmcnt(7)
	v_lshlrev_b32_e32 v140, 16, v128
	v_and_b32_e32 v141, 0xffff0000, v128
	v_lshlrev_b32_e32 v128, 16, v129
	v_and_b32_e32 v129, 0xffff0000, v129
	v_pk_fma_f32 v[62:63], v[62:63], v[100:101], v[128:129]
	v_lshlrev_b32_e32 v100, 16, v102
	v_and_b32_e32 v101, 0xffff0000, v102
	v_lshlrev_b32_e32 v102, 16, v103
	v_and_b32_e32 v103, 0xffff0000, v103
	v_lshlrev_b32_e32 v128, 16, v130
	v_and_b32_e32 v129, 0xffff0000, v130
	v_lshlrev_b32_e32 v130, 16, v131
	v_and_b32_e32 v131, 0xffff0000, v131
	v_pk_fma_f32 v[60:61], v[60:61], v[138:139], v[140:141]
	v_pk_fma_f32 v[102:103], v[58:59], v[102:103], v[130:131]
	v_pk_fma_f32 v[58:59], v[56:57], v[100:101], v[128:129]
	v_cvt_pk_bf16_f32 v56, v60, v61
	v_cvt_pk_bf16_f32 v57, v62, v63
	v_cvt_pk_bf16_f32 v58, v58, v59
	v_cvt_pk_bf16_f32 v59, v102, v103
	v_lshl_add_u64 v[60:61], v[136:137], 0, v[124:125]
	global_store_dwordx4 v[60:61], v[56:59], off
	s_waitcnt vmcnt(7)
	v_lshlrev_b32_e32 v62, 16, v116
	v_and_b32_e32 v63, 0xffff0000, v116
	v_lshlrev_b32_e32 v56, 16, v120
	v_and_b32_e32 v57, 0xffff0000, v120
	v_lshlrev_b32_e32 v58, 16, v121
	v_and_b32_e32 v59, 0xffff0000, v121
	v_lshlrev_b32_e32 v100, 16, v117
	v_and_b32_e32 v101, 0xffff0000, v117
	v_pk_fma_f32 v[54:55], v[54:55], v[58:59], v[100:101]
	v_pk_fma_f32 v[52:53], v[52:53], v[56:57], v[62:63]
	v_lshlrev_b32_e32 v56, 16, v122
	v_and_b32_e32 v57, 0xffff0000, v122
	v_lshlrev_b32_e32 v58, 16, v123
	v_and_b32_e32 v59, 0xffff0000, v123
	v_lshlrev_b32_e32 v62, 16, v118
	v_and_b32_e32 v63, 0xffff0000, v118
	v_lshlrev_b32_e32 v100, 16, v119
	v_and_b32_e32 v101, 0xffff0000, v119
	v_pk_fma_f32 v[58:59], v[50:51], v[58:59], v[100:101]
	v_pk_fma_f32 v[50:51], v[48:49], v[56:57], v[62:63]
	v_cvt_pk_bf16_f32 v48, v52, v53
	v_cvt_pk_bf16_f32 v49, v54, v55
	v_cvt_pk_bf16_f32 v50, v50, v51
	v_cvt_pk_bf16_f32 v51, v58, v59
	global_store_dwordx4 v[60:61], v[48:51], off offset:256
	s_waitcnt vmcnt(7)
	v_lshlrev_b32_e32 v52, 16, v96
	v_and_b32_e32 v53, 0xffff0000, v96
	v_lshlrev_b32_e32 v48, 16, v112
	v_and_b32_e32 v49, 0xffff0000, v112
	v_lshlrev_b32_e32 v50, 16, v113
	v_and_b32_e32 v51, 0xffff0000, v113
	v_lshlrev_b32_e32 v54, 16, v97
	v_and_b32_e32 v55, 0xffff0000, v97
	v_pk_fma_f32 v[46:47], v[46:47], v[50:51], v[54:55]
	v_pk_fma_f32 v[44:45], v[44:45], v[48:49], v[52:53]
	v_lshlrev_b32_e32 v48, 16, v114
	v_and_b32_e32 v49, 0xffff0000, v114
	v_lshlrev_b32_e32 v50, 16, v115
	v_and_b32_e32 v51, 0xffff0000, v115
	v_lshlrev_b32_e32 v52, 16, v98
	v_and_b32_e32 v53, 0xffff0000, v98
	v_lshlrev_b32_e32 v54, 16, v99
	v_and_b32_e32 v55, 0xffff0000, v99
	v_pk_fma_f32 v[50:51], v[42:43], v[50:51], v[54:55]
	v_pk_fma_f32 v[42:43], v[40:41], v[48:49], v[52:53]
	v_cvt_pk_bf16_f32 v40, v44, v45
	v_cvt_pk_bf16_f32 v41, v46, v47
	v_cvt_pk_bf16_f32 v42, v42, v43
	v_cvt_pk_bf16_f32 v43, v50, v51
	v_lshl_add_u64 v[44:45], v[134:135], 0, v[124:125]
	global_store_dwordx4 v[44:45], v[40:43], off
	s_waitcnt vmcnt(7)
	v_lshlrev_b32_e32 v46, 16, v104
	v_and_b32_e32 v47, 0xffff0000, v104
	v_lshlrev_b32_e32 v40, 16, v108
	v_and_b32_e32 v41, 0xffff0000, v108
	v_lshlrev_b32_e32 v42, 16, v109
	v_and_b32_e32 v43, 0xffff0000, v109
	v_lshlrev_b32_e32 v48, 16, v105
	v_and_b32_e32 v49, 0xffff0000, v105
	v_pk_fma_f32 v[38:39], v[38:39], v[42:43], v[48:49]
	v_pk_fma_f32 v[36:37], v[36:37], v[40:41], v[46:47]
	v_lshlrev_b32_e32 v40, 16, v110
	v_and_b32_e32 v41, 0xffff0000, v110
	v_lshlrev_b32_e32 v42, 16, v111
	v_and_b32_e32 v43, 0xffff0000, v111
	v_lshlrev_b32_e32 v46, 16, v106
	v_and_b32_e32 v47, 0xffff0000, v106
	v_lshlrev_b32_e32 v48, 16, v107
	v_and_b32_e32 v49, 0xffff0000, v107
	v_pk_fma_f32 v[42:43], v[34:35], v[42:43], v[48:49]
	v_pk_fma_f32 v[34:35], v[32:33], v[40:41], v[46:47]
	v_cvt_pk_bf16_f32 v32, v36, v37
	v_cvt_pk_bf16_f32 v33, v38, v39
	v_cvt_pk_bf16_f32 v34, v34, v35
	v_cvt_pk_bf16_f32 v35, v42, v43
	global_store_dwordx4 v[44:45], v[32:35], off offset:256
	s_waitcnt vmcnt(7)
	v_lshlrev_b32_e32 v36, 16, v80
	v_and_b32_e32 v37, 0xffff0000, v80
	v_lshlrev_b32_e32 v32, 16, v92
	v_and_b32_e32 v33, 0xffff0000, v92
	v_lshlrev_b32_e32 v34, 16, v93
	v_and_b32_e32 v35, 0xffff0000, v93
	v_lshlrev_b32_e32 v38, 16, v81
	v_and_b32_e32 v39, 0xffff0000, v81
	v_pk_fma_f32 v[30:31], v[30:31], v[34:35], v[38:39]
	v_pk_fma_f32 v[28:29], v[28:29], v[32:33], v[36:37]
	v_lshlrev_b32_e32 v32, 16, v94
	v_and_b32_e32 v33, 0xffff0000, v94
	v_lshlrev_b32_e32 v34, 16, v95
	v_and_b32_e32 v35, 0xffff0000, v95
	v_lshlrev_b32_e32 v36, 16, v82
	v_and_b32_e32 v37, 0xffff0000, v82
	v_lshlrev_b32_e32 v38, 16, v83
	v_and_b32_e32 v39, 0xffff0000, v83
	v_pk_fma_f32 v[34:35], v[26:27], v[34:35], v[38:39]
	v_pk_fma_f32 v[26:27], v[24:25], v[32:33], v[36:37]
	v_cvt_pk_bf16_f32 v24, v28, v29
	v_cvt_pk_bf16_f32 v25, v30, v31
	v_cvt_pk_bf16_f32 v26, v26, v27
	v_cvt_pk_bf16_f32 v27, v34, v35
	v_lshl_add_u64 v[28:29], v[132:133], 0, v[124:125]
	global_store_dwordx4 v[28:29], v[24:27], off
	s_waitcnt vmcnt(7)
	v_lshlrev_b32_e32 v30, 16, v84
	v_and_b32_e32 v31, 0xffff0000, v84
	v_lshlrev_b32_e32 v24, 16, v88
	v_and_b32_e32 v25, 0xffff0000, v88
	v_lshlrev_b32_e32 v26, 16, v89
	v_and_b32_e32 v27, 0xffff0000, v89
	v_lshlrev_b32_e32 v32, 16, v85
	v_and_b32_e32 v33, 0xffff0000, v85
	v_pk_fma_f32 v[22:23], v[22:23], v[26:27], v[32:33]
	v_pk_fma_f32 v[20:21], v[20:21], v[24:25], v[30:31]
	v_lshlrev_b32_e32 v24, 16, v90
	v_and_b32_e32 v25, 0xffff0000, v90
	v_lshlrev_b32_e32 v26, 16, v91
	v_and_b32_e32 v27, 0xffff0000, v91
	v_lshlrev_b32_e32 v30, 16, v86
	v_and_b32_e32 v31, 0xffff0000, v86
	v_lshlrev_b32_e32 v32, 16, v87
	v_and_b32_e32 v33, 0xffff0000, v87
	v_pk_fma_f32 v[26:27], v[18:19], v[26:27], v[32:33]
	v_pk_fma_f32 v[18:19], v[16:17], v[24:25], v[30:31]
	v_cvt_pk_bf16_f32 v16, v20, v21
	v_cvt_pk_bf16_f32 v17, v22, v23
	v_cvt_pk_bf16_f32 v18, v18, v19
	v_cvt_pk_bf16_f32 v19, v26, v27
	global_store_dwordx4 v[28:29], v[16:19], off offset:256
	s_waitcnt vmcnt(7)
	v_lshlrev_b32_e32 v20, 16, v64
	v_and_b32_e32 v21, 0xffff0000, v64
	v_lshlrev_b32_e32 v16, 16, v76
	v_and_b32_e32 v17, 0xffff0000, v76
	v_lshlrev_b32_e32 v18, 16, v77
	v_and_b32_e32 v19, 0xffff0000, v77
	v_lshlrev_b32_e32 v22, 16, v65
	v_and_b32_e32 v23, 0xffff0000, v65
	v_pk_fma_f32 v[14:15], v[14:15], v[18:19], v[22:23]
	v_pk_fma_f32 v[12:13], v[12:13], v[16:17], v[20:21]
	v_lshlrev_b32_e32 v16, 16, v78
	v_and_b32_e32 v17, 0xffff0000, v78
	v_lshlrev_b32_e32 v18, 16, v79
	v_and_b32_e32 v19, 0xffff0000, v79
	v_lshlrev_b32_e32 v20, 16, v66
	v_and_b32_e32 v21, 0xffff0000, v66
	v_lshlrev_b32_e32 v22, 16, v67
	v_and_b32_e32 v23, 0xffff0000, v67
	v_pk_fma_f32 v[18:19], v[10:11], v[18:19], v[22:23]
	v_pk_fma_f32 v[10:11], v[8:9], v[16:17], v[20:21]
	v_cvt_pk_bf16_f32 v8, v12, v13
	v_cvt_pk_bf16_f32 v9, v14, v15
	v_cvt_pk_bf16_f32 v10, v10, v11
	v_cvt_pk_bf16_f32 v11, v18, v19
	v_lshl_add_u64 v[12:13], v[126:127], 0, v[124:125]
	global_store_dwordx4 v[12:13], v[8:11], off
	s_waitcnt vmcnt(7)
	v_lshlrev_b32_e32 v14, 16, v68
	v_and_b32_e32 v15, 0xffff0000, v68
	v_lshlrev_b32_e32 v8, 16, v72
	v_and_b32_e32 v9, 0xffff0000, v72
	v_lshlrev_b32_e32 v10, 16, v73
	v_and_b32_e32 v11, 0xffff0000, v73
	v_lshlrev_b32_e32 v16, 16, v69
	v_and_b32_e32 v17, 0xffff0000, v69
	v_pk_fma_f32 v[6:7], v[6:7], v[10:11], v[16:17]
	v_pk_fma_f32 v[4:5], v[4:5], v[8:9], v[14:15]
	v_lshlrev_b32_e32 v8, 16, v74
	v_and_b32_e32 v9, 0xffff0000, v74
	v_lshlrev_b32_e32 v10, 16, v75
	v_and_b32_e32 v11, 0xffff0000, v75
	v_lshlrev_b32_e32 v14, 16, v70
	v_and_b32_e32 v15, 0xffff0000, v70
	v_lshlrev_b32_e32 v16, 16, v71
	v_and_b32_e32 v17, 0xffff0000, v71
	v_pk_fma_f32 v[10:11], v[2:3], v[10:11], v[16:17]
	v_pk_fma_f32 v[2:3], v[0:1], v[8:9], v[14:15]
	v_cvt_pk_bf16_f32 v0, v4, v5
	v_cvt_pk_bf16_f32 v1, v6, v7
	v_cvt_pk_bf16_f32 v2, v2, v3
	v_cvt_pk_bf16_f32 v3, v10, v11
	s_and_b64 vcc, exec, s[0:1]
	s_mov_b64 s[0:1], -1
	global_store_dwordx4 v[12:13], v[0:3], off offset:256
	s_cbranch_vccnz .LBB0_1118
	s_andn2_b64 vcc, exec, s[6:7]
	s_cbranch_vccnz .LBB0_1117
	s_mov_b32 s100, 1
	s_branch .LBB0_1117

.LBB0_1315:
	s_ashr_i32 s31, s30, 31
	s_lshl_b64 s[34:35], s[30:31], 20
	s_add_u32 s34, s50, s34
	s_addc_u32 s35, s51, s35
	s_and_b64 s[36:37], s[0:1], exec
	s_cselect_b32 s31, s35, s43
	s_cselect_b32 s39, s34, s42
	s_ashr_i32 s29, s28, 31
	s_lshl_b64 s[36:37], s[28:29], 20
	s_add_u32 s36, s52, s36
	s_addc_u32 s37, s53, s37
	s_and_b64 s[46:47], s[0:1], exec
	s_cselect_b32 s29, s37, s45
	s_cselect_b32 s41, s36, s44
	s_add_u32 s42, s42, 0x80080
	s_addc_u32 s43, s43, 0
	s_add_u32 s71, s44, 0x100
	v_mov_b32_e32 v0, 0
	s_addc_u32 s72, s45, 0
	s_mov_b32 s73, -2
	v_mov_b32_e32 v1, v0
	v_mov_b32_e32 v2, v0
	v_mov_b32_e32 v3, v0
	v_mov_b32_e32 v4, v0
	v_mov_b32_e32 v5, v0
	v_mov_b32_e32 v6, v0
	v_mov_b32_e32 v7, v0
	v_mov_b32_e32 v16, v0
	v_mov_b32_e32 v17, v0
	v_mov_b32_e32 v18, v0
	v_mov_b32_e32 v19, v0
	v_mov_b32_e32 v20, v0
	v_mov_b32_e32 v21, v0
	v_mov_b32_e32 v22, v0
	v_mov_b32_e32 v23, v0
	v_mov_b32_e32 v32, v0
	v_mov_b32_e32 v33, v0
	v_mov_b32_e32 v34, v0
	v_mov_b32_e32 v35, v0
	v_mov_b32_e32 v36, v0
	v_mov_b32_e32 v37, v0
	v_mov_b32_e32 v38, v0
	v_mov_b32_e32 v39, v0
	v_mov_b32_e32 v48, v0
	v_mov_b32_e32 v49, v0
	v_mov_b32_e32 v50, v0
	v_mov_b32_e32 v51, v0
	v_mov_b32_e32 v52, v0
	v_mov_b32_e32 v53, v0
	v_mov_b32_e32 v54, v0
	v_mov_b32_e32 v55, v0
	v_mov_b32_e32 v8, v0
	v_mov_b32_e32 v9, v0
	v_mov_b32_e32 v10, v0
	v_mov_b32_e32 v11, v0
	v_mov_b32_e32 v12, v0
	v_mov_b32_e32 v13, v0
	v_mov_b32_e32 v14, v0
	v_mov_b32_e32 v15, v0
	v_mov_b32_e32 v24, v0
	v_mov_b32_e32 v25, v0
	v_mov_b32_e32 v26, v0
	v_mov_b32_e32 v27, v0
	v_mov_b32_e32 v28, v0
	v_mov_b32_e32 v29, v0
	v_mov_b32_e32 v30, v0
	v_mov_b32_e32 v31, v0
	v_mov_b32_e32 v40, v0
	v_mov_b32_e32 v41, v0
	v_mov_b32_e32 v42, v0
	v_mov_b32_e32 v43, v0
	v_mov_b32_e32 v44, v0
	v_mov_b32_e32 v45, v0
	v_mov_b32_e32 v46, v0
	v_mov_b32_e32 v47, v0
	v_mov_b32_e32 v56, v0
	v_mov_b32_e32 v57, v0
	v_mov_b32_e32 v58, v0
	v_mov_b32_e32 v59, v0
	v_mov_b32_e32 v60, v0
	v_mov_b32_e32 v61, v0
	v_mov_b32_e32 v62, v0
	v_mov_b32_e32 v63, v0
	v_mov_b32_e32 v64, v0
	v_mov_b32_e32 v65, v0
	v_mov_b32_e32 v66, v0
	v_mov_b32_e32 v67, v0
	v_mov_b32_e32 v68, v0
	v_mov_b32_e32 v69, v0
	v_mov_b32_e32 v70, v0
	v_mov_b32_e32 v71, v0
	v_mov_b32_e32 v80, v0
	v_mov_b32_e32 v81, v0
	v_mov_b32_e32 v82, v0
	v_mov_b32_e32 v83, v0
	v_mov_b32_e32 v84, v0
	v_mov_b32_e32 v85, v0
	v_mov_b32_e32 v86, v0
	v_mov_b32_e32 v87, v0
	v_mov_b32_e32 v96, v0
	v_mov_b32_e32 v97, v0
	v_mov_b32_e32 v98, v0
	v_mov_b32_e32 v99, v0
	v_mov_b32_e32 v100, v0
	v_mov_b32_e32 v101, v0
	v_mov_b32_e32 v102, v0
	v_mov_b32_e32 v103, v0
	v_mov_b32_e32 v112, v0
	v_mov_b32_e32 v113, v0
	v_mov_b32_e32 v114, v0
	v_mov_b32_e32 v115, v0
	v_mov_b32_e32 v120, v0
	v_mov_b32_e32 v121, v0
	v_mov_b32_e32 v122, v0
	v_mov_b32_e32 v123, v0
	v_mov_b32_e32 v72, v0
	v_mov_b32_e32 v73, v0
	v_mov_b32_e32 v74, v0
	v_mov_b32_e32 v75, v0
	v_mov_b32_e32 v76, v0
	v_mov_b32_e32 v77, v0
	v_mov_b32_e32 v78, v0
	v_mov_b32_e32 v79, v0
	v_mov_b32_e32 v88, v0
	v_mov_b32_e32 v89, v0
	v_mov_b32_e32 v90, v0
	v_mov_b32_e32 v91, v0
	v_mov_b32_e32 v92, v0
	v_mov_b32_e32 v93, v0
	v_mov_b32_e32 v94, v0
	v_mov_b32_e32 v95, v0
	v_mov_b32_e32 v104, v0
	v_mov_b32_e32 v105, v0
	v_mov_b32_e32 v106, v0
	v_mov_b32_e32 v107, v0
	v_mov_b32_e32 v108, v0
	v_mov_b32_e32 v109, v0
	v_mov_b32_e32 v110, v0
	v_mov_b32_e32 v111, v0
	v_mov_b32_e32 v136, v0
	v_mov_b32_e32 v137, v0
	v_mov_b32_e32 v138, v0
	v_mov_b32_e32 v139, v0
	v_mov_b32_e32 v140, v0
	v_mov_b32_e32 v141, v0
	v_mov_b32_e32 v142, v0
	v_mov_b32_e32 v143, v0
	s_cmp_eq_u32 s100, 0
	s_cbranch_scc1 .Lmy_nobar_1316
	s_barrier
	s_mov_b32 s100, 0
.Lmy_nobar_1316:
.LBB0_1316:
	s_add_u32 s44, s42, 0xfff80080
	s_addc_u32 s45, s43, -1
	s_add_i32 s74, 0, 0x10000
	v_add_u32_e32 v132, s74, v252
	v_add_u32_e32 v156, s33, v252
	ds_read_b128 v[116:119], v132
	ds_read_b128 v[124:127], v132 offset:1024
	ds_read_b128 v[128:131], v132 offset:2048
	ds_read_b128 v[132:135], v132 offset:3072
	ds_read_b128 v[144:147], v156
	ds_read_b128 v[148:151], v156 offset:1024
	ds_read_b128 v[152:155], v156 offset:2048
	ds_read_b128 v[156:159], v156 offset:3072
	s_cmp_eq_u32 s73, 28
	s_cselect_b32 s47, s31, s45
	s_cselect_b32 s46, s39, s44
	s_cselect_b32 s45, s29, s72
	s_cselect_b32 s44, s41, s71
	v_lshl_add_u64 v[192:193], s[42:43], 0, v[220:221]
	s_add_i32 m0, s55, 0xc000
	ds_read_b128 v[160:163], v210
	ds_read_b128 v[164:167], v210 offset:1024
	ds_read_b128 v[168:171], v210 offset:2048
	ds_read_b128 v[172:175], v210 offset:3072
	ds_read_b128 v[176:179], v210 offset:4096
	ds_read_b128 v[180:183], v210 offset:5120
	ds_read_b128 v[184:187], v210 offset:6144
	ds_read_b128 v[188:191], v210 offset:7168
	global_load_lds_dwordx4 v[192:193], off
	v_lshl_add_u64 v[192:193], s[42:43], 0, v[222:223]
	s_add_i32 m0, s55, 0xe000
	s_nop 0
	global_load_lds_dwordx4 v[192:193], off
	s_waitcnt vmcnt(8)
	s_waitcnt lgkmcnt(0)
	s_barrier
	s_setprio 1
	s_waitcnt lgkmcnt(0)
	v_mfma_f32_16x16x32_bf16 v[140:143], v[116:119], v[160:163], v[140:143]
	v_mfma_f32_16x16x32_bf16 v[136:139], v[128:131], v[160:163], v[136:139]
	v_mfma_f32_16x16x32_bf16 v[108:111], v[116:119], v[168:171], v[108:111]
	v_mfma_f32_16x16x32_bf16 v[104:107], v[128:131], v[168:171], v[104:107]
	v_mfma_f32_16x16x32_bf16 v[92:95], v[116:119], v[176:179], v[92:95]
	v_mfma_f32_16x16x32_bf16 v[88:91], v[128:131], v[176:179], v[88:91]
	v_mfma_f32_16x16x32_bf16 v[76:79], v[116:119], v[184:187], v[76:79]
	v_mfma_f32_16x16x32_bf16 v[72:75], v[128:131], v[184:187], v[72:75]
	v_mfma_f32_16x16x32_bf16 v[140:143], v[124:127], v[164:167], v[140:143]
	v_mfma_f32_16x16x32_bf16 v[136:139], v[132:135], v[164:167], v[136:139]
	v_mfma_f32_16x16x32_bf16 v[108:111], v[124:127], v[172:175], v[108:111]
	v_mfma_f32_16x16x32_bf16 v[104:107], v[132:135], v[172:175], v[104:107]
	v_mfma_f32_16x16x32_bf16 v[92:95], v[124:127], v[180:183], v[92:95]
	v_mfma_f32_16x16x32_bf16 v[88:91], v[132:135], v[180:183], v[88:91]
	v_mfma_f32_16x16x32_bf16 v[76:79], v[124:127], v[188:191], v[76:79]
	v_mfma_f32_16x16x32_bf16 v[72:75], v[132:135], v[188:191], v[72:75]
	s_setprio 0
	s_setprio 1
	v_mfma_f32_16x16x32_bf16 v[120:123], v[144:147], v[160:163], v[120:123]
	v_mfma_f32_16x16x32_bf16 v[112:115], v[152:155], v[160:163], v[112:115]
	v_mfma_f32_16x16x32_bf16 v[100:103], v[144:147], v[168:171], v[100:103]
	v_mfma_f32_16x16x32_bf16 v[96:99], v[152:155], v[168:171], v[96:99]
	v_mfma_f32_16x16x32_bf16 v[84:87], v[144:147], v[176:179], v[84:87]
	v_mfma_f32_16x16x32_bf16 v[80:83], v[152:155], v[176:179], v[80:83]
	v_mfma_f32_16x16x32_bf16 v[68:71], v[144:147], v[184:187], v[68:71]
	v_mfma_f32_16x16x32_bf16 v[64:67], v[152:155], v[184:187], v[64:67]
	v_mfma_f32_16x16x32_bf16 v[120:123], v[148:151], v[164:167], v[120:123]
	v_mfma_f32_16x16x32_bf16 v[112:115], v[156:159], v[164:167], v[112:115]
	v_mfma_f32_16x16x32_bf16 v[100:103], v[148:151], v[172:175], v[100:103]
	v_mfma_f32_16x16x32_bf16 v[96:99], v[156:159], v[172:175], v[96:99]
	v_mfma_f32_16x16x32_bf16 v[84:87], v[148:151], v[180:183], v[84:87]
	v_mfma_f32_16x16x32_bf16 v[80:83], v[156:159], v[180:183], v[80:83]
	v_mfma_f32_16x16x32_bf16 v[68:71], v[148:151], v[188:191], v[68:71]
	v_mfma_f32_16x16x32_bf16 v[64:67], v[156:159], v[188:191], v[64:67]
	s_setprio 0
	s_barrier
	s_add_i32 s74, s74, s54
	v_lshl_add_u64 v[192:193], s[44:45], 0, v[208:209]
	s_mov_b32 m0, s74
	ds_read_b128 v[160:163], v210 offset:16384
	ds_read_b128 v[164:167], v210 offset:17408
	ds_read_b128 v[168:171], v210 offset:18432
	ds_read_b128 v[172:175], v210 offset:19456
	ds_read_b128 v[176:179], v210 offset:20480
	ds_read_b128 v[180:183], v210 offset:21504
	ds_read_b128 v[184:187], v210 offset:22528
	ds_read_b128 v[188:191], v210 offset:23552
	global_load_lds_dwordx4 v[192:193], off
	s_add_i32 m0, s74, 0x2000
	s_add_u32 s74, s44, 0x80000
	v_lshl_add_u64 v[194:195], s[44:45], 0, v[218:219]
	s_addc_u32 s75, s45, 0
	s_add_i32 s76, s33, s54
	global_load_lds_dwordx4 v[194:195], off
	v_lshl_add_u64 v[196:197], s[74:75], 0, v[208:209]
	s_mov_b32 m0, s76
	v_lshl_add_u64 v[198:199], s[46:47], 0, v[216:217]
	global_load_lds_dwordx4 v[196:197], off
	v_lshl_add_u64 v[196:197], s[74:75], 0, v[218:219]
	s_add_i32 m0, s76, 0x2000
	s_nop 0
	global_load_lds_dwordx4 v[196:197], off
	v_lshl_add_u64 v[196:197], s[46:47], 0, v[214:215]
	s_mov_b32 m0, s55
	s_nop 0
	global_load_lds_dwordx4 v[196:197], off
	s_mov_b32 m0, s56
	s_nop 0
	global_load_lds_dwordx4 v[198:199], off
	s_waitcnt vmcnt(8)
	s_waitcnt lgkmcnt(0)
	s_barrier
	s_setprio 1
	s_waitcnt lgkmcnt(0)
	v_mfma_f32_16x16x32_bf16 v[60:63], v[116:119], v[160:163], v[60:63]
	v_mfma_f32_16x16x32_bf16 v[56:59], v[128:131], v[160:163], v[56:59]
	v_mfma_f32_16x16x32_bf16 v[44:47], v[116:119], v[168:171], v[44:47]
	v_mfma_f32_16x16x32_bf16 v[40:43], v[128:131], v[168:171], v[40:43]
	v_mfma_f32_16x16x32_bf16 v[28:31], v[116:119], v[176:179], v[28:31]
	v_mfma_f32_16x16x32_bf16 v[24:27], v[128:131], v[176:179], v[24:27]
	v_mfma_f32_16x16x32_bf16 v[12:15], v[116:119], v[184:187], v[12:15]
	v_mfma_f32_16x16x32_bf16 v[8:11], v[128:131], v[184:187], v[8:11]
	v_mfma_f32_16x16x32_bf16 v[60:63], v[124:127], v[164:167], v[60:63]
	v_mfma_f32_16x16x32_bf16 v[56:59], v[132:135], v[164:167], v[56:59]
	v_mfma_f32_16x16x32_bf16 v[44:47], v[124:127], v[172:175], v[44:47]
	v_mfma_f32_16x16x32_bf16 v[40:43], v[132:135], v[172:175], v[40:43]
	v_mfma_f32_16x16x32_bf16 v[28:31], v[124:127], v[180:183], v[28:31]
	v_mfma_f32_16x16x32_bf16 v[24:27], v[132:135], v[180:183], v[24:27]
	v_mfma_f32_16x16x32_bf16 v[12:15], v[124:127], v[188:191], v[12:15]
	v_mfma_f32_16x16x32_bf16 v[8:11], v[132:135], v[188:191], v[8:11]
	s_setprio 0
	s_setprio 1
	v_mfma_f32_16x16x32_bf16 v[52:55], v[144:147], v[160:163], v[52:55]
	v_mfma_f32_16x16x32_bf16 v[48:51], v[152:155], v[160:163], v[48:51]
	v_mfma_f32_16x16x32_bf16 v[36:39], v[144:147], v[168:171], v[36:39]
	v_mfma_f32_16x16x32_bf16 v[32:35], v[152:155], v[168:171], v[32:35]
	v_mfma_f32_16x16x32_bf16 v[20:23], v[144:147], v[176:179], v[20:23]
	v_mfma_f32_16x16x32_bf16 v[16:19], v[152:155], v[176:179], v[16:19]
	v_mfma_f32_16x16x32_bf16 v[4:7], v[144:147], v[184:187], v[4:7]
	v_mfma_f32_16x16x32_bf16 v[0:3], v[152:155], v[184:187], v[0:3]
	v_mfma_f32_16x16x32_bf16 v[52:55], v[148:151], v[164:167], v[52:55]
	v_mfma_f32_16x16x32_bf16 v[48:51], v[156:159], v[164:167], v[48:51]
	v_mfma_f32_16x16x32_bf16 v[36:39], v[148:151], v[172:175], v[36:39]
	v_mfma_f32_16x16x32_bf16 v[32:35], v[156:159], v[172:175], v[32:35]
	v_mfma_f32_16x16x32_bf16 v[20:23], v[148:151], v[180:183], v[20:23]
	v_mfma_f32_16x16x32_bf16 v[16:19], v[156:159], v[180:183], v[16:19]
	v_mfma_f32_16x16x32_bf16 v[4:7], v[148:151], v[188:191], v[4:7]
	v_mfma_f32_16x16x32_bf16 v[0:3], v[156:159], v[188:191], v[0:3]
	s_setprio 0
	s_barrier
	s_add_i32 s74, 0, 0x18000
	s_add_i32 s75, 0, 0x1c000
	v_add_u32_e32 v132, s74, v252
	v_add_u32_e32 v156, s75, v252
	ds_read_b128 v[116:119], v132
	ds_read_b128 v[124:127], v132 offset:1024
	ds_read_b128 v[128:131], v132 offset:2048
	ds_read_b128 v[132:135], v132 offset:3072
	ds_read_b128 v[144:147], v156
	ds_read_b128 v[148:151], v156 offset:1024
	ds_read_b128 v[152:155], v156 offset:2048
	ds_read_b128 v[156:159], v156 offset:3072
	s_add_u32 s46, s46, 0x80000
	s_addc_u32 s47, s47, 0
	s_mov_b32 m0, s57
	v_lshl_add_u64 v[200:201], s[46:47], 0, v[214:215]
	ds_read_b128 v[160:163], v210 offset:32768
	ds_read_b128 v[164:167], v210 offset:33792
	ds_read_b128 v[168:171], v210 offset:34816
	ds_read_b128 v[172:175], v210 offset:35840
	ds_read_b128 v[176:179], v210 offset:36864
	ds_read_b128 v[180:183], v210 offset:37888
	ds_read_b128 v[184:187], v210 offset:38912
	ds_read_b128 v[188:191], v210 offset:39936
	global_load_lds_dwordx4 v[200:201], off
	v_lshl_add_u64 v[200:201], s[46:47], 0, v[216:217]
	s_mov_b32 m0, s58
	s_nop 0
	global_load_lds_dwordx4 v[200:201], off
	s_waitcnt vmcnt(8)
	s_waitcnt lgkmcnt(0)
	s_barrier
	s_setprio 1
	s_waitcnt lgkmcnt(0)
	v_mfma_f32_16x16x32_bf16 v[140:143], v[116:119], v[160:163], v[140:143]
	v_mfma_f32_16x16x32_bf16 v[136:139], v[128:131], v[160:163], v[136:139]
	v_mfma_f32_16x16x32_bf16 v[108:111], v[116:119], v[168:171], v[108:111]
	v_mfma_f32_16x16x32_bf16 v[104:107], v[128:131], v[168:171], v[104:107]
	v_mfma_f32_16x16x32_bf16 v[92:95], v[116:119], v[176:179], v[92:95]
	v_mfma_f32_16x16x32_bf16 v[88:91], v[128:131], v[176:179], v[88:91]
	v_mfma_f32_16x16x32_bf16 v[76:79], v[116:119], v[184:187], v[76:79]
	v_mfma_f32_16x16x32_bf16 v[72:75], v[128:131], v[184:187], v[72:75]
	v_mfma_f32_16x16x32_bf16 v[140:143], v[124:127], v[164:167], v[140:143]
	v_mfma_f32_16x16x32_bf16 v[136:139], v[132:135], v[164:167], v[136:139]
	v_mfma_f32_16x16x32_bf16 v[108:111], v[124:127], v[172:175], v[108:111]
	v_mfma_f32_16x16x32_bf16 v[104:107], v[132:135], v[172:175], v[104:107]
	v_mfma_f32_16x16x32_bf16 v[92:95], v[124:127], v[180:183], v[92:95]
	v_mfma_f32_16x16x32_bf16 v[88:91], v[132:135], v[180:183], v[88:91]
	v_mfma_f32_16x16x32_bf16 v[76:79], v[124:127], v[188:191], v[76:79]
	v_mfma_f32_16x16x32_bf16 v[72:75], v[132:135], v[188:191], v[72:75]
	s_setprio 0
	s_setprio 1
	v_mfma_f32_16x16x32_bf16 v[120:123], v[144:147], v[160:163], v[120:123]
	v_mfma_f32_16x16x32_bf16 v[112:115], v[152:155], v[160:163], v[112:115]
	v_mfma_f32_16x16x32_bf16 v[100:103], v[144:147], v[168:171], v[100:103]
	v_mfma_f32_16x16x32_bf16 v[96:99], v[152:155], v[168:171], v[96:99]
	v_mfma_f32_16x16x32_bf16 v[84:87], v[144:147], v[176:179], v[84:87]
	v_mfma_f32_16x16x32_bf16 v[80:83], v[152:155], v[176:179], v[80:83]
	v_mfma_f32_16x16x32_bf16 v[68:71], v[144:147], v[184:187], v[68:71]
	v_mfma_f32_16x16x32_bf16 v[64:67], v[152:155], v[184:187], v[64:67]
	v_mfma_f32_16x16x32_bf16 v[120:123], v[148:151], v[164:167], v[120:123]
	v_mfma_f32_16x16x32_bf16 v[112:115], v[156:159], v[164:167], v[112:115]
	v_mfma_f32_16x16x32_bf16 v[100:103], v[148:151], v[172:175], v[100:103]
	v_mfma_f32_16x16x32_bf16 v[96:99], v[156:159], v[172:175], v[96:99]
	v_mfma_f32_16x16x32_bf16 v[84:87], v[148:151], v[180:183], v[84:87]
	v_mfma_f32_16x16x32_bf16 v[80:83], v[156:159], v[180:183], v[80:83]
	v_mfma_f32_16x16x32_bf16 v[68:71], v[148:151], v[188:191], v[68:71]
	v_mfma_f32_16x16x32_bf16 v[64:67], v[156:159], v[188:191], v[64:67]
	s_setprio 0
	s_barrier
	s_add_i32 s46, s74, s54
	v_lshl_add_u64 v[192:193], v[192:193], 0, s[2:3]
	s_mov_b32 m0, s46
	ds_read_b128 v[160:163], v210 offset:49152
	ds_read_b128 v[164:167], v210 offset:50176
	ds_read_b128 v[168:171], v210 offset:51200
	ds_read_b128 v[172:175], v210 offset:52224
	ds_read_b128 v[176:179], v210 offset:53248
	ds_read_b128 v[180:183], v210 offset:54272
	ds_read_b128 v[184:187], v210 offset:55296
	ds_read_b128 v[188:191], v210 offset:56320
	global_load_lds_dwordx4 v[192:193], off
	s_add_i32 m0, s46, 0x2000
	s_add_u32 s44, s44, 0x80080
	v_lshl_add_u64 v[192:193], v[194:195], 0, s[2:3]
	s_addc_u32 s45, s45, 0
	s_add_i32 s46, s75, s54
	global_load_lds_dwordx4 v[192:193], off
	v_lshl_add_u64 v[192:193], s[44:45], 0, v[208:209]
	s_mov_b32 m0, s46
	s_nop 0
	global_load_lds_dwordx4 v[192:193], off
	v_lshl_add_u64 v[192:193], s[44:45], 0, v[218:219]
	s_add_i32 m0, s46, 0x2000
	s_nop 0
	global_load_lds_dwordx4 v[192:193], off
	v_lshl_add_u64 v[192:193], v[196:197], 0, s[2:3]
	s_mov_b32 m0, s66
	s_nop 0
	global_load_lds_dwordx4 v[192:193], off
	v_lshl_add_u64 v[192:193], v[198:199], 0, s[2:3]
	s_mov_b32 m0, s67
	s_nop 0
	global_load_lds_dwordx4 v[192:193], off
	s_waitcnt vmcnt(8)
	s_waitcnt lgkmcnt(0)
	s_barrier
	s_setprio 1
	s_waitcnt lgkmcnt(0)
	v_mfma_f32_16x16x32_bf16 v[60:63], v[116:119], v[160:163], v[60:63]
	v_mfma_f32_16x16x32_bf16 v[56:59], v[128:131], v[160:163], v[56:59]
	v_mfma_f32_16x16x32_bf16 v[44:47], v[116:119], v[168:171], v[44:47]
	v_mfma_f32_16x16x32_bf16 v[40:43], v[128:131], v[168:171], v[40:43]
	v_mfma_f32_16x16x32_bf16 v[28:31], v[116:119], v[176:179], v[28:31]
	v_mfma_f32_16x16x32_bf16 v[24:27], v[128:131], v[176:179], v[24:27]
	v_mfma_f32_16x16x32_bf16 v[12:15], v[116:119], v[184:187], v[12:15]
	v_mfma_f32_16x16x32_bf16 v[8:11], v[128:131], v[184:187], v[8:11]
	v_mfma_f32_16x16x32_bf16 v[60:63], v[124:127], v[164:167], v[60:63]
	v_mfma_f32_16x16x32_bf16 v[56:59], v[132:135], v[164:167], v[56:59]
	v_mfma_f32_16x16x32_bf16 v[44:47], v[124:127], v[172:175], v[44:47]
	v_mfma_f32_16x16x32_bf16 v[40:43], v[132:135], v[172:175], v[40:43]
	v_mfma_f32_16x16x32_bf16 v[28:31], v[124:127], v[180:183], v[28:31]
	v_mfma_f32_16x16x32_bf16 v[24:27], v[132:135], v[180:183], v[24:27]
	v_mfma_f32_16x16x32_bf16 v[12:15], v[124:127], v[188:191], v[12:15]
	v_mfma_f32_16x16x32_bf16 v[8:11], v[132:135], v[188:191], v[8:11]
	s_setprio 0
	s_setprio 1
	v_mfma_f32_16x16x32_bf16 v[52:55], v[144:147], v[160:163], v[52:55]
	v_mfma_f32_16x16x32_bf16 v[48:51], v[152:155], v[160:163], v[48:51]
	v_mfma_f32_16x16x32_bf16 v[36:39], v[144:147], v[168:171], v[36:39]
	v_mfma_f32_16x16x32_bf16 v[32:35], v[152:155], v[168:171], v[32:35]
	v_mfma_f32_16x16x32_bf16 v[20:23], v[144:147], v[176:179], v[20:23]
	v_mfma_f32_16x16x32_bf16 v[16:19], v[152:155], v[176:179], v[16:19]
	v_mfma_f32_16x16x32_bf16 v[4:7], v[144:147], v[184:187], v[4:7]
	v_mfma_f32_16x16x32_bf16 v[0:3], v[152:155], v[184:187], v[0:3]
	v_mfma_f32_16x16x32_bf16 v[52:55], v[148:151], v[164:167], v[52:55]
	v_mfma_f32_16x16x32_bf16 v[48:51], v[156:159], v[164:167], v[48:51]
	v_mfma_f32_16x16x32_bf16 v[36:39], v[148:151], v[172:175], v[36:39]
	v_mfma_f32_16x16x32_bf16 v[32:35], v[156:159], v[172:175], v[32:35]
	v_mfma_f32_16x16x32_bf16 v[20:23], v[148:151], v[180:183], v[20:23]
	v_mfma_f32_16x16x32_bf16 v[16:19], v[156:159], v[180:183], v[16:19]
	v_mfma_f32_16x16x32_bf16 v[4:7], v[148:151], v[188:191], v[4:7]
	v_mfma_f32_16x16x32_bf16 v[0:3], v[156:159], v[188:191], v[0:3]
	s_setprio 0
	s_barrier
	s_add_i32 s73, s73, 2
	s_add_u32 s42, s42, 0x100
	s_addc_u32 s43, s43, 0
	s_add_u32 s71, s71, 0x100
	s_addc_u32 s72, s72, 0
	s_cmp_gt_u32 s73, 29
	s_cbranch_scc0 .LBB0_1316
	s_and_b64 vcc, exec, s[26:27]
	s_cbranch_vccz .LBB0_1319
	s_barrier

.LBB0_1338:
	s_or_b64 exec, exec, s[40:41]
	s_andn2_b64 vcc, exec, s[0:1]
	s_mov_b64 s[0:1], -1
	s_cbranch_vccnz .LBB0_1308
	s_andn2_b64 vcc, exec, s[16:17]
	s_cbranch_vccnz .LBB0_1307
	s_mov_b32 s100, 1
	s_branch .LBB0_1307

.LBB0_1478:
	s_ashr_i32 s19, s18, 31
	s_lshl_b64 s[20:21], s[18:19], 20
	s_add_u32 s20, s38, s20
	s_addc_u32 s21, s39, s21
	s_and_b64 s[22:23], s[0:1], exec
	s_cselect_b32 s19, s21, s29
	s_cselect_b32 s25, s20, s28
	s_ashr_i32 s17, s16, 31
	s_lshl_b64 s[22:23], s[16:17], 20
	s_add_u32 s22, s40, s22
	s_addc_u32 s23, s41, s23
	s_and_b64 s[34:35], s[0:1], exec
	s_cselect_b32 s17, s23, s31
	s_cselect_b32 s53, s22, s30
	s_add_u32 s28, s28, 0x80080
	s_addc_u32 s29, s29, 0
	s_add_u32 s54, s30, 0x100
	v_mov_b32_e32 v0, 0
	s_addc_u32 s55, s31, 0
	s_mov_b32 s56, -2
	v_mov_b32_e32 v1, v0
	v_mov_b32_e32 v2, v0
	v_mov_b32_e32 v3, v0
	v_mov_b32_e32 v4, v0
	v_mov_b32_e32 v5, v0
	v_mov_b32_e32 v6, v0
	v_mov_b32_e32 v7, v0
	v_mov_b32_e32 v16, v0
	v_mov_b32_e32 v17, v0
	v_mov_b32_e32 v18, v0
	v_mov_b32_e32 v19, v0
	v_mov_b32_e32 v20, v0
	v_mov_b32_e32 v21, v0
	v_mov_b32_e32 v22, v0
	v_mov_b32_e32 v23, v0
	v_mov_b32_e32 v32, v0
	v_mov_b32_e32 v33, v0
	v_mov_b32_e32 v34, v0
	v_mov_b32_e32 v35, v0
	v_mov_b32_e32 v36, v0
	v_mov_b32_e32 v37, v0
	v_mov_b32_e32 v38, v0
	v_mov_b32_e32 v39, v0
	v_mov_b32_e32 v48, v0
	v_mov_b32_e32 v49, v0
	v_mov_b32_e32 v50, v0
	v_mov_b32_e32 v51, v0
	v_mov_b32_e32 v52, v0
	v_mov_b32_e32 v53, v0
	v_mov_b32_e32 v54, v0
	v_mov_b32_e32 v55, v0
	v_mov_b32_e32 v8, v0
	v_mov_b32_e32 v9, v0
	v_mov_b32_e32 v10, v0
	v_mov_b32_e32 v11, v0
	v_mov_b32_e32 v12, v0
	v_mov_b32_e32 v13, v0
	v_mov_b32_e32 v14, v0
	v_mov_b32_e32 v15, v0
	v_mov_b32_e32 v24, v0
	v_mov_b32_e32 v25, v0
	v_mov_b32_e32 v26, v0
	v_mov_b32_e32 v27, v0
	v_mov_b32_e32 v28, v0
	v_mov_b32_e32 v29, v0
	v_mov_b32_e32 v30, v0
	v_mov_b32_e32 v31, v0
	v_mov_b32_e32 v40, v0
	v_mov_b32_e32 v41, v0
	v_mov_b32_e32 v42, v0
	v_mov_b32_e32 v43, v0
	v_mov_b32_e32 v44, v0
	v_mov_b32_e32 v45, v0
	v_mov_b32_e32 v46, v0
	v_mov_b32_e32 v47, v0
	v_mov_b32_e32 v56, v0
	v_mov_b32_e32 v57, v0
	v_mov_b32_e32 v58, v0
	v_mov_b32_e32 v59, v0
	v_mov_b32_e32 v60, v0
	v_mov_b32_e32 v61, v0
	v_mov_b32_e32 v62, v0
	v_mov_b32_e32 v63, v0
	v_mov_b32_e32 v64, v0
	v_mov_b32_e32 v65, v0
	v_mov_b32_e32 v66, v0
	v_mov_b32_e32 v67, v0
	v_mov_b32_e32 v68, v0
	v_mov_b32_e32 v69, v0
	v_mov_b32_e32 v70, v0
	v_mov_b32_e32 v71, v0
	v_mov_b32_e32 v80, v0
	v_mov_b32_e32 v81, v0
	v_mov_b32_e32 v82, v0
	v_mov_b32_e32 v83, v0
	v_mov_b32_e32 v84, v0
	v_mov_b32_e32 v85, v0
	v_mov_b32_e32 v86, v0
	v_mov_b32_e32 v87, v0
	v_mov_b32_e32 v96, v0
	v_mov_b32_e32 v97, v0
	v_mov_b32_e32 v98, v0
	v_mov_b32_e32 v99, v0
	v_mov_b32_e32 v100, v0
	v_mov_b32_e32 v101, v0
	v_mov_b32_e32 v102, v0
	v_mov_b32_e32 v103, v0
	v_mov_b32_e32 v128, v0
	v_mov_b32_e32 v129, v0
	v_mov_b32_e32 v130, v0
	v_mov_b32_e32 v131, v0
	v_mov_b32_e32 v132, v0
	v_mov_b32_e32 v133, v0
	v_mov_b32_e32 v134, v0
	v_mov_b32_e32 v135, v0
	v_mov_b32_e32 v72, v0
	v_mov_b32_e32 v73, v0
	v_mov_b32_e32 v74, v0
	v_mov_b32_e32 v75, v0
	v_mov_b32_e32 v76, v0
	v_mov_b32_e32 v77, v0
	v_mov_b32_e32 v78, v0
	v_mov_b32_e32 v79, v0
	v_mov_b32_e32 v88, v0
	v_mov_b32_e32 v89, v0
	v_mov_b32_e32 v90, v0
	v_mov_b32_e32 v91, v0
	v_mov_b32_e32 v92, v0
	v_mov_b32_e32 v93, v0
	v_mov_b32_e32 v94, v0
	v_mov_b32_e32 v95, v0
	v_mov_b32_e32 v104, v0
	v_mov_b32_e32 v105, v0
	v_mov_b32_e32 v106, v0
	v_mov_b32_e32 v107, v0
	v_mov_b32_e32 v108, v0
	v_mov_b32_e32 v109, v0
	v_mov_b32_e32 v110, v0
	v_mov_b32_e32 v111, v0
	v_mov_b32_e32 v136, v0
	v_mov_b32_e32 v137, v0
	v_mov_b32_e32 v138, v0
	v_mov_b32_e32 v139, v0
	v_mov_b32_e32 v140, v0
	v_mov_b32_e32 v141, v0
	v_mov_b32_e32 v142, v0
	v_mov_b32_e32 v143, v0
	s_cmp_eq_u32 s100, 0
	s_cbranch_scc1 .Lmy_nobar_1479
	s_barrier
	s_mov_b32 s100, 0
.Lmy_nobar_1479:
.LBB0_1479:
	s_add_u32 s30, s28, 0xfff80080
	s_addc_u32 s31, s29, -1
	s_add_i32 s57, 0, 0x10000
	v_add_u32_e32 v124, s57, v157
	v_add_u32_e32 v154, s33, v157
	ds_read_b128 v[112:115], v124
	ds_read_b128 v[116:119], v124 offset:1024
	ds_read_b128 v[120:123], v124 offset:2048
	ds_read_b128 v[124:127], v124 offset:3072
	ds_read_b128 v[162:165], v154
	ds_read_b128 v[166:169], v154 offset:1024
	ds_read_b128 v[170:173], v154 offset:2048
	ds_read_b128 v[174:177], v154 offset:3072
	s_cmp_eq_u32 s56, 28
	s_cselect_b32 s35, s19, s31
	s_cselect_b32 s34, s25, s30
	s_cselect_b32 s31, s17, s55
	s_cselect_b32 s30, s53, s54
	v_lshl_add_u64 v[206:207], s[28:29], 0, v[150:151]
	s_add_i32 m0, s27, 0xc000
	ds_read_b128 v[178:181], v161
	ds_read_b128 v[182:185], v161 offset:1024
	ds_read_b128 v[186:189], v161 offset:2048
	ds_read_b128 v[190:193], v161 offset:3072
	ds_read_b128 v[194:197], v161 offset:4096
	ds_read_b128 v[198:201], v161 offset:5120
	ds_read_b128 v[202:205], v161 offset:6144
	ds_read_b128 v[214:217], v161 offset:7168
	global_load_lds_dwordx4 v[206:207], off
	v_lshl_add_u64 v[206:207], s[28:29], 0, v[152:153]
	s_add_i32 m0, s27, 0xe000
	s_nop 0
	global_load_lds_dwordx4 v[206:207], off
	s_waitcnt vmcnt(8)
	s_waitcnt lgkmcnt(0)
	s_barrier
	s_setprio 1
	s_waitcnt lgkmcnt(0)
	v_mfma_f32_16x16x32_bf16 v[140:143], v[112:115], v[178:181], v[140:143]
	v_mfma_f32_16x16x32_bf16 v[136:139], v[120:123], v[178:181], v[136:139]
	v_mfma_f32_16x16x32_bf16 v[108:111], v[112:115], v[186:189], v[108:111]
	v_mfma_f32_16x16x32_bf16 v[104:107], v[120:123], v[186:189], v[104:107]
	v_mfma_f32_16x16x32_bf16 v[92:95], v[112:115], v[194:197], v[92:95]
	v_mfma_f32_16x16x32_bf16 v[88:91], v[120:123], v[194:197], v[88:91]
	v_mfma_f32_16x16x32_bf16 v[76:79], v[112:115], v[202:205], v[76:79]
	v_mfma_f32_16x16x32_bf16 v[72:75], v[120:123], v[202:205], v[72:75]
	v_mfma_f32_16x16x32_bf16 v[140:143], v[116:119], v[182:185], v[140:143]
	v_mfma_f32_16x16x32_bf16 v[136:139], v[124:127], v[182:185], v[136:139]
	v_mfma_f32_16x16x32_bf16 v[108:111], v[116:119], v[190:193], v[108:111]
	v_mfma_f32_16x16x32_bf16 v[104:107], v[124:127], v[190:193], v[104:107]
	v_mfma_f32_16x16x32_bf16 v[92:95], v[116:119], v[198:201], v[92:95]
	v_mfma_f32_16x16x32_bf16 v[88:91], v[124:127], v[198:201], v[88:91]
	v_mfma_f32_16x16x32_bf16 v[76:79], v[116:119], v[214:217], v[76:79]
	v_mfma_f32_16x16x32_bf16 v[72:75], v[124:127], v[214:217], v[72:75]
	s_setprio 0
	s_setprio 1
	v_mfma_f32_16x16x32_bf16 v[132:135], v[162:165], v[178:181], v[132:135]
	v_mfma_f32_16x16x32_bf16 v[128:131], v[170:173], v[178:181], v[128:131]
	v_mfma_f32_16x16x32_bf16 v[100:103], v[162:165], v[186:189], v[100:103]
	v_mfma_f32_16x16x32_bf16 v[96:99], v[170:173], v[186:189], v[96:99]
	v_mfma_f32_16x16x32_bf16 v[84:87], v[162:165], v[194:197], v[84:87]
	v_mfma_f32_16x16x32_bf16 v[80:83], v[170:173], v[194:197], v[80:83]
	v_mfma_f32_16x16x32_bf16 v[68:71], v[162:165], v[202:205], v[68:71]
	v_mfma_f32_16x16x32_bf16 v[64:67], v[170:173], v[202:205], v[64:67]
	v_mfma_f32_16x16x32_bf16 v[132:135], v[166:169], v[182:185], v[132:135]
	v_mfma_f32_16x16x32_bf16 v[128:131], v[174:177], v[182:185], v[128:131]
	v_mfma_f32_16x16x32_bf16 v[100:103], v[166:169], v[190:193], v[100:103]
	v_mfma_f32_16x16x32_bf16 v[96:99], v[174:177], v[190:193], v[96:99]
	v_mfma_f32_16x16x32_bf16 v[84:87], v[166:169], v[198:201], v[84:87]
	v_mfma_f32_16x16x32_bf16 v[80:83], v[174:177], v[198:201], v[80:83]
	v_mfma_f32_16x16x32_bf16 v[68:71], v[166:169], v[214:217], v[68:71]
	v_mfma_f32_16x16x32_bf16 v[64:67], v[174:177], v[214:217], v[64:67]
	s_setprio 0
	s_barrier
	s_add_i32 s57, s57, s42
	v_lshl_add_u64 v[206:207], s[30:31], 0, v[208:209]
	s_mov_b32 m0, s57
	ds_read_b128 v[178:181], v161 offset:16384
	ds_read_b128 v[182:185], v161 offset:17408
	ds_read_b128 v[186:189], v161 offset:18432
	ds_read_b128 v[190:193], v161 offset:19456
	ds_read_b128 v[194:197], v161 offset:20480
	ds_read_b128 v[198:201], v161 offset:21504
	ds_read_b128 v[202:205], v161 offset:22528
	ds_read_b128 v[214:217], v161 offset:23552
	global_load_lds_dwordx4 v[206:207], off
	s_add_i32 m0, s57, 0x2000
	s_add_u32 s58, s30, 0x80000
	v_lshl_add_u64 v[210:211], s[30:31], 0, v[144:145]
	s_addc_u32 s59, s31, 0
	s_add_i32 s57, s33, s42
	global_load_lds_dwordx4 v[210:211], off
	v_lshl_add_u64 v[212:213], s[58:59], 0, v[208:209]
	s_mov_b32 m0, s57
	v_lshl_add_u64 v[218:219], s[34:35], 0, v[146:147]
	global_load_lds_dwordx4 v[212:213], off
	v_lshl_add_u64 v[212:213], s[58:59], 0, v[144:145]
	s_add_i32 m0, s57, 0x2000
	s_nop 0
	global_load_lds_dwordx4 v[212:213], off
	v_lshl_add_u64 v[212:213], s[34:35], 0, v[148:149]
	s_mov_b32 m0, s27
	s_nop 0
	global_load_lds_dwordx4 v[212:213], off
	s_mov_b32 m0, s44
	s_nop 0
	global_load_lds_dwordx4 v[218:219], off
	s_waitcnt vmcnt(8)
	s_waitcnt lgkmcnt(0)
	s_barrier
	s_setprio 1
	s_waitcnt lgkmcnt(0)
	v_mfma_f32_16x16x32_bf16 v[60:63], v[112:115], v[178:181], v[60:63]
	v_mfma_f32_16x16x32_bf16 v[56:59], v[120:123], v[178:181], v[56:59]
	v_mfma_f32_16x16x32_bf16 v[44:47], v[112:115], v[186:189], v[44:47]
	v_mfma_f32_16x16x32_bf16 v[40:43], v[120:123], v[186:189], v[40:43]
	v_mfma_f32_16x16x32_bf16 v[28:31], v[112:115], v[194:197], v[28:31]
	v_mfma_f32_16x16x32_bf16 v[24:27], v[120:123], v[194:197], v[24:27]
	v_mfma_f32_16x16x32_bf16 v[12:15], v[112:115], v[202:205], v[12:15]
	v_mfma_f32_16x16x32_bf16 v[8:11], v[120:123], v[202:205], v[8:11]
	v_mfma_f32_16x16x32_bf16 v[60:63], v[116:119], v[182:185], v[60:63]
	v_mfma_f32_16x16x32_bf16 v[56:59], v[124:127], v[182:185], v[56:59]
	v_mfma_f32_16x16x32_bf16 v[44:47], v[116:119], v[190:193], v[44:47]
	v_mfma_f32_16x16x32_bf16 v[40:43], v[124:127], v[190:193], v[40:43]
	v_mfma_f32_16x16x32_bf16 v[28:31], v[116:119], v[198:201], v[28:31]
	v_mfma_f32_16x16x32_bf16 v[24:27], v[124:127], v[198:201], v[24:27]
	v_mfma_f32_16x16x32_bf16 v[12:15], v[116:119], v[214:217], v[12:15]
	v_mfma_f32_16x16x32_bf16 v[8:11], v[124:127], v[214:217], v[8:11]
	s_setprio 0
	s_setprio 1
	v_mfma_f32_16x16x32_bf16 v[52:55], v[162:165], v[178:181], v[52:55]
	v_mfma_f32_16x16x32_bf16 v[48:51], v[170:173], v[178:181], v[48:51]
	v_mfma_f32_16x16x32_bf16 v[36:39], v[162:165], v[186:189], v[36:39]
	v_mfma_f32_16x16x32_bf16 v[32:35], v[170:173], v[186:189], v[32:35]
	v_mfma_f32_16x16x32_bf16 v[20:23], v[162:165], v[194:197], v[20:23]
	v_mfma_f32_16x16x32_bf16 v[16:19], v[170:173], v[194:197], v[16:19]
	v_mfma_f32_16x16x32_bf16 v[4:7], v[162:165], v[202:205], v[4:7]
	v_mfma_f32_16x16x32_bf16 v[0:3], v[170:173], v[202:205], v[0:3]
	v_mfma_f32_16x16x32_bf16 v[52:55], v[166:169], v[182:185], v[52:55]
	v_mfma_f32_16x16x32_bf16 v[48:51], v[174:177], v[182:185], v[48:51]
	v_mfma_f32_16x16x32_bf16 v[36:39], v[166:169], v[190:193], v[36:39]
	v_mfma_f32_16x16x32_bf16 v[32:35], v[174:177], v[190:193], v[32:35]
	v_mfma_f32_16x16x32_bf16 v[20:23], v[166:169], v[198:201], v[20:23]
	v_mfma_f32_16x16x32_bf16 v[16:19], v[174:177], v[198:201], v[16:19]
	v_mfma_f32_16x16x32_bf16 v[4:7], v[166:169], v[214:217], v[4:7]
	v_mfma_f32_16x16x32_bf16 v[0:3], v[174:177], v[214:217], v[0:3]
	s_setprio 0
	s_barrier
	s_add_i32 s57, 0, 0x18000
	s_add_i32 s58, 0, 0x1c000
	v_add_u32_e32 v124, s57, v157
	v_add_u32_e32 v154, s58, v157
	ds_read_b128 v[112:115], v124
	ds_read_b128 v[116:119], v124 offset:1024
	ds_read_b128 v[120:123], v124 offset:2048
	ds_read_b128 v[124:127], v124 offset:3072
	ds_read_b128 v[162:165], v154
	ds_read_b128 v[166:169], v154 offset:1024
	ds_read_b128 v[170:173], v154 offset:2048
	ds_read_b128 v[174:177], v154 offset:3072
	s_add_u32 s34, s34, 0x80000
	s_addc_u32 s35, s35, 0
	s_mov_b32 m0, s45
	v_lshl_add_u64 v[220:221], s[34:35], 0, v[148:149]
	ds_read_b128 v[178:181], v161 offset:32768
	ds_read_b128 v[182:185], v161 offset:33792
	ds_read_b128 v[186:189], v161 offset:34816
	ds_read_b128 v[190:193], v161 offset:35840
	ds_read_b128 v[194:197], v161 offset:36864
	ds_read_b128 v[198:201], v161 offset:37888
	ds_read_b128 v[202:205], v161 offset:38912
	ds_read_b128 v[214:217], v161 offset:39936
	global_load_lds_dwordx4 v[220:221], off
	v_lshl_add_u64 v[220:221], s[34:35], 0, v[146:147]
	s_mov_b32 m0, s46
	s_nop 0
	global_load_lds_dwordx4 v[220:221], off
	s_waitcnt vmcnt(8)
	s_waitcnt lgkmcnt(0)
	s_barrier
	s_setprio 1
	s_waitcnt lgkmcnt(0)
	v_mfma_f32_16x16x32_bf16 v[140:143], v[112:115], v[178:181], v[140:143]
	v_mfma_f32_16x16x32_bf16 v[136:139], v[120:123], v[178:181], v[136:139]
	v_mfma_f32_16x16x32_bf16 v[108:111], v[112:115], v[186:189], v[108:111]
	v_mfma_f32_16x16x32_bf16 v[104:107], v[120:123], v[186:189], v[104:107]
	v_mfma_f32_16x16x32_bf16 v[92:95], v[112:115], v[194:197], v[92:95]
	v_mfma_f32_16x16x32_bf16 v[88:91], v[120:123], v[194:197], v[88:91]
	v_mfma_f32_16x16x32_bf16 v[76:79], v[112:115], v[202:205], v[76:79]
	v_mfma_f32_16x16x32_bf16 v[72:75], v[120:123], v[202:205], v[72:75]
	v_mfma_f32_16x16x32_bf16 v[140:143], v[116:119], v[182:185], v[140:143]
	v_mfma_f32_16x16x32_bf16 v[136:139], v[124:127], v[182:185], v[136:139]
	v_mfma_f32_16x16x32_bf16 v[108:111], v[116:119], v[190:193], v[108:111]
	v_mfma_f32_16x16x32_bf16 v[104:107], v[124:127], v[190:193], v[104:107]
	v_mfma_f32_16x16x32_bf16 v[92:95], v[116:119], v[198:201], v[92:95]
	v_mfma_f32_16x16x32_bf16 v[88:91], v[124:127], v[198:201], v[88:91]
	v_mfma_f32_16x16x32_bf16 v[76:79], v[116:119], v[214:217], v[76:79]
	v_mfma_f32_16x16x32_bf16 v[72:75], v[124:127], v[214:217], v[72:75]
	s_setprio 0
	s_setprio 1
	v_mfma_f32_16x16x32_bf16 v[132:135], v[162:165], v[178:181], v[132:135]
	v_mfma_f32_16x16x32_bf16 v[128:131], v[170:173], v[178:181], v[128:131]
	v_mfma_f32_16x16x32_bf16 v[100:103], v[162:165], v[186:189], v[100:103]
	v_mfma_f32_16x16x32_bf16 v[96:99], v[170:173], v[186:189], v[96:99]
	v_mfma_f32_16x16x32_bf16 v[84:87], v[162:165], v[194:197], v[84:87]
	v_mfma_f32_16x16x32_bf16 v[80:83], v[170:173], v[194:197], v[80:83]
	v_mfma_f32_16x16x32_bf16 v[68:71], v[162:165], v[202:205], v[68:71]
	v_mfma_f32_16x16x32_bf16 v[64:67], v[170:173], v[202:205], v[64:67]
	v_mfma_f32_16x16x32_bf16 v[132:135], v[166:169], v[182:185], v[132:135]
	v_mfma_f32_16x16x32_bf16 v[128:131], v[174:177], v[182:185], v[128:131]
	v_mfma_f32_16x16x32_bf16 v[100:103], v[166:169], v[190:193], v[100:103]
	v_mfma_f32_16x16x32_bf16 v[96:99], v[174:177], v[190:193], v[96:99]
	v_mfma_f32_16x16x32_bf16 v[84:87], v[166:169], v[198:201], v[84:87]
	v_mfma_f32_16x16x32_bf16 v[80:83], v[174:177], v[198:201], v[80:83]
	v_mfma_f32_16x16x32_bf16 v[68:71], v[166:169], v[214:217], v[68:71]
	v_mfma_f32_16x16x32_bf16 v[64:67], v[174:177], v[214:217], v[64:67]
	s_setprio 0
	s_barrier
	s_add_i32 s34, s57, s42
	v_lshl_add_u64 v[206:207], v[206:207], 0, s[2:3]
	s_mov_b32 m0, s34
	ds_read_b128 v[178:181], v161 offset:49152
	ds_read_b128 v[182:185], v161 offset:50176
	ds_read_b128 v[186:189], v161 offset:51200
	ds_read_b128 v[190:193], v161 offset:52224
	ds_read_b128 v[194:197], v161 offset:53248
	ds_read_b128 v[198:201], v161 offset:54272
	ds_read_b128 v[202:205], v161 offset:55296
	ds_read_b128 v[214:217], v161 offset:56320
	global_load_lds_dwordx4 v[206:207], off
	s_add_i32 m0, s34, 0x2000
	s_add_u32 s30, s30, 0x80080
	v_lshl_add_u64 v[206:207], v[210:211], 0, s[2:3]
	s_addc_u32 s31, s31, 0
	s_add_i32 s34, s58, s42
	global_load_lds_dwordx4 v[206:207], off
	v_lshl_add_u64 v[206:207], s[30:31], 0, v[208:209]
	s_mov_b32 m0, s34
	s_nop 0
	global_load_lds_dwordx4 v[206:207], off
	v_lshl_add_u64 v[206:207], s[30:31], 0, v[144:145]
	s_add_i32 m0, s34, 0x2000
	s_nop 0
	global_load_lds_dwordx4 v[206:207], off
	v_lshl_add_u64 v[206:207], v[212:213], 0, s[2:3]
	s_mov_b32 m0, s49
	s_nop 0
	global_load_lds_dwordx4 v[206:207], off
	v_lshl_add_u64 v[206:207], v[218:219], 0, s[2:3]
	s_mov_b32 m0, s50
	s_nop 0
	global_load_lds_dwordx4 v[206:207], off
	s_waitcnt vmcnt(8)
	s_waitcnt lgkmcnt(0)
	s_barrier
	s_setprio 1
	s_waitcnt lgkmcnt(0)
	v_mfma_f32_16x16x32_bf16 v[60:63], v[112:115], v[178:181], v[60:63]
	v_mfma_f32_16x16x32_bf16 v[56:59], v[120:123], v[178:181], v[56:59]
	v_mfma_f32_16x16x32_bf16 v[44:47], v[112:115], v[186:189], v[44:47]
	v_mfma_f32_16x16x32_bf16 v[40:43], v[120:123], v[186:189], v[40:43]
	v_mfma_f32_16x16x32_bf16 v[28:31], v[112:115], v[194:197], v[28:31]
	v_mfma_f32_16x16x32_bf16 v[24:27], v[120:123], v[194:197], v[24:27]
	v_mfma_f32_16x16x32_bf16 v[12:15], v[112:115], v[202:205], v[12:15]
	v_mfma_f32_16x16x32_bf16 v[8:11], v[120:123], v[202:205], v[8:11]
	v_mfma_f32_16x16x32_bf16 v[60:63], v[116:119], v[182:185], v[60:63]
	v_mfma_f32_16x16x32_bf16 v[56:59], v[124:127], v[182:185], v[56:59]
	v_mfma_f32_16x16x32_bf16 v[44:47], v[116:119], v[190:193], v[44:47]
	v_mfma_f32_16x16x32_bf16 v[40:43], v[124:127], v[190:193], v[40:43]
	v_mfma_f32_16x16x32_bf16 v[28:31], v[116:119], v[198:201], v[28:31]
	v_mfma_f32_16x16x32_bf16 v[24:27], v[124:127], v[198:201], v[24:27]
	v_mfma_f32_16x16x32_bf16 v[12:15], v[116:119], v[214:217], v[12:15]
	v_mfma_f32_16x16x32_bf16 v[8:11], v[124:127], v[214:217], v[8:11]
	s_setprio 0
	s_setprio 1
	v_mfma_f32_16x16x32_bf16 v[52:55], v[162:165], v[178:181], v[52:55]
	v_mfma_f32_16x16x32_bf16 v[48:51], v[170:173], v[178:181], v[48:51]
	v_mfma_f32_16x16x32_bf16 v[36:39], v[162:165], v[186:189], v[36:39]
	v_mfma_f32_16x16x32_bf16 v[32:35], v[170:173], v[186:189], v[32:35]
	v_mfma_f32_16x16x32_bf16 v[20:23], v[162:165], v[194:197], v[20:23]
	v_mfma_f32_16x16x32_bf16 v[16:19], v[170:173], v[194:197], v[16:19]
	v_mfma_f32_16x16x32_bf16 v[4:7], v[162:165], v[202:205], v[4:7]
	v_mfma_f32_16x16x32_bf16 v[0:3], v[170:173], v[202:205], v[0:3]
	v_mfma_f32_16x16x32_bf16 v[52:55], v[166:169], v[182:185], v[52:55]
	v_mfma_f32_16x16x32_bf16 v[48:51], v[174:177], v[182:185], v[48:51]
	v_mfma_f32_16x16x32_bf16 v[36:39], v[166:169], v[190:193], v[36:39]
	v_mfma_f32_16x16x32_bf16 v[32:35], v[174:177], v[190:193], v[32:35]
	v_mfma_f32_16x16x32_bf16 v[20:23], v[166:169], v[198:201], v[20:23]
	v_mfma_f32_16x16x32_bf16 v[16:19], v[174:177], v[198:201], v[16:19]
	v_mfma_f32_16x16x32_bf16 v[4:7], v[166:169], v[214:217], v[4:7]
	v_mfma_f32_16x16x32_bf16 v[0:3], v[174:177], v[214:217], v[0:3]
	s_setprio 0
	s_barrier
	s_add_i32 s56, s56, 2
	s_add_u32 s28, s28, 0x100
	s_addc_u32 s29, s29, 0
	s_add_u32 s54, s54, 0x100
	s_addc_u32 s55, s55, 0
	s_cmp_gt_u32 s56, 29
	s_cbranch_scc0 .LBB0_1479
	s_ashr_i32 s28, s24, 5
	s_ashr_i32 s29, s28, 31
	s_lshl_b64 s[28:29], s[28:29], 13
	s_cmpk_lt_i32 s24, 0x80
	s_cselect_b32 s29, s29, 0
	s_cselect_b32 s28, s28, 0x8000
	s_lshl_b64 s[28:29], s[28:29], 2
	v_lshl_or_b32 v174, s26, 8, v159
	s_add_u32 s28, s47, s28
	v_lshl_add_u32 v176, s24, 8, v155
	s_addc_u32 s29, s48, s29
	v_ashrrev_i32_e32 v175, 31, v174
	v_ashrrev_i32_e32 v177, 31, v176
	v_lshl_add_u64 v[116:117], v[174:175], 2, s[28:29]
	v_lshl_add_u64 v[178:179], v[176:177], 2, s[12:13]
	global_load_dwordx4 v[120:123], v[116:117], off offset:16
	global_load_dwordx4 v[124:127], v[116:117], off
	global_load_dwordx4 v[112:115], v[116:117], off offset:528
	s_nop 0
	global_load_dwordx4 v[116:119], v[116:117], off offset:512
	v_or_b32_e32 v172, 16, v176
	global_load_dword v180, v[178:179], off
	v_ashrrev_i32_e32 v173, 31, v172
	v_lshl_add_u64 v[162:163], v[172:173], 2, s[12:13]
	global_load_dword v170, v[162:163], off
	v_or_b32_e32 v168, 32, v176
	v_ashrrev_i32_e32 v169, 31, v168
	v_lshl_add_u64 v[162:163], v[168:169], 2, s[12:13]
	global_load_dword v166, v[162:163], off
	v_or_b32_e32 v164, 48, v176
	v_ashrrev_i32_e32 v165, 31, v164
	v_lshl_add_u64 v[162:163], v[164:165], 2, s[12:13]
	global_load_dword v162, v[162:163], off
	s_nop 0
	global_load_dword v160, v[178:179], off offset:512
	global_load_dword v158, v[178:179], off offset:576
	global_load_dword v156, v[178:179], off offset:640
	global_load_dword v154, v[178:179], off offset:704
	s_and_b64 vcc, exec, s[14:15]
	s_cbranch_vccz .LBB0_1482
	s_barrier
.LBB0_1482:
	v_lshlrev_b64 v[176:177], 14, v[176:177]
	s_mov_b64 s[24:25], 0x200000
	v_readlane_b32 s58, v254, 51
	s_waitcnt vmcnt(0)
	v_pk_fma_f32 v[142:143], v[142:143], v[180:181], v[126:127] op_sel_hi:[1,0,1]
	v_pk_fma_f32 v[140:141], v[140:141], v[180:181], v[124:125] op_sel_hi:[1,0,1]
	v_pk_fma_f32 v[138:139], v[138:139], v[180:181], v[122:123] op_sel_hi:[1,0,1]
	v_pk_fma_f32 v[136:137], v[136:137], v[180:181], v[120:121] op_sel_hi:[1,0,1]
	v_max_f32_e32 v143, 0, v143
	v_max_f32_e32 v142, 0, v142
	v_max_f32_e32 v141, 0, v141
	v_max_f32_e32 v140, 0, v140
	v_max_f32_e32 v139, 0, v139
	v_max_f32_e32 v138, 0, v138
	v_max_f32_e32 v137, 0, v137
	v_max_f32_e32 v136, 0, v136
	v_pk_mul_f32 v[142:143], v[142:143], v[142:143]
	v_pk_mul_f32 v[140:141], v[140:141], v[140:141]
	v_pk_mul_f32 v[138:139], v[138:139], v[138:139]
	v_pk_mul_f32 v[136:137], v[136:137], v[136:137]
	v_cvt_pk_bf16_f32 v140, v140, v141
	v_cvt_pk_bf16_f32 v141, v142, v143
	v_cvt_pk_bf16_f32 v142, v136, v137
	v_cvt_pk_bf16_f32 v143, v138, v139
	v_lshl_add_u64 v[136:137], s[10:11], 0, v[176:177]
	v_lshlrev_b64 v[138:139], 1, v[174:175]
	v_pk_fma_f32 v[134:135], v[134:135], v[180:181], v[118:119] op_sel_hi:[1,0,1]
	v_pk_fma_f32 v[132:133], v[132:133], v[180:181], v[116:117] op_sel_hi:[1,0,1]
	v_pk_fma_f32 v[130:131], v[130:131], v[180:181], v[114:115] op_sel_hi:[1,0,1]
	v_pk_fma_f32 v[128:129], v[128:129], v[180:181], v[112:113] op_sel_hi:[1,0,1]
	v_lshl_add_u64 v[136:137], v[136:137], 0, v[138:139]
	v_max_f32_e32 v135, 0, v135
	v_max_f32_e32 v134, 0, v134
	v_max_f32_e32 v133, 0, v133
	v_max_f32_e32 v132, 0, v132
	v_max_f32_e32 v131, 0, v131
	v_max_f32_e32 v130, 0, v130
	v_max_f32_e32 v129, 0, v129
	v_max_f32_e32 v128, 0, v128
	global_store_dwordx4 v[136:137], v[140:143], off
	v_pk_mul_f32 v[134:135], v[134:135], v[134:135]
	v_pk_mul_f32 v[132:133], v[132:133], v[132:133]
	v_pk_mul_f32 v[140:141], v[130:131], v[130:131]
	v_pk_mul_f32 v[130:131], v[128:129], v[128:129]
	v_pk_fma_f32 v[108:109], v[108:109], v[170:171], v[124:125] op_sel_hi:[1,0,1]
	v_cvt_pk_bf16_f32 v128, v132, v133
	v_cvt_pk_bf16_f32 v129, v134, v135
	v_cvt_pk_bf16_f32 v130, v130, v131
	v_cvt_pk_bf16_f32 v131, v140, v141
	v_pk_fma_f32 v[110:111], v[110:111], v[170:171], v[126:127] op_sel_hi:[1,0,1]
	v_pk_fma_f32 v[106:107], v[106:107], v[170:171], v[122:123] op_sel_hi:[1,0,1]
	v_pk_fma_f32 v[104:105], v[104:105], v[170:171], v[120:121] op_sel_hi:[1,0,1]
	v_max_f32_e32 v109, 0, v109
	v_max_f32_e32 v108, 0, v108
	global_store_dwordx4 v[136:137], v[128:131], off offset:256
	v_max_f32_e32 v111, 0, v111
	v_max_f32_e32 v110, 0, v110
	v_lshlrev_b64 v[128:129], 14, v[172:173]
	v_max_f32_e32 v107, 0, v107
	v_max_f32_e32 v106, 0, v106
	v_max_f32_e32 v105, 0, v105
	v_max_f32_e32 v104, 0, v104
	v_pk_mul_f32 v[108:109], v[108:109], v[108:109]
	v_pk_mul_f32 v[110:111], v[110:111], v[110:111]
	v_pk_mul_f32 v[130:131], v[106:107], v[106:107]
	v_pk_mul_f32 v[106:107], v[104:105], v[104:105]
	v_cvt_pk_bf16_f32 v104, v108, v109
	v_lshl_add_u64 v[108:109], s[10:11], 0, v[128:129]
	v_pk_fma_f32 v[102:103], v[102:103], v[170:171], v[118:119] op_sel_hi:[1,0,1]
	v_pk_fma_f32 v[100:101], v[100:101], v[170:171], v[116:117] op_sel_hi:[1,0,1]
	v_pk_fma_f32 v[98:99], v[98:99], v[170:171], v[114:115] op_sel_hi:[1,0,1]
	v_pk_fma_f32 v[96:97], v[96:97], v[170:171], v[112:113] op_sel_hi:[1,0,1]
	v_cvt_pk_bf16_f32 v105, v110, v111
	v_cvt_pk_bf16_f32 v106, v106, v107
	v_cvt_pk_bf16_f32 v107, v130, v131
	v_lshl_add_u64 v[108:109], v[108:109], 0, v[138:139]
	v_max_f32_e32 v103, 0, v103
	v_max_f32_e32 v102, 0, v102
	v_max_f32_e32 v101, 0, v101
	v_max_f32_e32 v100, 0, v100
	v_max_f32_e32 v99, 0, v99
	v_max_f32_e32 v98, 0, v98
	v_max_f32_e32 v97, 0, v97
	v_max_f32_e32 v96, 0, v96
	global_store_dwordx4 v[108:109], v[104:107], off
	v_pk_mul_f32 v[102:103], v[102:103], v[102:103]
	v_pk_mul_f32 v[100:101], v[100:101], v[100:101]
	v_pk_mul_f32 v[104:105], v[98:99], v[98:99]
	v_pk_mul_f32 v[98:99], v[96:97], v[96:97]
	v_pk_fma_f32 v[92:93], v[92:93], v[166:167], v[124:125] op_sel_hi:[1,0,1]
	v_cvt_pk_bf16_f32 v96, v100, v101
	v_cvt_pk_bf16_f32 v97, v102, v103
	v_cvt_pk_bf16_f32 v98, v98, v99
	v_cvt_pk_bf16_f32 v99, v104, v105
	v_pk_fma_f32 v[94:95], v[94:95], v[166:167], v[126:127] op_sel_hi:[1,0,1]
	v_pk_fma_f32 v[90:91], v[90:91], v[166:167], v[122:123] op_sel_hi:[1,0,1]
	v_pk_fma_f32 v[88:89], v[88:89], v[166:167], v[120:121] op_sel_hi:[1,0,1]
	v_max_f32_e32 v93, 0, v93
	v_max_f32_e32 v92, 0, v92
	global_store_dwordx4 v[108:109], v[96:99], off offset:256
	v_max_f32_e32 v95, 0, v95
	v_max_f32_e32 v94, 0, v94
	v_lshlrev_b64 v[96:97], 14, v[168:169]
	v_max_f32_e32 v91, 0, v91
	v_max_f32_e32 v90, 0, v90
	v_max_f32_e32 v89, 0, v89
	v_max_f32_e32 v88, 0, v88
	v_pk_mul_f32 v[92:93], v[92:93], v[92:93]
	v_pk_mul_f32 v[94:95], v[94:95], v[94:95]
	v_pk_mul_f32 v[98:99], v[90:91], v[90:91]
	v_pk_mul_f32 v[90:91], v[88:89], v[88:89]
	v_cvt_pk_bf16_f32 v88, v92, v93
	v_lshl_add_u64 v[92:93], s[10:11], 0, v[96:97]
	v_pk_fma_f32 v[86:87], v[86:87], v[166:167], v[118:119] op_sel_hi:[1,0,1]
	v_pk_fma_f32 v[84:85], v[84:85], v[166:167], v[116:117] op_sel_hi:[1,0,1]
	v_pk_fma_f32 v[82:83], v[82:83], v[166:167], v[114:115] op_sel_hi:[1,0,1]
	v_pk_fma_f32 v[80:81], v[80:81], v[166:167], v[112:113] op_sel_hi:[1,0,1]
	v_cvt_pk_bf16_f32 v89, v94, v95
	v_cvt_pk_bf16_f32 v90, v90, v91
	v_cvt_pk_bf16_f32 v91, v98, v99
	v_lshl_add_u64 v[92:93], v[92:93], 0, v[138:139]
	v_max_f32_e32 v87, 0, v87
	v_max_f32_e32 v86, 0, v86
	v_max_f32_e32 v85, 0, v85
	v_max_f32_e32 v84, 0, v84
	v_max_f32_e32 v83, 0, v83
	v_max_f32_e32 v82, 0, v82
	v_max_f32_e32 v81, 0, v81
	v_max_f32_e32 v80, 0, v80
	global_store_dwordx4 v[92:93], v[88:91], off
	v_pk_mul_f32 v[86:87], v[86:87], v[86:87]
	v_pk_mul_f32 v[84:85], v[84:85], v[84:85]
	v_pk_mul_f32 v[88:89], v[82:83], v[82:83]
	v_pk_mul_f32 v[82:83], v[80:81], v[80:81]
	v_pk_fma_f32 v[76:77], v[76:77], v[162:163], v[124:125] op_sel_hi:[1,0,1]
	v_cvt_pk_bf16_f32 v80, v84, v85
	v_cvt_pk_bf16_f32 v81, v86, v87
	v_cvt_pk_bf16_f32 v82, v82, v83
	v_cvt_pk_bf16_f32 v83, v88, v89
	v_pk_fma_f32 v[78:79], v[78:79], v[162:163], v[126:127] op_sel_hi:[1,0,1]
	v_pk_fma_f32 v[74:75], v[74:75], v[162:163], v[122:123] op_sel_hi:[1,0,1]
	v_pk_fma_f32 v[72:73], v[72:73], v[162:163], v[120:121] op_sel_hi:[1,0,1]
	v_max_f32_e32 v77, 0, v77
	v_max_f32_e32 v76, 0, v76
	global_store_dwordx4 v[92:93], v[80:83], off offset:256
	v_max_f32_e32 v79, 0, v79
	v_max_f32_e32 v78, 0, v78
	v_lshlrev_b64 v[80:81], 14, v[164:165]
	v_max_f32_e32 v75, 0, v75
	v_max_f32_e32 v74, 0, v74
	v_max_f32_e32 v73, 0, v73
	v_max_f32_e32 v72, 0, v72
	v_pk_mul_f32 v[76:77], v[76:77], v[76:77]
	v_pk_mul_f32 v[78:79], v[78:79], v[78:79]
	v_pk_mul_f32 v[82:83], v[74:75], v[74:75]
	v_pk_mul_f32 v[74:75], v[72:73], v[72:73]
	v_cvt_pk_bf16_f32 v72, v76, v77
	v_lshl_add_u64 v[76:77], s[10:11], 0, v[80:81]
	v_pk_fma_f32 v[70:71], v[70:71], v[162:163], v[118:119] op_sel_hi:[1,0,1]
	v_pk_fma_f32 v[68:69], v[68:69], v[162:163], v[116:117] op_sel_hi:[1,0,1]
	v_pk_fma_f32 v[66:67], v[66:67], v[162:163], v[114:115] op_sel_hi:[1,0,1]
	v_pk_fma_f32 v[64:65], v[64:65], v[162:163], v[112:113] op_sel_hi:[1,0,1]
	v_cvt_pk_bf16_f32 v73, v78, v79
	v_cvt_pk_bf16_f32 v74, v74, v75
	v_cvt_pk_bf16_f32 v75, v82, v83
	v_lshl_add_u64 v[76:77], v[76:77], 0, v[138:139]
	v_max_f32_e32 v71, 0, v71
	v_max_f32_e32 v70, 0, v70
	v_max_f32_e32 v69, 0, v69
	v_max_f32_e32 v68, 0, v68
	v_max_f32_e32 v67, 0, v67
	v_max_f32_e32 v66, 0, v66
	v_max_f32_e32 v65, 0, v65
	v_max_f32_e32 v64, 0, v64
	v_pk_fma_f32 v[62:63], v[62:63], v[160:161], v[126:127] op_sel_hi:[1,0,1]
	global_store_dwordx4 v[76:77], v[72:75], off
	v_pk_mul_f32 v[70:71], v[70:71], v[70:71]
	v_pk_mul_f32 v[68:69], v[68:69], v[68:69]
	v_pk_mul_f32 v[72:73], v[66:67], v[66:67]
	v_pk_mul_f32 v[66:67], v[64:65], v[64:65]
	v_pk_fma_f32 v[60:61], v[60:61], v[160:161], v[124:125] op_sel_hi:[1,0,1]
	v_pk_fma_f32 v[58:59], v[58:59], v[160:161], v[122:123] op_sel_hi:[1,0,1]
	v_pk_fma_f32 v[56:57], v[56:57], v[160:161], v[120:121] op_sel_hi:[1,0,1]
	v_max_f32_e32 v63, 0, v63
	v_max_f32_e32 v62, 0, v62
	v_cvt_pk_bf16_f32 v64, v68, v69
	v_cvt_pk_bf16_f32 v65, v70, v71
	v_cvt_pk_bf16_f32 v66, v66, v67
	v_cvt_pk_bf16_f32 v67, v72, v73
	v_max_f32_e32 v61, 0, v61
	v_max_f32_e32 v60, 0, v60
	v_max_f32_e32 v59, 0, v59
	v_max_f32_e32 v58, 0, v58
	v_max_f32_e32 v57, 0, v57
	v_max_f32_e32 v56, 0, v56
	v_pk_mul_f32 v[62:63], v[62:63], v[62:63]
	global_store_dwordx4 v[76:77], v[64:67], off offset:256
	v_pk_mul_f32 v[60:61], v[60:61], v[60:61]
	v_pk_fma_f32 v[54:55], v[54:55], v[160:161], v[118:119] op_sel_hi:[1,0,1]
	v_pk_mul_f32 v[64:65], v[58:59], v[58:59]
	v_pk_mul_f32 v[58:59], v[56:57], v[56:57]
	v_cvt_pk_bf16_f32 v57, v62, v63
	v_add_co_u32_e32 v62, vcc, s78, v136
	v_pk_fma_f32 v[52:53], v[52:53], v[160:161], v[116:117] op_sel_hi:[1,0,1]
	v_pk_fma_f32 v[50:51], v[50:51], v[160:161], v[114:115] op_sel_hi:[1,0,1]
	v_pk_fma_f32 v[48:49], v[48:49], v[160:161], v[112:113] op_sel_hi:[1,0,1]
	v_cvt_pk_bf16_f32 v56, v60, v61
	v_cvt_pk_bf16_f32 v58, v58, v59
	v_cvt_pk_bf16_f32 v59, v64, v65
	v_addc_co_u32_e32 v63, vcc, 0, v137, vcc
	v_max_f32_e32 v55, 0, v55
	v_max_f32_e32 v54, 0, v54
	v_max_f32_e32 v53, 0, v53
	v_max_f32_e32 v52, 0, v52
	v_max_f32_e32 v51, 0, v51
	v_max_f32_e32 v50, 0, v50
	v_max_f32_e32 v49, 0, v49
	v_max_f32_e32 v48, 0, v48
	v_pk_fma_f32 v[46:47], v[46:47], v[158:159], v[126:127] op_sel_hi:[1,0,1]
	global_store_dwordx4 v[62:63], v[56:59], off
	v_pk_mul_f32 v[54:55], v[54:55], v[54:55]
	v_pk_mul_f32 v[52:53], v[52:53], v[52:53]
	v_pk_mul_f32 v[56:57], v[50:51], v[50:51]
	v_pk_mul_f32 v[50:51], v[48:49], v[48:49]
	v_pk_fma_f32 v[44:45], v[44:45], v[158:159], v[124:125] op_sel_hi:[1,0,1]
	v_pk_fma_f32 v[42:43], v[42:43], v[158:159], v[122:123] op_sel_hi:[1,0,1]
	v_pk_fma_f32 v[40:41], v[40:41], v[158:159], v[120:121] op_sel_hi:[1,0,1]
	v_max_f32_e32 v47, 0, v47
	v_max_f32_e32 v46, 0, v46
	v_lshl_add_u64 v[60:61], v[136:137], 0, s[24:25]
	v_cvt_pk_bf16_f32 v48, v52, v53
	v_cvt_pk_bf16_f32 v49, v54, v55
	v_cvt_pk_bf16_f32 v50, v50, v51
	v_cvt_pk_bf16_f32 v51, v56, v57
	v_max_f32_e32 v45, 0, v45
	v_max_f32_e32 v44, 0, v44
	v_max_f32_e32 v43, 0, v43
	v_max_f32_e32 v42, 0, v42
	v_max_f32_e32 v41, 0, v41
	v_max_f32_e32 v40, 0, v40
	v_pk_mul_f32 v[46:47], v[46:47], v[46:47]
	global_store_dwordx4 v[60:61], v[48:51], off offset:256
	v_pk_mul_f32 v[44:45], v[44:45], v[44:45]
	v_pk_fma_f32 v[38:39], v[38:39], v[158:159], v[118:119] op_sel_hi:[1,0,1]
	v_pk_mul_f32 v[48:49], v[42:43], v[42:43]
	v_pk_mul_f32 v[42:43], v[40:41], v[40:41]
	v_cvt_pk_bf16_f32 v41, v46, v47
	v_add_co_u32_e32 v46, vcc, s74, v136
	v_pk_fma_f32 v[36:37], v[36:37], v[158:159], v[116:117] op_sel_hi:[1,0,1]
	v_pk_fma_f32 v[34:35], v[34:35], v[158:159], v[114:115] op_sel_hi:[1,0,1]
	v_pk_fma_f32 v[32:33], v[32:33], v[158:159], v[112:113] op_sel_hi:[1,0,1]
	v_cvt_pk_bf16_f32 v40, v44, v45
	v_cvt_pk_bf16_f32 v42, v42, v43
	v_cvt_pk_bf16_f32 v43, v48, v49
	v_addc_co_u32_e32 v47, vcc, 0, v137, vcc
	v_max_f32_e32 v39, 0, v39
	v_max_f32_e32 v38, 0, v38
	v_max_f32_e32 v37, 0, v37
	v_max_f32_e32 v36, 0, v36
	v_max_f32_e32 v35, 0, v35
	v_max_f32_e32 v34, 0, v34
	v_max_f32_e32 v33, 0, v33
	v_max_f32_e32 v32, 0, v32
	v_pk_fma_f32 v[30:31], v[30:31], v[156:157], v[126:127] op_sel_hi:[1,0,1]
	s_mov_b64 s[24:25], 0x240000
	global_store_dwordx4 v[46:47], v[40:43], off
	v_pk_mul_f32 v[38:39], v[38:39], v[38:39]
	v_pk_mul_f32 v[36:37], v[36:37], v[36:37]
	v_pk_mul_f32 v[40:41], v[34:35], v[34:35]
	v_pk_mul_f32 v[34:35], v[32:33], v[32:33]
	v_pk_fma_f32 v[28:29], v[28:29], v[156:157], v[124:125] op_sel_hi:[1,0,1]
	v_pk_fma_f32 v[26:27], v[26:27], v[156:157], v[122:123] op_sel_hi:[1,0,1]
	v_pk_fma_f32 v[24:25], v[24:25], v[156:157], v[120:121] op_sel_hi:[1,0,1]
	v_max_f32_e32 v31, 0, v31
	v_max_f32_e32 v30, 0, v30
	v_lshl_add_u64 v[44:45], v[136:137], 0, s[24:25]
	v_cvt_pk_bf16_f32 v32, v36, v37
	v_cvt_pk_bf16_f32 v33, v38, v39
	v_cvt_pk_bf16_f32 v34, v34, v35
	v_cvt_pk_bf16_f32 v35, v40, v41
	v_max_f32_e32 v29, 0, v29
	v_max_f32_e32 v28, 0, v28
	v_max_f32_e32 v27, 0, v27
	v_max_f32_e32 v26, 0, v26
	v_max_f32_e32 v25, 0, v25
	v_max_f32_e32 v24, 0, v24
	v_pk_mul_f32 v[30:31], v[30:31], v[30:31]
	global_store_dwordx4 v[44:45], v[32:35], off offset:256
	v_pk_mul_f32 v[28:29], v[28:29], v[28:29]
	v_pk_fma_f32 v[22:23], v[22:23], v[156:157], v[118:119] op_sel_hi:[1,0,1]
	v_pk_mul_f32 v[32:33], v[26:27], v[26:27]
	v_pk_mul_f32 v[26:27], v[24:25], v[24:25]
	v_cvt_pk_bf16_f32 v25, v30, v31
	v_add_co_u32_e32 v30, vcc, s71, v136
	v_pk_fma_f32 v[20:21], v[20:21], v[156:157], v[116:117] op_sel_hi:[1,0,1]
	v_pk_fma_f32 v[18:19], v[18:19], v[156:157], v[114:115] op_sel_hi:[1,0,1]
	v_pk_fma_f32 v[16:17], v[16:17], v[156:157], v[112:113] op_sel_hi:[1,0,1]
	v_cvt_pk_bf16_f32 v24, v28, v29
	v_cvt_pk_bf16_f32 v26, v26, v27
	v_cvt_pk_bf16_f32 v27, v32, v33
	v_addc_co_u32_e32 v31, vcc, 0, v137, vcc
	v_max_f32_e32 v23, 0, v23
	v_max_f32_e32 v22, 0, v22
	v_max_f32_e32 v21, 0, v21
	v_max_f32_e32 v20, 0, v20
	v_max_f32_e32 v19, 0, v19
	v_max_f32_e32 v18, 0, v18
	v_max_f32_e32 v17, 0, v17
	v_max_f32_e32 v16, 0, v16
	v_pk_fma_f32 v[14:15], v[14:15], v[154:155], v[126:127] op_sel_hi:[1,0,1]
	s_mov_b64 s[24:25], 0x280000
	global_store_dwordx4 v[30:31], v[24:27], off
	v_pk_mul_f32 v[22:23], v[22:23], v[22:23]
	v_pk_mul_f32 v[20:21], v[20:21], v[20:21]
	v_pk_mul_f32 v[24:25], v[18:19], v[18:19]
	v_pk_mul_f32 v[18:19], v[16:17], v[16:17]
	v_pk_fma_f32 v[12:13], v[12:13], v[154:155], v[124:125] op_sel_hi:[1,0,1]
	v_pk_fma_f32 v[10:11], v[10:11], v[154:155], v[122:123] op_sel_hi:[1,0,1]
	v_pk_fma_f32 v[8:9], v[8:9], v[154:155], v[120:121] op_sel_hi:[1,0,1]
	v_max_f32_e32 v15, 0, v15
	v_max_f32_e32 v14, 0, v14
	v_lshl_add_u64 v[28:29], v[136:137], 0, s[24:25]
	v_cvt_pk_bf16_f32 v16, v20, v21
	v_cvt_pk_bf16_f32 v17, v22, v23
	v_cvt_pk_bf16_f32 v18, v18, v19
	v_cvt_pk_bf16_f32 v19, v24, v25
	v_max_f32_e32 v13, 0, v13
	v_max_f32_e32 v12, 0, v12
	v_max_f32_e32 v11, 0, v11
	v_max_f32_e32 v10, 0, v10
	v_max_f32_e32 v9, 0, v9
	v_max_f32_e32 v8, 0, v8
	v_pk_mul_f32 v[14:15], v[14:15], v[14:15]
	global_store_dwordx4 v[28:29], v[16:19], off offset:256
	v_pk_mul_f32 v[12:13], v[12:13], v[12:13]
	v_pk_fma_f32 v[6:7], v[6:7], v[154:155], v[118:119] op_sel_hi:[1,0,1]
	v_pk_mul_f32 v[16:17], v[10:11], v[10:11]
	v_pk_mul_f32 v[10:11], v[8:9], v[8:9]
	v_cvt_pk_bf16_f32 v9, v14, v15
	v_add_co_u32_e32 v14, vcc, s72, v136
	v_pk_fma_f32 v[4:5], v[4:5], v[154:155], v[116:117] op_sel_hi:[1,0,1]
	v_pk_fma_f32 v[2:3], v[2:3], v[154:155], v[114:115] op_sel_hi:[1,0,1]
	v_pk_fma_f32 v[0:1], v[0:1], v[154:155], v[112:113] op_sel_hi:[1,0,1]
	v_cvt_pk_bf16_f32 v8, v12, v13
	v_cvt_pk_bf16_f32 v10, v10, v11
	v_cvt_pk_bf16_f32 v11, v16, v17
	v_addc_co_u32_e32 v15, vcc, 0, v137, vcc
	v_max_f32_e32 v7, 0, v7
	v_max_f32_e32 v6, 0, v6
	v_max_f32_e32 v5, 0, v5
	v_max_f32_e32 v4, 0, v4
	v_max_f32_e32 v3, 0, v3
	v_max_f32_e32 v2, 0, v2
	v_max_f32_e32 v1, 0, v1
	v_max_f32_e32 v0, 0, v0
	s_mov_b64 s[24:25], 0x2c0000
	global_store_dwordx4 v[14:15], v[8:11], off
	v_pk_mul_f32 v[6:7], v[6:7], v[6:7]
	v_pk_mul_f32 v[4:5], v[4:5], v[4:5]
	v_pk_mul_f32 v[8:9], v[2:3], v[2:3]
	v_pk_mul_f32 v[2:3], v[0:1], v[0:1]
	v_lshl_add_u64 v[12:13], v[136:137], 0, s[24:25]
	v_cvt_pk_bf16_f32 v0, v4, v5
	v_cvt_pk_bf16_f32 v1, v6, v7
	v_cvt_pk_bf16_f32 v2, v2, v3
	v_cvt_pk_bf16_f32 v3, v8, v9
	s_mov_b64 s[24:25], -1
	s_andn2_b64 vcc, exec, s[0:1]
	global_store_dwordx4 v[12:13], v[0:3], off offset:256
	s_cbranch_vccnz .LBB0_1475
	s_andn2_b64 vcc, exec, s[6:7]
	s_cbranch_vccnz .LBB0_1474
	s_mov_b32 s100, 1
	s_branch .LBB0_1474

.LBB0_1558:
	s_ashr_i32 s31, s30, 31
	s_lshl_b64 s[34:35], s[30:31], 22
	s_add_u32 s34, s50, s34
	s_addc_u32 s35, s51, s35
	s_and_b64 s[36:37], s[0:1], exec
	s_cselect_b32 s31, s35, s43
	s_cselect_b32 s39, s34, s42
	s_ashr_i32 s29, s28, 31
	s_lshl_b64 s[36:37], s[28:29], 22
	s_add_u32 s36, s52, s36
	s_addc_u32 s37, s53, s37
	s_and_b64 s[46:47], s[0:1], exec
	s_cselect_b32 s29, s37, s45
	s_cselect_b32 s41, s36, s44
	s_add_u32 s42, s42, 0x200080
	s_addc_u32 s43, s43, 0
	s_add_u32 s71, s44, 0x100
	v_mov_b32_e32 v0, 0
	s_addc_u32 s72, s45, 0
	s_mov_b32 s73, -2
	v_mov_b32_e32 v1, v0
	v_mov_b32_e32 v2, v0
	v_mov_b32_e32 v3, v0
	v_mov_b32_e32 v4, v0
	v_mov_b32_e32 v5, v0
	v_mov_b32_e32 v6, v0
	v_mov_b32_e32 v7, v0
	v_mov_b32_e32 v16, v0
	v_mov_b32_e32 v17, v0
	v_mov_b32_e32 v18, v0
	v_mov_b32_e32 v19, v0
	v_mov_b32_e32 v20, v0
	v_mov_b32_e32 v21, v0
	v_mov_b32_e32 v22, v0
	v_mov_b32_e32 v23, v0
	v_mov_b32_e32 v32, v0
	v_mov_b32_e32 v33, v0
	v_mov_b32_e32 v34, v0
	v_mov_b32_e32 v35, v0
	v_mov_b32_e32 v36, v0
	v_mov_b32_e32 v37, v0
	v_mov_b32_e32 v38, v0
	v_mov_b32_e32 v39, v0
	v_mov_b32_e32 v48, v0
	v_mov_b32_e32 v49, v0
	v_mov_b32_e32 v50, v0
	v_mov_b32_e32 v51, v0
	v_mov_b32_e32 v52, v0
	v_mov_b32_e32 v53, v0
	v_mov_b32_e32 v54, v0
	v_mov_b32_e32 v55, v0
	v_mov_b32_e32 v8, v0
	v_mov_b32_e32 v9, v0
	v_mov_b32_e32 v10, v0
	v_mov_b32_e32 v11, v0
	v_mov_b32_e32 v12, v0
	v_mov_b32_e32 v13, v0
	v_mov_b32_e32 v14, v0
	v_mov_b32_e32 v15, v0
	v_mov_b32_e32 v24, v0
	v_mov_b32_e32 v25, v0
	v_mov_b32_e32 v26, v0
	v_mov_b32_e32 v27, v0
	v_mov_b32_e32 v28, v0
	v_mov_b32_e32 v29, v0
	v_mov_b32_e32 v30, v0
	v_mov_b32_e32 v31, v0
	v_mov_b32_e32 v40, v0
	v_mov_b32_e32 v41, v0
	v_mov_b32_e32 v42, v0
	v_mov_b32_e32 v43, v0
	v_mov_b32_e32 v44, v0
	v_mov_b32_e32 v45, v0
	v_mov_b32_e32 v46, v0
	v_mov_b32_e32 v47, v0
	v_mov_b32_e32 v56, v0
	v_mov_b32_e32 v57, v0
	v_mov_b32_e32 v58, v0
	v_mov_b32_e32 v59, v0
	v_mov_b32_e32 v60, v0
	v_mov_b32_e32 v61, v0
	v_mov_b32_e32 v62, v0
	v_mov_b32_e32 v63, v0
	v_mov_b32_e32 v64, v0
	v_mov_b32_e32 v65, v0
	v_mov_b32_e32 v66, v0
	v_mov_b32_e32 v67, v0
	v_mov_b32_e32 v68, v0
	v_mov_b32_e32 v69, v0
	v_mov_b32_e32 v70, v0
	v_mov_b32_e32 v71, v0
	v_mov_b32_e32 v80, v0
	v_mov_b32_e32 v81, v0
	v_mov_b32_e32 v82, v0
	v_mov_b32_e32 v83, v0
	v_mov_b32_e32 v84, v0
	v_mov_b32_e32 v85, v0
	v_mov_b32_e32 v86, v0
	v_mov_b32_e32 v87, v0
	v_mov_b32_e32 v96, v0
	v_mov_b32_e32 v97, v0
	v_mov_b32_e32 v98, v0
	v_mov_b32_e32 v99, v0
	v_mov_b32_e32 v100, v0
	v_mov_b32_e32 v101, v0
	v_mov_b32_e32 v102, v0
	v_mov_b32_e32 v103, v0
	v_mov_b32_e32 v112, v0
	v_mov_b32_e32 v113, v0
	v_mov_b32_e32 v114, v0
	v_mov_b32_e32 v115, v0
	v_mov_b32_e32 v120, v0
	v_mov_b32_e32 v121, v0
	v_mov_b32_e32 v122, v0
	v_mov_b32_e32 v123, v0
	v_mov_b32_e32 v72, v0
	v_mov_b32_e32 v73, v0
	v_mov_b32_e32 v74, v0
	v_mov_b32_e32 v75, v0
	v_mov_b32_e32 v76, v0
	v_mov_b32_e32 v77, v0
	v_mov_b32_e32 v78, v0
	v_mov_b32_e32 v79, v0
	v_mov_b32_e32 v88, v0
	v_mov_b32_e32 v89, v0
	v_mov_b32_e32 v90, v0
	v_mov_b32_e32 v91, v0
	v_mov_b32_e32 v92, v0
	v_mov_b32_e32 v93, v0
	v_mov_b32_e32 v94, v0
	v_mov_b32_e32 v95, v0
	v_mov_b32_e32 v104, v0
	v_mov_b32_e32 v105, v0
	v_mov_b32_e32 v106, v0
	v_mov_b32_e32 v107, v0
	v_mov_b32_e32 v108, v0
	v_mov_b32_e32 v109, v0
	v_mov_b32_e32 v110, v0
	v_mov_b32_e32 v111, v0
	v_mov_b32_e32 v136, v0
	v_mov_b32_e32 v137, v0
	v_mov_b32_e32 v138, v0
	v_mov_b32_e32 v139, v0
	v_mov_b32_e32 v140, v0
	v_mov_b32_e32 v141, v0
	v_mov_b32_e32 v142, v0
	v_mov_b32_e32 v143, v0
	s_cmp_eq_u32 s100, 0
	s_cbranch_scc1 .Lmy_nobar_1559
	s_barrier
	s_mov_b32 s100, 0
.Lmy_nobar_1559:
.LBB0_1559:
	s_add_u32 s44, s42, 0xffe00080
	s_addc_u32 s45, s43, -1
	s_add_i32 s74, 0, 0x10000
	v_add_u32_e32 v132, s74, v252
	v_add_u32_e32 v156, s33, v252
	ds_read_b128 v[116:119], v132
	ds_read_b128 v[124:127], v132 offset:1024
	ds_read_b128 v[128:131], v132 offset:2048
	ds_read_b128 v[132:135], v132 offset:3072
	ds_read_b128 v[144:147], v156
	ds_read_b128 v[148:151], v156 offset:1024
	ds_read_b128 v[152:155], v156 offset:2048
	ds_read_b128 v[156:159], v156 offset:3072
	s_cmpk_eq_i32 s73, 0x7c
	s_cselect_b32 s47, s31, s45
	s_cselect_b32 s46, s39, s44
	s_cselect_b32 s45, s29, s72
	s_cselect_b32 s44, s41, s71
	v_lshl_add_u64 v[192:193], s[42:43], 0, v[220:221]
	s_add_i32 m0, s55, 0xc000
	ds_read_b128 v[160:163], v210
	ds_read_b128 v[164:167], v210 offset:1024
	ds_read_b128 v[168:171], v210 offset:2048
	ds_read_b128 v[172:175], v210 offset:3072
	ds_read_b128 v[176:179], v210 offset:4096
	ds_read_b128 v[180:183], v210 offset:5120
	ds_read_b128 v[184:187], v210 offset:6144
	ds_read_b128 v[188:191], v210 offset:7168
	global_load_lds_dwordx4 v[192:193], off
	v_lshl_add_u64 v[192:193], s[42:43], 0, v[222:223]
	s_add_i32 m0, s55, 0xe000
	s_nop 0
	global_load_lds_dwordx4 v[192:193], off
	s_waitcnt vmcnt(8)
	s_waitcnt lgkmcnt(0)
	s_barrier
	s_setprio 1
	s_waitcnt lgkmcnt(0)
	v_mfma_f32_16x16x32_bf16 v[140:143], v[116:119], v[160:163], v[140:143]
	v_mfma_f32_16x16x32_bf16 v[136:139], v[128:131], v[160:163], v[136:139]
	v_mfma_f32_16x16x32_bf16 v[108:111], v[116:119], v[168:171], v[108:111]
	v_mfma_f32_16x16x32_bf16 v[104:107], v[128:131], v[168:171], v[104:107]
	v_mfma_f32_16x16x32_bf16 v[92:95], v[116:119], v[176:179], v[92:95]
	v_mfma_f32_16x16x32_bf16 v[88:91], v[128:131], v[176:179], v[88:91]
	v_mfma_f32_16x16x32_bf16 v[76:79], v[116:119], v[184:187], v[76:79]
	v_mfma_f32_16x16x32_bf16 v[72:75], v[128:131], v[184:187], v[72:75]
	v_mfma_f32_16x16x32_bf16 v[140:143], v[124:127], v[164:167], v[140:143]
	v_mfma_f32_16x16x32_bf16 v[136:139], v[132:135], v[164:167], v[136:139]
	v_mfma_f32_16x16x32_bf16 v[108:111], v[124:127], v[172:175], v[108:111]
	v_mfma_f32_16x16x32_bf16 v[104:107], v[132:135], v[172:175], v[104:107]
	v_mfma_f32_16x16x32_bf16 v[92:95], v[124:127], v[180:183], v[92:95]
	v_mfma_f32_16x16x32_bf16 v[88:91], v[132:135], v[180:183], v[88:91]
	v_mfma_f32_16x16x32_bf16 v[76:79], v[124:127], v[188:191], v[76:79]
	v_mfma_f32_16x16x32_bf16 v[72:75], v[132:135], v[188:191], v[72:75]
	s_setprio 0
	s_setprio 1
	v_mfma_f32_16x16x32_bf16 v[120:123], v[144:147], v[160:163], v[120:123]
	v_mfma_f32_16x16x32_bf16 v[112:115], v[152:155], v[160:163], v[112:115]
	v_mfma_f32_16x16x32_bf16 v[100:103], v[144:147], v[168:171], v[100:103]
	v_mfma_f32_16x16x32_bf16 v[96:99], v[152:155], v[168:171], v[96:99]
	v_mfma_f32_16x16x32_bf16 v[84:87], v[144:147], v[176:179], v[84:87]
	v_mfma_f32_16x16x32_bf16 v[80:83], v[152:155], v[176:179], v[80:83]
	v_mfma_f32_16x16x32_bf16 v[68:71], v[144:147], v[184:187], v[68:71]
	v_mfma_f32_16x16x32_bf16 v[64:67], v[152:155], v[184:187], v[64:67]
	v_mfma_f32_16x16x32_bf16 v[120:123], v[148:151], v[164:167], v[120:123]
	v_mfma_f32_16x16x32_bf16 v[112:115], v[156:159], v[164:167], v[112:115]
	v_mfma_f32_16x16x32_bf16 v[100:103], v[148:151], v[172:175], v[100:103]
	v_mfma_f32_16x16x32_bf16 v[96:99], v[156:159], v[172:175], v[96:99]
	v_mfma_f32_16x16x32_bf16 v[84:87], v[148:151], v[180:183], v[84:87]
	v_mfma_f32_16x16x32_bf16 v[80:83], v[156:159], v[180:183], v[80:83]
	v_mfma_f32_16x16x32_bf16 v[68:71], v[148:151], v[188:191], v[68:71]
	v_mfma_f32_16x16x32_bf16 v[64:67], v[156:159], v[188:191], v[64:67]
	s_setprio 0
	s_barrier
	s_add_i32 s74, s74, s54
	v_lshl_add_u64 v[192:193], s[44:45], 0, v[208:209]
	s_mov_b32 m0, s74
	ds_read_b128 v[160:163], v210 offset:16384
	ds_read_b128 v[164:167], v210 offset:17408
	ds_read_b128 v[168:171], v210 offset:18432
	ds_read_b128 v[172:175], v210 offset:19456
	ds_read_b128 v[176:179], v210 offset:20480
	ds_read_b128 v[180:183], v210 offset:21504
	ds_read_b128 v[184:187], v210 offset:22528
	ds_read_b128 v[188:191], v210 offset:23552
	global_load_lds_dwordx4 v[192:193], off
	s_add_i32 m0, s74, 0x2000
	s_add_u32 s74, s44, 0x200000
	v_lshl_add_u64 v[194:195], s[44:45], 0, v[218:219]
	s_addc_u32 s75, s45, 0
	s_add_i32 s76, s33, s54
	global_load_lds_dwordx4 v[194:195], off
	v_lshl_add_u64 v[196:197], s[74:75], 0, v[208:209]
	s_mov_b32 m0, s76
	v_lshl_add_u64 v[198:199], s[46:47], 0, v[216:217]
	global_load_lds_dwordx4 v[196:197], off
	v_lshl_add_u64 v[196:197], s[74:75], 0, v[218:219]
	s_add_i32 m0, s76, 0x2000
	s_nop 0
	global_load_lds_dwordx4 v[196:197], off
	v_lshl_add_u64 v[196:197], s[46:47], 0, v[214:215]
	s_mov_b32 m0, s55
	s_nop 0
	global_load_lds_dwordx4 v[196:197], off
	s_mov_b32 m0, s56
	s_nop 0
	global_load_lds_dwordx4 v[198:199], off
	s_waitcnt vmcnt(8)
	s_waitcnt lgkmcnt(0)
	s_barrier
	s_setprio 1
	s_waitcnt lgkmcnt(0)
	v_mfma_f32_16x16x32_bf16 v[60:63], v[116:119], v[160:163], v[60:63]
	v_mfma_f32_16x16x32_bf16 v[56:59], v[128:131], v[160:163], v[56:59]
	v_mfma_f32_16x16x32_bf16 v[44:47], v[116:119], v[168:171], v[44:47]
	v_mfma_f32_16x16x32_bf16 v[40:43], v[128:131], v[168:171], v[40:43]
	v_mfma_f32_16x16x32_bf16 v[28:31], v[116:119], v[176:179], v[28:31]
	v_mfma_f32_16x16x32_bf16 v[24:27], v[128:131], v[176:179], v[24:27]
	v_mfma_f32_16x16x32_bf16 v[12:15], v[116:119], v[184:187], v[12:15]
	v_mfma_f32_16x16x32_bf16 v[8:11], v[128:131], v[184:187], v[8:11]
	v_mfma_f32_16x16x32_bf16 v[60:63], v[124:127], v[164:167], v[60:63]
	v_mfma_f32_16x16x32_bf16 v[56:59], v[132:135], v[164:167], v[56:59]
	v_mfma_f32_16x16x32_bf16 v[44:47], v[124:127], v[172:175], v[44:47]
	v_mfma_f32_16x16x32_bf16 v[40:43], v[132:135], v[172:175], v[40:43]
	v_mfma_f32_16x16x32_bf16 v[28:31], v[124:127], v[180:183], v[28:31]
	v_mfma_f32_16x16x32_bf16 v[24:27], v[132:135], v[180:183], v[24:27]
	v_mfma_f32_16x16x32_bf16 v[12:15], v[124:127], v[188:191], v[12:15]
	v_mfma_f32_16x16x32_bf16 v[8:11], v[132:135], v[188:191], v[8:11]
	s_setprio 0
	s_setprio 1
	v_mfma_f32_16x16x32_bf16 v[52:55], v[144:147], v[160:163], v[52:55]
	v_mfma_f32_16x16x32_bf16 v[48:51], v[152:155], v[160:163], v[48:51]
	v_mfma_f32_16x16x32_bf16 v[36:39], v[144:147], v[168:171], v[36:39]
	v_mfma_f32_16x16x32_bf16 v[32:35], v[152:155], v[168:171], v[32:35]
	v_mfma_f32_16x16x32_bf16 v[20:23], v[144:147], v[176:179], v[20:23]
	v_mfma_f32_16x16x32_bf16 v[16:19], v[152:155], v[176:179], v[16:19]
	v_mfma_f32_16x16x32_bf16 v[4:7], v[144:147], v[184:187], v[4:7]
	v_mfma_f32_16x16x32_bf16 v[0:3], v[152:155], v[184:187], v[0:3]
	v_mfma_f32_16x16x32_bf16 v[52:55], v[148:151], v[164:167], v[52:55]
	v_mfma_f32_16x16x32_bf16 v[48:51], v[156:159], v[164:167], v[48:51]
	v_mfma_f32_16x16x32_bf16 v[36:39], v[148:151], v[172:175], v[36:39]
	v_mfma_f32_16x16x32_bf16 v[32:35], v[156:159], v[172:175], v[32:35]
	v_mfma_f32_16x16x32_bf16 v[20:23], v[148:151], v[180:183], v[20:23]
	v_mfma_f32_16x16x32_bf16 v[16:19], v[156:159], v[180:183], v[16:19]
	v_mfma_f32_16x16x32_bf16 v[4:7], v[148:151], v[188:191], v[4:7]
	v_mfma_f32_16x16x32_bf16 v[0:3], v[156:159], v[188:191], v[0:3]
	s_setprio 0
	s_barrier
	s_add_i32 s74, 0, 0x18000
	s_add_i32 s75, 0, 0x1c000
	v_add_u32_e32 v132, s74, v252
	v_add_u32_e32 v156, s75, v252
	ds_read_b128 v[116:119], v132
	ds_read_b128 v[124:127], v132 offset:1024
	ds_read_b128 v[128:131], v132 offset:2048
	ds_read_b128 v[132:135], v132 offset:3072
	ds_read_b128 v[144:147], v156
	ds_read_b128 v[148:151], v156 offset:1024
	ds_read_b128 v[152:155], v156 offset:2048
	ds_read_b128 v[156:159], v156 offset:3072
	s_add_u32 s46, s46, 0x200000
	s_addc_u32 s47, s47, 0
	s_mov_b32 m0, s57
	v_lshl_add_u64 v[200:201], s[46:47], 0, v[214:215]
	ds_read_b128 v[160:163], v210 offset:32768
	ds_read_b128 v[164:167], v210 offset:33792
	ds_read_b128 v[168:171], v210 offset:34816
	ds_read_b128 v[172:175], v210 offset:35840
	ds_read_b128 v[176:179], v210 offset:36864
	ds_read_b128 v[180:183], v210 offset:37888
	ds_read_b128 v[184:187], v210 offset:38912
	ds_read_b128 v[188:191], v210 offset:39936
	global_load_lds_dwordx4 v[200:201], off
	v_lshl_add_u64 v[200:201], s[46:47], 0, v[216:217]
	s_mov_b32 m0, s58
	s_nop 0
	global_load_lds_dwordx4 v[200:201], off
	s_waitcnt vmcnt(8)
	s_waitcnt lgkmcnt(0)
	s_barrier
	s_setprio 1
	s_waitcnt lgkmcnt(0)
	v_mfma_f32_16x16x32_bf16 v[140:143], v[116:119], v[160:163], v[140:143]
	v_mfma_f32_16x16x32_bf16 v[136:139], v[128:131], v[160:163], v[136:139]
	v_mfma_f32_16x16x32_bf16 v[108:111], v[116:119], v[168:171], v[108:111]
	v_mfma_f32_16x16x32_bf16 v[104:107], v[128:131], v[168:171], v[104:107]
	v_mfma_f32_16x16x32_bf16 v[92:95], v[116:119], v[176:179], v[92:95]
	v_mfma_f32_16x16x32_bf16 v[88:91], v[128:131], v[176:179], v[88:91]
	v_mfma_f32_16x16x32_bf16 v[76:79], v[116:119], v[184:187], v[76:79]
	v_mfma_f32_16x16x32_bf16 v[72:75], v[128:131], v[184:187], v[72:75]
	v_mfma_f32_16x16x32_bf16 v[140:143], v[124:127], v[164:167], v[140:143]
	v_mfma_f32_16x16x32_bf16 v[136:139], v[132:135], v[164:167], v[136:139]
	v_mfma_f32_16x16x32_bf16 v[108:111], v[124:127], v[172:175], v[108:111]
	v_mfma_f32_16x16x32_bf16 v[104:107], v[132:135], v[172:175], v[104:107]
	v_mfma_f32_16x16x32_bf16 v[92:95], v[124:127], v[180:183], v[92:95]
	v_mfma_f32_16x16x32_bf16 v[88:91], v[132:135], v[180:183], v[88:91]
	v_mfma_f32_16x16x32_bf16 v[76:79], v[124:127], v[188:191], v[76:79]
	v_mfma_f32_16x16x32_bf16 v[72:75], v[132:135], v[188:191], v[72:75]
	s_setprio 0
	s_setprio 1
	v_mfma_f32_16x16x32_bf16 v[120:123], v[144:147], v[160:163], v[120:123]
	v_mfma_f32_16x16x32_bf16 v[112:115], v[152:155], v[160:163], v[112:115]
	v_mfma_f32_16x16x32_bf16 v[100:103], v[144:147], v[168:171], v[100:103]
	v_mfma_f32_16x16x32_bf16 v[96:99], v[152:155], v[168:171], v[96:99]
	v_mfma_f32_16x16x32_bf16 v[84:87], v[144:147], v[176:179], v[84:87]
	v_mfma_f32_16x16x32_bf16 v[80:83], v[152:155], v[176:179], v[80:83]
	v_mfma_f32_16x16x32_bf16 v[68:71], v[144:147], v[184:187], v[68:71]
	v_mfma_f32_16x16x32_bf16 v[64:67], v[152:155], v[184:187], v[64:67]
	v_mfma_f32_16x16x32_bf16 v[120:123], v[148:151], v[164:167], v[120:123]
	v_mfma_f32_16x16x32_bf16 v[112:115], v[156:159], v[164:167], v[112:115]
	v_mfma_f32_16x16x32_bf16 v[100:103], v[148:151], v[172:175], v[100:103]
	v_mfma_f32_16x16x32_bf16 v[96:99], v[156:159], v[172:175], v[96:99]
	v_mfma_f32_16x16x32_bf16 v[84:87], v[148:151], v[180:183], v[84:87]
	v_mfma_f32_16x16x32_bf16 v[80:83], v[156:159], v[180:183], v[80:83]
	v_mfma_f32_16x16x32_bf16 v[68:71], v[148:151], v[188:191], v[68:71]
	v_mfma_f32_16x16x32_bf16 v[64:67], v[156:159], v[188:191], v[64:67]
	s_setprio 0
	s_barrier
	s_add_i32 s46, s74, s54
	v_lshl_add_u64 v[192:193], v[192:193], 0, s[2:3]
	s_mov_b32 m0, s46
	ds_read_b128 v[160:163], v210 offset:49152
	ds_read_b128 v[164:167], v210 offset:50176
	ds_read_b128 v[168:171], v210 offset:51200
	ds_read_b128 v[172:175], v210 offset:52224
	ds_read_b128 v[176:179], v210 offset:53248
	ds_read_b128 v[180:183], v210 offset:54272
	ds_read_b128 v[184:187], v210 offset:55296
	ds_read_b128 v[188:191], v210 offset:56320
	global_load_lds_dwordx4 v[192:193], off
	s_add_i32 m0, s46, 0x2000
	s_add_u32 s44, s44, 0x200080
	v_lshl_add_u64 v[192:193], v[194:195], 0, s[2:3]
	s_addc_u32 s45, s45, 0
	s_add_i32 s46, s75, s54
	global_load_lds_dwordx4 v[192:193], off
	v_lshl_add_u64 v[192:193], s[44:45], 0, v[208:209]
	s_mov_b32 m0, s46
	s_nop 0
	global_load_lds_dwordx4 v[192:193], off
	v_lshl_add_u64 v[192:193], s[44:45], 0, v[218:219]
	s_add_i32 m0, s46, 0x2000
	s_nop 0
	global_load_lds_dwordx4 v[192:193], off
	v_lshl_add_u64 v[192:193], v[196:197], 0, s[2:3]
	s_mov_b32 m0, s66
	s_nop 0
	global_load_lds_dwordx4 v[192:193], off
	v_lshl_add_u64 v[192:193], v[198:199], 0, s[2:3]
	s_mov_b32 m0, s67
	s_nop 0
	global_load_lds_dwordx4 v[192:193], off
	s_waitcnt vmcnt(8)
	s_waitcnt lgkmcnt(0)
	s_barrier
	s_setprio 1
	s_waitcnt lgkmcnt(0)
	v_mfma_f32_16x16x32_bf16 v[60:63], v[116:119], v[160:163], v[60:63]
	v_mfma_f32_16x16x32_bf16 v[56:59], v[128:131], v[160:163], v[56:59]
	v_mfma_f32_16x16x32_bf16 v[44:47], v[116:119], v[168:171], v[44:47]
	v_mfma_f32_16x16x32_bf16 v[40:43], v[128:131], v[168:171], v[40:43]
	v_mfma_f32_16x16x32_bf16 v[28:31], v[116:119], v[176:179], v[28:31]
	v_mfma_f32_16x16x32_bf16 v[24:27], v[128:131], v[176:179], v[24:27]
	v_mfma_f32_16x16x32_bf16 v[12:15], v[116:119], v[184:187], v[12:15]
	v_mfma_f32_16x16x32_bf16 v[8:11], v[128:131], v[184:187], v[8:11]
	v_mfma_f32_16x16x32_bf16 v[60:63], v[124:127], v[164:167], v[60:63]
	v_mfma_f32_16x16x32_bf16 v[56:59], v[132:135], v[164:167], v[56:59]
	v_mfma_f32_16x16x32_bf16 v[44:47], v[124:127], v[172:175], v[44:47]
	v_mfma_f32_16x16x32_bf16 v[40:43], v[132:135], v[172:175], v[40:43]
	v_mfma_f32_16x16x32_bf16 v[28:31], v[124:127], v[180:183], v[28:31]
	v_mfma_f32_16x16x32_bf16 v[24:27], v[132:135], v[180:183], v[24:27]
	v_mfma_f32_16x16x32_bf16 v[12:15], v[124:127], v[188:191], v[12:15]
	v_mfma_f32_16x16x32_bf16 v[8:11], v[132:135], v[188:191], v[8:11]
	s_setprio 0
	s_setprio 1
	v_mfma_f32_16x16x32_bf16 v[52:55], v[144:147], v[160:163], v[52:55]
	v_mfma_f32_16x16x32_bf16 v[48:51], v[152:155], v[160:163], v[48:51]
	v_mfma_f32_16x16x32_bf16 v[36:39], v[144:147], v[168:171], v[36:39]
	v_mfma_f32_16x16x32_bf16 v[32:35], v[152:155], v[168:171], v[32:35]
	v_mfma_f32_16x16x32_bf16 v[20:23], v[144:147], v[176:179], v[20:23]
	v_mfma_f32_16x16x32_bf16 v[16:19], v[152:155], v[176:179], v[16:19]
	v_mfma_f32_16x16x32_bf16 v[4:7], v[144:147], v[184:187], v[4:7]
	v_mfma_f32_16x16x32_bf16 v[0:3], v[152:155], v[184:187], v[0:3]
	v_mfma_f32_16x16x32_bf16 v[52:55], v[148:151], v[164:167], v[52:55]
	v_mfma_f32_16x16x32_bf16 v[48:51], v[156:159], v[164:167], v[48:51]
	v_mfma_f32_16x16x32_bf16 v[36:39], v[148:151], v[172:175], v[36:39]
	v_mfma_f32_16x16x32_bf16 v[32:35], v[156:159], v[172:175], v[32:35]
	v_mfma_f32_16x16x32_bf16 v[20:23], v[148:151], v[180:183], v[20:23]
	v_mfma_f32_16x16x32_bf16 v[16:19], v[156:159], v[180:183], v[16:19]
	v_mfma_f32_16x16x32_bf16 v[4:7], v[148:151], v[188:191], v[4:7]
	v_mfma_f32_16x16x32_bf16 v[0:3], v[156:159], v[188:191], v[0:3]
	s_setprio 0
	s_barrier
	s_add_i32 s73, s73, 2
	s_add_u32 s42, s42, 0x100
	s_addc_u32 s43, s43, 0
	s_add_u32 s71, s71, 0x100
	s_addc_u32 s72, s72, 0
	s_cmpk_gt_u32 s73, 0x7d
	s_cbranch_scc0 .LBB0_1559
	s_and_b64 vcc, exec, s[26:27]
	s_cbranch_vccz .LBB0_1562
	s_barrier

.LBB0_1603:
	s_ashr_i32 s23, s22, 31
	s_lshl_b64 s[24:25], s[22:23], 22
	s_add_u32 s24, s41, s24
	s_addc_u32 s25, s42, s25
	s_and_b64 s[26:27], s[0:1], exec
	s_cselect_b32 s23, s25, s31
	s_cselect_b32 s56, s24, s30
	s_ashr_i32 s21, s20, 31
	s_lshl_b64 s[26:27], s[20:21], 22
	s_add_u32 s26, s43, s26
	s_addc_u32 s27, s44, s27
	s_and_b64 s[36:37], s[0:1], exec
	s_cselect_b32 s21, s27, s35
	s_cselect_b32 s57, s26, s34
	s_add_u32 s30, s30, 0x200080
	s_addc_u32 s31, s31, 0
	s_add_u32 s58, s34, 0x100
	v_mov_b32_e32 v0, 0
	s_mov_b32 s73, s59
	s_addc_u32 s59, s35, 0
	s_mov_b32 s60, -2
	v_mov_b32_e32 v1, v0
	v_mov_b32_e32 v2, v0
	v_mov_b32_e32 v3, v0
	v_mov_b32_e32 v4, v0
	v_mov_b32_e32 v5, v0
	v_mov_b32_e32 v6, v0
	v_mov_b32_e32 v7, v0
	v_mov_b32_e32 v12, v0
	v_mov_b32_e32 v13, v0
	v_mov_b32_e32 v14, v0
	v_mov_b32_e32 v15, v0
	v_mov_b32_e32 v16, v0
	v_mov_b32_e32 v17, v0
	v_mov_b32_e32 v18, v0
	v_mov_b32_e32 v19, v0
	v_mov_b32_e32 v24, v0
	v_mov_b32_e32 v25, v0
	v_mov_b32_e32 v26, v0
	v_mov_b32_e32 v27, v0
	v_mov_b32_e32 v28, v0
	v_mov_b32_e32 v29, v0
	v_mov_b32_e32 v30, v0
	v_mov_b32_e32 v31, v0
	v_mov_b32_e32 v32, v0
	v_mov_b32_e32 v33, v0
	v_mov_b32_e32 v34, v0
	v_mov_b32_e32 v35, v0
	v_mov_b32_e32 v40, v0
	v_mov_b32_e32 v41, v0
	v_mov_b32_e32 v42, v0
	v_mov_b32_e32 v43, v0
	v_mov_b32_e32 v8, v0
	v_mov_b32_e32 v9, v0
	v_mov_b32_e32 v10, v0
	v_mov_b32_e32 v11, v0
	v_mov_b32_e32 v20, v0
	v_mov_b32_e32 v21, v0
	v_mov_b32_e32 v22, v0
	v_mov_b32_e32 v23, v0
	v_mov_b32_e32 v36, v0
	v_mov_b32_e32 v37, v0
	v_mov_b32_e32 v38, v0
	v_mov_b32_e32 v39, v0
	v_mov_b32_e32 v44, v0
	v_mov_b32_e32 v45, v0
	v_mov_b32_e32 v46, v0
	v_mov_b32_e32 v47, v0
	v_mov_b32_e32 v48, v0
	v_mov_b32_e32 v49, v0
	v_mov_b32_e32 v50, v0
	v_mov_b32_e32 v51, v0
	v_mov_b32_e32 v52, v0
	v_mov_b32_e32 v53, v0
	v_mov_b32_e32 v54, v0
	v_mov_b32_e32 v55, v0
	v_mov_b32_e32 v56, v0
	v_mov_b32_e32 v57, v0
	v_mov_b32_e32 v58, v0
	v_mov_b32_e32 v59, v0
	v_mov_b32_e32 v60, v0
	v_mov_b32_e32 v61, v0
	v_mov_b32_e32 v62, v0
	v_mov_b32_e32 v63, v0
	v_mov_b32_e32 v64, v0
	v_mov_b32_e32 v65, v0
	v_mov_b32_e32 v66, v0
	v_mov_b32_e32 v67, v0
	v_mov_b32_e32 v68, v0
	v_mov_b32_e32 v69, v0
	v_mov_b32_e32 v70, v0
	v_mov_b32_e32 v71, v0
	v_mov_b32_e32 v76, v0
	v_mov_b32_e32 v77, v0
	v_mov_b32_e32 v78, v0
	v_mov_b32_e32 v79, v0
	v_mov_b32_e32 v80, v0
	v_mov_b32_e32 v81, v0
	v_mov_b32_e32 v82, v0
	v_mov_b32_e32 v83, v0
	v_mov_b32_e32 v84, v0
	v_mov_b32_e32 v85, v0
	v_mov_b32_e32 v86, v0
	v_mov_b32_e32 v87, v0
	v_mov_b32_e32 v88, v0
	v_mov_b32_e32 v89, v0
	v_mov_b32_e32 v90, v0
	v_mov_b32_e32 v91, v0
	v_mov_b32_e32 v96, v0
	v_mov_b32_e32 v97, v0
	v_mov_b32_e32 v98, v0
	v_mov_b32_e32 v99, v0
	v_mov_b32_e32 v104, v0
	v_mov_b32_e32 v105, v0
	v_mov_b32_e32 v106, v0
	v_mov_b32_e32 v107, v0
	v_mov_b32_e32 v72, v0
	v_mov_b32_e32 v73, v0
	v_mov_b32_e32 v74, v0
	v_mov_b32_e32 v75, v0
	v_mov_b32_e32 v92, v0
	v_mov_b32_e32 v93, v0
	v_mov_b32_e32 v94, v0
	v_mov_b32_e32 v95, v0
	v_mov_b32_e32 v100, v0
	v_mov_b32_e32 v101, v0
	v_mov_b32_e32 v102, v0
	v_mov_b32_e32 v103, v0
	v_mov_b32_e32 v108, v0
	v_mov_b32_e32 v109, v0
	v_mov_b32_e32 v110, v0
	v_mov_b32_e32 v111, v0
	v_mov_b32_e32 v112, v0
	v_mov_b32_e32 v113, v0
	v_mov_b32_e32 v114, v0
	v_mov_b32_e32 v115, v0
	v_mov_b32_e32 v116, v0
	v_mov_b32_e32 v117, v0
	v_mov_b32_e32 v118, v0
	v_mov_b32_e32 v119, v0
	v_mov_b32_e32 v120, v0
	v_mov_b32_e32 v121, v0
	v_mov_b32_e32 v122, v0
	v_mov_b32_e32 v123, v0
	v_mov_b32_e32 v124, v0
	v_mov_b32_e32 v125, v0
	v_mov_b32_e32 v126, v0
	v_mov_b32_e32 v127, v0
	s_cmp_eq_u32 s100, 0
	s_cbranch_scc1 .Lmy_nobar_1604
	s_barrier
	s_mov_b32 s100, 0
.Lmy_nobar_1604:
.LBB0_1604:
	s_add_u32 s34, s30, 0xffe00080
	s_addc_u32 s35, s31, -1
	s_add_i32 s61, 0, 0x10000
	v_add_u32_e32 v140, s61, v161
	v_add_u32_e32 v158, s33, v161
	ds_read_b128 v[128:131], v140
	ds_read_b128 v[132:135], v140 offset:1024
	ds_read_b128 v[136:139], v140 offset:2048
	ds_read_b128 v[140:143], v140 offset:3072
	ds_read_b128 v[154:157], v158
	ds_read_b128 v[164:167], v158 offset:1024
	ds_read_b128 v[168:171], v158 offset:2048
	ds_read_b128 v[172:175], v158 offset:3072
	s_cmpk_eq_i32 s60, 0x7c
	s_cselect_b32 s37, s23, s35
	s_cselect_b32 s36, s56, s34
	s_cselect_b32 s35, s21, s59
	s_cselect_b32 s34, s57, s58
	v_lshl_add_u64 v[158:159], s[30:31], 0, v[150:151]
	s_add_i32 m0, s29, 0xc000
	ds_read_b128 v[176:179], v163
	ds_read_b128 v[180:183], v163 offset:1024
	ds_read_b128 v[184:187], v163 offset:2048
	ds_read_b128 v[188:191], v163 offset:3072
	ds_read_b128 v[192:195], v163 offset:4096
	ds_read_b128 v[196:199], v163 offset:5120
	ds_read_b128 v[200:203], v163 offset:6144
	ds_read_b128 v[204:207], v163 offset:7168
	global_load_lds_dwordx4 v[158:159], off
	v_lshl_add_u64 v[158:159], s[30:31], 0, v[152:153]
	s_add_i32 m0, s29, 0xe000
	s_nop 0
	global_load_lds_dwordx4 v[158:159], off
	s_waitcnt vmcnt(8)
	s_waitcnt lgkmcnt(0)
	s_barrier
	s_setprio 1
	s_waitcnt lgkmcnt(0)
	v_mfma_f32_16x16x32_bf16 v[124:127], v[128:131], v[176:179], v[124:127]
	v_mfma_f32_16x16x32_bf16 v[120:123], v[136:139], v[176:179], v[120:123]
	v_mfma_f32_16x16x32_bf16 v[116:119], v[128:131], v[184:187], v[116:119]
	v_mfma_f32_16x16x32_bf16 v[112:115], v[136:139], v[184:187], v[112:115]
	v_mfma_f32_16x16x32_bf16 v[108:111], v[128:131], v[192:195], v[108:111]
	v_mfma_f32_16x16x32_bf16 v[100:103], v[136:139], v[192:195], v[100:103]
	v_mfma_f32_16x16x32_bf16 v[92:95], v[128:131], v[200:203], v[92:95]
	v_mfma_f32_16x16x32_bf16 v[72:75], v[136:139], v[200:203], v[72:75]
	v_mfma_f32_16x16x32_bf16 v[124:127], v[132:135], v[180:183], v[124:127]
	v_mfma_f32_16x16x32_bf16 v[120:123], v[140:143], v[180:183], v[120:123]
	v_mfma_f32_16x16x32_bf16 v[116:119], v[132:135], v[188:191], v[116:119]
	v_mfma_f32_16x16x32_bf16 v[112:115], v[140:143], v[188:191], v[112:115]
	v_mfma_f32_16x16x32_bf16 v[108:111], v[132:135], v[196:199], v[108:111]
	v_mfma_f32_16x16x32_bf16 v[100:103], v[140:143], v[196:199], v[100:103]
	v_mfma_f32_16x16x32_bf16 v[92:95], v[132:135], v[204:207], v[92:95]
	v_mfma_f32_16x16x32_bf16 v[72:75], v[140:143], v[204:207], v[72:75]
	s_setprio 0
	s_setprio 1
	v_mfma_f32_16x16x32_bf16 v[104:107], v[154:157], v[176:179], v[104:107]
	v_mfma_f32_16x16x32_bf16 v[96:99], v[168:171], v[176:179], v[96:99]
	v_mfma_f32_16x16x32_bf16 v[88:91], v[154:157], v[184:187], v[88:91]
	v_mfma_f32_16x16x32_bf16 v[84:87], v[168:171], v[184:187], v[84:87]
	v_mfma_f32_16x16x32_bf16 v[80:83], v[154:157], v[192:195], v[80:83]
	v_mfma_f32_16x16x32_bf16 v[76:79], v[168:171], v[192:195], v[76:79]
	v_mfma_f32_16x16x32_bf16 v[68:71], v[154:157], v[200:203], v[68:71]
	v_mfma_f32_16x16x32_bf16 v[64:67], v[168:171], v[200:203], v[64:67]
	v_mfma_f32_16x16x32_bf16 v[104:107], v[164:167], v[180:183], v[104:107]
	v_mfma_f32_16x16x32_bf16 v[96:99], v[172:175], v[180:183], v[96:99]
	v_mfma_f32_16x16x32_bf16 v[88:91], v[164:167], v[188:191], v[88:91]
	v_mfma_f32_16x16x32_bf16 v[84:87], v[172:175], v[188:191], v[84:87]
	v_mfma_f32_16x16x32_bf16 v[80:83], v[164:167], v[196:199], v[80:83]
	v_mfma_f32_16x16x32_bf16 v[76:79], v[172:175], v[196:199], v[76:79]
	v_mfma_f32_16x16x32_bf16 v[68:71], v[164:167], v[204:207], v[68:71]
	v_mfma_f32_16x16x32_bf16 v[64:67], v[172:175], v[204:207], v[64:67]
	s_setprio 0
	s_barrier
	s_add_i32 s61, s61, s45
	v_lshl_add_u64 v[158:159], s[34:35], 0, v[208:209]
	s_mov_b32 m0, s61
	ds_read_b128 v[176:179], v163 offset:16384
	ds_read_b128 v[180:183], v163 offset:17408
	ds_read_b128 v[184:187], v163 offset:18432
	ds_read_b128 v[188:191], v163 offset:19456
	ds_read_b128 v[192:195], v163 offset:20480
	ds_read_b128 v[196:199], v163 offset:21504
	ds_read_b128 v[200:203], v163 offset:22528
	ds_read_b128 v[204:207], v163 offset:23552
	global_load_lds_dwordx4 v[158:159], off
	s_add_i32 m0, s61, 0x2000
	s_add_u32 s62, s34, 0x200000
	v_lshl_add_u64 v[210:211], s[34:35], 0, v[148:149]
	s_addc_u32 s63, s35, 0
	s_add_i32 s61, s33, s45
	global_load_lds_dwordx4 v[210:211], off
	v_lshl_add_u64 v[212:213], s[62:63], 0, v[208:209]
	s_mov_b32 m0, s61
	v_lshl_add_u64 v[214:215], s[36:37], 0, v[146:147]
	global_load_lds_dwordx4 v[212:213], off
	v_lshl_add_u64 v[212:213], s[62:63], 0, v[148:149]
	s_add_i32 m0, s61, 0x2000
	s_nop 0
	global_load_lds_dwordx4 v[212:213], off
	v_lshl_add_u64 v[212:213], s[36:37], 0, v[144:145]
	s_mov_b32 m0, s29
	s_nop 0
	global_load_lds_dwordx4 v[212:213], off
	s_mov_b32 m0, s46
	s_nop 0
	global_load_lds_dwordx4 v[214:215], off
	s_waitcnt vmcnt(8)
	s_waitcnt lgkmcnt(0)
	s_barrier
	s_setprio 1
	s_waitcnt lgkmcnt(0)
	v_mfma_f32_16x16x32_bf16 v[60:63], v[128:131], v[176:179], v[60:63]
	v_mfma_f32_16x16x32_bf16 v[56:59], v[136:139], v[176:179], v[56:59]
	v_mfma_f32_16x16x32_bf16 v[52:55], v[128:131], v[184:187], v[52:55]
	v_mfma_f32_16x16x32_bf16 v[48:51], v[136:139], v[184:187], v[48:51]
	v_mfma_f32_16x16x32_bf16 v[44:47], v[128:131], v[192:195], v[44:47]
	v_mfma_f32_16x16x32_bf16 v[36:39], v[136:139], v[192:195], v[36:39]
	v_mfma_f32_16x16x32_bf16 v[20:23], v[128:131], v[200:203], v[20:23]
	v_mfma_f32_16x16x32_bf16 v[8:11], v[136:139], v[200:203], v[8:11]
	v_mfma_f32_16x16x32_bf16 v[60:63], v[132:135], v[180:183], v[60:63]
	v_mfma_f32_16x16x32_bf16 v[56:59], v[140:143], v[180:183], v[56:59]
	v_mfma_f32_16x16x32_bf16 v[52:55], v[132:135], v[188:191], v[52:55]
	v_mfma_f32_16x16x32_bf16 v[48:51], v[140:143], v[188:191], v[48:51]
	v_mfma_f32_16x16x32_bf16 v[44:47], v[132:135], v[196:199], v[44:47]
	v_mfma_f32_16x16x32_bf16 v[36:39], v[140:143], v[196:199], v[36:39]
	v_mfma_f32_16x16x32_bf16 v[20:23], v[132:135], v[204:207], v[20:23]
	v_mfma_f32_16x16x32_bf16 v[8:11], v[140:143], v[204:207], v[8:11]
	s_setprio 0
	s_setprio 1
	v_mfma_f32_16x16x32_bf16 v[40:43], v[154:157], v[176:179], v[40:43]
	v_mfma_f32_16x16x32_bf16 v[32:35], v[168:171], v[176:179], v[32:35]
	v_mfma_f32_16x16x32_bf16 v[28:31], v[154:157], v[184:187], v[28:31]
	v_mfma_f32_16x16x32_bf16 v[24:27], v[168:171], v[184:187], v[24:27]
	v_mfma_f32_16x16x32_bf16 v[16:19], v[154:157], v[192:195], v[16:19]
	v_mfma_f32_16x16x32_bf16 v[12:15], v[168:171], v[192:195], v[12:15]
	v_mfma_f32_16x16x32_bf16 v[4:7], v[154:157], v[200:203], v[4:7]
	v_mfma_f32_16x16x32_bf16 v[0:3], v[168:171], v[200:203], v[0:3]
	v_mfma_f32_16x16x32_bf16 v[40:43], v[164:167], v[180:183], v[40:43]
	v_mfma_f32_16x16x32_bf16 v[32:35], v[172:175], v[180:183], v[32:35]
	v_mfma_f32_16x16x32_bf16 v[28:31], v[164:167], v[188:191], v[28:31]
	v_mfma_f32_16x16x32_bf16 v[24:27], v[172:175], v[188:191], v[24:27]
	v_mfma_f32_16x16x32_bf16 v[16:19], v[164:167], v[196:199], v[16:19]
	v_mfma_f32_16x16x32_bf16 v[12:15], v[172:175], v[196:199], v[12:15]
	v_mfma_f32_16x16x32_bf16 v[4:7], v[164:167], v[204:207], v[4:7]
	v_mfma_f32_16x16x32_bf16 v[0:3], v[172:175], v[204:207], v[0:3]
	s_setprio 0
	s_barrier
	s_add_i32 s61, 0, 0x18000
	s_add_i32 s62, 0, 0x1c000
	v_add_u32_e32 v140, s61, v161
	v_add_u32_e32 v172, s62, v161
	ds_read_b128 v[128:131], v140
	ds_read_b128 v[132:135], v140 offset:1024
	ds_read_b128 v[136:139], v140 offset:2048
	ds_read_b128 v[140:143], v140 offset:3072
	ds_read_b128 v[154:157], v172
	ds_read_b128 v[164:167], v172 offset:1024
	ds_read_b128 v[168:171], v172 offset:2048
	ds_read_b128 v[172:175], v172 offset:3072
	s_add_u32 s36, s36, 0x200000
	s_addc_u32 s37, s37, 0
	s_mov_b32 m0, s47
	v_lshl_add_u64 v[216:217], s[36:37], 0, v[144:145]
	ds_read_b128 v[176:179], v163 offset:32768
	ds_read_b128 v[180:183], v163 offset:33792
	ds_read_b128 v[184:187], v163 offset:34816
	ds_read_b128 v[188:191], v163 offset:35840
	ds_read_b128 v[192:195], v163 offset:36864
	ds_read_b128 v[196:199], v163 offset:37888
	ds_read_b128 v[200:203], v163 offset:38912
	ds_read_b128 v[204:207], v163 offset:39936
	global_load_lds_dwordx4 v[216:217], off
	v_lshl_add_u64 v[216:217], s[36:37], 0, v[146:147]
	s_mov_b32 m0, s48
	s_nop 0
	global_load_lds_dwordx4 v[216:217], off
	s_waitcnt vmcnt(8)
	s_waitcnt lgkmcnt(0)
	s_barrier
	s_setprio 1
	s_waitcnt lgkmcnt(0)
	v_mfma_f32_16x16x32_bf16 v[124:127], v[128:131], v[176:179], v[124:127]
	v_mfma_f32_16x16x32_bf16 v[120:123], v[136:139], v[176:179], v[120:123]
	v_mfma_f32_16x16x32_bf16 v[116:119], v[128:131], v[184:187], v[116:119]
	v_mfma_f32_16x16x32_bf16 v[112:115], v[136:139], v[184:187], v[112:115]
	v_mfma_f32_16x16x32_bf16 v[108:111], v[128:131], v[192:195], v[108:111]
	v_mfma_f32_16x16x32_bf16 v[100:103], v[136:139], v[192:195], v[100:103]
	v_mfma_f32_16x16x32_bf16 v[92:95], v[128:131], v[200:203], v[92:95]
	v_mfma_f32_16x16x32_bf16 v[72:75], v[136:139], v[200:203], v[72:75]
	v_mfma_f32_16x16x32_bf16 v[124:127], v[132:135], v[180:183], v[124:127]
	v_mfma_f32_16x16x32_bf16 v[120:123], v[140:143], v[180:183], v[120:123]
	v_mfma_f32_16x16x32_bf16 v[116:119], v[132:135], v[188:191], v[116:119]
	v_mfma_f32_16x16x32_bf16 v[112:115], v[140:143], v[188:191], v[112:115]
	v_mfma_f32_16x16x32_bf16 v[108:111], v[132:135], v[196:199], v[108:111]
	v_mfma_f32_16x16x32_bf16 v[100:103], v[140:143], v[196:199], v[100:103]
	v_mfma_f32_16x16x32_bf16 v[92:95], v[132:135], v[204:207], v[92:95]
	v_mfma_f32_16x16x32_bf16 v[72:75], v[140:143], v[204:207], v[72:75]
	s_setprio 0
	s_setprio 1
	v_mfma_f32_16x16x32_bf16 v[104:107], v[154:157], v[176:179], v[104:107]
	v_mfma_f32_16x16x32_bf16 v[96:99], v[168:171], v[176:179], v[96:99]
	v_mfma_f32_16x16x32_bf16 v[88:91], v[154:157], v[184:187], v[88:91]
	v_mfma_f32_16x16x32_bf16 v[84:87], v[168:171], v[184:187], v[84:87]
	v_mfma_f32_16x16x32_bf16 v[80:83], v[154:157], v[192:195], v[80:83]
	v_mfma_f32_16x16x32_bf16 v[76:79], v[168:171], v[192:195], v[76:79]
	v_mfma_f32_16x16x32_bf16 v[68:71], v[154:157], v[200:203], v[68:71]
	v_mfma_f32_16x16x32_bf16 v[64:67], v[168:171], v[200:203], v[64:67]
	v_mfma_f32_16x16x32_bf16 v[104:107], v[164:167], v[180:183], v[104:107]
	v_mfma_f32_16x16x32_bf16 v[96:99], v[172:175], v[180:183], v[96:99]
	v_mfma_f32_16x16x32_bf16 v[88:91], v[164:167], v[188:191], v[88:91]
	v_mfma_f32_16x16x32_bf16 v[84:87], v[172:175], v[188:191], v[84:87]
	v_mfma_f32_16x16x32_bf16 v[80:83], v[164:167], v[196:199], v[80:83]
	v_mfma_f32_16x16x32_bf16 v[76:79], v[172:175], v[196:199], v[76:79]
	v_mfma_f32_16x16x32_bf16 v[68:71], v[164:167], v[204:207], v[68:71]
	v_mfma_f32_16x16x32_bf16 v[64:67], v[172:175], v[204:207], v[64:67]
	s_setprio 0
	s_barrier
	s_add_i32 s36, s61, s45
	v_lshl_add_u64 v[158:159], v[158:159], 0, s[2:3]
	s_mov_b32 m0, s36
	ds_read_b128 v[176:179], v163 offset:49152
	ds_read_b128 v[180:183], v163 offset:50176
	ds_read_b128 v[184:187], v163 offset:51200
	ds_read_b128 v[188:191], v163 offset:52224
	ds_read_b128 v[192:195], v163 offset:53248
	ds_read_b128 v[196:199], v163 offset:54272
	ds_read_b128 v[200:203], v163 offset:55296
	ds_read_b128 v[204:207], v163 offset:56320
	global_load_lds_dwordx4 v[158:159], off
	s_add_i32 m0, s36, 0x2000
	s_add_u32 s34, s34, 0x200080
	v_lshl_add_u64 v[158:159], v[210:211], 0, s[2:3]
	s_addc_u32 s35, s35, 0
	s_add_i32 s36, s62, s45
	global_load_lds_dwordx4 v[158:159], off
	v_lshl_add_u64 v[158:159], s[34:35], 0, v[208:209]
	s_mov_b32 m0, s36
	s_nop 0
	global_load_lds_dwordx4 v[158:159], off
	v_lshl_add_u64 v[158:159], s[34:35], 0, v[148:149]
	s_add_i32 m0, s36, 0x2000
	s_nop 0
	global_load_lds_dwordx4 v[158:159], off
	v_lshl_add_u64 v[158:159], v[212:213], 0, s[2:3]
	s_mov_b32 m0, s51
	s_nop 0
	global_load_lds_dwordx4 v[158:159], off
	v_lshl_add_u64 v[158:159], v[214:215], 0, s[2:3]
	s_mov_b32 m0, s52
	s_nop 0
	global_load_lds_dwordx4 v[158:159], off
	s_waitcnt vmcnt(8)
	s_waitcnt lgkmcnt(0)
	s_barrier
	s_setprio 1
	s_waitcnt lgkmcnt(0)
	v_mfma_f32_16x16x32_bf16 v[60:63], v[128:131], v[176:179], v[60:63]
	v_mfma_f32_16x16x32_bf16 v[56:59], v[136:139], v[176:179], v[56:59]
	v_mfma_f32_16x16x32_bf16 v[52:55], v[128:131], v[184:187], v[52:55]
	v_mfma_f32_16x16x32_bf16 v[48:51], v[136:139], v[184:187], v[48:51]
	v_mfma_f32_16x16x32_bf16 v[44:47], v[128:131], v[192:195], v[44:47]
	v_mfma_f32_16x16x32_bf16 v[36:39], v[136:139], v[192:195], v[36:39]
	v_mfma_f32_16x16x32_bf16 v[20:23], v[128:131], v[200:203], v[20:23]
	v_mfma_f32_16x16x32_bf16 v[8:11], v[136:139], v[200:203], v[8:11]
	v_mfma_f32_16x16x32_bf16 v[60:63], v[132:135], v[180:183], v[60:63]
	v_mfma_f32_16x16x32_bf16 v[56:59], v[140:143], v[180:183], v[56:59]
	v_mfma_f32_16x16x32_bf16 v[52:55], v[132:135], v[188:191], v[52:55]
	v_mfma_f32_16x16x32_bf16 v[48:51], v[140:143], v[188:191], v[48:51]
	v_mfma_f32_16x16x32_bf16 v[44:47], v[132:135], v[196:199], v[44:47]
	v_mfma_f32_16x16x32_bf16 v[36:39], v[140:143], v[196:199], v[36:39]
	v_mfma_f32_16x16x32_bf16 v[20:23], v[132:135], v[204:207], v[20:23]
	v_mfma_f32_16x16x32_bf16 v[8:11], v[140:143], v[204:207], v[8:11]
	s_setprio 0
	s_setprio 1
	v_mfma_f32_16x16x32_bf16 v[40:43], v[154:157], v[176:179], v[40:43]
	v_mfma_f32_16x16x32_bf16 v[32:35], v[168:171], v[176:179], v[32:35]
	v_mfma_f32_16x16x32_bf16 v[28:31], v[154:157], v[184:187], v[28:31]
	v_mfma_f32_16x16x32_bf16 v[24:27], v[168:171], v[184:187], v[24:27]
	v_mfma_f32_16x16x32_bf16 v[16:19], v[154:157], v[192:195], v[16:19]
	v_mfma_f32_16x16x32_bf16 v[12:15], v[168:171], v[192:195], v[12:15]
	v_mfma_f32_16x16x32_bf16 v[4:7], v[154:157], v[200:203], v[4:7]
	v_mfma_f32_16x16x32_bf16 v[0:3], v[168:171], v[200:203], v[0:3]
	v_mfma_f32_16x16x32_bf16 v[40:43], v[164:167], v[180:183], v[40:43]
	v_mfma_f32_16x16x32_bf16 v[32:35], v[172:175], v[180:183], v[32:35]
	v_mfma_f32_16x16x32_bf16 v[28:31], v[164:167], v[188:191], v[28:31]
	v_mfma_f32_16x16x32_bf16 v[24:27], v[172:175], v[188:191], v[24:27]
	v_mfma_f32_16x16x32_bf16 v[16:19], v[164:167], v[196:199], v[16:19]
	v_mfma_f32_16x16x32_bf16 v[12:15], v[172:175], v[196:199], v[12:15]
	v_mfma_f32_16x16x32_bf16 v[4:7], v[164:167], v[204:207], v[4:7]
	v_mfma_f32_16x16x32_bf16 v[0:3], v[172:175], v[204:207], v[0:3]
	s_setprio 0
	s_barrier
	s_add_i32 s60, s60, 2
	s_add_u32 s30, s30, 0x100
	s_addc_u32 s31, s31, 0
	s_add_u32 s58, s58, 0x100
	s_addc_u32 s59, s59, 0
	s_cmpk_gt_u32 s60, 0x7d
	s_cbranch_scc0 .LBB0_1604
	s_and_b64 vcc, exec, s[8:9]
	s_cbranch_vccz .LBB0_1607
	s_barrier

.LBB0_1610:
	s_lshl_b32 s23, s28, 8
	s_lshl_b64 s[36:37], s[36:37], 2
	s_add_u32 s36, s49, s36
	v_lshl_or_b32 v128, s55, 8, v162
	s_addc_u32 s37, s50, s37
	s_add_i32 s21, s21, s23
	v_ashrrev_i32_e32 v129, 31, v128
	v_add_u32_e32 v158, s21, v160
	v_lshlrev_b64 v[154:155], 2, v[128:129]
	v_ashrrev_i32_e32 v159, 31, v158
	v_or_b32_e32 v180, 16, v158
	v_or_b32_e32 v196, 32, v158
	v_or_b32_e32 v218, 48, v158
	v_lshl_add_u64 v[156:157], s[34:35], 0, v[154:155]
	v_lshlrev_b64 v[210:211], 13, v[158:159]
	v_ashrrev_i32_e32 v181, 31, v180
	v_ashrrev_i32_e32 v197, 31, v196
	v_ashrrev_i32_e32 v219, 31, v218
	v_lshl_add_u64 v[128:129], s[36:37], 0, v[154:155]
	v_lshl_add_u64 v[176:177], v[156:157], 0, v[210:211]
	v_lshlrev_b64 v[212:213], 13, v[180:181]
	v_lshlrev_b64 v[234:235], 13, v[196:197]
	v_lshlrev_b64 v[236:237], 13, v[218:219]
	global_load_dwordx4 v[164:167], v[176:177], off
	global_load_dwordx4 v[140:143], v[128:129], off
	global_load_dwordx4 v[136:139], v[128:129], off offset:16
	global_load_dwordx4 v[168:171], v[176:177], off offset:16
	global_load_dwordx4 v[172:175], v[176:177], off offset:512
	global_load_dwordx4 v[132:135], v[128:129], off offset:512
	s_nop 0
	global_load_dwordx4 v[128:131], v[128:129], off offset:528
	s_nop 0
	global_load_dwordx4 v[176:179], v[176:177], off offset:528
	v_lshl_add_u64 v[192:193], v[156:157], 0, v[212:213]
	v_lshl_add_u64 v[214:215], v[156:157], 0, v[234:235]
	v_lshl_add_u64 v[230:231], v[156:157], 0, v[236:237]
	global_load_dwordx4 v[180:183], v[192:193], off
	global_load_dwordx4 v[184:187], v[192:193], off offset:16
	global_load_dwordx4 v[188:191], v[192:193], off offset:528
	s_nop 0
	global_load_dwordx4 v[192:195], v[192:193], off offset:512
	s_nop 0
	global_load_dwordx4 v[196:199], v[214:215], off
	global_load_dwordx4 v[200:203], v[214:215], off offset:16
	global_load_dwordx4 v[204:207], v[214:215], off offset:528
	s_nop 0
	global_load_dwordx4 v[214:217], v[214:215], off offset:512
	s_nop 0
	global_load_dwordx4 v[218:221], v[230:231], off
	global_load_dwordx4 v[222:225], v[230:231], off offset:16
	global_load_dwordx4 v[226:229], v[230:231], off offset:512
	s_nop 0
	global_load_dwordx4 v[230:233], v[230:231], off offset:528
	v_lshl_add_u64 v[154:155], s[30:31], 0, v[154:155]
	v_lshl_add_u64 v[210:211], v[154:155], 0, v[210:211]
	v_lshl_add_u64 v[212:213], v[154:155], 0, v[212:213]
	v_lshl_add_u64 v[236:237], v[154:155], 0, v[236:237]
	v_lshl_add_u64 v[234:235], v[154:155], 0, v[234:235]
	s_andn2_b64 vcc, exec, s[0:1]
	s_mov_b64 s[0:1], -1
	s_waitcnt vmcnt(0)
	v_pk_fma_f32 v[126:127], v[126:127], v[142:143], v[166:167]
	v_pk_fma_f32 v[124:125], v[124:125], v[140:141], v[164:165]
	v_pk_fma_f32 v[122:123], v[122:123], v[138:139], v[170:171]
	v_pk_fma_f32 v[120:121], v[120:121], v[136:137], v[168:169]
	v_pk_fma_f32 v[106:107], v[106:107], v[134:135], v[174:175]
	v_pk_fma_f32 v[104:105], v[104:105], v[132:133], v[172:173]
	v_pk_fma_f32 v[98:99], v[98:99], v[130:131], v[178:179]
	v_pk_fma_f32 v[96:97], v[96:97], v[128:129], v[176:177]
	global_store_dwordx4 v[210:211], v[124:127], off
	global_store_dwordx4 v[210:211], v[120:123], off offset:16
	global_store_dwordx4 v[210:211], v[104:107], off offset:512
	global_store_dwordx4 v[210:211], v[96:99], off offset:528
	v_pk_fma_f32 v[86:87], v[86:87], v[130:131], v[190:191]
	v_pk_fma_f32 v[106:107], v[114:115], v[138:139], v[186:187]
	v_pk_fma_f32 v[98:99], v[118:119], v[142:143], v[182:183]
	v_pk_fma_f32 v[96:97], v[116:117], v[140:141], v[180:181]
	v_pk_fma_f32 v[80:81], v[80:81], v[132:133], v[214:215]
	v_pk_fma_f32 v[66:67], v[66:67], v[130:131], v[232:233]
	v_pk_fma_f32 v[64:65], v[64:65], v[128:129], v[230:231]
	v_pk_fma_f32 v[104:105], v[112:113], v[136:137], v[184:185]
	v_pk_fma_f32 v[90:91], v[90:91], v[134:135], v[194:195]
	v_pk_fma_f32 v[88:89], v[88:89], v[132:133], v[192:193]
	v_pk_fma_f32 v[84:85], v[84:85], v[128:129], v[188:189]
	v_pk_fma_f32 v[110:111], v[110:111], v[142:143], v[198:199]
	v_pk_fma_f32 v[108:109], v[108:109], v[140:141], v[196:197]
	v_pk_fma_f32 v[102:103], v[102:103], v[138:139], v[202:203]
	v_pk_fma_f32 v[100:101], v[100:101], v[136:137], v[200:201]
	v_pk_fma_f32 v[82:83], v[82:83], v[134:135], v[216:217]
	v_pk_fma_f32 v[78:79], v[78:79], v[130:131], v[206:207]
	v_pk_fma_f32 v[76:77], v[76:77], v[128:129], v[204:205]
	v_pk_fma_f32 v[94:95], v[94:95], v[142:143], v[220:221]
	v_pk_fma_f32 v[92:93], v[92:93], v[140:141], v[218:219]
	global_store_dwordx4 v[212:213], v[96:99], off
	global_store_dwordx4 v[212:213], v[104:107], off offset:16
	global_store_dwordx4 v[212:213], v[88:91], off offset:512
	global_store_dwordx4 v[212:213], v[84:87], off offset:528
	global_store_dwordx4 v[234:235], v[108:111], off
	global_store_dwordx4 v[234:235], v[100:103], off offset:16
	global_store_dwordx4 v[234:235], v[80:83], off offset:512
	global_store_dwordx4 v[234:235], v[76:79], off offset:528
	global_store_dwordx4 v[236:237], v[92:95], off
	global_store_dwordx4 v[236:237], v[64:67], off offset:528
	v_add_u32_e32 v80, 0x90, v158
; #define PG8_BAR __builtin_amdgcn_s_barrier()
; template <class Epi, class Sched, bool ALIGN_EPI = false, bool SP2 = false>
; __device__ __forceinline__ void gemm_phase(PG8_LAS unsigned char* lds, const Gemm g, const Sched& S, const Epi& E, const int tid) {
;     ...
;         if constexpr (ALIGN_EPI) { if (wr == 1) PG8_BAR; }
;     __device__ __forceinline__ void operator()(const f32x4 (&acc)[2][2][4][2], const Unit& un, int wr, int wc, int fr, int fq) const {
;     ...
;         for (int ai = 0; ai < 2; ++ai) {
;             f32x4 xa[4][2][2];
; #pragma unroll
;             for (int m = 0; m < 4; ++m)
; #pragma unroll
;                 for (int bj = 0; bj < 2; ++bj) { const float* sp = src + (size_t)(rbase + ai * 128 + m * 16 - radj) * D + cw + bj * 128; xa[m][bj][0] = *(const f32x4*)sp; xa[m][bj][1] = *(const f32x4*)(sp + 4); }
; #pragma unroll
;             for (int m = 0; m < 4; ++m)
; #pragma unroll
;                 for (int bj = 0; bj < 2; ++bj) { float* dp = dst + (size_t)(rbase + ai * 128 + m * 16 - radj) * D + cw + bj * 128;
;                     *(f32x4*)dp = xa[m][bj][0] + g0[bj] * acc[ai][bj][m][0]; *(f32x4*)(dp + 4) = xa[m][bj][1] + g1[bj] * acc[ai][bj][m][1]; } }
	v_add_u32_e32 v96, 0xa0, v158
	v_add_u32_e32 v64, 0x80, v158
	v_add_u32_e32 v112, 0xb0, v158
	v_ashrrev_i32_e32 v65, 31, v64
	v_ashrrev_i32_e32 v81, 31, v80
	v_ashrrev_i32_e32 v97, 31, v96
	v_ashrrev_i32_e32 v113, 31, v112
	v_pk_fma_f32 v[74:75], v[74:75], v[138:139], v[224:225]
	v_pk_fma_f32 v[72:73], v[72:73], v[136:137], v[222:223]
	v_pk_fma_f32 v[70:71], v[70:71], v[134:135], v[228:229]
	v_pk_fma_f32 v[68:69], v[68:69], v[132:133], v[226:227]
	v_lshlrev_b64 v[164:165], 13, v[64:65]
	v_lshlrev_b64 v[166:167], 13, v[80:81]
	v_lshlrev_b64 v[168:169], 13, v[96:97]
	v_lshlrev_b64 v[158:159], 13, v[112:113]
	global_store_dwordx4 v[236:237], v[72:75], off offset:16
	global_store_dwordx4 v[236:237], v[68:71], off offset:512
	v_lshl_add_u64 v[76:77], v[156:157], 0, v[164:165]
	v_lshl_add_u64 v[92:93], v[156:157], 0, v[166:167]
	v_lshl_add_u64 v[108:109], v[156:157], 0, v[168:169]
	v_lshl_add_u64 v[124:125], v[156:157], 0, v[158:159]
	global_load_dwordx4 v[64:67], v[76:77], off
	global_load_dwordx4 v[68:71], v[76:77], off offset:16
	global_load_dwordx4 v[72:75], v[76:77], off offset:528
	s_nop 0
	global_load_dwordx4 v[76:79], v[76:77], off offset:512
	s_nop 0
	global_load_dwordx4 v[80:83], v[92:93], off
	global_load_dwordx4 v[84:87], v[92:93], off offset:16
	global_load_dwordx4 v[88:91], v[92:93], off offset:528
	s_nop 0
	global_load_dwordx4 v[92:95], v[92:93], off offset:512
	s_nop 0
	global_load_dwordx4 v[96:99], v[108:109], off
	global_load_dwordx4 v[100:103], v[108:109], off offset:16
	global_load_dwordx4 v[104:107], v[108:109], off offset:528
	s_nop 0
	global_load_dwordx4 v[108:111], v[108:109], off offset:512
	s_nop 0
	global_load_dwordx4 v[112:115], v[124:125], off
	global_load_dwordx4 v[116:119], v[124:125], off offset:16
	global_load_dwordx4 v[120:123], v[124:125], off offset:512
	s_nop 0
	global_load_dwordx4 v[124:127], v[124:125], off offset:528
	v_lshl_add_u64 v[156:157], v[154:155], 0, v[164:165]
	v_lshl_add_u64 v[164:165], v[154:155], 0, v[166:167]
	v_lshl_add_u64 v[166:167], v[154:155], 0, v[168:169]
	v_lshl_add_u64 v[154:155], v[154:155], 0, v[158:159]
	s_waitcnt vmcnt(15)
	v_pk_fma_f32 v[62:63], v[62:63], v[142:143], v[66:67]
	v_pk_fma_f32 v[60:61], v[60:61], v[140:141], v[64:65]
	s_waitcnt vmcnt(14)
	v_pk_fma_f32 v[58:59], v[58:59], v[138:139], v[70:71]
	s_waitcnt vmcnt(3)
	v_pk_fma_f32 v[22:23], v[22:23], v[142:143], v[114:115]
	v_pk_fma_f32 v[20:21], v[20:21], v[140:141], v[112:113]
	s_waitcnt vmcnt(2)
	v_pk_fma_f32 v[10:11], v[10:11], v[138:139], v[118:119]
	v_pk_fma_f32 v[8:9], v[8:9], v[136:137], v[116:117]
	s_waitcnt vmcnt(1)
	v_pk_fma_f32 v[6:7], v[6:7], v[134:135], v[122:123]
	v_pk_fma_f32 v[4:5], v[4:5], v[132:133], v[120:121]
	s_waitcnt vmcnt(0)
	v_pk_fma_f32 v[2:3], v[2:3], v[130:131], v[126:127]
	v_pk_fma_f32 v[0:1], v[0:1], v[128:129], v[124:125]
	v_pk_fma_f32 v[56:57], v[56:57], v[136:137], v[68:69]
	v_pk_fma_f32 v[42:43], v[42:43], v[134:135], v[78:79]
	v_pk_fma_f32 v[40:41], v[40:41], v[132:133], v[76:77]
	v_pk_fma_f32 v[34:35], v[34:35], v[130:131], v[74:75]
	v_pk_fma_f32 v[32:33], v[32:33], v[128:129], v[72:73]
	v_pk_fma_f32 v[54:55], v[54:55], v[142:143], v[82:83]
	v_pk_fma_f32 v[52:53], v[52:53], v[140:141], v[80:81]
	v_pk_fma_f32 v[50:51], v[50:51], v[138:139], v[86:87]
	v_pk_fma_f32 v[48:49], v[48:49], v[136:137], v[84:85]
	v_pk_fma_f32 v[30:31], v[30:31], v[134:135], v[94:95]
	v_pk_fma_f32 v[28:29], v[28:29], v[132:133], v[92:93]
	v_pk_fma_f32 v[26:27], v[26:27], v[130:131], v[90:91]
	v_pk_fma_f32 v[24:25], v[24:25], v[128:129], v[88:89]
	v_pk_fma_f32 v[46:47], v[46:47], v[142:143], v[98:99]
	v_pk_fma_f32 v[44:45], v[44:45], v[140:141], v[96:97]
	v_pk_fma_f32 v[38:39], v[38:39], v[138:139], v[102:103]
	v_pk_fma_f32 v[36:37], v[36:37], v[136:137], v[100:101]
	v_pk_fma_f32 v[18:19], v[18:19], v[134:135], v[110:111]
	v_pk_fma_f32 v[16:17], v[16:17], v[132:133], v[108:109]
	v_pk_fma_f32 v[14:15], v[14:15], v[130:131], v[106:107]
	v_pk_fma_f32 v[12:13], v[12:13], v[128:129], v[104:105]
	global_store_dwordx4 v[156:157], v[60:63], off
	global_store_dwordx4 v[156:157], v[56:59], off offset:16
	global_store_dwordx4 v[156:157], v[40:43], off offset:512
	global_store_dwordx4 v[156:157], v[32:35], off offset:528
	global_store_dwordx4 v[164:165], v[52:55], off
	global_store_dwordx4 v[164:165], v[48:51], off offset:16
	global_store_dwordx4 v[164:165], v[28:31], off offset:512
	global_store_dwordx4 v[164:165], v[24:27], off offset:528
	global_store_dwordx4 v[166:167], v[44:47], off
	global_store_dwordx4 v[166:167], v[36:39], off offset:16
	global_store_dwordx4 v[166:167], v[16:19], off offset:512
	global_store_dwordx4 v[166:167], v[12:15], off offset:528
	global_store_dwordx4 v[154:155], v[20:23], off
	global_store_dwordx4 v[154:155], v[8:11], off offset:16
	global_store_dwordx4 v[154:155], v[4:7], off offset:512
	global_store_dwordx4 v[154:155], v[0:3], off offset:528
	s_cbranch_vccnz .LBB0_1596
	s_andn2_b64 vcc, exec, s[16:17]
	s_cbranch_vccnz .LBB0_1595
	s_mov_b32 s100, 1
	s_branch .LBB0_1595

; __global__ void __launch_bounds__(512, 2) mega_fwd(Args args) {
	.amdhsa_kernel _Z8mega_fwd4Args
		.amdhsa_group_segment_fixed_size 0
		.amdhsa_private_segment_fixed_size 0
		.amdhsa_kernarg_size 552
		.amdhsa_user_sgpr_count 2
		.amdhsa_user_sgpr_dispatch_ptr 0
		.amdhsa_user_sgpr_queue_ptr 0
		.amdhsa_user_sgpr_kernarg_segment_ptr 1
		.amdhsa_user_sgpr_dispatch_id 0
		.amdhsa_user_sgpr_kernarg_preload_length 0
		.amdhsa_user_sgpr_kernarg_preload_offset 0
		.amdhsa_user_sgpr_private_segment_size 0
		.amdhsa_uses_dynamic_stack 0
		.amdhsa_enable_private_segment 0
		.amdhsa_system_sgpr_workgroup_id_x 1
		.amdhsa_system_sgpr_workgroup_id_y 0
		.amdhsa_system_sgpr_workgroup_id_z 0
		.amdhsa_system_sgpr_workgroup_info 0
		.amdhsa_system_vgpr_workitem_id 0
		.amdhsa_next_free_vgpr 256
		.amdhsa_next_free_sgpr 102
		.amdhsa_accum_offset 256
		.amdhsa_reserve_vcc 1
		.amdhsa_float_round_mode_32 0
		.amdhsa_float_round_mode_16_64 0
		.amdhsa_float_denorm_mode_32 3
		.amdhsa_float_denorm_mode_16_64 3
		.amdhsa_dx10_clamp 1
		.amdhsa_ieee_mode 1
		.amdhsa_fp16_overflow 0
		.amdhsa_tg_split 0
		.amdhsa_exception_fp_ieee_invalid_op 0
		.amdhsa_exception_fp_denorm_src 0
		.amdhsa_exception_fp_ieee_div_zero 0
		.amdhsa_exception_fp_ieee_overflow 0
		.amdhsa_exception_fp_ieee_underflow 0
		.amdhsa_exception_fp_ieee_inexact 0
		.amdhsa_exception_int_div_zero 0
	.end_amdhsa_kernel

; __global__ void __launch_bounds__(512, 2) mega_fwd(Args args) {
amdhsa.kernels:
  - .agpr_count:     0
    .args:
      - .offset:         0
        .size:           296
        .value_kind:     by_value
      - .offset:         296
        .size:           4
        .value_kind:     hidden_block_count_x
      - .offset:         300
        .size:           4
        .value_kind:     hidden_block_count_y
      - .offset:         304
        .size:           4
        .value_kind:     hidden_block_count_z
      - .offset:         308
        .size:           2
        .value_kind:     hidden_group_size_x
      - .offset:         310
        .size:           2
        .value_kind:     hidden_group_size_y
      - .offset:         312
        .size:           2
        .value_kind:     hidden_group_size_z
      - .offset:         314
        .size:           2
        .value_kind:     hidden_remainder_x
      - .offset:         316
        .size:           2
        .value_kind:     hidden_remainder_y
      - .offset:         318
        .size:           2
        .value_kind:     hidden_remainder_z
      - .offset:         336
        .size:           8
        .value_kind:     hidden_global_offset_x
      - .offset:         344
        .size:           8
        .value_kind:     hidden_global_offset_y
      - .offset:         352
        .size:           8
        .value_kind:     hidden_global_offset_z
      - .offset:         360
        .size:           2
        .value_kind:     hidden_grid_dims
      - .offset:         416
        .size:           4
        .value_kind:     hidden_dynamic_lds_size
    .group_segment_fixed_size: 0
    .kernarg_segment_align: 8
    .kernarg_segment_size: 552
    .language:       OpenCL C
    .language_version:
      - 2
      - 0
    .max_flat_workgroup_size: 512
    .name:           _Z8mega_fwd4Args
    .private_segment_fixed_size: 0
    .sgpr_count:     108
    .sgpr_spill_count: 138
    .symbol:         _Z8mega_fwd4Args.kd
    .uniform_work_group_size: 1
    .uses_dynamic_stack: false
    .vgpr_count:     256
    .vgpr_spill_count: 0
    .wavefront_size: 64
